# v1 + first K-iteration peeled with SrcC=0 (no accumulator zero-init) + no s_setprio flips in GEMM loops
# speedup vs baseline: 1.0245x; 1.0051x over previous
; #define PG8_STAGE(bufoff, gbase, voff) do { _Pragma("unroll") for (int _i = 0; _i < 2; ++_i) \
;         __builtin_amdgcn_global_load_lds((const unsigned*)((const char*)(gbase) + (voff)[_i]), (PG8_LAS unsigned*)(lds + (bufoff) + ldsw + _i * 8192), 16, 0, 0); } while (0)
; #define PG8_LDA(dst, b, h) do { _Pragma("unroll") for (int m = 0; m < 4; ++m) _Pragma("unroll") for (int k = 0; k < 2; ++k) dst[m][k] = *(const PG8_LAS bf16x8*)(lds + PG8_SA(b, h) + aoff + m * 2048 + k * 1024); } while (0)
; #define PG8_LDB(dst, b, h) do { _Pragma("unroll") for (int n = 0; n < 2; ++n) _Pragma("unroll") for (int k = 0; k < 2; ++k) dst[n][k] = *(const PG8_LAS bf16x8*)(lds + PG8_SB(b, h) + boff + n * 2048 + k * 1024); } while (0)
; #define PG8_WAIT_V(n) asm volatile("s_waitcnt vmcnt(" #n ")" ::: "memory")
; #define PG8_WAIT_L(n) asm volatile("s_waitcnt lgkmcnt(" #n ")" ::: "memory")
; #define PG8_BAR __builtin_amdgcn_s_barrier()
; template <class Epi, class Sched, bool ALIGN_EPI = false, bool SP2 = false>
; __device__ __forceinline__ void gemm_phase(PG8_LAS unsigned char* lds, const Gemm g, const Sched& S, const Epi& E) {
;     ...
;                 for (int n = 0; n < 2; ++n) acc[a][b][m][n] = (f32x4){0.f, 0.f, 0.f, 0.f};
;     ...
;         const bool has_next = S.next(ui + 1, nxt);
;         const char* nA = has_next ? (const char*)g.A + (size_t)nxt.pm * tstep : cA; const char* nB = has_next ? (const char*)g.Bt + (size_t)nxt.pn * tstep : cB;
;         for (int t = 0; t < nt; t += 2) {
;             const bool last = (t == nt - 2);
;             const char* a1 = cA + (size_t)(t + 1) * kstep;
;             const char* a2 = last ? nA : cA + (size_t)(t + 2) * kstep; const char* b2 = last ? nB : cB + (size_t)(t + 2) * kstep;
;             const char* a3 = a2 + kstep; const char* b3 = b2 + kstep;
;             if (last && has_next) S.a_ready(nxt);
;             if constexpr (SP2) {
;             PG8_LDB(B0, 0, 0); PG8_LDB(B1, 0, 1); PG8_SCHED; PG8_LDA(At, 0, 0); PG8_STAGE(PG8_SA(1, 1), a1 + hstep, voffA);
;             PG8_WAIT_V(8); PG8_WAIT_L(0); PG8_BAR; PG8_MMA(0, 0, At, B0); PG8_MMA(0, 1, At, B1); PG8_BAR; PG8_SCHED;
;             PG8_LDA(At, 0, 1); PG8_STAGE(PG8_SB(0, 0), b2, voffB); PG8_STAGE(PG8_SB(0, 1), b2 + hstep, voffB); PG8_STAGE(PG8_SA(0, 0), a2, voffA);
;             PG8_WAIT_V(8); PG8_WAIT_L(0); PG8_BAR; PG8_MMA(1, 0, At, B0); PG8_MMA(1, 1, At, B1); PG8_BAR; PG8_SCHED;
.LBB0_177:
	s_ashr_i32 s23, s22, 31
	s_lshl_b64 s[24:25], s[22:23], 19
	s_add_u32 s24, s44, s24
	s_addc_u32 s25, s45, s25
	s_and_b64 s[26:27], s[0:1], exec
	s_cselect_b32 s23, s25, s29
	s_cselect_b32 s47, s24, s28
	s_ashr_i32 s21, s20, 31
	s_lshl_b64 s[26:27], s[20:21], 19
	s_add_u32 s26, s94, s26
	s_addc_u32 s27, s95, s27
	s_and_b64 s[34:35], s[0:1], exec
	s_cselect_b32 s21, s27, s31
	s_cselect_b32 s48, s26, s30
	s_add_u32 s28, s28, 0x40080
	s_addc_u32 s29, s29, 0
	s_add_u32 s49, s30, 0x100
	s_addc_u32 s50, s31, 0
	s_mov_b32 s51, -2
	ds_read_b128 v[152:155], v148
	ds_read_b128 v[156:159], v148 offset:1024
	ds_read_b128 v[166:169], v148 offset:2048
	ds_read_b128 v[170:173], v148 offset:3072
	ds_read_b128 v[174:177], v149
	ds_read_b128 v[178:181], v149 offset:1024
	ds_read_b128 v[182:185], v149 offset:2048
	ds_read_b128 v[186:189], v149 offset:3072
	s_add_u32 s30, s28, 0xfffc0080
	s_addc_u32 s31, s29, -1
	s_cmp_eq_u32 s51, 12
	s_cselect_b32 s35, s23, s31
	s_cselect_b32 s34, s47, s30
	s_cselect_b32 s31, s21, s50
	s_cselect_b32 s30, s48, s49
	v_lshl_add_u64 v[160:161], s[28:29], 0, v[136:137]
	s_add_i32 m0, s11, 0xc000
	ds_read_b128 v[190:193], v150
	ds_read_b128 v[194:197], v150 offset:1024
	ds_read_b128 v[198:201], v150 offset:2048
	ds_read_b128 v[202:205], v150 offset:3072
	ds_read_b128 v[206:209], v150 offset:4096
	ds_read_b128 v[210:213], v150 offset:5120
	ds_read_b128 v[214:217], v150 offset:6144
	ds_read_b128 v[218:221], v150 offset:7168
	global_load_lds_dwordx4 v[160:161], off
	v_lshl_add_u64 v[160:161], s[28:29], 0, v[138:139]
	s_add_i32 m0, s11, 0xe000
	s_nop 0
	global_load_lds_dwordx4 v[160:161], off
	s_waitcnt vmcnt(8)
	s_waitcnt lgkmcnt(0)
	s_barrier
	s_waitcnt lgkmcnt(0)
	v_mfma_f32_16x16x32_bf16 v[124:127], v[152:155], v[190:193], 0
	v_mfma_f32_16x16x32_bf16 v[120:123], v[166:169], v[190:193], 0
	v_mfma_f32_16x16x32_bf16 v[116:119], v[152:155], v[198:201], 0
	v_mfma_f32_16x16x32_bf16 v[112:115], v[166:169], v[198:201], 0
	v_mfma_f32_16x16x32_bf16 v[100:103], v[152:155], v[206:209], 0
	v_mfma_f32_16x16x32_bf16 v[96:99], v[166:169], v[206:209], 0
	v_mfma_f32_16x16x32_bf16 v[84:87], v[152:155], v[214:217], 0
	v_mfma_f32_16x16x32_bf16 v[80:83], v[166:169], v[214:217], 0
	v_mfma_f32_16x16x32_bf16 v[124:127], v[156:159], v[194:197], v[124:127]
	v_mfma_f32_16x16x32_bf16 v[120:123], v[170:173], v[194:197], v[120:123]
	v_mfma_f32_16x16x32_bf16 v[116:119], v[156:159], v[202:205], v[116:119]
	v_mfma_f32_16x16x32_bf16 v[112:115], v[170:173], v[202:205], v[112:115]
	v_mfma_f32_16x16x32_bf16 v[100:103], v[156:159], v[210:213], v[100:103]
	v_mfma_f32_16x16x32_bf16 v[96:99], v[170:173], v[210:213], v[96:99]
	v_mfma_f32_16x16x32_bf16 v[84:87], v[156:159], v[218:221], v[84:87]
	v_mfma_f32_16x16x32_bf16 v[80:83], v[170:173], v[218:221], v[80:83]
	v_mfma_f32_16x16x32_bf16 v[108:111], v[174:177], v[190:193], 0
	v_mfma_f32_16x16x32_bf16 v[104:107], v[182:185], v[190:193], 0
	v_mfma_f32_16x16x32_bf16 v[92:95], v[174:177], v[198:201], 0
	v_mfma_f32_16x16x32_bf16 v[88:91], v[182:185], v[198:201], 0
	v_mfma_f32_16x16x32_bf16 v[76:79], v[174:177], v[206:209], 0
	v_mfma_f32_16x16x32_bf16 v[72:75], v[182:185], v[206:209], 0
	v_mfma_f32_16x16x32_bf16 v[68:71], v[174:177], v[214:217], 0
	v_mfma_f32_16x16x32_bf16 v[64:67], v[182:185], v[214:217], 0
	v_mfma_f32_16x16x32_bf16 v[108:111], v[178:181], v[194:197], v[108:111]
	v_mfma_f32_16x16x32_bf16 v[104:107], v[186:189], v[194:197], v[104:107]
	v_mfma_f32_16x16x32_bf16 v[92:95], v[178:181], v[202:205], v[92:95]
	v_mfma_f32_16x16x32_bf16 v[88:91], v[186:189], v[202:205], v[88:91]
	v_mfma_f32_16x16x32_bf16 v[76:79], v[178:181], v[210:213], v[76:79]
	v_mfma_f32_16x16x32_bf16 v[72:75], v[186:189], v[210:213], v[72:75]
	v_mfma_f32_16x16x32_bf16 v[68:71], v[178:181], v[218:221], v[68:71]
	v_mfma_f32_16x16x32_bf16 v[64:67], v[186:189], v[218:221], v[64:67]
	s_barrier
	s_add_i32 s52, s41, s10
	v_lshl_add_u64 v[160:161], s[30:31], 0, v[130:131]
	s_mov_b32 m0, s52
	ds_read_b128 v[190:193], v150 offset:16384
	ds_read_b128 v[194:197], v150 offset:17408
	ds_read_b128 v[198:201], v150 offset:18432
	ds_read_b128 v[202:205], v150 offset:19456
	ds_read_b128 v[206:209], v150 offset:20480
	ds_read_b128 v[210:213], v150 offset:21504
	ds_read_b128 v[214:217], v150 offset:22528
	ds_read_b128 v[218:221], v150 offset:23552
	global_load_lds_dwordx4 v[160:161], off
	s_add_i32 m0, s52, 0x2000
	s_add_u32 s52, s30, 0x40000
	v_lshl_add_u64 v[222:223], s[30:31], 0, v[134:135]
	s_addc_u32 s53, s31, 0
	s_add_i32 s54, s43, s10
	global_load_lds_dwordx4 v[222:223], off
	v_lshl_add_u64 v[224:225], s[52:53], 0, v[130:131]
	s_mov_b32 m0, s54
	v_lshl_add_u64 v[226:227], s[34:35], 0, v[132:133]
	global_load_lds_dwordx4 v[224:225], off
	v_lshl_add_u64 v[224:225], s[52:53], 0, v[134:135]
	s_add_i32 m0, s54, 0x2000
	s_nop 0
	global_load_lds_dwordx4 v[224:225], off
	v_lshl_add_u64 v[224:225], s[34:35], 0, v[128:129]
	s_mov_b32 m0, s11
	s_nop 0
	global_load_lds_dwordx4 v[224:225], off
	s_mov_b32 m0, s19
	s_nop 0
	global_load_lds_dwordx4 v[226:227], off
	s_waitcnt vmcnt(8)
	s_waitcnt lgkmcnt(0)
	s_barrier
; #define PG8_STAGE(bufoff, gbase, voff) do { _Pragma("unroll") for (int _i = 0; _i < 2; ++_i) \
;         __builtin_amdgcn_global_load_lds((const unsigned*)((const char*)(gbase) + (voff)[_i]), (PG8_LAS unsigned*)(lds + (bufoff) + ldsw + _i * 8192), 16, 0, 0); } while (0)
; #define PG8_LDA(dst, b, h) do { _Pragma("unroll") for (int m = 0; m < 4; ++m) _Pragma("unroll") for (int k = 0; k < 2; ++k) dst[m][k] = *(const PG8_LAS bf16x8*)(lds + PG8_SA(b, h) + aoff + m * 2048 + k * 1024); } while (0)
; #define PG8_LDB(dst, b, h) do { _Pragma("unroll") for (int n = 0; n < 2; ++n) _Pragma("unroll") for (int k = 0; k < 2; ++k) dst[n][k] = *(const PG8_LAS bf16x8*)(lds + PG8_SB(b, h) + boff + n * 2048 + k * 1024); } while (0)
; #define PG8_MMA(ai, bj, At, Bt) do { __builtin_amdgcn_s_setprio(1); _Pragma("unroll") for (int m = 0; m < 4; ++m) _Pragma("unroll") for (int n = 0; n < 2; ++n) _Pragma("unroll") for (int k = 0; k < 2; ++k) \
;         acc[ai][bj][m][n] = __builtin_amdgcn_mfma_f32_16x16x32_bf16(Bt[n][k], At[m][k], acc[ai][bj][m][n], 0, 0, 0); __builtin_amdgcn_s_setprio(0); } while (0)
; #define PG8_WAIT_V(n) asm volatile("s_waitcnt vmcnt(" #n ")" ::: "memory")
; #define PG8_WAIT_L(n) asm volatile("s_waitcnt lgkmcnt(" #n ")" ::: "memory")
; #define PG8_BAR __builtin_amdgcn_s_barrier()
; #define PG8_SCHED __builtin_amdgcn_sched_barrier(0)
; template <class Epi, class Sched, bool ALIGN_EPI = false, bool SP2 = false>
; __device__ __forceinline__ void gemm_phase(PG8_LAS unsigned char* lds, const Gemm g, const Sched& S, const Epi& E) {
;     ...
;             PG8_WAIT_V(8); PG8_WAIT_L(0); PG8_BAR; PG8_MMA(1, 0, At, B0); PG8_MMA(1, 1, At, B1); PG8_BAR; PG8_SCHED;
;             PG8_LDB(B0, 1, 0); PG8_LDB(B1, 1, 1); PG8_SCHED; PG8_LDA(At, 1, 0); PG8_STAGE(PG8_SA(0, 1), a2 + hstep, voffA);
;             PG8_WAIT_V(8); PG8_WAIT_L(0); PG8_BAR; PG8_MMA(0, 0, At, B0); PG8_MMA(0, 1, At, B1); PG8_BAR; PG8_SCHED;
	s_waitcnt lgkmcnt(0)
	v_mfma_f32_16x16x32_bf16 v[60:63], v[152:155], v[190:193], 0
	v_mfma_f32_16x16x32_bf16 v[56:59], v[166:169], v[190:193], 0
	v_mfma_f32_16x16x32_bf16 v[52:55], v[152:155], v[198:201], 0
	v_mfma_f32_16x16x32_bf16 v[48:51], v[166:169], v[198:201], 0
	v_mfma_f32_16x16x32_bf16 v[36:39], v[152:155], v[206:209], 0
	v_mfma_f32_16x16x32_bf16 v[32:35], v[166:169], v[206:209], 0
	v_mfma_f32_16x16x32_bf16 v[20:23], v[152:155], v[214:217], 0
	v_mfma_f32_16x16x32_bf16 v[16:19], v[166:169], v[214:217], 0
	v_mfma_f32_16x16x32_bf16 v[60:63], v[156:159], v[194:197], v[60:63]
	v_mfma_f32_16x16x32_bf16 v[56:59], v[170:173], v[194:197], v[56:59]
	v_mfma_f32_16x16x32_bf16 v[52:55], v[156:159], v[202:205], v[52:55]
	v_mfma_f32_16x16x32_bf16 v[48:51], v[170:173], v[202:205], v[48:51]
	v_mfma_f32_16x16x32_bf16 v[36:39], v[156:159], v[210:213], v[36:39]
	v_mfma_f32_16x16x32_bf16 v[32:35], v[170:173], v[210:213], v[32:35]
	v_mfma_f32_16x16x32_bf16 v[20:23], v[156:159], v[218:221], v[20:23]
	v_mfma_f32_16x16x32_bf16 v[16:19], v[170:173], v[218:221], v[16:19]
	v_mfma_f32_16x16x32_bf16 v[44:47], v[174:177], v[190:193], 0
	v_mfma_f32_16x16x32_bf16 v[40:43], v[182:185], v[190:193], 0
	v_mfma_f32_16x16x32_bf16 v[28:31], v[174:177], v[198:201], 0
	v_mfma_f32_16x16x32_bf16 v[24:27], v[182:185], v[198:201], 0
	v_mfma_f32_16x16x32_bf16 v[12:15], v[174:177], v[206:209], 0
	v_mfma_f32_16x16x32_bf16 v[8:11], v[182:185], v[206:209], 0
	v_mfma_f32_16x16x32_bf16 v[4:7], v[174:177], v[214:217], 0
	v_mfma_f32_16x16x32_bf16 v[0:3], v[182:185], v[214:217], 0
	v_mfma_f32_16x16x32_bf16 v[44:47], v[178:181], v[194:197], v[44:47]
	v_mfma_f32_16x16x32_bf16 v[40:43], v[186:189], v[194:197], v[40:43]
	v_mfma_f32_16x16x32_bf16 v[28:31], v[178:181], v[202:205], v[28:31]
	v_mfma_f32_16x16x32_bf16 v[24:27], v[186:189], v[202:205], v[24:27]
	v_mfma_f32_16x16x32_bf16 v[12:15], v[178:181], v[210:213], v[12:15]
	v_mfma_f32_16x16x32_bf16 v[8:11], v[186:189], v[210:213], v[8:11]
	v_mfma_f32_16x16x32_bf16 v[4:7], v[178:181], v[218:221], v[4:7]
	v_mfma_f32_16x16x32_bf16 v[0:3], v[186:189], v[218:221], v[0:3]
	s_barrier
	s_add_i32 s52, 0, 0x18000
	v_add_u32_e32 v151, s52, v146
	s_add_i32 s53, 0, 0x1c000
	ds_read_b128 v[152:155], v151
	ds_read_b128 v[156:159], v151 offset:1024
	ds_read_b128 v[166:169], v151 offset:2048
	ds_read_b128 v[170:173], v151 offset:3072
	v_add_u32_e32 v151, s53, v146
	ds_read_b128 v[174:177], v151
	ds_read_b128 v[178:181], v151 offset:1024
	ds_read_b128 v[182:185], v151 offset:2048
	ds_read_b128 v[186:189], v151 offset:3072
	s_add_u32 s34, s34, 0x40000
	s_addc_u32 s35, s35, 0
	s_mov_b32 m0, s33
	v_lshl_add_u64 v[228:229], s[34:35], 0, v[128:129]
	ds_read_b128 v[190:193], v150 offset:32768
	ds_read_b128 v[194:197], v150 offset:33792
	ds_read_b128 v[198:201], v150 offset:34816
	ds_read_b128 v[202:205], v150 offset:35840
	ds_read_b128 v[206:209], v150 offset:36864
	ds_read_b128 v[210:213], v150 offset:37888
	ds_read_b128 v[214:217], v150 offset:38912
	ds_read_b128 v[218:221], v150 offset:39936
	global_load_lds_dwordx4 v[228:229], off
	v_lshl_add_u64 v[228:229], s[34:35], 0, v[132:133]
	s_mov_b32 m0, s36
	s_nop 0
	global_load_lds_dwordx4 v[228:229], off
	s_waitcnt vmcnt(8)
	s_waitcnt lgkmcnt(0)
	s_barrier
	s_waitcnt lgkmcnt(0)
	v_mfma_f32_16x16x32_bf16 v[124:127], v[152:155], v[190:193], v[124:127]
	v_mfma_f32_16x16x32_bf16 v[120:123], v[166:169], v[190:193], v[120:123]
	v_mfma_f32_16x16x32_bf16 v[116:119], v[152:155], v[198:201], v[116:119]
	v_mfma_f32_16x16x32_bf16 v[112:115], v[166:169], v[198:201], v[112:115]
	v_mfma_f32_16x16x32_bf16 v[100:103], v[152:155], v[206:209], v[100:103]
	v_mfma_f32_16x16x32_bf16 v[96:99], v[166:169], v[206:209], v[96:99]
	v_mfma_f32_16x16x32_bf16 v[84:87], v[152:155], v[214:217], v[84:87]
	v_mfma_f32_16x16x32_bf16 v[80:83], v[166:169], v[214:217], v[80:83]
	v_mfma_f32_16x16x32_bf16 v[124:127], v[156:159], v[194:197], v[124:127]
	v_mfma_f32_16x16x32_bf16 v[120:123], v[170:173], v[194:197], v[120:123]
	v_mfma_f32_16x16x32_bf16 v[116:119], v[156:159], v[202:205], v[116:119]
	v_mfma_f32_16x16x32_bf16 v[112:115], v[170:173], v[202:205], v[112:115]
	v_mfma_f32_16x16x32_bf16 v[100:103], v[156:159], v[210:213], v[100:103]
	v_mfma_f32_16x16x32_bf16 v[96:99], v[170:173], v[210:213], v[96:99]
	v_mfma_f32_16x16x32_bf16 v[84:87], v[156:159], v[218:221], v[84:87]
	v_mfma_f32_16x16x32_bf16 v[80:83], v[170:173], v[218:221], v[80:83]
	v_mfma_f32_16x16x32_bf16 v[108:111], v[174:177], v[190:193], v[108:111]
	v_mfma_f32_16x16x32_bf16 v[104:107], v[182:185], v[190:193], v[104:107]
	v_mfma_f32_16x16x32_bf16 v[92:95], v[174:177], v[198:201], v[92:95]
	v_mfma_f32_16x16x32_bf16 v[88:91], v[182:185], v[198:201], v[88:91]
	v_mfma_f32_16x16x32_bf16 v[76:79], v[174:177], v[206:209], v[76:79]
	v_mfma_f32_16x16x32_bf16 v[72:75], v[182:185], v[206:209], v[72:75]
	v_mfma_f32_16x16x32_bf16 v[68:71], v[174:177], v[214:217], v[68:71]
	v_mfma_f32_16x16x32_bf16 v[64:67], v[182:185], v[214:217], v[64:67]
	v_mfma_f32_16x16x32_bf16 v[108:111], v[178:181], v[194:197], v[108:111]
	v_mfma_f32_16x16x32_bf16 v[104:107], v[186:189], v[194:197], v[104:107]
	v_mfma_f32_16x16x32_bf16 v[92:95], v[178:181], v[202:205], v[92:95]
	v_mfma_f32_16x16x32_bf16 v[88:91], v[186:189], v[202:205], v[88:91]
	v_mfma_f32_16x16x32_bf16 v[76:79], v[178:181], v[210:213], v[76:79]
	v_mfma_f32_16x16x32_bf16 v[72:75], v[186:189], v[210:213], v[72:75]
	v_mfma_f32_16x16x32_bf16 v[68:71], v[178:181], v[218:221], v[68:71]
	v_mfma_f32_16x16x32_bf16 v[64:67], v[186:189], v[218:221], v[64:67]
	s_barrier
; #define PG8_STAGE(bufoff, gbase, voff) do { _Pragma("unroll") for (int _i = 0; _i < 2; ++_i) \
;         __builtin_amdgcn_global_load_lds((const unsigned*)((const char*)(gbase) + (voff)[_i]), (PG8_LAS unsigned*)(lds + (bufoff) + ldsw + _i * 8192), 16, 0, 0); } while (0)
; #define PG8_LDA(dst, b, h) do { _Pragma("unroll") for (int m = 0; m < 4; ++m) _Pragma("unroll") for (int k = 0; k < 2; ++k) dst[m][k] = *(const PG8_LAS bf16x8*)(lds + PG8_SA(b, h) + aoff + m * 2048 + k * 1024); } while (0)
; #define PG8_LDB(dst, b, h) do { _Pragma("unroll") for (int n = 0; n < 2; ++n) _Pragma("unroll") for (int k = 0; k < 2; ++k) dst[n][k] = *(const PG8_LAS bf16x8*)(lds + PG8_SB(b, h) + boff + n * 2048 + k * 1024); } while (0)
; #define PG8_MMA(ai, bj, At, Bt) do { __builtin_amdgcn_s_setprio(1); _Pragma("unroll") for (int m = 0; m < 4; ++m) _Pragma("unroll") for (int n = 0; n < 2; ++n) _Pragma("unroll") for (int k = 0; k < 2; ++k) \
;         acc[ai][bj][m][n] = __builtin_amdgcn_mfma_f32_16x16x32_bf16(Bt[n][k], At[m][k], acc[ai][bj][m][n], 0, 0, 0); __builtin_amdgcn_s_setprio(0); } while (0)
; #define PG8_WAIT_V(n) asm volatile("s_waitcnt vmcnt(" #n ")" ::: "memory")
; #define PG8_WAIT_L(n) asm volatile("s_waitcnt lgkmcnt(" #n ")" ::: "memory")
; #define PG8_BAR __builtin_amdgcn_s_barrier()
; #define PG8_SCHED __builtin_amdgcn_sched_barrier(0)
; template <class Epi, class Sched, bool ALIGN_EPI = false, bool SP2 = false>
; __device__ __forceinline__ void gemm_phase(PG8_LAS unsigned char* lds, const Gemm g, const Sched& S, const Epi& E) {
;     ...
;         for (int t = 0; t < nt; t += 2) {
;             const bool last = (t == nt - 2);
;             const char* a1 = cA + (size_t)(t + 1) * kstep;
;             const char* a2 = last ? nA : cA + (size_t)(t + 2) * kstep; const char* b2 = last ? nB : cB + (size_t)(t + 2) * kstep;
;             const char* a3 = a2 + kstep; const char* b3 = b2 + kstep;
;             if (last && has_next) S.a_ready(nxt);
;             if constexpr (SP2) {
;             PG8_LDB(B0, 0, 0); PG8_LDB(B1, 0, 1); PG8_SCHED; PG8_LDA(At, 0, 0); PG8_STAGE(PG8_SA(1, 1), a1 + hstep, voffA);
;     ...
;             PG8_LDA(At, 1, 1); PG8_STAGE(PG8_SB(1, 0), b3, voffB); PG8_STAGE(PG8_SB(1, 1), b3 + hstep, voffB); PG8_STAGE(PG8_SA(1, 0), a3, voffA);
;             PG8_WAIT_V(8); PG8_WAIT_L(0); PG8_BAR; PG8_MMA(1, 0, At, B0); PG8_MMA(1, 1, At, B1); PG8_BAR; PG8_SCHED;
	s_add_i32 s34, s52, s10
	v_lshl_add_u64 v[160:161], v[160:161], 0, s[6:7]
	s_mov_b32 m0, s34
	ds_read_b128 v[190:193], v150 offset:49152
	ds_read_b128 v[194:197], v150 offset:50176
	ds_read_b128 v[198:201], v150 offset:51200
	ds_read_b128 v[202:205], v150 offset:52224
	ds_read_b128 v[206:209], v150 offset:53248
	ds_read_b128 v[210:213], v150 offset:54272
	ds_read_b128 v[214:217], v150 offset:55296
	ds_read_b128 v[218:221], v150 offset:56320
	global_load_lds_dwordx4 v[160:161], off
	s_add_i32 m0, s34, 0x2000
	s_add_u32 s30, s30, 0x40080
	v_lshl_add_u64 v[160:161], v[222:223], 0, s[6:7]
	s_addc_u32 s31, s31, 0
	s_add_i32 s34, s53, s10
	global_load_lds_dwordx4 v[160:161], off
	v_lshl_add_u64 v[160:161], s[30:31], 0, v[130:131]
	s_mov_b32 m0, s34
	s_nop 0
	global_load_lds_dwordx4 v[160:161], off
	v_lshl_add_u64 v[160:161], s[30:31], 0, v[134:135]
	s_add_i32 m0, s34, 0x2000
	s_nop 0
	global_load_lds_dwordx4 v[160:161], off
	v_lshl_add_u64 v[160:161], v[224:225], 0, s[6:7]
	s_mov_b32 m0, s38
	s_nop 0
	global_load_lds_dwordx4 v[160:161], off
	v_lshl_add_u64 v[160:161], v[226:227], 0, s[6:7]
	s_mov_b32 m0, s39
	s_nop 0
	global_load_lds_dwordx4 v[160:161], off
	s_waitcnt vmcnt(8)
	s_waitcnt lgkmcnt(0)
	s_barrier
	s_waitcnt lgkmcnt(0)
	v_mfma_f32_16x16x32_bf16 v[60:63], v[152:155], v[190:193], v[60:63]
	v_mfma_f32_16x16x32_bf16 v[56:59], v[166:169], v[190:193], v[56:59]
	v_mfma_f32_16x16x32_bf16 v[52:55], v[152:155], v[198:201], v[52:55]
	v_mfma_f32_16x16x32_bf16 v[48:51], v[166:169], v[198:201], v[48:51]
	v_mfma_f32_16x16x32_bf16 v[36:39], v[152:155], v[206:209], v[36:39]
	v_mfma_f32_16x16x32_bf16 v[32:35], v[166:169], v[206:209], v[32:35]
	v_mfma_f32_16x16x32_bf16 v[20:23], v[152:155], v[214:217], v[20:23]
	v_mfma_f32_16x16x32_bf16 v[16:19], v[166:169], v[214:217], v[16:19]
	v_mfma_f32_16x16x32_bf16 v[60:63], v[156:159], v[194:197], v[60:63]
	v_mfma_f32_16x16x32_bf16 v[56:59], v[170:173], v[194:197], v[56:59]
	v_mfma_f32_16x16x32_bf16 v[52:55], v[156:159], v[202:205], v[52:55]
	v_mfma_f32_16x16x32_bf16 v[48:51], v[170:173], v[202:205], v[48:51]
	v_mfma_f32_16x16x32_bf16 v[36:39], v[156:159], v[210:213], v[36:39]
	v_mfma_f32_16x16x32_bf16 v[32:35], v[170:173], v[210:213], v[32:35]
	v_mfma_f32_16x16x32_bf16 v[20:23], v[156:159], v[218:221], v[20:23]
	v_mfma_f32_16x16x32_bf16 v[16:19], v[170:173], v[218:221], v[16:19]
	v_mfma_f32_16x16x32_bf16 v[44:47], v[174:177], v[190:193], v[44:47]
	v_mfma_f32_16x16x32_bf16 v[40:43], v[182:185], v[190:193], v[40:43]
	v_mfma_f32_16x16x32_bf16 v[28:31], v[174:177], v[198:201], v[28:31]
	v_mfma_f32_16x16x32_bf16 v[24:27], v[182:185], v[198:201], v[24:27]
	v_mfma_f32_16x16x32_bf16 v[12:15], v[174:177], v[206:209], v[12:15]
	v_mfma_f32_16x16x32_bf16 v[8:11], v[182:185], v[206:209], v[8:11]
	v_mfma_f32_16x16x32_bf16 v[4:7], v[174:177], v[214:217], v[4:7]
	v_mfma_f32_16x16x32_bf16 v[0:3], v[182:185], v[214:217], v[0:3]
	v_mfma_f32_16x16x32_bf16 v[44:47], v[178:181], v[194:197], v[44:47]
	v_mfma_f32_16x16x32_bf16 v[40:43], v[186:189], v[194:197], v[40:43]
	v_mfma_f32_16x16x32_bf16 v[28:31], v[178:181], v[202:205], v[28:31]
	v_mfma_f32_16x16x32_bf16 v[24:27], v[186:189], v[202:205], v[24:27]
	v_mfma_f32_16x16x32_bf16 v[12:15], v[178:181], v[210:213], v[12:15]
	v_mfma_f32_16x16x32_bf16 v[8:11], v[186:189], v[210:213], v[8:11]
	v_mfma_f32_16x16x32_bf16 v[4:7], v[178:181], v[218:221], v[4:7]
	v_mfma_f32_16x16x32_bf16 v[0:3], v[186:189], v[218:221], v[0:3]
	s_barrier
	s_add_i32 s51, s51, 2
	s_add_u32 s28, s28, 0x100
	s_addc_u32 s29, s29, 0
	s_add_u32 s49, s49, 0x100
	s_addc_u32 s50, s50, 0
	s_cmp_gt_u32 s51, 13
	s_cbranch_scc1 .Lpeel_exit0
.LBB0_178:
	ds_read_b128 v[152:155], v148
	ds_read_b128 v[156:159], v148 offset:1024
	ds_read_b128 v[166:169], v148 offset:2048
	ds_read_b128 v[170:173], v148 offset:3072
	ds_read_b128 v[174:177], v149
	ds_read_b128 v[178:181], v149 offset:1024
	ds_read_b128 v[182:185], v149 offset:2048
	ds_read_b128 v[186:189], v149 offset:3072
	s_add_u32 s30, s28, 0xfffc0080
	s_addc_u32 s31, s29, -1
	s_cmp_eq_u32 s51, 12
	s_cselect_b32 s35, s23, s31
	s_cselect_b32 s34, s47, s30
	s_cselect_b32 s31, s21, s50
	s_cselect_b32 s30, s48, s49
	v_lshl_add_u64 v[160:161], s[28:29], 0, v[136:137]
	s_add_i32 m0, s11, 0xc000
	ds_read_b128 v[190:193], v150
	ds_read_b128 v[194:197], v150 offset:1024
	ds_read_b128 v[198:201], v150 offset:2048
	ds_read_b128 v[202:205], v150 offset:3072
	ds_read_b128 v[206:209], v150 offset:4096
	ds_read_b128 v[210:213], v150 offset:5120
	ds_read_b128 v[214:217], v150 offset:6144
	ds_read_b128 v[218:221], v150 offset:7168
	global_load_lds_dwordx4 v[160:161], off
	v_lshl_add_u64 v[160:161], s[28:29], 0, v[138:139]
	s_add_i32 m0, s11, 0xe000
	s_nop 0
	global_load_lds_dwordx4 v[160:161], off
	s_waitcnt vmcnt(8)
	s_waitcnt lgkmcnt(0)
	s_barrier
; #define PG8_STAGE(bufoff, gbase, voff) do { _Pragma("unroll") for (int _i = 0; _i < 2; ++_i) \
;         __builtin_amdgcn_global_load_lds((const unsigned*)((const char*)(gbase) + (voff)[_i]), (PG8_LAS unsigned*)(lds + (bufoff) + ldsw + _i * 8192), 16, 0, 0); } while (0)
; #define PG8_LDA(dst, b, h) do { _Pragma("unroll") for (int m = 0; m < 4; ++m) _Pragma("unroll") for (int k = 0; k < 2; ++k) dst[m][k] = *(const PG8_LAS bf16x8*)(lds + PG8_SA(b, h) + aoff + m * 2048 + k * 1024); } while (0)
; #define PG8_LDB(dst, b, h) do { _Pragma("unroll") for (int n = 0; n < 2; ++n) _Pragma("unroll") for (int k = 0; k < 2; ++k) dst[n][k] = *(const PG8_LAS bf16x8*)(lds + PG8_SB(b, h) + boff + n * 2048 + k * 1024); } while (0)
; #define PG8_MMA(ai, bj, At, Bt) do { __builtin_amdgcn_s_setprio(1); _Pragma("unroll") for (int m = 0; m < 4; ++m) _Pragma("unroll") for (int n = 0; n < 2; ++n) _Pragma("unroll") for (int k = 0; k < 2; ++k) \
;         acc[ai][bj][m][n] = __builtin_amdgcn_mfma_f32_16x16x32_bf16(Bt[n][k], At[m][k], acc[ai][bj][m][n], 0, 0, 0); __builtin_amdgcn_s_setprio(0); } while (0)
; #define PG8_WAIT_V(n) asm volatile("s_waitcnt vmcnt(" #n ")" ::: "memory")
; #define PG8_WAIT_L(n) asm volatile("s_waitcnt lgkmcnt(" #n ")" ::: "memory")
; #define PG8_BAR __builtin_amdgcn_s_barrier()
; #define PG8_SCHED __builtin_amdgcn_sched_barrier(0)
; template <class Epi, class Sched, bool ALIGN_EPI = false, bool SP2 = false>
; __device__ __forceinline__ void gemm_phase(PG8_LAS unsigned char* lds, const Gemm g, const Sched& S, const Epi& E) {
;     ...
;             PG8_LDB(B0, 0, 0); PG8_LDB(B1, 0, 1); PG8_SCHED; PG8_LDA(At, 0, 0); PG8_STAGE(PG8_SA(1, 1), a1 + hstep, voffA);
;             PG8_WAIT_V(8); PG8_WAIT_L(0); PG8_BAR; PG8_MMA(0, 0, At, B0); PG8_MMA(0, 1, At, B1); PG8_BAR; PG8_SCHED;
;             PG8_LDA(At, 0, 1); PG8_STAGE(PG8_SB(0, 0), b2, voffB); PG8_STAGE(PG8_SB(0, 1), b2 + hstep, voffB); PG8_STAGE(PG8_SA(0, 0), a2, voffA);
;             PG8_WAIT_V(8); PG8_WAIT_L(0); PG8_BAR; PG8_MMA(1, 0, At, B0); PG8_MMA(1, 1, At, B1); PG8_BAR; PG8_SCHED;
;             PG8_LDB(B0, 1, 0); PG8_LDB(B1, 1, 1); PG8_SCHED; PG8_LDA(At, 1, 0); PG8_STAGE(PG8_SA(0, 1), a2 + hstep, voffA);
;             PG8_WAIT_V(8); PG8_WAIT_L(0); PG8_BAR; PG8_MMA(0, 0, At, B0); PG8_MMA(0, 1, At, B1); PG8_BAR; PG8_SCHED;
	s_waitcnt lgkmcnt(0)
	v_mfma_f32_16x16x32_bf16 v[124:127], v[152:155], v[190:193], v[124:127]
	v_mfma_f32_16x16x32_bf16 v[120:123], v[166:169], v[190:193], v[120:123]
	v_mfma_f32_16x16x32_bf16 v[116:119], v[152:155], v[198:201], v[116:119]
	v_mfma_f32_16x16x32_bf16 v[112:115], v[166:169], v[198:201], v[112:115]
	v_mfma_f32_16x16x32_bf16 v[100:103], v[152:155], v[206:209], v[100:103]
	v_mfma_f32_16x16x32_bf16 v[96:99], v[166:169], v[206:209], v[96:99]
	v_mfma_f32_16x16x32_bf16 v[84:87], v[152:155], v[214:217], v[84:87]
	v_mfma_f32_16x16x32_bf16 v[80:83], v[166:169], v[214:217], v[80:83]
	v_mfma_f32_16x16x32_bf16 v[124:127], v[156:159], v[194:197], v[124:127]
	v_mfma_f32_16x16x32_bf16 v[120:123], v[170:173], v[194:197], v[120:123]
	v_mfma_f32_16x16x32_bf16 v[116:119], v[156:159], v[202:205], v[116:119]
	v_mfma_f32_16x16x32_bf16 v[112:115], v[170:173], v[202:205], v[112:115]
	v_mfma_f32_16x16x32_bf16 v[100:103], v[156:159], v[210:213], v[100:103]
	v_mfma_f32_16x16x32_bf16 v[96:99], v[170:173], v[210:213], v[96:99]
	v_mfma_f32_16x16x32_bf16 v[84:87], v[156:159], v[218:221], v[84:87]
	v_mfma_f32_16x16x32_bf16 v[80:83], v[170:173], v[218:221], v[80:83]
	v_mfma_f32_16x16x32_bf16 v[108:111], v[174:177], v[190:193], v[108:111]
	v_mfma_f32_16x16x32_bf16 v[104:107], v[182:185], v[190:193], v[104:107]
	v_mfma_f32_16x16x32_bf16 v[92:95], v[174:177], v[198:201], v[92:95]
	v_mfma_f32_16x16x32_bf16 v[88:91], v[182:185], v[198:201], v[88:91]
	v_mfma_f32_16x16x32_bf16 v[76:79], v[174:177], v[206:209], v[76:79]
	v_mfma_f32_16x16x32_bf16 v[72:75], v[182:185], v[206:209], v[72:75]
	v_mfma_f32_16x16x32_bf16 v[68:71], v[174:177], v[214:217], v[68:71]
	v_mfma_f32_16x16x32_bf16 v[64:67], v[182:185], v[214:217], v[64:67]
	v_mfma_f32_16x16x32_bf16 v[108:111], v[178:181], v[194:197], v[108:111]
	v_mfma_f32_16x16x32_bf16 v[104:107], v[186:189], v[194:197], v[104:107]
	v_mfma_f32_16x16x32_bf16 v[92:95], v[178:181], v[202:205], v[92:95]
	v_mfma_f32_16x16x32_bf16 v[88:91], v[186:189], v[202:205], v[88:91]
	v_mfma_f32_16x16x32_bf16 v[76:79], v[178:181], v[210:213], v[76:79]
	v_mfma_f32_16x16x32_bf16 v[72:75], v[186:189], v[210:213], v[72:75]
	v_mfma_f32_16x16x32_bf16 v[68:71], v[178:181], v[218:221], v[68:71]
	v_mfma_f32_16x16x32_bf16 v[64:67], v[186:189], v[218:221], v[64:67]
	s_barrier
	s_add_i32 s52, s41, s10
	v_lshl_add_u64 v[160:161], s[30:31], 0, v[130:131]
	s_mov_b32 m0, s52
	ds_read_b128 v[190:193], v150 offset:16384
	ds_read_b128 v[194:197], v150 offset:17408
	ds_read_b128 v[198:201], v150 offset:18432
	ds_read_b128 v[202:205], v150 offset:19456
	ds_read_b128 v[206:209], v150 offset:20480
	ds_read_b128 v[210:213], v150 offset:21504
	ds_read_b128 v[214:217], v150 offset:22528
	ds_read_b128 v[218:221], v150 offset:23552
	global_load_lds_dwordx4 v[160:161], off
	s_add_i32 m0, s52, 0x2000
	s_add_u32 s52, s30, 0x40000
	v_lshl_add_u64 v[222:223], s[30:31], 0, v[134:135]
	s_addc_u32 s53, s31, 0
	s_add_i32 s54, s43, s10
	global_load_lds_dwordx4 v[222:223], off
	v_lshl_add_u64 v[224:225], s[52:53], 0, v[130:131]
	s_mov_b32 m0, s54
	v_lshl_add_u64 v[226:227], s[34:35], 0, v[132:133]
	global_load_lds_dwordx4 v[224:225], off
	v_lshl_add_u64 v[224:225], s[52:53], 0, v[134:135]
	s_add_i32 m0, s54, 0x2000
	s_nop 0
	global_load_lds_dwordx4 v[224:225], off
	v_lshl_add_u64 v[224:225], s[34:35], 0, v[128:129]
	s_mov_b32 m0, s11
	s_nop 0
	global_load_lds_dwordx4 v[224:225], off
	s_mov_b32 m0, s19
	s_nop 0
	global_load_lds_dwordx4 v[226:227], off
	s_waitcnt vmcnt(8)
	s_waitcnt lgkmcnt(0)
	s_barrier
	s_waitcnt lgkmcnt(0)
	v_mfma_f32_16x16x32_bf16 v[60:63], v[152:155], v[190:193], v[60:63]
	v_mfma_f32_16x16x32_bf16 v[56:59], v[166:169], v[190:193], v[56:59]
	v_mfma_f32_16x16x32_bf16 v[52:55], v[152:155], v[198:201], v[52:55]
	v_mfma_f32_16x16x32_bf16 v[48:51], v[166:169], v[198:201], v[48:51]
	v_mfma_f32_16x16x32_bf16 v[36:39], v[152:155], v[206:209], v[36:39]
	v_mfma_f32_16x16x32_bf16 v[32:35], v[166:169], v[206:209], v[32:35]
	v_mfma_f32_16x16x32_bf16 v[20:23], v[152:155], v[214:217], v[20:23]
	v_mfma_f32_16x16x32_bf16 v[16:19], v[166:169], v[214:217], v[16:19]
	v_mfma_f32_16x16x32_bf16 v[60:63], v[156:159], v[194:197], v[60:63]
	v_mfma_f32_16x16x32_bf16 v[56:59], v[170:173], v[194:197], v[56:59]
	v_mfma_f32_16x16x32_bf16 v[52:55], v[156:159], v[202:205], v[52:55]
	v_mfma_f32_16x16x32_bf16 v[48:51], v[170:173], v[202:205], v[48:51]
	v_mfma_f32_16x16x32_bf16 v[36:39], v[156:159], v[210:213], v[36:39]
	v_mfma_f32_16x16x32_bf16 v[32:35], v[170:173], v[210:213], v[32:35]
	v_mfma_f32_16x16x32_bf16 v[20:23], v[156:159], v[218:221], v[20:23]
	v_mfma_f32_16x16x32_bf16 v[16:19], v[170:173], v[218:221], v[16:19]
	v_mfma_f32_16x16x32_bf16 v[44:47], v[174:177], v[190:193], v[44:47]
	v_mfma_f32_16x16x32_bf16 v[40:43], v[182:185], v[190:193], v[40:43]
	v_mfma_f32_16x16x32_bf16 v[28:31], v[174:177], v[198:201], v[28:31]
	v_mfma_f32_16x16x32_bf16 v[24:27], v[182:185], v[198:201], v[24:27]
	v_mfma_f32_16x16x32_bf16 v[12:15], v[174:177], v[206:209], v[12:15]
	v_mfma_f32_16x16x32_bf16 v[8:11], v[182:185], v[206:209], v[8:11]
	v_mfma_f32_16x16x32_bf16 v[4:7], v[174:177], v[214:217], v[4:7]
	v_mfma_f32_16x16x32_bf16 v[0:3], v[182:185], v[214:217], v[0:3]
	v_mfma_f32_16x16x32_bf16 v[44:47], v[178:181], v[194:197], v[44:47]
	v_mfma_f32_16x16x32_bf16 v[40:43], v[186:189], v[194:197], v[40:43]
	v_mfma_f32_16x16x32_bf16 v[28:31], v[178:181], v[202:205], v[28:31]
	v_mfma_f32_16x16x32_bf16 v[24:27], v[186:189], v[202:205], v[24:27]
	v_mfma_f32_16x16x32_bf16 v[12:15], v[178:181], v[210:213], v[12:15]
	v_mfma_f32_16x16x32_bf16 v[8:11], v[186:189], v[210:213], v[8:11]
	v_mfma_f32_16x16x32_bf16 v[4:7], v[178:181], v[218:221], v[4:7]
	v_mfma_f32_16x16x32_bf16 v[0:3], v[186:189], v[218:221], v[0:3]
	s_barrier
; #define PG8_STAGE(bufoff, gbase, voff) do { _Pragma("unroll") for (int _i = 0; _i < 2; ++_i) \
;         __builtin_amdgcn_global_load_lds((const unsigned*)((const char*)(gbase) + (voff)[_i]), (PG8_LAS unsigned*)(lds + (bufoff) + ldsw + _i * 8192), 16, 0, 0); } while (0)
; #define PG8_LDA(dst, b, h) do { _Pragma("unroll") for (int m = 0; m < 4; ++m) _Pragma("unroll") for (int k = 0; k < 2; ++k) dst[m][k] = *(const PG8_LAS bf16x8*)(lds + PG8_SA(b, h) + aoff + m * 2048 + k * 1024); } while (0)
; #define PG8_LDB(dst, b, h) do { _Pragma("unroll") for (int n = 0; n < 2; ++n) _Pragma("unroll") for (int k = 0; k < 2; ++k) dst[n][k] = *(const PG8_LAS bf16x8*)(lds + PG8_SB(b, h) + boff + n * 2048 + k * 1024); } while (0)
; #define PG8_MMA(ai, bj, At, Bt) do { __builtin_amdgcn_s_setprio(1); _Pragma("unroll") for (int m = 0; m < 4; ++m) _Pragma("unroll") for (int n = 0; n < 2; ++n) _Pragma("unroll") for (int k = 0; k < 2; ++k) \
;         acc[ai][bj][m][n] = __builtin_amdgcn_mfma_f32_16x16x32_bf16(Bt[n][k], At[m][k], acc[ai][bj][m][n], 0, 0, 0); __builtin_amdgcn_s_setprio(0); } while (0)
; #define PG8_WAIT_V(n) asm volatile("s_waitcnt vmcnt(" #n ")" ::: "memory")
; #define PG8_WAIT_L(n) asm volatile("s_waitcnt lgkmcnt(" #n ")" ::: "memory")
; #define PG8_BAR __builtin_amdgcn_s_barrier()
; #define PG8_SCHED __builtin_amdgcn_sched_barrier(0)
; template <class Epi, class Sched, bool ALIGN_EPI = false, bool SP2 = false>
; __device__ __forceinline__ void gemm_phase(PG8_LAS unsigned char* lds, const Gemm g, const Sched& S, const Epi& E) {
;     ...
;         for (int t = 0; t < nt; t += 2) {
;     ...
;             PG8_LDB(B0, 1, 0); PG8_LDB(B1, 1, 1); PG8_SCHED; PG8_LDA(At, 1, 0); PG8_STAGE(PG8_SA(0, 1), a2 + hstep, voffA);
;             PG8_WAIT_V(8); PG8_WAIT_L(0); PG8_BAR; PG8_MMA(0, 0, At, B0); PG8_MMA(0, 1, At, B1); PG8_BAR; PG8_SCHED;
;             PG8_LDA(At, 1, 1); PG8_STAGE(PG8_SB(1, 0), b3, voffB); PG8_STAGE(PG8_SB(1, 1), b3 + hstep, voffB); PG8_STAGE(PG8_SA(1, 0), a3, voffA);
;             PG8_WAIT_V(8); PG8_WAIT_L(0); PG8_BAR; PG8_MMA(1, 0, At, B0); PG8_MMA(1, 1, At, B1); PG8_BAR; PG8_SCHED;
	s_add_i32 s52, 0, 0x18000
	v_add_u32_e32 v151, s52, v146
	s_add_i32 s53, 0, 0x1c000
	ds_read_b128 v[152:155], v151
	ds_read_b128 v[156:159], v151 offset:1024
	ds_read_b128 v[166:169], v151 offset:2048
	ds_read_b128 v[170:173], v151 offset:3072
	v_add_u32_e32 v151, s53, v146
	ds_read_b128 v[174:177], v151
	ds_read_b128 v[178:181], v151 offset:1024
	ds_read_b128 v[182:185], v151 offset:2048
	ds_read_b128 v[186:189], v151 offset:3072
	s_add_u32 s34, s34, 0x40000
	s_addc_u32 s35, s35, 0
	s_mov_b32 m0, s33
	v_lshl_add_u64 v[228:229], s[34:35], 0, v[128:129]
	ds_read_b128 v[190:193], v150 offset:32768
	ds_read_b128 v[194:197], v150 offset:33792
	ds_read_b128 v[198:201], v150 offset:34816
	ds_read_b128 v[202:205], v150 offset:35840
	ds_read_b128 v[206:209], v150 offset:36864
	ds_read_b128 v[210:213], v150 offset:37888
	ds_read_b128 v[214:217], v150 offset:38912
	ds_read_b128 v[218:221], v150 offset:39936
	global_load_lds_dwordx4 v[228:229], off
	v_lshl_add_u64 v[228:229], s[34:35], 0, v[132:133]
	s_mov_b32 m0, s36
	s_nop 0
	global_load_lds_dwordx4 v[228:229], off
	s_waitcnt vmcnt(8)
	s_waitcnt lgkmcnt(0)
	s_barrier
	s_waitcnt lgkmcnt(0)
	v_mfma_f32_16x16x32_bf16 v[124:127], v[152:155], v[190:193], v[124:127]
	v_mfma_f32_16x16x32_bf16 v[120:123], v[166:169], v[190:193], v[120:123]
	v_mfma_f32_16x16x32_bf16 v[116:119], v[152:155], v[198:201], v[116:119]
	v_mfma_f32_16x16x32_bf16 v[112:115], v[166:169], v[198:201], v[112:115]
	v_mfma_f32_16x16x32_bf16 v[100:103], v[152:155], v[206:209], v[100:103]
	v_mfma_f32_16x16x32_bf16 v[96:99], v[166:169], v[206:209], v[96:99]
	v_mfma_f32_16x16x32_bf16 v[84:87], v[152:155], v[214:217], v[84:87]
	v_mfma_f32_16x16x32_bf16 v[80:83], v[166:169], v[214:217], v[80:83]
	v_mfma_f32_16x16x32_bf16 v[124:127], v[156:159], v[194:197], v[124:127]
	v_mfma_f32_16x16x32_bf16 v[120:123], v[170:173], v[194:197], v[120:123]
	v_mfma_f32_16x16x32_bf16 v[116:119], v[156:159], v[202:205], v[116:119]
	v_mfma_f32_16x16x32_bf16 v[112:115], v[170:173], v[202:205], v[112:115]
	v_mfma_f32_16x16x32_bf16 v[100:103], v[156:159], v[210:213], v[100:103]
	v_mfma_f32_16x16x32_bf16 v[96:99], v[170:173], v[210:213], v[96:99]
	v_mfma_f32_16x16x32_bf16 v[84:87], v[156:159], v[218:221], v[84:87]
	v_mfma_f32_16x16x32_bf16 v[80:83], v[170:173], v[218:221], v[80:83]
	v_mfma_f32_16x16x32_bf16 v[108:111], v[174:177], v[190:193], v[108:111]
	v_mfma_f32_16x16x32_bf16 v[104:107], v[182:185], v[190:193], v[104:107]
	v_mfma_f32_16x16x32_bf16 v[92:95], v[174:177], v[198:201], v[92:95]
	v_mfma_f32_16x16x32_bf16 v[88:91], v[182:185], v[198:201], v[88:91]
	v_mfma_f32_16x16x32_bf16 v[76:79], v[174:177], v[206:209], v[76:79]
	v_mfma_f32_16x16x32_bf16 v[72:75], v[182:185], v[206:209], v[72:75]
	v_mfma_f32_16x16x32_bf16 v[68:71], v[174:177], v[214:217], v[68:71]
	v_mfma_f32_16x16x32_bf16 v[64:67], v[182:185], v[214:217], v[64:67]
	v_mfma_f32_16x16x32_bf16 v[108:111], v[178:181], v[194:197], v[108:111]
	v_mfma_f32_16x16x32_bf16 v[104:107], v[186:189], v[194:197], v[104:107]
	v_mfma_f32_16x16x32_bf16 v[92:95], v[178:181], v[202:205], v[92:95]
	v_mfma_f32_16x16x32_bf16 v[88:91], v[186:189], v[202:205], v[88:91]
	v_mfma_f32_16x16x32_bf16 v[76:79], v[178:181], v[210:213], v[76:79]
	v_mfma_f32_16x16x32_bf16 v[72:75], v[186:189], v[210:213], v[72:75]
	v_mfma_f32_16x16x32_bf16 v[68:71], v[178:181], v[218:221], v[68:71]
	v_mfma_f32_16x16x32_bf16 v[64:67], v[186:189], v[218:221], v[64:67]
	s_barrier
	s_add_i32 s34, s52, s10
	v_lshl_add_u64 v[160:161], v[160:161], 0, s[6:7]
	s_mov_b32 m0, s34
	ds_read_b128 v[190:193], v150 offset:49152
	ds_read_b128 v[194:197], v150 offset:50176
	ds_read_b128 v[198:201], v150 offset:51200
	ds_read_b128 v[202:205], v150 offset:52224
	ds_read_b128 v[206:209], v150 offset:53248
	ds_read_b128 v[210:213], v150 offset:54272
	ds_read_b128 v[214:217], v150 offset:55296
	ds_read_b128 v[218:221], v150 offset:56320
	global_load_lds_dwordx4 v[160:161], off
	s_add_i32 m0, s34, 0x2000
	s_add_u32 s30, s30, 0x40080
	v_lshl_add_u64 v[160:161], v[222:223], 0, s[6:7]
	s_addc_u32 s31, s31, 0
	s_add_i32 s34, s53, s10
	global_load_lds_dwordx4 v[160:161], off
	v_lshl_add_u64 v[160:161], s[30:31], 0, v[130:131]
	s_mov_b32 m0, s34
	s_nop 0
	global_load_lds_dwordx4 v[160:161], off
	v_lshl_add_u64 v[160:161], s[30:31], 0, v[134:135]
	s_add_i32 m0, s34, 0x2000
	s_nop 0
	global_load_lds_dwordx4 v[160:161], off
	v_lshl_add_u64 v[160:161], v[224:225], 0, s[6:7]
	s_mov_b32 m0, s38
	s_nop 0
	global_load_lds_dwordx4 v[160:161], off
	v_lshl_add_u64 v[160:161], v[226:227], 0, s[6:7]
	s_mov_b32 m0, s39
	s_nop 0
	global_load_lds_dwordx4 v[160:161], off
	s_waitcnt vmcnt(8)
	s_waitcnt lgkmcnt(0)
	s_barrier
	s_waitcnt lgkmcnt(0)
	v_mfma_f32_16x16x32_bf16 v[60:63], v[152:155], v[190:193], v[60:63]
	v_mfma_f32_16x16x32_bf16 v[56:59], v[166:169], v[190:193], v[56:59]
	v_mfma_f32_16x16x32_bf16 v[52:55], v[152:155], v[198:201], v[52:55]
	v_mfma_f32_16x16x32_bf16 v[48:51], v[166:169], v[198:201], v[48:51]
	v_mfma_f32_16x16x32_bf16 v[36:39], v[152:155], v[206:209], v[36:39]
	v_mfma_f32_16x16x32_bf16 v[32:35], v[166:169], v[206:209], v[32:35]
	v_mfma_f32_16x16x32_bf16 v[20:23], v[152:155], v[214:217], v[20:23]
	v_mfma_f32_16x16x32_bf16 v[16:19], v[166:169], v[214:217], v[16:19]
	v_mfma_f32_16x16x32_bf16 v[60:63], v[156:159], v[194:197], v[60:63]
	v_mfma_f32_16x16x32_bf16 v[56:59], v[170:173], v[194:197], v[56:59]
	v_mfma_f32_16x16x32_bf16 v[52:55], v[156:159], v[202:205], v[52:55]
	v_mfma_f32_16x16x32_bf16 v[48:51], v[170:173], v[202:205], v[48:51]
	v_mfma_f32_16x16x32_bf16 v[36:39], v[156:159], v[210:213], v[36:39]
	v_mfma_f32_16x16x32_bf16 v[32:35], v[170:173], v[210:213], v[32:35]
	v_mfma_f32_16x16x32_bf16 v[20:23], v[156:159], v[218:221], v[20:23]
	v_mfma_f32_16x16x32_bf16 v[16:19], v[170:173], v[218:221], v[16:19]
	v_mfma_f32_16x16x32_bf16 v[44:47], v[174:177], v[190:193], v[44:47]
	v_mfma_f32_16x16x32_bf16 v[40:43], v[182:185], v[190:193], v[40:43]
	v_mfma_f32_16x16x32_bf16 v[28:31], v[174:177], v[198:201], v[28:31]
	v_mfma_f32_16x16x32_bf16 v[24:27], v[182:185], v[198:201], v[24:27]
	v_mfma_f32_16x16x32_bf16 v[12:15], v[174:177], v[206:209], v[12:15]
	v_mfma_f32_16x16x32_bf16 v[8:11], v[182:185], v[206:209], v[8:11]
	v_mfma_f32_16x16x32_bf16 v[4:7], v[174:177], v[214:217], v[4:7]
	v_mfma_f32_16x16x32_bf16 v[0:3], v[182:185], v[214:217], v[0:3]
	v_mfma_f32_16x16x32_bf16 v[44:47], v[178:181], v[194:197], v[44:47]
	v_mfma_f32_16x16x32_bf16 v[40:43], v[186:189], v[194:197], v[40:43]
	v_mfma_f32_16x16x32_bf16 v[28:31], v[178:181], v[202:205], v[28:31]
	v_mfma_f32_16x16x32_bf16 v[24:27], v[186:189], v[202:205], v[24:27]
	v_mfma_f32_16x16x32_bf16 v[12:15], v[178:181], v[210:213], v[12:15]
	v_mfma_f32_16x16x32_bf16 v[8:11], v[186:189], v[210:213], v[8:11]
	v_mfma_f32_16x16x32_bf16 v[4:7], v[178:181], v[218:221], v[4:7]
	v_mfma_f32_16x16x32_bf16 v[0:3], v[186:189], v[218:221], v[0:3]
	s_barrier
	s_add_i32 s51, s51, 2
	s_add_u32 s28, s28, 0x100
	s_addc_u32 s29, s29, 0
	s_add_u32 s49, s49, 0x100
	s_addc_u32 s50, s50, 0
	s_cmp_gt_u32 s51, 13
	s_cbranch_scc0 .LBB0_178
; #define PG8_BAR __builtin_amdgcn_s_barrier()
; template <class Epi, class Sched, bool ALIGN_EPI = false, bool SP2 = false>
; __device__ __forceinline__ void gemm_phase(PG8_LAS unsigned char* lds, const Gemm g, const Sched& S, const Epi& E) {
;     ...
;         if constexpr (ALIGN_EPI) { if (wr == 0) PG8_BAR; }
;         if constexpr (!Epi::AFTER_DRAIN) { E(acc, cur, wr, wc, fr, fq); S.done(cur); }
.Lpeel_exit0:
	s_and_b64 vcc, exec, s[16:17]
	s_cbranch_vccz .LBB0_181
	s_barrier

; #define PG8_STAGE(bufoff, gbase, voff) do { _Pragma("unroll") for (int _i = 0; _i < 2; ++_i) \
;         __builtin_amdgcn_global_load_lds((const unsigned*)((const char*)(gbase) + (voff)[_i]), (PG8_LAS unsigned*)(lds + (bufoff) + ldsw + _i * 8192), 16, 0, 0); } while (0)
; #define PG8_LDA(dst, b, h) do { _Pragma("unroll") for (int m = 0; m < 4; ++m) _Pragma("unroll") for (int k = 0; k < 2; ++k) dst[m][k] = *(const PG8_LAS bf16x8*)(lds + PG8_SA(b, h) + aoff + m * 2048 + k * 1024); } while (0)
; #define PG8_LDB(dst, b, h) do { _Pragma("unroll") for (int n = 0; n < 2; ++n) _Pragma("unroll") for (int k = 0; k < 2; ++k) dst[n][k] = *(const PG8_LAS bf16x8*)(lds + PG8_SB(b, h) + boff + n * 2048 + k * 1024); } while (0)
; #define PG8_WAIT_V(n) asm volatile("s_waitcnt vmcnt(" #n ")" ::: "memory")
; #define PG8_WAIT_L(n) asm volatile("s_waitcnt lgkmcnt(" #n ")" ::: "memory")
; #define PG8_BAR __builtin_amdgcn_s_barrier()
; template <class Epi, class Sched, bool ALIGN_EPI = false, bool SP2 = false>
; __device__ __forceinline__ void gemm_phase(PG8_LAS unsigned char* lds, const Gemm g, const Sched& S, const Epi& E) {
;     ...
;                 for (int n = 0; n < 2; ++n) acc[a][b][m][n] = (f32x4){0.f, 0.f, 0.f, 0.f};
;     ...
;         const bool has_next = S.next(ui + 1, nxt);
;         const char* nA = has_next ? (const char*)g.A + (size_t)nxt.pm * tstep : cA; const char* nB = has_next ? (const char*)g.Bt + (size_t)nxt.pn * tstep : cB;
;         for (int t = 0; t < nt; t += 2) {
;             const bool last = (t == nt - 2);
;             const char* a1 = cA + (size_t)(t + 1) * kstep;
;             const char* a2 = last ? nA : cA + (size_t)(t + 2) * kstep; const char* b2 = last ? nB : cB + (size_t)(t + 2) * kstep;
;             const char* a3 = a2 + kstep; const char* b3 = b2 + kstep;
;             if (last && has_next) S.a_ready(nxt);
;             if constexpr (SP2) {
;             PG8_LDB(B0, 0, 0); PG8_LDB(B1, 0, 1); PG8_SCHED; PG8_LDA(At, 0, 0); PG8_STAGE(PG8_SA(1, 1), a1 + hstep, voffA);
;             PG8_WAIT_V(8); PG8_WAIT_L(0); PG8_BAR; PG8_MMA(0, 0, At, B0); PG8_MMA(0, 1, At, B1); PG8_BAR; PG8_SCHED;
;             PG8_LDA(At, 0, 1); PG8_STAGE(PG8_SB(0, 0), b2, voffB); PG8_STAGE(PG8_SB(0, 1), b2 + hstep, voffB); PG8_STAGE(PG8_SA(0, 0), a2, voffA);
;             PG8_WAIT_V(8); PG8_WAIT_L(0); PG8_BAR; PG8_MMA(1, 0, At, B0); PG8_MMA(1, 1, At, B1); PG8_BAR; PG8_SCHED;
.LBB0_602:
	s_ashr_i32 s23, s22, 31
	s_lshl_b64 s[24:25], s[22:23], 19
	s_add_u32 s24, s56, s24
	s_addc_u32 s25, s57, s25
	s_and_b64 s[26:27], s[4:5], exec
	s_cselect_b32 s23, s25, s31
	s_cselect_b32 s49, s24, s30
	s_ashr_i32 s21, s20, 31
	s_lshl_b64 s[26:27], s[20:21], 19
	v_readlane_b32 s36, v237, 41
	v_readlane_b32 s37, v237, 42
	s_add_u32 s26, s36, s26
	s_addc_u32 s27, s37, s27
	s_and_b64 s[36:37], s[4:5], exec
	s_cselect_b32 s21, s27, s35
	s_cselect_b32 s50, s26, s34
	s_add_u32 s30, s30, 0x40080
	s_addc_u32 s31, s31, 0
	s_add_u32 s51, s34, 0x100
	s_addc_u32 s52, s35, 0
	s_mov_b32 s53, -2
	ds_read_b128 v[144:147], v151
	ds_read_b128 v[154:157], v151 offset:1024
	ds_read_b128 v[158:161], v151 offset:2048
	ds_read_b128 v[164:167], v151 offset:3072
	ds_read_b128 v[168:171], v152
	ds_read_b128 v[172:175], v152 offset:1024
	ds_read_b128 v[176:179], v152 offset:2048
	ds_read_b128 v[180:183], v152 offset:3072
	s_add_u32 s34, s30, 0xfffc0080
	s_addc_u32 s35, s31, -1
	s_cmp_eq_u32 s53, 12
	s_cselect_b32 s37, s23, s35
	s_cselect_b32 s36, s49, s34
	s_cselect_b32 s35, s21, s52
	s_cselect_b32 s34, s50, s51
	v_lshl_add_u64 v[216:217], s[30:31], 0, v[136:137]
	s_add_i32 m0, s11, 0xc000
	ds_read_b128 v[184:187], v153
	ds_read_b128 v[188:191], v153 offset:1024
	ds_read_b128 v[192:195], v153 offset:2048
	ds_read_b128 v[196:199], v153 offset:3072
	ds_read_b128 v[200:203], v153 offset:4096
	ds_read_b128 v[204:207], v153 offset:5120
	ds_read_b128 v[208:211], v153 offset:6144
	ds_read_b128 v[212:215], v153 offset:7168
	global_load_lds_dwordx4 v[216:217], off
	v_lshl_add_u64 v[216:217], s[30:31], 0, v[138:139]
	s_add_i32 m0, s11, 0xe000
	s_nop 0
	global_load_lds_dwordx4 v[216:217], off
	s_waitcnt vmcnt(8)
	s_waitcnt lgkmcnt(0)
	s_barrier
	s_waitcnt lgkmcnt(0)
	v_mfma_f32_16x16x32_bf16 v[124:127], v[144:147], v[184:187], 0
	v_mfma_f32_16x16x32_bf16 v[120:123], v[158:161], v[184:187], 0
	v_mfma_f32_16x16x32_bf16 v[108:111], v[144:147], v[192:195], 0
	v_mfma_f32_16x16x32_bf16 v[104:107], v[158:161], v[192:195], 0
	v_mfma_f32_16x16x32_bf16 v[92:95], v[144:147], v[200:203], 0
	v_mfma_f32_16x16x32_bf16 v[88:91], v[158:161], v[200:203], 0
	v_mfma_f32_16x16x32_bf16 v[76:79], v[144:147], v[208:211], 0
	v_mfma_f32_16x16x32_bf16 v[72:75], v[158:161], v[208:211], 0
	v_mfma_f32_16x16x32_bf16 v[124:127], v[154:157], v[188:191], v[124:127]
	v_mfma_f32_16x16x32_bf16 v[120:123], v[164:167], v[188:191], v[120:123]
	v_mfma_f32_16x16x32_bf16 v[108:111], v[154:157], v[196:199], v[108:111]
	v_mfma_f32_16x16x32_bf16 v[104:107], v[164:167], v[196:199], v[104:107]
	v_mfma_f32_16x16x32_bf16 v[92:95], v[154:157], v[204:207], v[92:95]
	v_mfma_f32_16x16x32_bf16 v[88:91], v[164:167], v[204:207], v[88:91]
	v_mfma_f32_16x16x32_bf16 v[76:79], v[154:157], v[212:215], v[76:79]
	v_mfma_f32_16x16x32_bf16 v[72:75], v[164:167], v[212:215], v[72:75]
	v_mfma_f32_16x16x32_bf16 v[116:119], v[168:171], v[184:187], 0
	v_mfma_f32_16x16x32_bf16 v[112:115], v[176:179], v[184:187], 0
	v_mfma_f32_16x16x32_bf16 v[100:103], v[168:171], v[192:195], 0
	v_mfma_f32_16x16x32_bf16 v[96:99], v[176:179], v[192:195], 0
	v_mfma_f32_16x16x32_bf16 v[84:87], v[168:171], v[200:203], 0
	v_mfma_f32_16x16x32_bf16 v[80:83], v[176:179], v[200:203], 0
	v_mfma_f32_16x16x32_bf16 v[68:71], v[168:171], v[208:211], 0
	v_mfma_f32_16x16x32_bf16 v[64:67], v[176:179], v[208:211], 0
	v_mfma_f32_16x16x32_bf16 v[116:119], v[172:175], v[188:191], v[116:119]
	v_mfma_f32_16x16x32_bf16 v[112:115], v[180:183], v[188:191], v[112:115]
	v_mfma_f32_16x16x32_bf16 v[100:103], v[172:175], v[196:199], v[100:103]
	v_mfma_f32_16x16x32_bf16 v[96:99], v[180:183], v[196:199], v[96:99]
	v_mfma_f32_16x16x32_bf16 v[84:87], v[172:175], v[204:207], v[84:87]
	v_mfma_f32_16x16x32_bf16 v[80:83], v[180:183], v[204:207], v[80:83]
	v_mfma_f32_16x16x32_bf16 v[68:71], v[172:175], v[212:215], v[68:71]
	v_mfma_f32_16x16x32_bf16 v[64:67], v[180:183], v[212:215], v[64:67]
	s_barrier
	s_add_i32 s54, s46, s10
	v_lshl_add_u64 v[216:217], s[34:35], 0, v[130:131]
	s_mov_b32 m0, s54
	ds_read_b128 v[184:187], v153 offset:16384
	ds_read_b128 v[188:191], v153 offset:17408
	ds_read_b128 v[192:195], v153 offset:18432
	ds_read_b128 v[196:199], v153 offset:19456
	ds_read_b128 v[200:203], v153 offset:20480
	ds_read_b128 v[204:207], v153 offset:21504
	ds_read_b128 v[208:211], v153 offset:22528
	ds_read_b128 v[212:215], v153 offset:23552
	global_load_lds_dwordx4 v[216:217], off
	s_add_i32 m0, s54, 0x2000
	s_add_u32 s54, s34, 0x40000
	v_lshl_add_u64 v[218:219], s[34:35], 0, v[134:135]
	s_addc_u32 s55, s35, 0
	s_add_i32 s58, s47, s10
	global_load_lds_dwordx4 v[218:219], off
	v_lshl_add_u64 v[220:221], s[54:55], 0, v[130:131]
	s_mov_b32 m0, s58
	v_lshl_add_u64 v[222:223], s[36:37], 0, v[132:133]
	global_load_lds_dwordx4 v[220:221], off
	v_lshl_add_u64 v[220:221], s[54:55], 0, v[134:135]
	s_add_i32 m0, s58, 0x2000
	s_nop 0
	global_load_lds_dwordx4 v[220:221], off
	v_lshl_add_u64 v[220:221], s[36:37], 0, v[128:129]
	s_mov_b32 m0, s11
	s_nop 0
	global_load_lds_dwordx4 v[220:221], off
	s_mov_b32 m0, s29
	s_nop 0
	global_load_lds_dwordx4 v[222:223], off
	s_waitcnt vmcnt(8)
	s_waitcnt lgkmcnt(0)
	s_barrier
; #define PG8_STAGE(bufoff, gbase, voff) do { _Pragma("unroll") for (int _i = 0; _i < 2; ++_i) \
;         __builtin_amdgcn_global_load_lds((const unsigned*)((const char*)(gbase) + (voff)[_i]), (PG8_LAS unsigned*)(lds + (bufoff) + ldsw + _i * 8192), 16, 0, 0); } while (0)
; #define PG8_LDA(dst, b, h) do { _Pragma("unroll") for (int m = 0; m < 4; ++m) _Pragma("unroll") for (int k = 0; k < 2; ++k) dst[m][k] = *(const PG8_LAS bf16x8*)(lds + PG8_SA(b, h) + aoff + m * 2048 + k * 1024); } while (0)
; #define PG8_LDB(dst, b, h) do { _Pragma("unroll") for (int n = 0; n < 2; ++n) _Pragma("unroll") for (int k = 0; k < 2; ++k) dst[n][k] = *(const PG8_LAS bf16x8*)(lds + PG8_SB(b, h) + boff + n * 2048 + k * 1024); } while (0)
; #define PG8_MMA(ai, bj, At, Bt) do { __builtin_amdgcn_s_setprio(1); _Pragma("unroll") for (int m = 0; m < 4; ++m) _Pragma("unroll") for (int n = 0; n < 2; ++n) _Pragma("unroll") for (int k = 0; k < 2; ++k) \
;         acc[ai][bj][m][n] = __builtin_amdgcn_mfma_f32_16x16x32_bf16(Bt[n][k], At[m][k], acc[ai][bj][m][n], 0, 0, 0); __builtin_amdgcn_s_setprio(0); } while (0)
; #define PG8_WAIT_V(n) asm volatile("s_waitcnt vmcnt(" #n ")" ::: "memory")
; #define PG8_WAIT_L(n) asm volatile("s_waitcnt lgkmcnt(" #n ")" ::: "memory")
; #define PG8_BAR __builtin_amdgcn_s_barrier()
; #define PG8_SCHED __builtin_amdgcn_sched_barrier(0)
; template <class Epi, class Sched, bool ALIGN_EPI = false, bool SP2 = false>
; __device__ __forceinline__ void gemm_phase(PG8_LAS unsigned char* lds, const Gemm g, const Sched& S, const Epi& E) {
;     ...
;             PG8_WAIT_V(8); PG8_WAIT_L(0); PG8_BAR; PG8_MMA(1, 0, At, B0); PG8_MMA(1, 1, At, B1); PG8_BAR; PG8_SCHED;
;             PG8_LDB(B0, 1, 0); PG8_LDB(B1, 1, 1); PG8_SCHED; PG8_LDA(At, 1, 0); PG8_STAGE(PG8_SA(0, 1), a2 + hstep, voffA);
;             PG8_WAIT_V(8); PG8_WAIT_L(0); PG8_BAR; PG8_MMA(0, 0, At, B0); PG8_MMA(0, 1, At, B1); PG8_BAR; PG8_SCHED;
	s_waitcnt lgkmcnt(0)
	v_mfma_f32_16x16x32_bf16 v[60:63], v[144:147], v[184:187], 0
	v_mfma_f32_16x16x32_bf16 v[56:59], v[158:161], v[184:187], 0
	v_mfma_f32_16x16x32_bf16 v[44:47], v[144:147], v[192:195], 0
	v_mfma_f32_16x16x32_bf16 v[40:43], v[158:161], v[192:195], 0
	v_mfma_f32_16x16x32_bf16 v[28:31], v[144:147], v[200:203], 0
	v_mfma_f32_16x16x32_bf16 v[24:27], v[158:161], v[200:203], 0
	v_mfma_f32_16x16x32_bf16 v[12:15], v[144:147], v[208:211], 0
	v_mfma_f32_16x16x32_bf16 v[8:11], v[158:161], v[208:211], 0
	v_mfma_f32_16x16x32_bf16 v[60:63], v[154:157], v[188:191], v[60:63]
	v_mfma_f32_16x16x32_bf16 v[56:59], v[164:167], v[188:191], v[56:59]
	v_mfma_f32_16x16x32_bf16 v[44:47], v[154:157], v[196:199], v[44:47]
	v_mfma_f32_16x16x32_bf16 v[40:43], v[164:167], v[196:199], v[40:43]
	v_mfma_f32_16x16x32_bf16 v[28:31], v[154:157], v[204:207], v[28:31]
	v_mfma_f32_16x16x32_bf16 v[24:27], v[164:167], v[204:207], v[24:27]
	v_mfma_f32_16x16x32_bf16 v[12:15], v[154:157], v[212:215], v[12:15]
	v_mfma_f32_16x16x32_bf16 v[8:11], v[164:167], v[212:215], v[8:11]
	v_mfma_f32_16x16x32_bf16 v[52:55], v[168:171], v[184:187], 0
	v_mfma_f32_16x16x32_bf16 v[48:51], v[176:179], v[184:187], 0
	v_mfma_f32_16x16x32_bf16 v[36:39], v[168:171], v[192:195], 0
	v_mfma_f32_16x16x32_bf16 v[32:35], v[176:179], v[192:195], 0
	v_mfma_f32_16x16x32_bf16 v[20:23], v[168:171], v[200:203], 0
	v_mfma_f32_16x16x32_bf16 v[16:19], v[176:179], v[200:203], 0
	v_mfma_f32_16x16x32_bf16 v[4:7], v[168:171], v[208:211], 0
	v_mfma_f32_16x16x32_bf16 v[0:3], v[176:179], v[208:211], 0
	v_mfma_f32_16x16x32_bf16 v[52:55], v[172:175], v[188:191], v[52:55]
	v_mfma_f32_16x16x32_bf16 v[48:51], v[180:183], v[188:191], v[48:51]
	v_mfma_f32_16x16x32_bf16 v[36:39], v[172:175], v[196:199], v[36:39]
	v_mfma_f32_16x16x32_bf16 v[32:35], v[180:183], v[196:199], v[32:35]
	v_mfma_f32_16x16x32_bf16 v[20:23], v[172:175], v[204:207], v[20:23]
	v_mfma_f32_16x16x32_bf16 v[16:19], v[180:183], v[204:207], v[16:19]
	v_mfma_f32_16x16x32_bf16 v[4:7], v[172:175], v[212:215], v[4:7]
	v_mfma_f32_16x16x32_bf16 v[0:3], v[180:183], v[212:215], v[0:3]
	s_barrier
	s_add_i32 s54, 0, 0x18000
	s_add_i32 s55, 0, 0x1c000
	v_add_u32_e32 v164, s54, v149
	v_add_u32_e32 v180, s55, v149
	ds_read_b128 v[144:147], v164
	ds_read_b128 v[154:157], v164 offset:1024
	ds_read_b128 v[158:161], v164 offset:2048
	ds_read_b128 v[164:167], v164 offset:3072
	ds_read_b128 v[168:171], v180
	ds_read_b128 v[172:175], v180 offset:1024
	ds_read_b128 v[176:179], v180 offset:2048
	ds_read_b128 v[180:183], v180 offset:3072
	s_add_u32 s36, s36, 0x40000
	s_addc_u32 s37, s37, 0
	s_mov_b32 m0, s33
	v_lshl_add_u64 v[224:225], s[36:37], 0, v[128:129]
	ds_read_b128 v[184:187], v153 offset:32768
	ds_read_b128 v[188:191], v153 offset:33792
	ds_read_b128 v[192:195], v153 offset:34816
	ds_read_b128 v[196:199], v153 offset:35840
	ds_read_b128 v[200:203], v153 offset:36864
	ds_read_b128 v[204:207], v153 offset:37888
	ds_read_b128 v[208:211], v153 offset:38912
	ds_read_b128 v[212:215], v153 offset:39936
	global_load_lds_dwordx4 v[224:225], off
	v_lshl_add_u64 v[224:225], s[36:37], 0, v[132:133]
	s_mov_b32 m0, s38
	s_nop 0
	global_load_lds_dwordx4 v[224:225], off
	s_waitcnt vmcnt(8)
	s_waitcnt lgkmcnt(0)
	s_barrier
	s_waitcnt lgkmcnt(0)
	v_mfma_f32_16x16x32_bf16 v[124:127], v[144:147], v[184:187], v[124:127]
	v_mfma_f32_16x16x32_bf16 v[120:123], v[158:161], v[184:187], v[120:123]
	v_mfma_f32_16x16x32_bf16 v[108:111], v[144:147], v[192:195], v[108:111]
	v_mfma_f32_16x16x32_bf16 v[104:107], v[158:161], v[192:195], v[104:107]
	v_mfma_f32_16x16x32_bf16 v[92:95], v[144:147], v[200:203], v[92:95]
	v_mfma_f32_16x16x32_bf16 v[88:91], v[158:161], v[200:203], v[88:91]
	v_mfma_f32_16x16x32_bf16 v[76:79], v[144:147], v[208:211], v[76:79]
	v_mfma_f32_16x16x32_bf16 v[72:75], v[158:161], v[208:211], v[72:75]
	v_mfma_f32_16x16x32_bf16 v[124:127], v[154:157], v[188:191], v[124:127]
	v_mfma_f32_16x16x32_bf16 v[120:123], v[164:167], v[188:191], v[120:123]
	v_mfma_f32_16x16x32_bf16 v[108:111], v[154:157], v[196:199], v[108:111]
	v_mfma_f32_16x16x32_bf16 v[104:107], v[164:167], v[196:199], v[104:107]
	v_mfma_f32_16x16x32_bf16 v[92:95], v[154:157], v[204:207], v[92:95]
	v_mfma_f32_16x16x32_bf16 v[88:91], v[164:167], v[204:207], v[88:91]
	v_mfma_f32_16x16x32_bf16 v[76:79], v[154:157], v[212:215], v[76:79]
	v_mfma_f32_16x16x32_bf16 v[72:75], v[164:167], v[212:215], v[72:75]
	v_mfma_f32_16x16x32_bf16 v[116:119], v[168:171], v[184:187], v[116:119]
	v_mfma_f32_16x16x32_bf16 v[112:115], v[176:179], v[184:187], v[112:115]
	v_mfma_f32_16x16x32_bf16 v[100:103], v[168:171], v[192:195], v[100:103]
	v_mfma_f32_16x16x32_bf16 v[96:99], v[176:179], v[192:195], v[96:99]
	v_mfma_f32_16x16x32_bf16 v[84:87], v[168:171], v[200:203], v[84:87]
	v_mfma_f32_16x16x32_bf16 v[80:83], v[176:179], v[200:203], v[80:83]
	v_mfma_f32_16x16x32_bf16 v[68:71], v[168:171], v[208:211], v[68:71]
	v_mfma_f32_16x16x32_bf16 v[64:67], v[176:179], v[208:211], v[64:67]
	v_mfma_f32_16x16x32_bf16 v[116:119], v[172:175], v[188:191], v[116:119]
	v_mfma_f32_16x16x32_bf16 v[112:115], v[180:183], v[188:191], v[112:115]
	v_mfma_f32_16x16x32_bf16 v[100:103], v[172:175], v[196:199], v[100:103]
	v_mfma_f32_16x16x32_bf16 v[96:99], v[180:183], v[196:199], v[96:99]
	v_mfma_f32_16x16x32_bf16 v[84:87], v[172:175], v[204:207], v[84:87]
	v_mfma_f32_16x16x32_bf16 v[80:83], v[180:183], v[204:207], v[80:83]
	v_mfma_f32_16x16x32_bf16 v[68:71], v[172:175], v[212:215], v[68:71]
	v_mfma_f32_16x16x32_bf16 v[64:67], v[180:183], v[212:215], v[64:67]
	s_barrier
; #define PG8_STAGE(bufoff, gbase, voff) do { _Pragma("unroll") for (int _i = 0; _i < 2; ++_i) \
;         __builtin_amdgcn_global_load_lds((const unsigned*)((const char*)(gbase) + (voff)[_i]), (PG8_LAS unsigned*)(lds + (bufoff) + ldsw + _i * 8192), 16, 0, 0); } while (0)
; #define PG8_LDA(dst, b, h) do { _Pragma("unroll") for (int m = 0; m < 4; ++m) _Pragma("unroll") for (int k = 0; k < 2; ++k) dst[m][k] = *(const PG8_LAS bf16x8*)(lds + PG8_SA(b, h) + aoff + m * 2048 + k * 1024); } while (0)
; #define PG8_LDB(dst, b, h) do { _Pragma("unroll") for (int n = 0; n < 2; ++n) _Pragma("unroll") for (int k = 0; k < 2; ++k) dst[n][k] = *(const PG8_LAS bf16x8*)(lds + PG8_SB(b, h) + boff + n * 2048 + k * 1024); } while (0)
; #define PG8_MMA(ai, bj, At, Bt) do { __builtin_amdgcn_s_setprio(1); _Pragma("unroll") for (int m = 0; m < 4; ++m) _Pragma("unroll") for (int n = 0; n < 2; ++n) _Pragma("unroll") for (int k = 0; k < 2; ++k) \
;         acc[ai][bj][m][n] = __builtin_amdgcn_mfma_f32_16x16x32_bf16(Bt[n][k], At[m][k], acc[ai][bj][m][n], 0, 0, 0); __builtin_amdgcn_s_setprio(0); } while (0)
; #define PG8_WAIT_V(n) asm volatile("s_waitcnt vmcnt(" #n ")" ::: "memory")
; #define PG8_WAIT_L(n) asm volatile("s_waitcnt lgkmcnt(" #n ")" ::: "memory")
; #define PG8_BAR __builtin_amdgcn_s_barrier()
; #define PG8_SCHED __builtin_amdgcn_sched_barrier(0)
; template <class Epi, class Sched, bool ALIGN_EPI = false, bool SP2 = false>
; __device__ __forceinline__ void gemm_phase(PG8_LAS unsigned char* lds, const Gemm g, const Sched& S, const Epi& E) {
;     ...
;         for (int t = 0; t < nt; t += 2) {
;             const bool last = (t == nt - 2);
;             const char* a1 = cA + (size_t)(t + 1) * kstep;
;             const char* a2 = last ? nA : cA + (size_t)(t + 2) * kstep; const char* b2 = last ? nB : cB + (size_t)(t + 2) * kstep;
;             const char* a3 = a2 + kstep; const char* b3 = b2 + kstep;
;             if (last && has_next) S.a_ready(nxt);
;             if constexpr (SP2) {
;             PG8_LDB(B0, 0, 0); PG8_LDB(B1, 0, 1); PG8_SCHED; PG8_LDA(At, 0, 0); PG8_STAGE(PG8_SA(1, 1), a1 + hstep, voffA);
;     ...
;             PG8_LDA(At, 1, 1); PG8_STAGE(PG8_SB(1, 0), b3, voffB); PG8_STAGE(PG8_SB(1, 1), b3 + hstep, voffB); PG8_STAGE(PG8_SA(1, 0), a3, voffA);
;             PG8_WAIT_V(8); PG8_WAIT_L(0); PG8_BAR; PG8_MMA(1, 0, At, B0); PG8_MMA(1, 1, At, B1); PG8_BAR; PG8_SCHED;
	s_add_i32 s36, s54, s10
	v_lshl_add_u64 v[216:217], v[216:217], 0, s[16:17]
	s_mov_b32 m0, s36
	ds_read_b128 v[184:187], v153 offset:49152
	ds_read_b128 v[188:191], v153 offset:50176
	ds_read_b128 v[192:195], v153 offset:51200
	ds_read_b128 v[196:199], v153 offset:52224
	ds_read_b128 v[200:203], v153 offset:53248
	ds_read_b128 v[204:207], v153 offset:54272
	ds_read_b128 v[208:211], v153 offset:55296
	ds_read_b128 v[212:215], v153 offset:56320
	global_load_lds_dwordx4 v[216:217], off
	s_add_i32 m0, s36, 0x2000
	s_add_u32 s34, s34, 0x40080
	v_lshl_add_u64 v[216:217], v[218:219], 0, s[16:17]
	s_addc_u32 s35, s35, 0
	s_add_i32 s36, s55, s10
	global_load_lds_dwordx4 v[216:217], off
	v_lshl_add_u64 v[216:217], s[34:35], 0, v[130:131]
	s_mov_b32 m0, s36
	s_nop 0
	global_load_lds_dwordx4 v[216:217], off
	v_lshl_add_u64 v[216:217], s[34:35], 0, v[134:135]
	s_add_i32 m0, s36, 0x2000
	s_nop 0
	global_load_lds_dwordx4 v[216:217], off
	v_lshl_add_u64 v[216:217], v[220:221], 0, s[16:17]
	s_mov_b32 m0, s40
	s_nop 0
	global_load_lds_dwordx4 v[216:217], off
	v_lshl_add_u64 v[216:217], v[222:223], 0, s[16:17]
	s_mov_b32 m0, s41
	s_nop 0
	global_load_lds_dwordx4 v[216:217], off
	s_waitcnt vmcnt(8)
	s_waitcnt lgkmcnt(0)
	s_barrier
	s_waitcnt lgkmcnt(0)
	v_mfma_f32_16x16x32_bf16 v[60:63], v[144:147], v[184:187], v[60:63]
	v_mfma_f32_16x16x32_bf16 v[56:59], v[158:161], v[184:187], v[56:59]
	v_mfma_f32_16x16x32_bf16 v[44:47], v[144:147], v[192:195], v[44:47]
	v_mfma_f32_16x16x32_bf16 v[40:43], v[158:161], v[192:195], v[40:43]
	v_mfma_f32_16x16x32_bf16 v[28:31], v[144:147], v[200:203], v[28:31]
	v_mfma_f32_16x16x32_bf16 v[24:27], v[158:161], v[200:203], v[24:27]
	v_mfma_f32_16x16x32_bf16 v[12:15], v[144:147], v[208:211], v[12:15]
	v_mfma_f32_16x16x32_bf16 v[8:11], v[158:161], v[208:211], v[8:11]
	v_mfma_f32_16x16x32_bf16 v[60:63], v[154:157], v[188:191], v[60:63]
	v_mfma_f32_16x16x32_bf16 v[56:59], v[164:167], v[188:191], v[56:59]
	v_mfma_f32_16x16x32_bf16 v[44:47], v[154:157], v[196:199], v[44:47]
	v_mfma_f32_16x16x32_bf16 v[40:43], v[164:167], v[196:199], v[40:43]
	v_mfma_f32_16x16x32_bf16 v[28:31], v[154:157], v[204:207], v[28:31]
	v_mfma_f32_16x16x32_bf16 v[24:27], v[164:167], v[204:207], v[24:27]
	v_mfma_f32_16x16x32_bf16 v[12:15], v[154:157], v[212:215], v[12:15]
	v_mfma_f32_16x16x32_bf16 v[8:11], v[164:167], v[212:215], v[8:11]
	v_mfma_f32_16x16x32_bf16 v[52:55], v[168:171], v[184:187], v[52:55]
	v_mfma_f32_16x16x32_bf16 v[48:51], v[176:179], v[184:187], v[48:51]
	v_mfma_f32_16x16x32_bf16 v[36:39], v[168:171], v[192:195], v[36:39]
	v_mfma_f32_16x16x32_bf16 v[32:35], v[176:179], v[192:195], v[32:35]
	v_mfma_f32_16x16x32_bf16 v[20:23], v[168:171], v[200:203], v[20:23]
	v_mfma_f32_16x16x32_bf16 v[16:19], v[176:179], v[200:203], v[16:19]
	v_mfma_f32_16x16x32_bf16 v[4:7], v[168:171], v[208:211], v[4:7]
	v_mfma_f32_16x16x32_bf16 v[0:3], v[176:179], v[208:211], v[0:3]
	v_mfma_f32_16x16x32_bf16 v[52:55], v[172:175], v[188:191], v[52:55]
	v_mfma_f32_16x16x32_bf16 v[48:51], v[180:183], v[188:191], v[48:51]
	v_mfma_f32_16x16x32_bf16 v[36:39], v[172:175], v[196:199], v[36:39]
	v_mfma_f32_16x16x32_bf16 v[32:35], v[180:183], v[196:199], v[32:35]
	v_mfma_f32_16x16x32_bf16 v[20:23], v[172:175], v[204:207], v[20:23]
	v_mfma_f32_16x16x32_bf16 v[16:19], v[180:183], v[204:207], v[16:19]
	v_mfma_f32_16x16x32_bf16 v[4:7], v[172:175], v[212:215], v[4:7]
	v_mfma_f32_16x16x32_bf16 v[0:3], v[180:183], v[212:215], v[0:3]
	s_barrier
	s_add_i32 s53, s53, 2
	s_add_u32 s30, s30, 0x100
	s_addc_u32 s31, s31, 0
	s_add_u32 s51, s51, 0x100
	s_addc_u32 s52, s52, 0
	s_cmp_gt_u32 s53, 13
	s_cbranch_scc1 .Lpeel_exit1
.LBB0_603:
	ds_read_b128 v[144:147], v151
	ds_read_b128 v[154:157], v151 offset:1024
	ds_read_b128 v[158:161], v151 offset:2048
	ds_read_b128 v[164:167], v151 offset:3072
	ds_read_b128 v[168:171], v152
	ds_read_b128 v[172:175], v152 offset:1024
	ds_read_b128 v[176:179], v152 offset:2048
	ds_read_b128 v[180:183], v152 offset:3072
	s_add_u32 s34, s30, 0xfffc0080
	s_addc_u32 s35, s31, -1
	s_cmp_eq_u32 s53, 12
	s_cselect_b32 s37, s23, s35
	s_cselect_b32 s36, s49, s34
	s_cselect_b32 s35, s21, s52
	s_cselect_b32 s34, s50, s51
	v_lshl_add_u64 v[216:217], s[30:31], 0, v[136:137]
	s_add_i32 m0, s11, 0xc000
	ds_read_b128 v[184:187], v153
	ds_read_b128 v[188:191], v153 offset:1024
	ds_read_b128 v[192:195], v153 offset:2048
	ds_read_b128 v[196:199], v153 offset:3072
	ds_read_b128 v[200:203], v153 offset:4096
	ds_read_b128 v[204:207], v153 offset:5120
	ds_read_b128 v[208:211], v153 offset:6144
	ds_read_b128 v[212:215], v153 offset:7168
	global_load_lds_dwordx4 v[216:217], off
	v_lshl_add_u64 v[216:217], s[30:31], 0, v[138:139]
	s_add_i32 m0, s11, 0xe000
	s_nop 0
	global_load_lds_dwordx4 v[216:217], off
	s_waitcnt vmcnt(8)
	s_waitcnt lgkmcnt(0)
	s_barrier
; #define PG8_STAGE(bufoff, gbase, voff) do { _Pragma("unroll") for (int _i = 0; _i < 2; ++_i) \
;         __builtin_amdgcn_global_load_lds((const unsigned*)((const char*)(gbase) + (voff)[_i]), (PG8_LAS unsigned*)(lds + (bufoff) + ldsw + _i * 8192), 16, 0, 0); } while (0)
; #define PG8_LDA(dst, b, h) do { _Pragma("unroll") for (int m = 0; m < 4; ++m) _Pragma("unroll") for (int k = 0; k < 2; ++k) dst[m][k] = *(const PG8_LAS bf16x8*)(lds + PG8_SA(b, h) + aoff + m * 2048 + k * 1024); } while (0)
; #define PG8_LDB(dst, b, h) do { _Pragma("unroll") for (int n = 0; n < 2; ++n) _Pragma("unroll") for (int k = 0; k < 2; ++k) dst[n][k] = *(const PG8_LAS bf16x8*)(lds + PG8_SB(b, h) + boff + n * 2048 + k * 1024); } while (0)
; #define PG8_MMA(ai, bj, At, Bt) do { __builtin_amdgcn_s_setprio(1); _Pragma("unroll") for (int m = 0; m < 4; ++m) _Pragma("unroll") for (int n = 0; n < 2; ++n) _Pragma("unroll") for (int k = 0; k < 2; ++k) \
;         acc[ai][bj][m][n] = __builtin_amdgcn_mfma_f32_16x16x32_bf16(Bt[n][k], At[m][k], acc[ai][bj][m][n], 0, 0, 0); __builtin_amdgcn_s_setprio(0); } while (0)
; #define PG8_WAIT_V(n) asm volatile("s_waitcnt vmcnt(" #n ")" ::: "memory")
; #define PG8_WAIT_L(n) asm volatile("s_waitcnt lgkmcnt(" #n ")" ::: "memory")
; #define PG8_BAR __builtin_amdgcn_s_barrier()
; #define PG8_SCHED __builtin_amdgcn_sched_barrier(0)
; template <class Epi, class Sched, bool ALIGN_EPI = false, bool SP2 = false>
; __device__ __forceinline__ void gemm_phase(PG8_LAS unsigned char* lds, const Gemm g, const Sched& S, const Epi& E) {
;     ...
;             PG8_LDB(B0, 0, 0); PG8_LDB(B1, 0, 1); PG8_SCHED; PG8_LDA(At, 0, 0); PG8_STAGE(PG8_SA(1, 1), a1 + hstep, voffA);
;             PG8_WAIT_V(8); PG8_WAIT_L(0); PG8_BAR; PG8_MMA(0, 0, At, B0); PG8_MMA(0, 1, At, B1); PG8_BAR; PG8_SCHED;
;             PG8_LDA(At, 0, 1); PG8_STAGE(PG8_SB(0, 0), b2, voffB); PG8_STAGE(PG8_SB(0, 1), b2 + hstep, voffB); PG8_STAGE(PG8_SA(0, 0), a2, voffA);
;             PG8_WAIT_V(8); PG8_WAIT_L(0); PG8_BAR; PG8_MMA(1, 0, At, B0); PG8_MMA(1, 1, At, B1); PG8_BAR; PG8_SCHED;
;             PG8_LDB(B0, 1, 0); PG8_LDB(B1, 1, 1); PG8_SCHED; PG8_LDA(At, 1, 0); PG8_STAGE(PG8_SA(0, 1), a2 + hstep, voffA);
;             PG8_WAIT_V(8); PG8_WAIT_L(0); PG8_BAR; PG8_MMA(0, 0, At, B0); PG8_MMA(0, 1, At, B1); PG8_BAR; PG8_SCHED;
	s_waitcnt lgkmcnt(0)
	v_mfma_f32_16x16x32_bf16 v[124:127], v[144:147], v[184:187], v[124:127]
	v_mfma_f32_16x16x32_bf16 v[120:123], v[158:161], v[184:187], v[120:123]
	v_mfma_f32_16x16x32_bf16 v[108:111], v[144:147], v[192:195], v[108:111]
	v_mfma_f32_16x16x32_bf16 v[104:107], v[158:161], v[192:195], v[104:107]
	v_mfma_f32_16x16x32_bf16 v[92:95], v[144:147], v[200:203], v[92:95]
	v_mfma_f32_16x16x32_bf16 v[88:91], v[158:161], v[200:203], v[88:91]
	v_mfma_f32_16x16x32_bf16 v[76:79], v[144:147], v[208:211], v[76:79]
	v_mfma_f32_16x16x32_bf16 v[72:75], v[158:161], v[208:211], v[72:75]
	v_mfma_f32_16x16x32_bf16 v[124:127], v[154:157], v[188:191], v[124:127]
	v_mfma_f32_16x16x32_bf16 v[120:123], v[164:167], v[188:191], v[120:123]
	v_mfma_f32_16x16x32_bf16 v[108:111], v[154:157], v[196:199], v[108:111]
	v_mfma_f32_16x16x32_bf16 v[104:107], v[164:167], v[196:199], v[104:107]
	v_mfma_f32_16x16x32_bf16 v[92:95], v[154:157], v[204:207], v[92:95]
	v_mfma_f32_16x16x32_bf16 v[88:91], v[164:167], v[204:207], v[88:91]
	v_mfma_f32_16x16x32_bf16 v[76:79], v[154:157], v[212:215], v[76:79]
	v_mfma_f32_16x16x32_bf16 v[72:75], v[164:167], v[212:215], v[72:75]
	v_mfma_f32_16x16x32_bf16 v[116:119], v[168:171], v[184:187], v[116:119]
	v_mfma_f32_16x16x32_bf16 v[112:115], v[176:179], v[184:187], v[112:115]
	v_mfma_f32_16x16x32_bf16 v[100:103], v[168:171], v[192:195], v[100:103]
	v_mfma_f32_16x16x32_bf16 v[96:99], v[176:179], v[192:195], v[96:99]
	v_mfma_f32_16x16x32_bf16 v[84:87], v[168:171], v[200:203], v[84:87]
	v_mfma_f32_16x16x32_bf16 v[80:83], v[176:179], v[200:203], v[80:83]
	v_mfma_f32_16x16x32_bf16 v[68:71], v[168:171], v[208:211], v[68:71]
	v_mfma_f32_16x16x32_bf16 v[64:67], v[176:179], v[208:211], v[64:67]
	v_mfma_f32_16x16x32_bf16 v[116:119], v[172:175], v[188:191], v[116:119]
	v_mfma_f32_16x16x32_bf16 v[112:115], v[180:183], v[188:191], v[112:115]
	v_mfma_f32_16x16x32_bf16 v[100:103], v[172:175], v[196:199], v[100:103]
	v_mfma_f32_16x16x32_bf16 v[96:99], v[180:183], v[196:199], v[96:99]
	v_mfma_f32_16x16x32_bf16 v[84:87], v[172:175], v[204:207], v[84:87]
	v_mfma_f32_16x16x32_bf16 v[80:83], v[180:183], v[204:207], v[80:83]
	v_mfma_f32_16x16x32_bf16 v[68:71], v[172:175], v[212:215], v[68:71]
	v_mfma_f32_16x16x32_bf16 v[64:67], v[180:183], v[212:215], v[64:67]
	s_barrier
	s_add_i32 s54, s46, s10
	v_lshl_add_u64 v[216:217], s[34:35], 0, v[130:131]
	s_mov_b32 m0, s54
	ds_read_b128 v[184:187], v153 offset:16384
	ds_read_b128 v[188:191], v153 offset:17408
	ds_read_b128 v[192:195], v153 offset:18432
	ds_read_b128 v[196:199], v153 offset:19456
	ds_read_b128 v[200:203], v153 offset:20480
	ds_read_b128 v[204:207], v153 offset:21504
	ds_read_b128 v[208:211], v153 offset:22528
	ds_read_b128 v[212:215], v153 offset:23552
	global_load_lds_dwordx4 v[216:217], off
	s_add_i32 m0, s54, 0x2000
	s_add_u32 s54, s34, 0x40000
	v_lshl_add_u64 v[218:219], s[34:35], 0, v[134:135]
	s_addc_u32 s55, s35, 0
	s_add_i32 s58, s47, s10
	global_load_lds_dwordx4 v[218:219], off
	v_lshl_add_u64 v[220:221], s[54:55], 0, v[130:131]
	s_mov_b32 m0, s58
	v_lshl_add_u64 v[222:223], s[36:37], 0, v[132:133]
	global_load_lds_dwordx4 v[220:221], off
	v_lshl_add_u64 v[220:221], s[54:55], 0, v[134:135]
	s_add_i32 m0, s58, 0x2000
	s_nop 0
	global_load_lds_dwordx4 v[220:221], off
	v_lshl_add_u64 v[220:221], s[36:37], 0, v[128:129]
	s_mov_b32 m0, s11
	s_nop 0
	global_load_lds_dwordx4 v[220:221], off
	s_mov_b32 m0, s29
	s_nop 0
	global_load_lds_dwordx4 v[222:223], off
	s_waitcnt vmcnt(8)
	s_waitcnt lgkmcnt(0)
	s_barrier
	s_waitcnt lgkmcnt(0)
	v_mfma_f32_16x16x32_bf16 v[60:63], v[144:147], v[184:187], v[60:63]
	v_mfma_f32_16x16x32_bf16 v[56:59], v[158:161], v[184:187], v[56:59]
	v_mfma_f32_16x16x32_bf16 v[44:47], v[144:147], v[192:195], v[44:47]
	v_mfma_f32_16x16x32_bf16 v[40:43], v[158:161], v[192:195], v[40:43]
	v_mfma_f32_16x16x32_bf16 v[28:31], v[144:147], v[200:203], v[28:31]
	v_mfma_f32_16x16x32_bf16 v[24:27], v[158:161], v[200:203], v[24:27]
	v_mfma_f32_16x16x32_bf16 v[12:15], v[144:147], v[208:211], v[12:15]
	v_mfma_f32_16x16x32_bf16 v[8:11], v[158:161], v[208:211], v[8:11]
	v_mfma_f32_16x16x32_bf16 v[60:63], v[154:157], v[188:191], v[60:63]
	v_mfma_f32_16x16x32_bf16 v[56:59], v[164:167], v[188:191], v[56:59]
	v_mfma_f32_16x16x32_bf16 v[44:47], v[154:157], v[196:199], v[44:47]
	v_mfma_f32_16x16x32_bf16 v[40:43], v[164:167], v[196:199], v[40:43]
	v_mfma_f32_16x16x32_bf16 v[28:31], v[154:157], v[204:207], v[28:31]
	v_mfma_f32_16x16x32_bf16 v[24:27], v[164:167], v[204:207], v[24:27]
	v_mfma_f32_16x16x32_bf16 v[12:15], v[154:157], v[212:215], v[12:15]
	v_mfma_f32_16x16x32_bf16 v[8:11], v[164:167], v[212:215], v[8:11]
	v_mfma_f32_16x16x32_bf16 v[52:55], v[168:171], v[184:187], v[52:55]
	v_mfma_f32_16x16x32_bf16 v[48:51], v[176:179], v[184:187], v[48:51]
	v_mfma_f32_16x16x32_bf16 v[36:39], v[168:171], v[192:195], v[36:39]
	v_mfma_f32_16x16x32_bf16 v[32:35], v[176:179], v[192:195], v[32:35]
	v_mfma_f32_16x16x32_bf16 v[20:23], v[168:171], v[200:203], v[20:23]
	v_mfma_f32_16x16x32_bf16 v[16:19], v[176:179], v[200:203], v[16:19]
	v_mfma_f32_16x16x32_bf16 v[4:7], v[168:171], v[208:211], v[4:7]
	v_mfma_f32_16x16x32_bf16 v[0:3], v[176:179], v[208:211], v[0:3]
	v_mfma_f32_16x16x32_bf16 v[52:55], v[172:175], v[188:191], v[52:55]
	v_mfma_f32_16x16x32_bf16 v[48:51], v[180:183], v[188:191], v[48:51]
	v_mfma_f32_16x16x32_bf16 v[36:39], v[172:175], v[196:199], v[36:39]
	v_mfma_f32_16x16x32_bf16 v[32:35], v[180:183], v[196:199], v[32:35]
	v_mfma_f32_16x16x32_bf16 v[20:23], v[172:175], v[204:207], v[20:23]
	v_mfma_f32_16x16x32_bf16 v[16:19], v[180:183], v[204:207], v[16:19]
	v_mfma_f32_16x16x32_bf16 v[4:7], v[172:175], v[212:215], v[4:7]
	v_mfma_f32_16x16x32_bf16 v[0:3], v[180:183], v[212:215], v[0:3]
	s_barrier
; #define PG8_STAGE(bufoff, gbase, voff) do { _Pragma("unroll") for (int _i = 0; _i < 2; ++_i) \
;         __builtin_amdgcn_global_load_lds((const unsigned*)((const char*)(gbase) + (voff)[_i]), (PG8_LAS unsigned*)(lds + (bufoff) + ldsw + _i * 8192), 16, 0, 0); } while (0)
; #define PG8_LDA(dst, b, h) do { _Pragma("unroll") for (int m = 0; m < 4; ++m) _Pragma("unroll") for (int k = 0; k < 2; ++k) dst[m][k] = *(const PG8_LAS bf16x8*)(lds + PG8_SA(b, h) + aoff + m * 2048 + k * 1024); } while (0)
; #define PG8_LDB(dst, b, h) do { _Pragma("unroll") for (int n = 0; n < 2; ++n) _Pragma("unroll") for (int k = 0; k < 2; ++k) dst[n][k] = *(const PG8_LAS bf16x8*)(lds + PG8_SB(b, h) + boff + n * 2048 + k * 1024); } while (0)
; #define PG8_MMA(ai, bj, At, Bt) do { __builtin_amdgcn_s_setprio(1); _Pragma("unroll") for (int m = 0; m < 4; ++m) _Pragma("unroll") for (int n = 0; n < 2; ++n) _Pragma("unroll") for (int k = 0; k < 2; ++k) \
;         acc[ai][bj][m][n] = __builtin_amdgcn_mfma_f32_16x16x32_bf16(Bt[n][k], At[m][k], acc[ai][bj][m][n], 0, 0, 0); __builtin_amdgcn_s_setprio(0); } while (0)
; #define PG8_WAIT_V(n) asm volatile("s_waitcnt vmcnt(" #n ")" ::: "memory")
; #define PG8_WAIT_L(n) asm volatile("s_waitcnt lgkmcnt(" #n ")" ::: "memory")
; #define PG8_BAR __builtin_amdgcn_s_barrier()
; #define PG8_SCHED __builtin_amdgcn_sched_barrier(0)
; template <class Epi, class Sched, bool ALIGN_EPI = false, bool SP2 = false>
; __device__ __forceinline__ void gemm_phase(PG8_LAS unsigned char* lds, const Gemm g, const Sched& S, const Epi& E) {
;     ...
;         for (int t = 0; t < nt; t += 2) {
;     ...
;             PG8_LDB(B0, 1, 0); PG8_LDB(B1, 1, 1); PG8_SCHED; PG8_LDA(At, 1, 0); PG8_STAGE(PG8_SA(0, 1), a2 + hstep, voffA);
;             PG8_WAIT_V(8); PG8_WAIT_L(0); PG8_BAR; PG8_MMA(0, 0, At, B0); PG8_MMA(0, 1, At, B1); PG8_BAR; PG8_SCHED;
;             PG8_LDA(At, 1, 1); PG8_STAGE(PG8_SB(1, 0), b3, voffB); PG8_STAGE(PG8_SB(1, 1), b3 + hstep, voffB); PG8_STAGE(PG8_SA(1, 0), a3, voffA);
;             PG8_WAIT_V(8); PG8_WAIT_L(0); PG8_BAR; PG8_MMA(1, 0, At, B0); PG8_MMA(1, 1, At, B1); PG8_BAR; PG8_SCHED;
	s_add_i32 s54, 0, 0x18000
	s_add_i32 s55, 0, 0x1c000
	v_add_u32_e32 v164, s54, v149
	v_add_u32_e32 v180, s55, v149
	ds_read_b128 v[144:147], v164
	ds_read_b128 v[154:157], v164 offset:1024
	ds_read_b128 v[158:161], v164 offset:2048
	ds_read_b128 v[164:167], v164 offset:3072
	ds_read_b128 v[168:171], v180
	ds_read_b128 v[172:175], v180 offset:1024
	ds_read_b128 v[176:179], v180 offset:2048
	ds_read_b128 v[180:183], v180 offset:3072
	s_add_u32 s36, s36, 0x40000
	s_addc_u32 s37, s37, 0
	s_mov_b32 m0, s33
	v_lshl_add_u64 v[224:225], s[36:37], 0, v[128:129]
	ds_read_b128 v[184:187], v153 offset:32768
	ds_read_b128 v[188:191], v153 offset:33792
	ds_read_b128 v[192:195], v153 offset:34816
	ds_read_b128 v[196:199], v153 offset:35840
	ds_read_b128 v[200:203], v153 offset:36864
	ds_read_b128 v[204:207], v153 offset:37888
	ds_read_b128 v[208:211], v153 offset:38912
	ds_read_b128 v[212:215], v153 offset:39936
	global_load_lds_dwordx4 v[224:225], off
	v_lshl_add_u64 v[224:225], s[36:37], 0, v[132:133]
	s_mov_b32 m0, s38
	s_nop 0
	global_load_lds_dwordx4 v[224:225], off
	s_waitcnt vmcnt(8)
	s_waitcnt lgkmcnt(0)
	s_barrier
	s_waitcnt lgkmcnt(0)
	v_mfma_f32_16x16x32_bf16 v[124:127], v[144:147], v[184:187], v[124:127]
	v_mfma_f32_16x16x32_bf16 v[120:123], v[158:161], v[184:187], v[120:123]
	v_mfma_f32_16x16x32_bf16 v[108:111], v[144:147], v[192:195], v[108:111]
	v_mfma_f32_16x16x32_bf16 v[104:107], v[158:161], v[192:195], v[104:107]
	v_mfma_f32_16x16x32_bf16 v[92:95], v[144:147], v[200:203], v[92:95]
	v_mfma_f32_16x16x32_bf16 v[88:91], v[158:161], v[200:203], v[88:91]
	v_mfma_f32_16x16x32_bf16 v[76:79], v[144:147], v[208:211], v[76:79]
	v_mfma_f32_16x16x32_bf16 v[72:75], v[158:161], v[208:211], v[72:75]
	v_mfma_f32_16x16x32_bf16 v[124:127], v[154:157], v[188:191], v[124:127]
	v_mfma_f32_16x16x32_bf16 v[120:123], v[164:167], v[188:191], v[120:123]
	v_mfma_f32_16x16x32_bf16 v[108:111], v[154:157], v[196:199], v[108:111]
	v_mfma_f32_16x16x32_bf16 v[104:107], v[164:167], v[196:199], v[104:107]
	v_mfma_f32_16x16x32_bf16 v[92:95], v[154:157], v[204:207], v[92:95]
	v_mfma_f32_16x16x32_bf16 v[88:91], v[164:167], v[204:207], v[88:91]
	v_mfma_f32_16x16x32_bf16 v[76:79], v[154:157], v[212:215], v[76:79]
	v_mfma_f32_16x16x32_bf16 v[72:75], v[164:167], v[212:215], v[72:75]
	v_mfma_f32_16x16x32_bf16 v[116:119], v[168:171], v[184:187], v[116:119]
	v_mfma_f32_16x16x32_bf16 v[112:115], v[176:179], v[184:187], v[112:115]
	v_mfma_f32_16x16x32_bf16 v[100:103], v[168:171], v[192:195], v[100:103]
	v_mfma_f32_16x16x32_bf16 v[96:99], v[176:179], v[192:195], v[96:99]
	v_mfma_f32_16x16x32_bf16 v[84:87], v[168:171], v[200:203], v[84:87]
	v_mfma_f32_16x16x32_bf16 v[80:83], v[176:179], v[200:203], v[80:83]
	v_mfma_f32_16x16x32_bf16 v[68:71], v[168:171], v[208:211], v[68:71]
	v_mfma_f32_16x16x32_bf16 v[64:67], v[176:179], v[208:211], v[64:67]
	v_mfma_f32_16x16x32_bf16 v[116:119], v[172:175], v[188:191], v[116:119]
	v_mfma_f32_16x16x32_bf16 v[112:115], v[180:183], v[188:191], v[112:115]
	v_mfma_f32_16x16x32_bf16 v[100:103], v[172:175], v[196:199], v[100:103]
	v_mfma_f32_16x16x32_bf16 v[96:99], v[180:183], v[196:199], v[96:99]
	v_mfma_f32_16x16x32_bf16 v[84:87], v[172:175], v[204:207], v[84:87]
	v_mfma_f32_16x16x32_bf16 v[80:83], v[180:183], v[204:207], v[80:83]
	v_mfma_f32_16x16x32_bf16 v[68:71], v[172:175], v[212:215], v[68:71]
	v_mfma_f32_16x16x32_bf16 v[64:67], v[180:183], v[212:215], v[64:67]
	s_barrier
	s_add_i32 s36, s54, s10
	v_lshl_add_u64 v[216:217], v[216:217], 0, s[16:17]
	s_mov_b32 m0, s36
	ds_read_b128 v[184:187], v153 offset:49152
	ds_read_b128 v[188:191], v153 offset:50176
	ds_read_b128 v[192:195], v153 offset:51200
	ds_read_b128 v[196:199], v153 offset:52224
	ds_read_b128 v[200:203], v153 offset:53248
	ds_read_b128 v[204:207], v153 offset:54272
	ds_read_b128 v[208:211], v153 offset:55296
	ds_read_b128 v[212:215], v153 offset:56320
	global_load_lds_dwordx4 v[216:217], off
	s_add_i32 m0, s36, 0x2000
	s_add_u32 s34, s34, 0x40080
	v_lshl_add_u64 v[216:217], v[218:219], 0, s[16:17]
	s_addc_u32 s35, s35, 0
	s_add_i32 s36, s55, s10
	global_load_lds_dwordx4 v[216:217], off
	v_lshl_add_u64 v[216:217], s[34:35], 0, v[130:131]
	s_mov_b32 m0, s36
	s_nop 0
	global_load_lds_dwordx4 v[216:217], off
	v_lshl_add_u64 v[216:217], s[34:35], 0, v[134:135]
	s_add_i32 m0, s36, 0x2000
	s_nop 0
	global_load_lds_dwordx4 v[216:217], off
	v_lshl_add_u64 v[216:217], v[220:221], 0, s[16:17]
	s_mov_b32 m0, s40
	s_nop 0
	global_load_lds_dwordx4 v[216:217], off
	v_lshl_add_u64 v[216:217], v[222:223], 0, s[16:17]
	s_mov_b32 m0, s41
	s_nop 0
	global_load_lds_dwordx4 v[216:217], off
	s_waitcnt vmcnt(8)
	s_waitcnt lgkmcnt(0)
	s_barrier
	s_waitcnt lgkmcnt(0)
	v_mfma_f32_16x16x32_bf16 v[60:63], v[144:147], v[184:187], v[60:63]
	v_mfma_f32_16x16x32_bf16 v[56:59], v[158:161], v[184:187], v[56:59]
	v_mfma_f32_16x16x32_bf16 v[44:47], v[144:147], v[192:195], v[44:47]
	v_mfma_f32_16x16x32_bf16 v[40:43], v[158:161], v[192:195], v[40:43]
	v_mfma_f32_16x16x32_bf16 v[28:31], v[144:147], v[200:203], v[28:31]
	v_mfma_f32_16x16x32_bf16 v[24:27], v[158:161], v[200:203], v[24:27]
	v_mfma_f32_16x16x32_bf16 v[12:15], v[144:147], v[208:211], v[12:15]
	v_mfma_f32_16x16x32_bf16 v[8:11], v[158:161], v[208:211], v[8:11]
	v_mfma_f32_16x16x32_bf16 v[60:63], v[154:157], v[188:191], v[60:63]
	v_mfma_f32_16x16x32_bf16 v[56:59], v[164:167], v[188:191], v[56:59]
	v_mfma_f32_16x16x32_bf16 v[44:47], v[154:157], v[196:199], v[44:47]
	v_mfma_f32_16x16x32_bf16 v[40:43], v[164:167], v[196:199], v[40:43]
	v_mfma_f32_16x16x32_bf16 v[28:31], v[154:157], v[204:207], v[28:31]
	v_mfma_f32_16x16x32_bf16 v[24:27], v[164:167], v[204:207], v[24:27]
	v_mfma_f32_16x16x32_bf16 v[12:15], v[154:157], v[212:215], v[12:15]
	v_mfma_f32_16x16x32_bf16 v[8:11], v[164:167], v[212:215], v[8:11]
	v_mfma_f32_16x16x32_bf16 v[52:55], v[168:171], v[184:187], v[52:55]
	v_mfma_f32_16x16x32_bf16 v[48:51], v[176:179], v[184:187], v[48:51]
	v_mfma_f32_16x16x32_bf16 v[36:39], v[168:171], v[192:195], v[36:39]
	v_mfma_f32_16x16x32_bf16 v[32:35], v[176:179], v[192:195], v[32:35]
	v_mfma_f32_16x16x32_bf16 v[20:23], v[168:171], v[200:203], v[20:23]
	v_mfma_f32_16x16x32_bf16 v[16:19], v[176:179], v[200:203], v[16:19]
	v_mfma_f32_16x16x32_bf16 v[4:7], v[168:171], v[208:211], v[4:7]
	v_mfma_f32_16x16x32_bf16 v[0:3], v[176:179], v[208:211], v[0:3]
	v_mfma_f32_16x16x32_bf16 v[52:55], v[172:175], v[188:191], v[52:55]
	v_mfma_f32_16x16x32_bf16 v[48:51], v[180:183], v[188:191], v[48:51]
	v_mfma_f32_16x16x32_bf16 v[36:39], v[172:175], v[196:199], v[36:39]
	v_mfma_f32_16x16x32_bf16 v[32:35], v[180:183], v[196:199], v[32:35]
	v_mfma_f32_16x16x32_bf16 v[20:23], v[172:175], v[204:207], v[20:23]
	v_mfma_f32_16x16x32_bf16 v[16:19], v[180:183], v[204:207], v[16:19]
	v_mfma_f32_16x16x32_bf16 v[4:7], v[172:175], v[212:215], v[4:7]
	v_mfma_f32_16x16x32_bf16 v[0:3], v[180:183], v[212:215], v[0:3]
	s_barrier
	s_add_i32 s53, s53, 2
	s_add_u32 s30, s30, 0x100
	s_addc_u32 s31, s31, 0
	s_add_u32 s51, s51, 0x100
	s_addc_u32 s52, s52, 0
	s_cmp_gt_u32 s53, 13
	s_cbranch_scc0 .LBB0_603
; #define PG8_BAR __builtin_amdgcn_s_barrier()
; template <class Epi, class Sched, bool ALIGN_EPI = false, bool SP2 = false>
; __device__ __forceinline__ void gemm_phase(PG8_LAS unsigned char* lds, const Gemm g, const Sched& S, const Epi& E) {
;     ...
;         if constexpr (ALIGN_EPI) { if (wr == 0) PG8_BAR; }
;         if constexpr (!Epi::AFTER_DRAIN) { E(acc, cur, wr, wc, fr, fq); S.done(cur); }
.Lpeel_exit1:
	s_and_b64 vcc, exec, s[18:19]
	s_cbranch_vccz .LBB0_606
	s_barrier

; #define PG8_STAGE(bufoff, gbase, voff) do { _Pragma("unroll") for (int _i = 0; _i < 2; ++_i) \
;         __builtin_amdgcn_global_load_lds((const unsigned*)((const char*)(gbase) + (voff)[_i]), (PG8_LAS unsigned*)(lds + (bufoff) + ldsw + _i * 8192), 16, 0, 0); } while (0)
; #define PG8_LDA(dst, b, h) do { _Pragma("unroll") for (int m = 0; m < 4; ++m) _Pragma("unroll") for (int k = 0; k < 2; ++k) dst[m][k] = *(const PG8_LAS bf16x8*)(lds + PG8_SA(b, h) + aoff + m * 2048 + k * 1024); } while (0)
; #define PG8_LDB(dst, b, h) do { _Pragma("unroll") for (int n = 0; n < 2; ++n) _Pragma("unroll") for (int k = 0; k < 2; ++k) dst[n][k] = *(const PG8_LAS bf16x8*)(lds + PG8_SB(b, h) + boff + n * 2048 + k * 1024); } while (0)
; #define PG8_WAIT_V(n) asm volatile("s_waitcnt vmcnt(" #n ")" ::: "memory")
; #define PG8_WAIT_L(n) asm volatile("s_waitcnt lgkmcnt(" #n ")" ::: "memory")
; #define PG8_BAR __builtin_amdgcn_s_barrier()
; template <class Epi, class Sched, bool ALIGN_EPI = false, bool SP2 = false>
; __device__ __forceinline__ void gemm_phase(PG8_LAS unsigned char* lds, const Gemm g, const Sched& S, const Epi& E) {
;     ...
;                 for (int n = 0; n < 2; ++n) acc[a][b][m][n] = (f32x4){0.f, 0.f, 0.f, 0.f};
;     ...
;         const bool has_next = S.next(ui + 1, nxt);
;         const char* nA = has_next ? (const char*)g.A + (size_t)nxt.pm * tstep : cA; const char* nB = has_next ? (const char*)g.Bt + (size_t)nxt.pn * tstep : cB;
;         for (int t = 0; t < nt; t += 2) {
;             const bool last = (t == nt - 2);
;             const char* a1 = cA + (size_t)(t + 1) * kstep;
;             const char* a2 = last ? nA : cA + (size_t)(t + 2) * kstep; const char* b2 = last ? nB : cB + (size_t)(t + 2) * kstep;
;             const char* a3 = a2 + kstep; const char* b3 = b2 + kstep;
;             if (last && has_next) S.a_ready(nxt);
;             if constexpr (SP2) {
;             PG8_LDB(B0, 0, 0); PG8_LDB(B1, 0, 1); PG8_SCHED; PG8_LDA(At, 0, 0); PG8_STAGE(PG8_SA(1, 1), a1 + hstep, voffA);
;             PG8_WAIT_V(8); PG8_WAIT_L(0); PG8_BAR; PG8_MMA(0, 0, At, B0); PG8_MMA(0, 1, At, B1); PG8_BAR; PG8_SCHED;
;             PG8_LDA(At, 0, 1); PG8_STAGE(PG8_SB(0, 0), b2, voffB); PG8_STAGE(PG8_SB(0, 1), b2 + hstep, voffB); PG8_STAGE(PG8_SA(0, 0), a2, voffA);
;             PG8_WAIT_V(8); PG8_WAIT_L(0); PG8_BAR; PG8_MMA(1, 0, At, B0); PG8_MMA(1, 1, At, B1); PG8_BAR; PG8_SCHED;
.LBB0_712:
	s_ashr_i32 s19, s18, 31
	s_lshl_b64 s[20:21], s[18:19], 19
	s_add_u32 s20, s68, s20
	s_addc_u32 s21, s69, s21
	s_and_b64 s[22:23], s[4:5], exec
	s_cselect_b32 s19, s21, s27
	s_cselect_b32 s43, s20, s26
	s_ashr_i32 s17, s16, 31
	s_lshl_b64 s[22:23], s[16:17], 19
	s_add_u32 s22, s74, s22
	s_addc_u32 s23, s75, s23
	s_and_b64 s[30:31], s[4:5], exec
	s_cselect_b32 s17, s23, s29
	s_cselect_b32 s46, s22, s28
	s_add_u32 s26, s26, 0x40080
	s_addc_u32 s27, s27, 0
	s_add_u32 s47, s28, 0x100
	s_addc_u32 s48, s29, 0
	s_mov_b32 s49, -2
	ds_read_b128 v[144:147], v157
	ds_read_b128 v[148:151], v157 offset:1024
	ds_read_b128 v[164:167], v157 offset:2048
	ds_read_b128 v[168:171], v157 offset:3072
	ds_read_b128 v[172:175], v158
	ds_read_b128 v[176:179], v158 offset:1024
	ds_read_b128 v[180:183], v158 offset:2048
	ds_read_b128 v[184:187], v158 offset:3072
	s_add_u32 s28, s26, 0xfffc0080
	s_addc_u32 s29, s27, -1
	s_cmp_eq_u32 s49, 12
	s_cselect_b32 s31, s19, s29
	s_cselect_b32 s30, s43, s28
	s_cselect_b32 s29, s17, s48
	s_cselect_b32 s28, s46, s47
	v_lshl_add_u64 v[160:161], s[26:27], 0, v[136:137]
	s_add_i32 m0, s11, 0xc000
	ds_read_b128 v[188:191], v159
	ds_read_b128 v[192:195], v159 offset:1024
	ds_read_b128 v[196:199], v159 offset:2048
	ds_read_b128 v[200:203], v159 offset:3072
	ds_read_b128 v[204:207], v159 offset:4096
	ds_read_b128 v[208:211], v159 offset:5120
	ds_read_b128 v[212:215], v159 offset:6144
	ds_read_b128 v[216:219], v159 offset:7168
	global_load_lds_dwordx4 v[160:161], off
	v_lshl_add_u64 v[160:161], s[26:27], 0, v[138:139]
	s_add_i32 m0, s11, 0xe000
	s_nop 0
	global_load_lds_dwordx4 v[160:161], off
	s_waitcnt vmcnt(8)
	s_waitcnt lgkmcnt(0)
	s_barrier
	s_waitcnt lgkmcnt(0)
	v_mfma_f32_16x16x32_bf16 v[124:127], v[144:147], v[188:191], 0
	v_mfma_f32_16x16x32_bf16 v[120:123], v[164:167], v[188:191], 0
	v_mfma_f32_16x16x32_bf16 v[108:111], v[144:147], v[196:199], 0
	v_mfma_f32_16x16x32_bf16 v[104:107], v[164:167], v[196:199], 0
	v_mfma_f32_16x16x32_bf16 v[92:95], v[144:147], v[204:207], 0
	v_mfma_f32_16x16x32_bf16 v[88:91], v[164:167], v[204:207], 0
	v_mfma_f32_16x16x32_bf16 v[76:79], v[144:147], v[212:215], 0
	v_mfma_f32_16x16x32_bf16 v[72:75], v[164:167], v[212:215], 0
	v_mfma_f32_16x16x32_bf16 v[124:127], v[148:151], v[192:195], v[124:127]
	v_mfma_f32_16x16x32_bf16 v[120:123], v[168:171], v[192:195], v[120:123]
	v_mfma_f32_16x16x32_bf16 v[108:111], v[148:151], v[200:203], v[108:111]
	v_mfma_f32_16x16x32_bf16 v[104:107], v[168:171], v[200:203], v[104:107]
	v_mfma_f32_16x16x32_bf16 v[92:95], v[148:151], v[208:211], v[92:95]
	v_mfma_f32_16x16x32_bf16 v[88:91], v[168:171], v[208:211], v[88:91]
	v_mfma_f32_16x16x32_bf16 v[76:79], v[148:151], v[216:219], v[76:79]
	v_mfma_f32_16x16x32_bf16 v[72:75], v[168:171], v[216:219], v[72:75]
	v_mfma_f32_16x16x32_bf16 v[116:119], v[172:175], v[188:191], 0
	v_mfma_f32_16x16x32_bf16 v[112:115], v[180:183], v[188:191], 0
	v_mfma_f32_16x16x32_bf16 v[100:103], v[172:175], v[196:199], 0
	v_mfma_f32_16x16x32_bf16 v[96:99], v[180:183], v[196:199], 0
	v_mfma_f32_16x16x32_bf16 v[84:87], v[172:175], v[204:207], 0
	v_mfma_f32_16x16x32_bf16 v[80:83], v[180:183], v[204:207], 0
	v_mfma_f32_16x16x32_bf16 v[68:71], v[172:175], v[212:215], 0
	v_mfma_f32_16x16x32_bf16 v[64:67], v[180:183], v[212:215], 0
	v_mfma_f32_16x16x32_bf16 v[116:119], v[176:179], v[192:195], v[116:119]
	v_mfma_f32_16x16x32_bf16 v[112:115], v[184:187], v[192:195], v[112:115]
	v_mfma_f32_16x16x32_bf16 v[100:103], v[176:179], v[200:203], v[100:103]
	v_mfma_f32_16x16x32_bf16 v[96:99], v[184:187], v[200:203], v[96:99]
	v_mfma_f32_16x16x32_bf16 v[84:87], v[176:179], v[208:211], v[84:87]
	v_mfma_f32_16x16x32_bf16 v[80:83], v[184:187], v[208:211], v[80:83]
	v_mfma_f32_16x16x32_bf16 v[68:71], v[176:179], v[216:219], v[68:71]
	v_mfma_f32_16x16x32_bf16 v[64:67], v[184:187], v[216:219], v[64:67]
	s_barrier
	s_add_i32 s50, s39, s3
	v_lshl_add_u64 v[160:161], s[28:29], 0, v[130:131]
	s_mov_b32 m0, s50
	ds_read_b128 v[188:191], v159 offset:16384
	ds_read_b128 v[192:195], v159 offset:17408
	ds_read_b128 v[196:199], v159 offset:18432
	ds_read_b128 v[200:203], v159 offset:19456
	ds_read_b128 v[204:207], v159 offset:20480
	ds_read_b128 v[208:211], v159 offset:21504
	ds_read_b128 v[212:215], v159 offset:22528
	ds_read_b128 v[216:219], v159 offset:23552
	global_load_lds_dwordx4 v[160:161], off
	s_add_i32 m0, s50, 0x2000
	s_add_u32 s50, s28, 0x40000
	v_lshl_add_u64 v[220:221], s[28:29], 0, v[134:135]
	s_addc_u32 s51, s29, 0
	s_add_i32 s52, s40, s3
	global_load_lds_dwordx4 v[220:221], off
	v_lshl_add_u64 v[222:223], s[50:51], 0, v[130:131]
	s_mov_b32 m0, s52
	v_lshl_add_u64 v[224:225], s[30:31], 0, v[132:133]
	global_load_lds_dwordx4 v[222:223], off
	v_lshl_add_u64 v[222:223], s[50:51], 0, v[134:135]
	s_add_i32 m0, s52, 0x2000
	s_nop 0
	global_load_lds_dwordx4 v[222:223], off
	v_lshl_add_u64 v[222:223], s[30:31], 0, v[128:129]
	s_mov_b32 m0, s11
	s_nop 0
	global_load_lds_dwordx4 v[222:223], off
	s_mov_b32 m0, s25
	s_nop 0
	global_load_lds_dwordx4 v[224:225], off
	s_waitcnt vmcnt(8)
	s_waitcnt lgkmcnt(0)
	s_barrier
; #define PG8_STAGE(bufoff, gbase, voff) do { _Pragma("unroll") for (int _i = 0; _i < 2; ++_i) \
;         __builtin_amdgcn_global_load_lds((const unsigned*)((const char*)(gbase) + (voff)[_i]), (PG8_LAS unsigned*)(lds + (bufoff) + ldsw + _i * 8192), 16, 0, 0); } while (0)
; #define PG8_LDA(dst, b, h) do { _Pragma("unroll") for (int m = 0; m < 4; ++m) _Pragma("unroll") for (int k = 0; k < 2; ++k) dst[m][k] = *(const PG8_LAS bf16x8*)(lds + PG8_SA(b, h) + aoff + m * 2048 + k * 1024); } while (0)
; #define PG8_LDB(dst, b, h) do { _Pragma("unroll") for (int n = 0; n < 2; ++n) _Pragma("unroll") for (int k = 0; k < 2; ++k) dst[n][k] = *(const PG8_LAS bf16x8*)(lds + PG8_SB(b, h) + boff + n * 2048 + k * 1024); } while (0)
; #define PG8_MMA(ai, bj, At, Bt) do { __builtin_amdgcn_s_setprio(1); _Pragma("unroll") for (int m = 0; m < 4; ++m) _Pragma("unroll") for (int n = 0; n < 2; ++n) _Pragma("unroll") for (int k = 0; k < 2; ++k) \
;         acc[ai][bj][m][n] = __builtin_amdgcn_mfma_f32_16x16x32_bf16(Bt[n][k], At[m][k], acc[ai][bj][m][n], 0, 0, 0); __builtin_amdgcn_s_setprio(0); } while (0)
; #define PG8_WAIT_V(n) asm volatile("s_waitcnt vmcnt(" #n ")" ::: "memory")
; #define PG8_WAIT_L(n) asm volatile("s_waitcnt lgkmcnt(" #n ")" ::: "memory")
; #define PG8_BAR __builtin_amdgcn_s_barrier()
; #define PG8_SCHED __builtin_amdgcn_sched_barrier(0)
; template <class Epi, class Sched, bool ALIGN_EPI = false, bool SP2 = false>
; __device__ __forceinline__ void gemm_phase(PG8_LAS unsigned char* lds, const Gemm g, const Sched& S, const Epi& E) {
;     ...
;             PG8_WAIT_V(8); PG8_WAIT_L(0); PG8_BAR; PG8_MMA(1, 0, At, B0); PG8_MMA(1, 1, At, B1); PG8_BAR; PG8_SCHED;
;             PG8_LDB(B0, 1, 0); PG8_LDB(B1, 1, 1); PG8_SCHED; PG8_LDA(At, 1, 0); PG8_STAGE(PG8_SA(0, 1), a2 + hstep, voffA);
;             PG8_WAIT_V(8); PG8_WAIT_L(0); PG8_BAR; PG8_MMA(0, 0, At, B0); PG8_MMA(0, 1, At, B1); PG8_BAR; PG8_SCHED;
	s_waitcnt lgkmcnt(0)
	v_mfma_f32_16x16x32_bf16 v[60:63], v[144:147], v[188:191], 0
	v_mfma_f32_16x16x32_bf16 v[56:59], v[164:167], v[188:191], 0
	v_mfma_f32_16x16x32_bf16 v[44:47], v[144:147], v[196:199], 0
	v_mfma_f32_16x16x32_bf16 v[40:43], v[164:167], v[196:199], 0
	v_mfma_f32_16x16x32_bf16 v[28:31], v[144:147], v[204:207], 0
	v_mfma_f32_16x16x32_bf16 v[24:27], v[164:167], v[204:207], 0
	v_mfma_f32_16x16x32_bf16 v[12:15], v[144:147], v[212:215], 0
	v_mfma_f32_16x16x32_bf16 v[8:11], v[164:167], v[212:215], 0
	v_mfma_f32_16x16x32_bf16 v[60:63], v[148:151], v[192:195], v[60:63]
	v_mfma_f32_16x16x32_bf16 v[56:59], v[168:171], v[192:195], v[56:59]
	v_mfma_f32_16x16x32_bf16 v[44:47], v[148:151], v[200:203], v[44:47]
	v_mfma_f32_16x16x32_bf16 v[40:43], v[168:171], v[200:203], v[40:43]
	v_mfma_f32_16x16x32_bf16 v[28:31], v[148:151], v[208:211], v[28:31]
	v_mfma_f32_16x16x32_bf16 v[24:27], v[168:171], v[208:211], v[24:27]
	v_mfma_f32_16x16x32_bf16 v[12:15], v[148:151], v[216:219], v[12:15]
	v_mfma_f32_16x16x32_bf16 v[8:11], v[168:171], v[216:219], v[8:11]
	v_mfma_f32_16x16x32_bf16 v[52:55], v[172:175], v[188:191], 0
	v_mfma_f32_16x16x32_bf16 v[48:51], v[180:183], v[188:191], 0
	v_mfma_f32_16x16x32_bf16 v[36:39], v[172:175], v[196:199], 0
	v_mfma_f32_16x16x32_bf16 v[32:35], v[180:183], v[196:199], 0
	v_mfma_f32_16x16x32_bf16 v[20:23], v[172:175], v[204:207], 0
	v_mfma_f32_16x16x32_bf16 v[16:19], v[180:183], v[204:207], 0
	v_mfma_f32_16x16x32_bf16 v[4:7], v[172:175], v[212:215], 0
	v_mfma_f32_16x16x32_bf16 v[0:3], v[180:183], v[212:215], 0
	v_mfma_f32_16x16x32_bf16 v[52:55], v[176:179], v[192:195], v[52:55]
	v_mfma_f32_16x16x32_bf16 v[48:51], v[184:187], v[192:195], v[48:51]
	v_mfma_f32_16x16x32_bf16 v[36:39], v[176:179], v[200:203], v[36:39]
	v_mfma_f32_16x16x32_bf16 v[32:35], v[184:187], v[200:203], v[32:35]
	v_mfma_f32_16x16x32_bf16 v[20:23], v[176:179], v[208:211], v[20:23]
	v_mfma_f32_16x16x32_bf16 v[16:19], v[184:187], v[208:211], v[16:19]
	v_mfma_f32_16x16x32_bf16 v[4:7], v[176:179], v[216:219], v[4:7]
	v_mfma_f32_16x16x32_bf16 v[0:3], v[184:187], v[216:219], v[0:3]
	s_barrier
	s_add_i32 s50, 0, 0x18000
	s_add_i32 s51, 0, 0x1c000
	v_add_u32_e32 v168, s50, v155
	v_add_u32_e32 v184, s51, v155
	ds_read_b128 v[144:147], v168
	ds_read_b128 v[148:151], v168 offset:1024
	ds_read_b128 v[164:167], v168 offset:2048
	ds_read_b128 v[168:171], v168 offset:3072
	ds_read_b128 v[172:175], v184
	ds_read_b128 v[176:179], v184 offset:1024
	ds_read_b128 v[180:183], v184 offset:2048
	ds_read_b128 v[184:187], v184 offset:3072
	s_add_u32 s30, s30, 0x40000
	s_addc_u32 s31, s31, 0
	s_mov_b32 m0, s33
	v_lshl_add_u64 v[226:227], s[30:31], 0, v[128:129]
	ds_read_b128 v[188:191], v159 offset:32768
	ds_read_b128 v[192:195], v159 offset:33792
	ds_read_b128 v[196:199], v159 offset:34816
	ds_read_b128 v[200:203], v159 offset:35840
	ds_read_b128 v[204:207], v159 offset:36864
	ds_read_b128 v[208:211], v159 offset:37888
	ds_read_b128 v[212:215], v159 offset:38912
	ds_read_b128 v[216:219], v159 offset:39936
	global_load_lds_dwordx4 v[226:227], off
	v_lshl_add_u64 v[226:227], s[30:31], 0, v[132:133]
	s_mov_b32 m0, s34
	s_nop 0
	global_load_lds_dwordx4 v[226:227], off
	s_waitcnt vmcnt(8)
	s_waitcnt lgkmcnt(0)
	s_barrier
	s_waitcnt lgkmcnt(0)
	v_mfma_f32_16x16x32_bf16 v[124:127], v[144:147], v[188:191], v[124:127]
	v_mfma_f32_16x16x32_bf16 v[120:123], v[164:167], v[188:191], v[120:123]
	v_mfma_f32_16x16x32_bf16 v[108:111], v[144:147], v[196:199], v[108:111]
	v_mfma_f32_16x16x32_bf16 v[104:107], v[164:167], v[196:199], v[104:107]
	v_mfma_f32_16x16x32_bf16 v[92:95], v[144:147], v[204:207], v[92:95]
	v_mfma_f32_16x16x32_bf16 v[88:91], v[164:167], v[204:207], v[88:91]
	v_mfma_f32_16x16x32_bf16 v[76:79], v[144:147], v[212:215], v[76:79]
	v_mfma_f32_16x16x32_bf16 v[72:75], v[164:167], v[212:215], v[72:75]
	v_mfma_f32_16x16x32_bf16 v[124:127], v[148:151], v[192:195], v[124:127]
	v_mfma_f32_16x16x32_bf16 v[120:123], v[168:171], v[192:195], v[120:123]
	v_mfma_f32_16x16x32_bf16 v[108:111], v[148:151], v[200:203], v[108:111]
	v_mfma_f32_16x16x32_bf16 v[104:107], v[168:171], v[200:203], v[104:107]
	v_mfma_f32_16x16x32_bf16 v[92:95], v[148:151], v[208:211], v[92:95]
	v_mfma_f32_16x16x32_bf16 v[88:91], v[168:171], v[208:211], v[88:91]
	v_mfma_f32_16x16x32_bf16 v[76:79], v[148:151], v[216:219], v[76:79]
	v_mfma_f32_16x16x32_bf16 v[72:75], v[168:171], v[216:219], v[72:75]
	v_mfma_f32_16x16x32_bf16 v[116:119], v[172:175], v[188:191], v[116:119]
	v_mfma_f32_16x16x32_bf16 v[112:115], v[180:183], v[188:191], v[112:115]
	v_mfma_f32_16x16x32_bf16 v[100:103], v[172:175], v[196:199], v[100:103]
	v_mfma_f32_16x16x32_bf16 v[96:99], v[180:183], v[196:199], v[96:99]
	v_mfma_f32_16x16x32_bf16 v[84:87], v[172:175], v[204:207], v[84:87]
	v_mfma_f32_16x16x32_bf16 v[80:83], v[180:183], v[204:207], v[80:83]
	v_mfma_f32_16x16x32_bf16 v[68:71], v[172:175], v[212:215], v[68:71]
	v_mfma_f32_16x16x32_bf16 v[64:67], v[180:183], v[212:215], v[64:67]
	v_mfma_f32_16x16x32_bf16 v[116:119], v[176:179], v[192:195], v[116:119]
	v_mfma_f32_16x16x32_bf16 v[112:115], v[184:187], v[192:195], v[112:115]
	v_mfma_f32_16x16x32_bf16 v[100:103], v[176:179], v[200:203], v[100:103]
	v_mfma_f32_16x16x32_bf16 v[96:99], v[184:187], v[200:203], v[96:99]
	v_mfma_f32_16x16x32_bf16 v[84:87], v[176:179], v[208:211], v[84:87]
	v_mfma_f32_16x16x32_bf16 v[80:83], v[184:187], v[208:211], v[80:83]
	v_mfma_f32_16x16x32_bf16 v[68:71], v[176:179], v[216:219], v[68:71]
	v_mfma_f32_16x16x32_bf16 v[64:67], v[184:187], v[216:219], v[64:67]
	s_barrier
; #define PG8_STAGE(bufoff, gbase, voff) do { _Pragma("unroll") for (int _i = 0; _i < 2; ++_i) \
;         __builtin_amdgcn_global_load_lds((const unsigned*)((const char*)(gbase) + (voff)[_i]), (PG8_LAS unsigned*)(lds + (bufoff) + ldsw + _i * 8192), 16, 0, 0); } while (0)
; #define PG8_LDA(dst, b, h) do { _Pragma("unroll") for (int m = 0; m < 4; ++m) _Pragma("unroll") for (int k = 0; k < 2; ++k) dst[m][k] = *(const PG8_LAS bf16x8*)(lds + PG8_SA(b, h) + aoff + m * 2048 + k * 1024); } while (0)
; #define PG8_LDB(dst, b, h) do { _Pragma("unroll") for (int n = 0; n < 2; ++n) _Pragma("unroll") for (int k = 0; k < 2; ++k) dst[n][k] = *(const PG8_LAS bf16x8*)(lds + PG8_SB(b, h) + boff + n * 2048 + k * 1024); } while (0)
; #define PG8_MMA(ai, bj, At, Bt) do { __builtin_amdgcn_s_setprio(1); _Pragma("unroll") for (int m = 0; m < 4; ++m) _Pragma("unroll") for (int n = 0; n < 2; ++n) _Pragma("unroll") for (int k = 0; k < 2; ++k) \
;         acc[ai][bj][m][n] = __builtin_amdgcn_mfma_f32_16x16x32_bf16(Bt[n][k], At[m][k], acc[ai][bj][m][n], 0, 0, 0); __builtin_amdgcn_s_setprio(0); } while (0)
; #define PG8_WAIT_V(n) asm volatile("s_waitcnt vmcnt(" #n ")" ::: "memory")
; #define PG8_WAIT_L(n) asm volatile("s_waitcnt lgkmcnt(" #n ")" ::: "memory")
; #define PG8_BAR __builtin_amdgcn_s_barrier()
; #define PG8_SCHED __builtin_amdgcn_sched_barrier(0)
; template <class Epi, class Sched, bool ALIGN_EPI = false, bool SP2 = false>
; __device__ __forceinline__ void gemm_phase(PG8_LAS unsigned char* lds, const Gemm g, const Sched& S, const Epi& E) {
;     ...
;         for (int t = 0; t < nt; t += 2) {
;             const bool last = (t == nt - 2);
;             const char* a1 = cA + (size_t)(t + 1) * kstep;
;             const char* a2 = last ? nA : cA + (size_t)(t + 2) * kstep; const char* b2 = last ? nB : cB + (size_t)(t + 2) * kstep;
;             const char* a3 = a2 + kstep; const char* b3 = b2 + kstep;
;             if (last && has_next) S.a_ready(nxt);
;             if constexpr (SP2) {
;             PG8_LDB(B0, 0, 0); PG8_LDB(B1, 0, 1); PG8_SCHED; PG8_LDA(At, 0, 0); PG8_STAGE(PG8_SA(1, 1), a1 + hstep, voffA);
;     ...
;             PG8_LDA(At, 1, 1); PG8_STAGE(PG8_SB(1, 0), b3, voffB); PG8_STAGE(PG8_SB(1, 1), b3 + hstep, voffB); PG8_STAGE(PG8_SA(1, 0), a3, voffA);
;             PG8_WAIT_V(8); PG8_WAIT_L(0); PG8_BAR; PG8_MMA(1, 0, At, B0); PG8_MMA(1, 1, At, B1); PG8_BAR; PG8_SCHED;
	s_add_i32 s30, s50, s3
	v_lshl_add_u64 v[160:161], v[160:161], 0, s[6:7]
	s_mov_b32 m0, s30
	ds_read_b128 v[188:191], v159 offset:49152
	ds_read_b128 v[192:195], v159 offset:50176
	ds_read_b128 v[196:199], v159 offset:51200
	ds_read_b128 v[200:203], v159 offset:52224
	ds_read_b128 v[204:207], v159 offset:53248
	ds_read_b128 v[208:211], v159 offset:54272
	ds_read_b128 v[212:215], v159 offset:55296
	ds_read_b128 v[216:219], v159 offset:56320
	global_load_lds_dwordx4 v[160:161], off
	s_add_i32 m0, s30, 0x2000
	s_add_u32 s28, s28, 0x40080
	v_lshl_add_u64 v[160:161], v[220:221], 0, s[6:7]
	s_addc_u32 s29, s29, 0
	s_add_i32 s30, s51, s3
	global_load_lds_dwordx4 v[160:161], off
	v_lshl_add_u64 v[160:161], s[28:29], 0, v[130:131]
	s_mov_b32 m0, s30
	s_nop 0
	global_load_lds_dwordx4 v[160:161], off
	v_lshl_add_u64 v[160:161], s[28:29], 0, v[134:135]
	s_add_i32 m0, s30, 0x2000
	s_nop 0
	global_load_lds_dwordx4 v[160:161], off
	v_lshl_add_u64 v[160:161], v[222:223], 0, s[6:7]
	s_mov_b32 m0, s37
	s_nop 0
	global_load_lds_dwordx4 v[160:161], off
	v_lshl_add_u64 v[160:161], v[224:225], 0, s[6:7]
	s_mov_b32 m0, s38
	s_nop 0
	global_load_lds_dwordx4 v[160:161], off
	s_waitcnt vmcnt(8)
	s_waitcnt lgkmcnt(0)
	s_barrier
	s_waitcnt lgkmcnt(0)
	v_mfma_f32_16x16x32_bf16 v[60:63], v[144:147], v[188:191], v[60:63]
	v_mfma_f32_16x16x32_bf16 v[56:59], v[164:167], v[188:191], v[56:59]
	v_mfma_f32_16x16x32_bf16 v[44:47], v[144:147], v[196:199], v[44:47]
	v_mfma_f32_16x16x32_bf16 v[40:43], v[164:167], v[196:199], v[40:43]
	v_mfma_f32_16x16x32_bf16 v[28:31], v[144:147], v[204:207], v[28:31]
	v_mfma_f32_16x16x32_bf16 v[24:27], v[164:167], v[204:207], v[24:27]
	v_mfma_f32_16x16x32_bf16 v[12:15], v[144:147], v[212:215], v[12:15]
	v_mfma_f32_16x16x32_bf16 v[8:11], v[164:167], v[212:215], v[8:11]
	v_mfma_f32_16x16x32_bf16 v[60:63], v[148:151], v[192:195], v[60:63]
	v_mfma_f32_16x16x32_bf16 v[56:59], v[168:171], v[192:195], v[56:59]
	v_mfma_f32_16x16x32_bf16 v[44:47], v[148:151], v[200:203], v[44:47]
	v_mfma_f32_16x16x32_bf16 v[40:43], v[168:171], v[200:203], v[40:43]
	v_mfma_f32_16x16x32_bf16 v[28:31], v[148:151], v[208:211], v[28:31]
	v_mfma_f32_16x16x32_bf16 v[24:27], v[168:171], v[208:211], v[24:27]
	v_mfma_f32_16x16x32_bf16 v[12:15], v[148:151], v[216:219], v[12:15]
	v_mfma_f32_16x16x32_bf16 v[8:11], v[168:171], v[216:219], v[8:11]
	v_mfma_f32_16x16x32_bf16 v[52:55], v[172:175], v[188:191], v[52:55]
	v_mfma_f32_16x16x32_bf16 v[48:51], v[180:183], v[188:191], v[48:51]
	v_mfma_f32_16x16x32_bf16 v[36:39], v[172:175], v[196:199], v[36:39]
	v_mfma_f32_16x16x32_bf16 v[32:35], v[180:183], v[196:199], v[32:35]
	v_mfma_f32_16x16x32_bf16 v[20:23], v[172:175], v[204:207], v[20:23]
	v_mfma_f32_16x16x32_bf16 v[16:19], v[180:183], v[204:207], v[16:19]
	v_mfma_f32_16x16x32_bf16 v[4:7], v[172:175], v[212:215], v[4:7]
	v_mfma_f32_16x16x32_bf16 v[0:3], v[180:183], v[212:215], v[0:3]
	v_mfma_f32_16x16x32_bf16 v[52:55], v[176:179], v[192:195], v[52:55]
	v_mfma_f32_16x16x32_bf16 v[48:51], v[184:187], v[192:195], v[48:51]
	v_mfma_f32_16x16x32_bf16 v[36:39], v[176:179], v[200:203], v[36:39]
	v_mfma_f32_16x16x32_bf16 v[32:35], v[184:187], v[200:203], v[32:35]
	v_mfma_f32_16x16x32_bf16 v[20:23], v[176:179], v[208:211], v[20:23]
	v_mfma_f32_16x16x32_bf16 v[16:19], v[184:187], v[208:211], v[16:19]
	v_mfma_f32_16x16x32_bf16 v[4:7], v[176:179], v[216:219], v[4:7]
	v_mfma_f32_16x16x32_bf16 v[0:3], v[184:187], v[216:219], v[0:3]
	s_barrier
	s_add_i32 s49, s49, 2
	s_add_u32 s26, s26, 0x100
	s_addc_u32 s27, s27, 0
	s_add_u32 s47, s47, 0x100
	s_addc_u32 s48, s48, 0
	s_cmp_gt_u32 s49, 13
	s_cbranch_scc1 .Lpeel_exit2
.LBB0_713:
	ds_read_b128 v[144:147], v157
	ds_read_b128 v[148:151], v157 offset:1024
	ds_read_b128 v[164:167], v157 offset:2048
	ds_read_b128 v[168:171], v157 offset:3072
	ds_read_b128 v[172:175], v158
	ds_read_b128 v[176:179], v158 offset:1024
	ds_read_b128 v[180:183], v158 offset:2048
	ds_read_b128 v[184:187], v158 offset:3072
	s_add_u32 s28, s26, 0xfffc0080
	s_addc_u32 s29, s27, -1
	s_cmp_eq_u32 s49, 12
	s_cselect_b32 s31, s19, s29
	s_cselect_b32 s30, s43, s28
	s_cselect_b32 s29, s17, s48
	s_cselect_b32 s28, s46, s47
	v_lshl_add_u64 v[160:161], s[26:27], 0, v[136:137]
	s_add_i32 m0, s11, 0xc000
	ds_read_b128 v[188:191], v159
	ds_read_b128 v[192:195], v159 offset:1024
	ds_read_b128 v[196:199], v159 offset:2048
	ds_read_b128 v[200:203], v159 offset:3072
	ds_read_b128 v[204:207], v159 offset:4096
	ds_read_b128 v[208:211], v159 offset:5120
	ds_read_b128 v[212:215], v159 offset:6144
	ds_read_b128 v[216:219], v159 offset:7168
	global_load_lds_dwordx4 v[160:161], off
	v_lshl_add_u64 v[160:161], s[26:27], 0, v[138:139]
	s_add_i32 m0, s11, 0xe000
	s_nop 0
	global_load_lds_dwordx4 v[160:161], off
	s_waitcnt vmcnt(8)
	s_waitcnt lgkmcnt(0)
	s_barrier
; #define PG8_STAGE(bufoff, gbase, voff) do { _Pragma("unroll") for (int _i = 0; _i < 2; ++_i) \
;         __builtin_amdgcn_global_load_lds((const unsigned*)((const char*)(gbase) + (voff)[_i]), (PG8_LAS unsigned*)(lds + (bufoff) + ldsw + _i * 8192), 16, 0, 0); } while (0)
; #define PG8_LDA(dst, b, h) do { _Pragma("unroll") for (int m = 0; m < 4; ++m) _Pragma("unroll") for (int k = 0; k < 2; ++k) dst[m][k] = *(const PG8_LAS bf16x8*)(lds + PG8_SA(b, h) + aoff + m * 2048 + k * 1024); } while (0)
; #define PG8_LDB(dst, b, h) do { _Pragma("unroll") for (int n = 0; n < 2; ++n) _Pragma("unroll") for (int k = 0; k < 2; ++k) dst[n][k] = *(const PG8_LAS bf16x8*)(lds + PG8_SB(b, h) + boff + n * 2048 + k * 1024); } while (0)
; #define PG8_MMA(ai, bj, At, Bt) do { __builtin_amdgcn_s_setprio(1); _Pragma("unroll") for (int m = 0; m < 4; ++m) _Pragma("unroll") for (int n = 0; n < 2; ++n) _Pragma("unroll") for (int k = 0; k < 2; ++k) \
;         acc[ai][bj][m][n] = __builtin_amdgcn_mfma_f32_16x16x32_bf16(Bt[n][k], At[m][k], acc[ai][bj][m][n], 0, 0, 0); __builtin_amdgcn_s_setprio(0); } while (0)
; #define PG8_WAIT_V(n) asm volatile("s_waitcnt vmcnt(" #n ")" ::: "memory")
; #define PG8_WAIT_L(n) asm volatile("s_waitcnt lgkmcnt(" #n ")" ::: "memory")
; #define PG8_BAR __builtin_amdgcn_s_barrier()
; #define PG8_SCHED __builtin_amdgcn_sched_barrier(0)
; template <class Epi, class Sched, bool ALIGN_EPI = false, bool SP2 = false>
; __device__ __forceinline__ void gemm_phase(PG8_LAS unsigned char* lds, const Gemm g, const Sched& S, const Epi& E) {
;     ...
;             PG8_LDB(B0, 0, 0); PG8_LDB(B1, 0, 1); PG8_SCHED; PG8_LDA(At, 0, 0); PG8_STAGE(PG8_SA(1, 1), a1 + hstep, voffA);
;             PG8_WAIT_V(8); PG8_WAIT_L(0); PG8_BAR; PG8_MMA(0, 0, At, B0); PG8_MMA(0, 1, At, B1); PG8_BAR; PG8_SCHED;
;             PG8_LDA(At, 0, 1); PG8_STAGE(PG8_SB(0, 0), b2, voffB); PG8_STAGE(PG8_SB(0, 1), b2 + hstep, voffB); PG8_STAGE(PG8_SA(0, 0), a2, voffA);
;             PG8_WAIT_V(8); PG8_WAIT_L(0); PG8_BAR; PG8_MMA(1, 0, At, B0); PG8_MMA(1, 1, At, B1); PG8_BAR; PG8_SCHED;
;             PG8_LDB(B0, 1, 0); PG8_LDB(B1, 1, 1); PG8_SCHED; PG8_LDA(At, 1, 0); PG8_STAGE(PG8_SA(0, 1), a2 + hstep, voffA);
;             PG8_WAIT_V(8); PG8_WAIT_L(0); PG8_BAR; PG8_MMA(0, 0, At, B0); PG8_MMA(0, 1, At, B1); PG8_BAR; PG8_SCHED;
	s_waitcnt lgkmcnt(0)
	v_mfma_f32_16x16x32_bf16 v[124:127], v[144:147], v[188:191], v[124:127]
	v_mfma_f32_16x16x32_bf16 v[120:123], v[164:167], v[188:191], v[120:123]
	v_mfma_f32_16x16x32_bf16 v[108:111], v[144:147], v[196:199], v[108:111]
	v_mfma_f32_16x16x32_bf16 v[104:107], v[164:167], v[196:199], v[104:107]
	v_mfma_f32_16x16x32_bf16 v[92:95], v[144:147], v[204:207], v[92:95]
	v_mfma_f32_16x16x32_bf16 v[88:91], v[164:167], v[204:207], v[88:91]
	v_mfma_f32_16x16x32_bf16 v[76:79], v[144:147], v[212:215], v[76:79]
	v_mfma_f32_16x16x32_bf16 v[72:75], v[164:167], v[212:215], v[72:75]
	v_mfma_f32_16x16x32_bf16 v[124:127], v[148:151], v[192:195], v[124:127]
	v_mfma_f32_16x16x32_bf16 v[120:123], v[168:171], v[192:195], v[120:123]
	v_mfma_f32_16x16x32_bf16 v[108:111], v[148:151], v[200:203], v[108:111]
	v_mfma_f32_16x16x32_bf16 v[104:107], v[168:171], v[200:203], v[104:107]
	v_mfma_f32_16x16x32_bf16 v[92:95], v[148:151], v[208:211], v[92:95]
	v_mfma_f32_16x16x32_bf16 v[88:91], v[168:171], v[208:211], v[88:91]
	v_mfma_f32_16x16x32_bf16 v[76:79], v[148:151], v[216:219], v[76:79]
	v_mfma_f32_16x16x32_bf16 v[72:75], v[168:171], v[216:219], v[72:75]
	v_mfma_f32_16x16x32_bf16 v[116:119], v[172:175], v[188:191], v[116:119]
	v_mfma_f32_16x16x32_bf16 v[112:115], v[180:183], v[188:191], v[112:115]
	v_mfma_f32_16x16x32_bf16 v[100:103], v[172:175], v[196:199], v[100:103]
	v_mfma_f32_16x16x32_bf16 v[96:99], v[180:183], v[196:199], v[96:99]
	v_mfma_f32_16x16x32_bf16 v[84:87], v[172:175], v[204:207], v[84:87]
	v_mfma_f32_16x16x32_bf16 v[80:83], v[180:183], v[204:207], v[80:83]
	v_mfma_f32_16x16x32_bf16 v[68:71], v[172:175], v[212:215], v[68:71]
	v_mfma_f32_16x16x32_bf16 v[64:67], v[180:183], v[212:215], v[64:67]
	v_mfma_f32_16x16x32_bf16 v[116:119], v[176:179], v[192:195], v[116:119]
	v_mfma_f32_16x16x32_bf16 v[112:115], v[184:187], v[192:195], v[112:115]
	v_mfma_f32_16x16x32_bf16 v[100:103], v[176:179], v[200:203], v[100:103]
	v_mfma_f32_16x16x32_bf16 v[96:99], v[184:187], v[200:203], v[96:99]
	v_mfma_f32_16x16x32_bf16 v[84:87], v[176:179], v[208:211], v[84:87]
	v_mfma_f32_16x16x32_bf16 v[80:83], v[184:187], v[208:211], v[80:83]
	v_mfma_f32_16x16x32_bf16 v[68:71], v[176:179], v[216:219], v[68:71]
	v_mfma_f32_16x16x32_bf16 v[64:67], v[184:187], v[216:219], v[64:67]
	s_barrier
	s_add_i32 s50, s39, s3
	v_lshl_add_u64 v[160:161], s[28:29], 0, v[130:131]
	s_mov_b32 m0, s50
	ds_read_b128 v[188:191], v159 offset:16384
	ds_read_b128 v[192:195], v159 offset:17408
	ds_read_b128 v[196:199], v159 offset:18432
	ds_read_b128 v[200:203], v159 offset:19456
	ds_read_b128 v[204:207], v159 offset:20480
	ds_read_b128 v[208:211], v159 offset:21504
	ds_read_b128 v[212:215], v159 offset:22528
	ds_read_b128 v[216:219], v159 offset:23552
	global_load_lds_dwordx4 v[160:161], off
	s_add_i32 m0, s50, 0x2000
	s_add_u32 s50, s28, 0x40000
	v_lshl_add_u64 v[220:221], s[28:29], 0, v[134:135]
	s_addc_u32 s51, s29, 0
	s_add_i32 s52, s40, s3
	global_load_lds_dwordx4 v[220:221], off
	v_lshl_add_u64 v[222:223], s[50:51], 0, v[130:131]
	s_mov_b32 m0, s52
	v_lshl_add_u64 v[224:225], s[30:31], 0, v[132:133]
	global_load_lds_dwordx4 v[222:223], off
	v_lshl_add_u64 v[222:223], s[50:51], 0, v[134:135]
	s_add_i32 m0, s52, 0x2000
	s_nop 0
	global_load_lds_dwordx4 v[222:223], off
	v_lshl_add_u64 v[222:223], s[30:31], 0, v[128:129]
	s_mov_b32 m0, s11
	s_nop 0
	global_load_lds_dwordx4 v[222:223], off
	s_mov_b32 m0, s25
	s_nop 0
	global_load_lds_dwordx4 v[224:225], off
	s_waitcnt vmcnt(8)
	s_waitcnt lgkmcnt(0)
	s_barrier
	s_waitcnt lgkmcnt(0)
	v_mfma_f32_16x16x32_bf16 v[60:63], v[144:147], v[188:191], v[60:63]
	v_mfma_f32_16x16x32_bf16 v[56:59], v[164:167], v[188:191], v[56:59]
	v_mfma_f32_16x16x32_bf16 v[44:47], v[144:147], v[196:199], v[44:47]
	v_mfma_f32_16x16x32_bf16 v[40:43], v[164:167], v[196:199], v[40:43]
	v_mfma_f32_16x16x32_bf16 v[28:31], v[144:147], v[204:207], v[28:31]
	v_mfma_f32_16x16x32_bf16 v[24:27], v[164:167], v[204:207], v[24:27]
	v_mfma_f32_16x16x32_bf16 v[12:15], v[144:147], v[212:215], v[12:15]
	v_mfma_f32_16x16x32_bf16 v[8:11], v[164:167], v[212:215], v[8:11]
	v_mfma_f32_16x16x32_bf16 v[60:63], v[148:151], v[192:195], v[60:63]
	v_mfma_f32_16x16x32_bf16 v[56:59], v[168:171], v[192:195], v[56:59]
	v_mfma_f32_16x16x32_bf16 v[44:47], v[148:151], v[200:203], v[44:47]
	v_mfma_f32_16x16x32_bf16 v[40:43], v[168:171], v[200:203], v[40:43]
	v_mfma_f32_16x16x32_bf16 v[28:31], v[148:151], v[208:211], v[28:31]
	v_mfma_f32_16x16x32_bf16 v[24:27], v[168:171], v[208:211], v[24:27]
	v_mfma_f32_16x16x32_bf16 v[12:15], v[148:151], v[216:219], v[12:15]
	v_mfma_f32_16x16x32_bf16 v[8:11], v[168:171], v[216:219], v[8:11]
	v_mfma_f32_16x16x32_bf16 v[52:55], v[172:175], v[188:191], v[52:55]
	v_mfma_f32_16x16x32_bf16 v[48:51], v[180:183], v[188:191], v[48:51]
	v_mfma_f32_16x16x32_bf16 v[36:39], v[172:175], v[196:199], v[36:39]
	v_mfma_f32_16x16x32_bf16 v[32:35], v[180:183], v[196:199], v[32:35]
	v_mfma_f32_16x16x32_bf16 v[20:23], v[172:175], v[204:207], v[20:23]
	v_mfma_f32_16x16x32_bf16 v[16:19], v[180:183], v[204:207], v[16:19]
	v_mfma_f32_16x16x32_bf16 v[4:7], v[172:175], v[212:215], v[4:7]
	v_mfma_f32_16x16x32_bf16 v[0:3], v[180:183], v[212:215], v[0:3]
	v_mfma_f32_16x16x32_bf16 v[52:55], v[176:179], v[192:195], v[52:55]
	v_mfma_f32_16x16x32_bf16 v[48:51], v[184:187], v[192:195], v[48:51]
	v_mfma_f32_16x16x32_bf16 v[36:39], v[176:179], v[200:203], v[36:39]
	v_mfma_f32_16x16x32_bf16 v[32:35], v[184:187], v[200:203], v[32:35]
	v_mfma_f32_16x16x32_bf16 v[20:23], v[176:179], v[208:211], v[20:23]
	v_mfma_f32_16x16x32_bf16 v[16:19], v[184:187], v[208:211], v[16:19]
	v_mfma_f32_16x16x32_bf16 v[4:7], v[176:179], v[216:219], v[4:7]
	v_mfma_f32_16x16x32_bf16 v[0:3], v[184:187], v[216:219], v[0:3]
	s_barrier
; #define PG8_STAGE(bufoff, gbase, voff) do { _Pragma("unroll") for (int _i = 0; _i < 2; ++_i) \
;         __builtin_amdgcn_global_load_lds((const unsigned*)((const char*)(gbase) + (voff)[_i]), (PG8_LAS unsigned*)(lds + (bufoff) + ldsw + _i * 8192), 16, 0, 0); } while (0)
; #define PG8_LDA(dst, b, h) do { _Pragma("unroll") for (int m = 0; m < 4; ++m) _Pragma("unroll") for (int k = 0; k < 2; ++k) dst[m][k] = *(const PG8_LAS bf16x8*)(lds + PG8_SA(b, h) + aoff + m * 2048 + k * 1024); } while (0)
; #define PG8_LDB(dst, b, h) do { _Pragma("unroll") for (int n = 0; n < 2; ++n) _Pragma("unroll") for (int k = 0; k < 2; ++k) dst[n][k] = *(const PG8_LAS bf16x8*)(lds + PG8_SB(b, h) + boff + n * 2048 + k * 1024); } while (0)
; #define PG8_MMA(ai, bj, At, Bt) do { __builtin_amdgcn_s_setprio(1); _Pragma("unroll") for (int m = 0; m < 4; ++m) _Pragma("unroll") for (int n = 0; n < 2; ++n) _Pragma("unroll") for (int k = 0; k < 2; ++k) \
;         acc[ai][bj][m][n] = __builtin_amdgcn_mfma_f32_16x16x32_bf16(Bt[n][k], At[m][k], acc[ai][bj][m][n], 0, 0, 0); __builtin_amdgcn_s_setprio(0); } while (0)
; #define PG8_WAIT_V(n) asm volatile("s_waitcnt vmcnt(" #n ")" ::: "memory")
; #define PG8_WAIT_L(n) asm volatile("s_waitcnt lgkmcnt(" #n ")" ::: "memory")
; #define PG8_BAR __builtin_amdgcn_s_barrier()
; #define PG8_SCHED __builtin_amdgcn_sched_barrier(0)
; template <class Epi, class Sched, bool ALIGN_EPI = false, bool SP2 = false>
; __device__ __forceinline__ void gemm_phase(PG8_LAS unsigned char* lds, const Gemm g, const Sched& S, const Epi& E) {
;     ...
;         for (int t = 0; t < nt; t += 2) {
;     ...
;             PG8_LDB(B0, 1, 0); PG8_LDB(B1, 1, 1); PG8_SCHED; PG8_LDA(At, 1, 0); PG8_STAGE(PG8_SA(0, 1), a2 + hstep, voffA);
;             PG8_WAIT_V(8); PG8_WAIT_L(0); PG8_BAR; PG8_MMA(0, 0, At, B0); PG8_MMA(0, 1, At, B1); PG8_BAR; PG8_SCHED;
;             PG8_LDA(At, 1, 1); PG8_STAGE(PG8_SB(1, 0), b3, voffB); PG8_STAGE(PG8_SB(1, 1), b3 + hstep, voffB); PG8_STAGE(PG8_SA(1, 0), a3, voffA);
;             PG8_WAIT_V(8); PG8_WAIT_L(0); PG8_BAR; PG8_MMA(1, 0, At, B0); PG8_MMA(1, 1, At, B1); PG8_BAR; PG8_SCHED;
	s_add_i32 s50, 0, 0x18000
	s_add_i32 s51, 0, 0x1c000
	v_add_u32_e32 v168, s50, v155
	v_add_u32_e32 v184, s51, v155
	ds_read_b128 v[144:147], v168
	ds_read_b128 v[148:151], v168 offset:1024
	ds_read_b128 v[164:167], v168 offset:2048
	ds_read_b128 v[168:171], v168 offset:3072
	ds_read_b128 v[172:175], v184
	ds_read_b128 v[176:179], v184 offset:1024
	ds_read_b128 v[180:183], v184 offset:2048
	ds_read_b128 v[184:187], v184 offset:3072
	s_add_u32 s30, s30, 0x40000
	s_addc_u32 s31, s31, 0
	s_mov_b32 m0, s33
	v_lshl_add_u64 v[226:227], s[30:31], 0, v[128:129]
	ds_read_b128 v[188:191], v159 offset:32768
	ds_read_b128 v[192:195], v159 offset:33792
	ds_read_b128 v[196:199], v159 offset:34816
	ds_read_b128 v[200:203], v159 offset:35840
	ds_read_b128 v[204:207], v159 offset:36864
	ds_read_b128 v[208:211], v159 offset:37888
	ds_read_b128 v[212:215], v159 offset:38912
	ds_read_b128 v[216:219], v159 offset:39936
	global_load_lds_dwordx4 v[226:227], off
	v_lshl_add_u64 v[226:227], s[30:31], 0, v[132:133]
	s_mov_b32 m0, s34
	s_nop 0
	global_load_lds_dwordx4 v[226:227], off
	s_waitcnt vmcnt(8)
	s_waitcnt lgkmcnt(0)
	s_barrier
	s_waitcnt lgkmcnt(0)
	v_mfma_f32_16x16x32_bf16 v[124:127], v[144:147], v[188:191], v[124:127]
	v_mfma_f32_16x16x32_bf16 v[120:123], v[164:167], v[188:191], v[120:123]
	v_mfma_f32_16x16x32_bf16 v[108:111], v[144:147], v[196:199], v[108:111]
	v_mfma_f32_16x16x32_bf16 v[104:107], v[164:167], v[196:199], v[104:107]
	v_mfma_f32_16x16x32_bf16 v[92:95], v[144:147], v[204:207], v[92:95]
	v_mfma_f32_16x16x32_bf16 v[88:91], v[164:167], v[204:207], v[88:91]
	v_mfma_f32_16x16x32_bf16 v[76:79], v[144:147], v[212:215], v[76:79]
	v_mfma_f32_16x16x32_bf16 v[72:75], v[164:167], v[212:215], v[72:75]
	v_mfma_f32_16x16x32_bf16 v[124:127], v[148:151], v[192:195], v[124:127]
	v_mfma_f32_16x16x32_bf16 v[120:123], v[168:171], v[192:195], v[120:123]
	v_mfma_f32_16x16x32_bf16 v[108:111], v[148:151], v[200:203], v[108:111]
	v_mfma_f32_16x16x32_bf16 v[104:107], v[168:171], v[200:203], v[104:107]
	v_mfma_f32_16x16x32_bf16 v[92:95], v[148:151], v[208:211], v[92:95]
	v_mfma_f32_16x16x32_bf16 v[88:91], v[168:171], v[208:211], v[88:91]
	v_mfma_f32_16x16x32_bf16 v[76:79], v[148:151], v[216:219], v[76:79]
	v_mfma_f32_16x16x32_bf16 v[72:75], v[168:171], v[216:219], v[72:75]
	v_mfma_f32_16x16x32_bf16 v[116:119], v[172:175], v[188:191], v[116:119]
	v_mfma_f32_16x16x32_bf16 v[112:115], v[180:183], v[188:191], v[112:115]
	v_mfma_f32_16x16x32_bf16 v[100:103], v[172:175], v[196:199], v[100:103]
	v_mfma_f32_16x16x32_bf16 v[96:99], v[180:183], v[196:199], v[96:99]
	v_mfma_f32_16x16x32_bf16 v[84:87], v[172:175], v[204:207], v[84:87]
	v_mfma_f32_16x16x32_bf16 v[80:83], v[180:183], v[204:207], v[80:83]
	v_mfma_f32_16x16x32_bf16 v[68:71], v[172:175], v[212:215], v[68:71]
	v_mfma_f32_16x16x32_bf16 v[64:67], v[180:183], v[212:215], v[64:67]
	v_mfma_f32_16x16x32_bf16 v[116:119], v[176:179], v[192:195], v[116:119]
	v_mfma_f32_16x16x32_bf16 v[112:115], v[184:187], v[192:195], v[112:115]
	v_mfma_f32_16x16x32_bf16 v[100:103], v[176:179], v[200:203], v[100:103]
	v_mfma_f32_16x16x32_bf16 v[96:99], v[184:187], v[200:203], v[96:99]
	v_mfma_f32_16x16x32_bf16 v[84:87], v[176:179], v[208:211], v[84:87]
	v_mfma_f32_16x16x32_bf16 v[80:83], v[184:187], v[208:211], v[80:83]
	v_mfma_f32_16x16x32_bf16 v[68:71], v[176:179], v[216:219], v[68:71]
	v_mfma_f32_16x16x32_bf16 v[64:67], v[184:187], v[216:219], v[64:67]
	s_barrier
	s_add_i32 s30, s50, s3
	v_lshl_add_u64 v[160:161], v[160:161], 0, s[6:7]
	s_mov_b32 m0, s30
	ds_read_b128 v[188:191], v159 offset:49152
	ds_read_b128 v[192:195], v159 offset:50176
	ds_read_b128 v[196:199], v159 offset:51200
	ds_read_b128 v[200:203], v159 offset:52224
	ds_read_b128 v[204:207], v159 offset:53248
	ds_read_b128 v[208:211], v159 offset:54272
	ds_read_b128 v[212:215], v159 offset:55296
	ds_read_b128 v[216:219], v159 offset:56320
	global_load_lds_dwordx4 v[160:161], off
	s_add_i32 m0, s30, 0x2000
	s_add_u32 s28, s28, 0x40080
	v_lshl_add_u64 v[160:161], v[220:221], 0, s[6:7]
	s_addc_u32 s29, s29, 0
	s_add_i32 s30, s51, s3
	global_load_lds_dwordx4 v[160:161], off
	v_lshl_add_u64 v[160:161], s[28:29], 0, v[130:131]
	s_mov_b32 m0, s30
	s_nop 0
	global_load_lds_dwordx4 v[160:161], off
	v_lshl_add_u64 v[160:161], s[28:29], 0, v[134:135]
	s_add_i32 m0, s30, 0x2000
	s_nop 0
	global_load_lds_dwordx4 v[160:161], off
	v_lshl_add_u64 v[160:161], v[222:223], 0, s[6:7]
	s_mov_b32 m0, s37
	s_nop 0
	global_load_lds_dwordx4 v[160:161], off
	v_lshl_add_u64 v[160:161], v[224:225], 0, s[6:7]
	s_mov_b32 m0, s38
	s_nop 0
	global_load_lds_dwordx4 v[160:161], off
	s_waitcnt vmcnt(8)
	s_waitcnt lgkmcnt(0)
	s_barrier
	s_waitcnt lgkmcnt(0)
	v_mfma_f32_16x16x32_bf16 v[60:63], v[144:147], v[188:191], v[60:63]
	v_mfma_f32_16x16x32_bf16 v[56:59], v[164:167], v[188:191], v[56:59]
	v_mfma_f32_16x16x32_bf16 v[44:47], v[144:147], v[196:199], v[44:47]
	v_mfma_f32_16x16x32_bf16 v[40:43], v[164:167], v[196:199], v[40:43]
	v_mfma_f32_16x16x32_bf16 v[28:31], v[144:147], v[204:207], v[28:31]
	v_mfma_f32_16x16x32_bf16 v[24:27], v[164:167], v[204:207], v[24:27]
	v_mfma_f32_16x16x32_bf16 v[12:15], v[144:147], v[212:215], v[12:15]
	v_mfma_f32_16x16x32_bf16 v[8:11], v[164:167], v[212:215], v[8:11]
	v_mfma_f32_16x16x32_bf16 v[60:63], v[148:151], v[192:195], v[60:63]
	v_mfma_f32_16x16x32_bf16 v[56:59], v[168:171], v[192:195], v[56:59]
	v_mfma_f32_16x16x32_bf16 v[44:47], v[148:151], v[200:203], v[44:47]
	v_mfma_f32_16x16x32_bf16 v[40:43], v[168:171], v[200:203], v[40:43]
	v_mfma_f32_16x16x32_bf16 v[28:31], v[148:151], v[208:211], v[28:31]
	v_mfma_f32_16x16x32_bf16 v[24:27], v[168:171], v[208:211], v[24:27]
	v_mfma_f32_16x16x32_bf16 v[12:15], v[148:151], v[216:219], v[12:15]
	v_mfma_f32_16x16x32_bf16 v[8:11], v[168:171], v[216:219], v[8:11]
	v_mfma_f32_16x16x32_bf16 v[52:55], v[172:175], v[188:191], v[52:55]
	v_mfma_f32_16x16x32_bf16 v[48:51], v[180:183], v[188:191], v[48:51]
	v_mfma_f32_16x16x32_bf16 v[36:39], v[172:175], v[196:199], v[36:39]
	v_mfma_f32_16x16x32_bf16 v[32:35], v[180:183], v[196:199], v[32:35]
	v_mfma_f32_16x16x32_bf16 v[20:23], v[172:175], v[204:207], v[20:23]
	v_mfma_f32_16x16x32_bf16 v[16:19], v[180:183], v[204:207], v[16:19]
	v_mfma_f32_16x16x32_bf16 v[4:7], v[172:175], v[212:215], v[4:7]
	v_mfma_f32_16x16x32_bf16 v[0:3], v[180:183], v[212:215], v[0:3]
	v_mfma_f32_16x16x32_bf16 v[52:55], v[176:179], v[192:195], v[52:55]
	v_mfma_f32_16x16x32_bf16 v[48:51], v[184:187], v[192:195], v[48:51]
	v_mfma_f32_16x16x32_bf16 v[36:39], v[176:179], v[200:203], v[36:39]
	v_mfma_f32_16x16x32_bf16 v[32:35], v[184:187], v[200:203], v[32:35]
	v_mfma_f32_16x16x32_bf16 v[20:23], v[176:179], v[208:211], v[20:23]
	v_mfma_f32_16x16x32_bf16 v[16:19], v[184:187], v[208:211], v[16:19]
	v_mfma_f32_16x16x32_bf16 v[4:7], v[176:179], v[216:219], v[4:7]
	v_mfma_f32_16x16x32_bf16 v[0:3], v[184:187], v[216:219], v[0:3]
	s_barrier
	s_add_i32 s49, s49, 2
	s_add_u32 s26, s26, 0x100
	s_addc_u32 s27, s27, 0
	s_add_u32 s47, s47, 0x100
	s_addc_u32 s48, s48, 0
	s_cmp_gt_u32 s49, 13
	s_cbranch_scc0 .LBB0_713
; #define PG8_BAR __builtin_amdgcn_s_barrier()
; template <class Epi, class Sched, bool ALIGN_EPI = false, bool SP2 = false>
; __device__ __forceinline__ void gemm_phase(PG8_LAS unsigned char* lds, const Gemm g, const Sched& S, const Epi& E) {
;     ...
;         if constexpr (ALIGN_EPI) { if (wr == 0) PG8_BAR; }
;         if constexpr (!Epi::AFTER_DRAIN) { E(acc, cur, wr, wc, fr, fq); S.done(cur); }
.Lpeel_exit2:
	s_and_b64 vcc, exec, s[14:15]
	s_cbranch_vccz .LBB0_716
	s_barrier

; #define PG8_STAGE(bufoff, gbase, voff) do { _Pragma("unroll") for (int _i = 0; _i < 2; ++_i) \
;         __builtin_amdgcn_global_load_lds((const unsigned*)((const char*)(gbase) + (voff)[_i]), (PG8_LAS unsigned*)(lds + (bufoff) + ldsw + _i * 8192), 16, 0, 0); } while (0)
; #define PG8_LDA(dst, b, h) do { _Pragma("unroll") for (int m = 0; m < 4; ++m) _Pragma("unroll") for (int k = 0; k < 2; ++k) dst[m][k] = *(const PG8_LAS bf16x8*)(lds + PG8_SA(b, h) + aoff + m * 2048 + k * 1024); } while (0)
; #define PG8_LDB(dst, b, h) do { _Pragma("unroll") for (int n = 0; n < 2; ++n) _Pragma("unroll") for (int k = 0; k < 2; ++k) dst[n][k] = *(const PG8_LAS bf16x8*)(lds + PG8_SB(b, h) + boff + n * 2048 + k * 1024); } while (0)
; template <class Epi, class Sched, bool ALIGN_EPI = false, bool SP2 = false>
; __device__ __forceinline__ void gemm_phase(PG8_LAS unsigned char* lds, const Gemm g, const Sched& S, const Epi& E) {
;     ...
;         const bool has_next = S.next(ui + 1, nxt);
;         const char* nA = has_next ? (const char*)g.A + (size_t)nxt.pm * tstep : cA; const char* nB = has_next ? (const char*)g.Bt + (size_t)nxt.pn * tstep : cB;
;         for (int t = 0; t < nt; t += 2) {
;             const bool last = (t == nt - 2);
;             const char* a1 = cA + (size_t)(t + 1) * kstep;
;             const char* a2 = last ? nA : cA + (size_t)(t + 2) * kstep; const char* b2 = last ? nB : cB + (size_t)(t + 2) * kstep;
;             const char* a3 = a2 + kstep; const char* b3 = b2 + kstep;
;             if (last && has_next) S.a_ready(nxt);
;             if constexpr (SP2) {
;             PG8_LDB(B0, 0, 0); PG8_LDB(B1, 0, 1); PG8_SCHED; PG8_LDA(At, 0, 0); PG8_STAGE(PG8_SA(1, 1), a1 + hstep, voffA);
;             PG8_WAIT_V(8); PG8_WAIT_L(0); PG8_BAR; PG8_MMA(0, 0, At, B0); PG8_MMA(0, 1, At, B1); PG8_BAR; PG8_SCHED;
;             PG8_LDA(At, 0, 1); PG8_STAGE(PG8_SB(0, 0), b2, voffB); PG8_STAGE(PG8_SB(0, 1), b2 + hstep, voffB); PG8_STAGE(PG8_SA(0, 0), a2, voffA);
;             PG8_WAIT_V(8); PG8_WAIT_L(0); PG8_BAR; PG8_MMA(1, 0, At, B0); PG8_MMA(1, 1, At, B1); PG8_BAR; PG8_SCHED;
;     ...
;         for (int a = 0; a < 2; ++a)
; #pragma unroll
;             for (int b = 0; b < 2; ++b)
; #pragma unroll
;                 for (int m = 0; m < 4; ++m)
; #pragma unroll
;                     for (int n = 0; n < 2; ++n) acc[a][b][m][n] = (f32x4){0.f, 0.f, 0.f, 0.f};
.LBB0_802:
	s_ashr_i32 s23, s22, 31
	s_lshl_b64 s[24:25], s[22:23], 19
	s_add_u32 s24, s44, s24
	s_addc_u32 s25, s45, s25
	s_and_b64 s[26:27], s[4:5], exec
	s_cselect_b32 s23, s25, s35
	s_cselect_b32 s29, s24, s34
	s_ashr_i32 s21, s20, 31
	s_lshl_b64 s[26:27], s[20:21], 19
	s_add_u32 s26, s70, s26
	s_addc_u32 s27, s71, s27
	s_and_b64 s[38:39], s[4:5], exec
	s_cselect_b32 s21, s27, s37
	s_cselect_b32 s52, s26, s36
	s_add_u32 s34, s34, 0x40080
	s_addc_u32 s35, s35, 0
	s_add_u32 s53, s36, 0x100
	s_addc_u32 s54, s37, 0
	s_mov_b32 s55, -2
	s_waitcnt lgkmcnt(0)
	ds_read_b128 v[144:147], v152
	ds_read_b128 v[158:161], v152 offset:1024
	ds_read_b128 v[164:167], v152 offset:2048
	ds_read_b128 v[168:171], v152 offset:3072
	ds_read_b128 v[172:175], v153
	ds_read_b128 v[176:179], v153 offset:1024
	ds_read_b128 v[180:183], v153 offset:2048
	ds_read_b128 v[184:187], v153 offset:3072
	s_add_u32 s36, s34, 0xfffc0080
	s_addc_u32 s37, s35, -1
	s_cmp_eq_u32 s55, 12
	s_cselect_b32 s39, s23, s37
	s_cselect_b32 s38, s29, s36
	s_cselect_b32 s37, s21, s54
	s_cselect_b32 s36, s52, s53
	v_lshl_add_u64 v[220:221], s[34:35], 0, v[136:137]
	s_add_i32 m0, s10, 0xc000
	ds_read_b128 v[188:191], v155
	ds_read_b128 v[192:195], v155 offset:1024
	ds_read_b128 v[196:199], v155 offset:2048
	ds_read_b128 v[200:203], v155 offset:3072
	ds_read_b128 v[204:207], v155 offset:4096
	ds_read_b128 v[208:211], v155 offset:5120
	ds_read_b128 v[212:215], v155 offset:6144
	ds_read_b128 v[216:219], v155 offset:7168
	global_load_lds_dwordx4 v[220:221], off
	v_lshl_add_u64 v[220:221], s[34:35], 0, v[138:139]
	s_add_i32 m0, s10, 0xe000
	s_nop 0
	global_load_lds_dwordx4 v[220:221], off
	s_waitcnt vmcnt(8)
	s_waitcnt lgkmcnt(0)
	s_barrier
	s_waitcnt lgkmcnt(0)
	v_mfma_f32_16x16x32_bf16 v[124:127], v[144:147], v[188:191], 0
	v_mfma_f32_16x16x32_bf16 v[120:123], v[164:167], v[188:191], 0
	v_mfma_f32_16x16x32_bf16 v[108:111], v[144:147], v[196:199], 0
	v_mfma_f32_16x16x32_bf16 v[104:107], v[164:167], v[196:199], 0
	v_mfma_f32_16x16x32_bf16 v[92:95], v[144:147], v[204:207], 0
	v_mfma_f32_16x16x32_bf16 v[88:91], v[164:167], v[204:207], 0
	v_mfma_f32_16x16x32_bf16 v[76:79], v[144:147], v[212:215], 0
	v_mfma_f32_16x16x32_bf16 v[72:75], v[164:167], v[212:215], 0
	v_mfma_f32_16x16x32_bf16 v[124:127], v[158:161], v[192:195], v[124:127]
	v_mfma_f32_16x16x32_bf16 v[120:123], v[168:171], v[192:195], v[120:123]
	v_mfma_f32_16x16x32_bf16 v[108:111], v[158:161], v[200:203], v[108:111]
	v_mfma_f32_16x16x32_bf16 v[104:107], v[168:171], v[200:203], v[104:107]
	v_mfma_f32_16x16x32_bf16 v[92:95], v[158:161], v[208:211], v[92:95]
	v_mfma_f32_16x16x32_bf16 v[88:91], v[168:171], v[208:211], v[88:91]
	v_mfma_f32_16x16x32_bf16 v[76:79], v[158:161], v[216:219], v[76:79]
	v_mfma_f32_16x16x32_bf16 v[72:75], v[168:171], v[216:219], v[72:75]
	v_mfma_f32_16x16x32_bf16 v[116:119], v[172:175], v[188:191], 0
	v_mfma_f32_16x16x32_bf16 v[112:115], v[180:183], v[188:191], 0
	v_mfma_f32_16x16x32_bf16 v[100:103], v[172:175], v[196:199], 0
	v_mfma_f32_16x16x32_bf16 v[96:99], v[180:183], v[196:199], 0
	v_mfma_f32_16x16x32_bf16 v[84:87], v[172:175], v[204:207], 0
	v_mfma_f32_16x16x32_bf16 v[80:83], v[180:183], v[204:207], 0
	v_mfma_f32_16x16x32_bf16 v[68:71], v[172:175], v[212:215], 0
	v_mfma_f32_16x16x32_bf16 v[64:67], v[180:183], v[212:215], 0
	v_mfma_f32_16x16x32_bf16 v[116:119], v[176:179], v[192:195], v[116:119]
	v_mfma_f32_16x16x32_bf16 v[112:115], v[184:187], v[192:195], v[112:115]
	v_mfma_f32_16x16x32_bf16 v[100:103], v[176:179], v[200:203], v[100:103]
	v_mfma_f32_16x16x32_bf16 v[96:99], v[184:187], v[200:203], v[96:99]
	v_mfma_f32_16x16x32_bf16 v[84:87], v[176:179], v[208:211], v[84:87]
	v_mfma_f32_16x16x32_bf16 v[80:83], v[184:187], v[208:211], v[80:83]
	v_mfma_f32_16x16x32_bf16 v[68:71], v[176:179], v[216:219], v[68:71]
	v_mfma_f32_16x16x32_bf16 v[64:67], v[184:187], v[216:219], v[64:67]
	s_barrier
	s_add_i32 s58, s49, s3
	v_lshl_add_u64 v[220:221], s[36:37], 0, v[130:131]
	s_mov_b32 m0, s58
	ds_read_b128 v[188:191], v155 offset:16384
	ds_read_b128 v[192:195], v155 offset:17408
	ds_read_b128 v[196:199], v155 offset:18432
	ds_read_b128 v[200:203], v155 offset:19456
	ds_read_b128 v[204:207], v155 offset:20480
	ds_read_b128 v[208:211], v155 offset:21504
	ds_read_b128 v[212:215], v155 offset:22528
	ds_read_b128 v[216:219], v155 offset:23552
	global_load_lds_dwordx4 v[220:221], off
	s_add_i32 m0, s58, 0x2000
	s_add_u32 s58, s36, 0x40000
	v_lshl_add_u64 v[222:223], s[36:37], 0, v[134:135]
	s_addc_u32 s59, s37, 0
	s_add_i32 s64, s50, s3
	global_load_lds_dwordx4 v[222:223], off
	v_lshl_add_u64 v[224:225], s[58:59], 0, v[130:131]
	s_mov_b32 m0, s64
	v_lshl_add_u64 v[226:227], s[38:39], 0, v[132:133]
	global_load_lds_dwordx4 v[224:225], off
	v_lshl_add_u64 v[224:225], s[58:59], 0, v[134:135]
	s_add_i32 m0, s64, 0x2000
	s_nop 0
	global_load_lds_dwordx4 v[224:225], off
	v_lshl_add_u64 v[224:225], s[38:39], 0, v[128:129]
	s_mov_b32 m0, s10
	s_nop 0
	global_load_lds_dwordx4 v[224:225], off
	s_mov_b32 m0, s11
	s_nop 0
	global_load_lds_dwordx4 v[226:227], off
	s_waitcnt vmcnt(8)
	s_waitcnt lgkmcnt(0)
	s_barrier
; #define PG8_STAGE(bufoff, gbase, voff) do { _Pragma("unroll") for (int _i = 0; _i < 2; ++_i) \
;         __builtin_amdgcn_global_load_lds((const unsigned*)((const char*)(gbase) + (voff)[_i]), (PG8_LAS unsigned*)(lds + (bufoff) + ldsw + _i * 8192), 16, 0, 0); } while (0)
; #define PG8_LDA(dst, b, h) do { _Pragma("unroll") for (int m = 0; m < 4; ++m) _Pragma("unroll") for (int k = 0; k < 2; ++k) dst[m][k] = *(const PG8_LAS bf16x8*)(lds + PG8_SA(b, h) + aoff + m * 2048 + k * 1024); } while (0)
; #define PG8_LDB(dst, b, h) do { _Pragma("unroll") for (int n = 0; n < 2; ++n) _Pragma("unroll") for (int k = 0; k < 2; ++k) dst[n][k] = *(const PG8_LAS bf16x8*)(lds + PG8_SB(b, h) + boff + n * 2048 + k * 1024); } while (0)
; #define PG8_MMA(ai, bj, At, Bt) do { __builtin_amdgcn_s_setprio(1); _Pragma("unroll") for (int m = 0; m < 4; ++m) _Pragma("unroll") for (int n = 0; n < 2; ++n) _Pragma("unroll") for (int k = 0; k < 2; ++k) \
;         acc[ai][bj][m][n] = __builtin_amdgcn_mfma_f32_16x16x32_bf16(Bt[n][k], At[m][k], acc[ai][bj][m][n], 0, 0, 0); __builtin_amdgcn_s_setprio(0); } while (0)
; #define PG8_WAIT_V(n) asm volatile("s_waitcnt vmcnt(" #n ")" ::: "memory")
; #define PG8_WAIT_L(n) asm volatile("s_waitcnt lgkmcnt(" #n ")" ::: "memory")
; #define PG8_BAR __builtin_amdgcn_s_barrier()
; #define PG8_SCHED __builtin_amdgcn_sched_barrier(0)
; template <class Epi, class Sched, bool ALIGN_EPI = false, bool SP2 = false>
; __device__ __forceinline__ void gemm_phase(PG8_LAS unsigned char* lds, const Gemm g, const Sched& S, const Epi& E) {
;     ...
;             PG8_WAIT_V(8); PG8_WAIT_L(0); PG8_BAR; PG8_MMA(1, 0, At, B0); PG8_MMA(1, 1, At, B1); PG8_BAR; PG8_SCHED;
;             PG8_LDB(B0, 1, 0); PG8_LDB(B1, 1, 1); PG8_SCHED; PG8_LDA(At, 1, 0); PG8_STAGE(PG8_SA(0, 1), a2 + hstep, voffA);
;             PG8_WAIT_V(8); PG8_WAIT_L(0); PG8_BAR; PG8_MMA(0, 0, At, B0); PG8_MMA(0, 1, At, B1); PG8_BAR; PG8_SCHED;
	s_waitcnt lgkmcnt(0)
	v_mfma_f32_16x16x32_bf16 v[60:63], v[144:147], v[188:191], 0
	v_mfma_f32_16x16x32_bf16 v[56:59], v[164:167], v[188:191], 0
	v_mfma_f32_16x16x32_bf16 v[44:47], v[144:147], v[196:199], 0
	v_mfma_f32_16x16x32_bf16 v[40:43], v[164:167], v[196:199], 0
	v_mfma_f32_16x16x32_bf16 v[28:31], v[144:147], v[204:207], 0
	v_mfma_f32_16x16x32_bf16 v[24:27], v[164:167], v[204:207], 0
	v_mfma_f32_16x16x32_bf16 v[12:15], v[144:147], v[212:215], 0
	v_mfma_f32_16x16x32_bf16 v[8:11], v[164:167], v[212:215], 0
	v_mfma_f32_16x16x32_bf16 v[60:63], v[158:161], v[192:195], v[60:63]
	v_mfma_f32_16x16x32_bf16 v[56:59], v[168:171], v[192:195], v[56:59]
	v_mfma_f32_16x16x32_bf16 v[44:47], v[158:161], v[200:203], v[44:47]
	v_mfma_f32_16x16x32_bf16 v[40:43], v[168:171], v[200:203], v[40:43]
	v_mfma_f32_16x16x32_bf16 v[28:31], v[158:161], v[208:211], v[28:31]
	v_mfma_f32_16x16x32_bf16 v[24:27], v[168:171], v[208:211], v[24:27]
	v_mfma_f32_16x16x32_bf16 v[12:15], v[158:161], v[216:219], v[12:15]
	v_mfma_f32_16x16x32_bf16 v[8:11], v[168:171], v[216:219], v[8:11]
	v_mfma_f32_16x16x32_bf16 v[52:55], v[172:175], v[188:191], 0
	v_mfma_f32_16x16x32_bf16 v[48:51], v[180:183], v[188:191], 0
	v_mfma_f32_16x16x32_bf16 v[36:39], v[172:175], v[196:199], 0
	v_mfma_f32_16x16x32_bf16 v[32:35], v[180:183], v[196:199], 0
	v_mfma_f32_16x16x32_bf16 v[20:23], v[172:175], v[204:207], 0
	v_mfma_f32_16x16x32_bf16 v[16:19], v[180:183], v[204:207], 0
	v_mfma_f32_16x16x32_bf16 v[4:7], v[172:175], v[212:215], 0
	v_mfma_f32_16x16x32_bf16 v[0:3], v[180:183], v[212:215], 0
	v_mfma_f32_16x16x32_bf16 v[52:55], v[176:179], v[192:195], v[52:55]
	v_mfma_f32_16x16x32_bf16 v[48:51], v[184:187], v[192:195], v[48:51]
	v_mfma_f32_16x16x32_bf16 v[36:39], v[176:179], v[200:203], v[36:39]
	v_mfma_f32_16x16x32_bf16 v[32:35], v[184:187], v[200:203], v[32:35]
	v_mfma_f32_16x16x32_bf16 v[20:23], v[176:179], v[208:211], v[20:23]
	v_mfma_f32_16x16x32_bf16 v[16:19], v[184:187], v[208:211], v[16:19]
	v_mfma_f32_16x16x32_bf16 v[4:7], v[176:179], v[216:219], v[4:7]
	v_mfma_f32_16x16x32_bf16 v[0:3], v[184:187], v[216:219], v[0:3]
	s_barrier
	s_add_i32 s58, 0, 0x18000
	v_add_u32_e32 v157, s58, v150
	s_add_i32 s59, 0, 0x1c000
	ds_read_b128 v[144:147], v157
	ds_read_b128 v[158:161], v157 offset:1024
	ds_read_b128 v[164:167], v157 offset:2048
	ds_read_b128 v[168:171], v157 offset:3072
	v_add_u32_e32 v157, s59, v150
	ds_read_b128 v[172:175], v157
	ds_read_b128 v[176:179], v157 offset:1024
	ds_read_b128 v[180:183], v157 offset:2048
	ds_read_b128 v[184:187], v157 offset:3072
	s_add_u32 s38, s38, 0x40000
	s_addc_u32 s39, s39, 0
	s_mov_b32 m0, s31
	v_lshl_add_u64 v[228:229], s[38:39], 0, v[128:129]
	ds_read_b128 v[188:191], v155 offset:32768
	ds_read_b128 v[192:195], v155 offset:33792
	ds_read_b128 v[196:199], v155 offset:34816
	ds_read_b128 v[200:203], v155 offset:35840
	ds_read_b128 v[204:207], v155 offset:36864
	ds_read_b128 v[208:211], v155 offset:37888
	ds_read_b128 v[212:215], v155 offset:38912
	ds_read_b128 v[216:219], v155 offset:39936
	global_load_lds_dwordx4 v[228:229], off
	v_lshl_add_u64 v[228:229], s[38:39], 0, v[132:133]
	s_mov_b32 m0, s33
	s_nop 0
	global_load_lds_dwordx4 v[228:229], off
	s_waitcnt vmcnt(8)
	s_waitcnt lgkmcnt(0)
	s_barrier
	s_waitcnt lgkmcnt(0)
	v_mfma_f32_16x16x32_bf16 v[124:127], v[144:147], v[188:191], v[124:127]
	v_mfma_f32_16x16x32_bf16 v[120:123], v[164:167], v[188:191], v[120:123]
	v_mfma_f32_16x16x32_bf16 v[108:111], v[144:147], v[196:199], v[108:111]
	v_mfma_f32_16x16x32_bf16 v[104:107], v[164:167], v[196:199], v[104:107]
	v_mfma_f32_16x16x32_bf16 v[92:95], v[144:147], v[204:207], v[92:95]
	v_mfma_f32_16x16x32_bf16 v[88:91], v[164:167], v[204:207], v[88:91]
	v_mfma_f32_16x16x32_bf16 v[76:79], v[144:147], v[212:215], v[76:79]
	v_mfma_f32_16x16x32_bf16 v[72:75], v[164:167], v[212:215], v[72:75]
	v_mfma_f32_16x16x32_bf16 v[124:127], v[158:161], v[192:195], v[124:127]
	v_mfma_f32_16x16x32_bf16 v[120:123], v[168:171], v[192:195], v[120:123]
	v_mfma_f32_16x16x32_bf16 v[108:111], v[158:161], v[200:203], v[108:111]
	v_mfma_f32_16x16x32_bf16 v[104:107], v[168:171], v[200:203], v[104:107]
	v_mfma_f32_16x16x32_bf16 v[92:95], v[158:161], v[208:211], v[92:95]
	v_mfma_f32_16x16x32_bf16 v[88:91], v[168:171], v[208:211], v[88:91]
	v_mfma_f32_16x16x32_bf16 v[76:79], v[158:161], v[216:219], v[76:79]
	v_mfma_f32_16x16x32_bf16 v[72:75], v[168:171], v[216:219], v[72:75]
	v_mfma_f32_16x16x32_bf16 v[116:119], v[172:175], v[188:191], v[116:119]
	v_mfma_f32_16x16x32_bf16 v[112:115], v[180:183], v[188:191], v[112:115]
	v_mfma_f32_16x16x32_bf16 v[100:103], v[172:175], v[196:199], v[100:103]
	v_mfma_f32_16x16x32_bf16 v[96:99], v[180:183], v[196:199], v[96:99]
	v_mfma_f32_16x16x32_bf16 v[84:87], v[172:175], v[204:207], v[84:87]
	v_mfma_f32_16x16x32_bf16 v[80:83], v[180:183], v[204:207], v[80:83]
	v_mfma_f32_16x16x32_bf16 v[68:71], v[172:175], v[212:215], v[68:71]
	v_mfma_f32_16x16x32_bf16 v[64:67], v[180:183], v[212:215], v[64:67]
	v_mfma_f32_16x16x32_bf16 v[116:119], v[176:179], v[192:195], v[116:119]
	v_mfma_f32_16x16x32_bf16 v[112:115], v[184:187], v[192:195], v[112:115]
	v_mfma_f32_16x16x32_bf16 v[100:103], v[176:179], v[200:203], v[100:103]
	v_mfma_f32_16x16x32_bf16 v[96:99], v[184:187], v[200:203], v[96:99]
	v_mfma_f32_16x16x32_bf16 v[84:87], v[176:179], v[208:211], v[84:87]
	v_mfma_f32_16x16x32_bf16 v[80:83], v[184:187], v[208:211], v[80:83]
	v_mfma_f32_16x16x32_bf16 v[68:71], v[176:179], v[216:219], v[68:71]
	v_mfma_f32_16x16x32_bf16 v[64:67], v[184:187], v[216:219], v[64:67]
	s_barrier
; #define PG8_STAGE(bufoff, gbase, voff) do { _Pragma("unroll") for (int _i = 0; _i < 2; ++_i) \
;         __builtin_amdgcn_global_load_lds((const unsigned*)((const char*)(gbase) + (voff)[_i]), (PG8_LAS unsigned*)(lds + (bufoff) + ldsw + _i * 8192), 16, 0, 0); } while (0)
; #define PG8_LDA(dst, b, h) do { _Pragma("unroll") for (int m = 0; m < 4; ++m) _Pragma("unroll") for (int k = 0; k < 2; ++k) dst[m][k] = *(const PG8_LAS bf16x8*)(lds + PG8_SA(b, h) + aoff + m * 2048 + k * 1024); } while (0)
; #define PG8_LDB(dst, b, h) do { _Pragma("unroll") for (int n = 0; n < 2; ++n) _Pragma("unroll") for (int k = 0; k < 2; ++k) dst[n][k] = *(const PG8_LAS bf16x8*)(lds + PG8_SB(b, h) + boff + n * 2048 + k * 1024); } while (0)
; template <class Epi, class Sched, bool ALIGN_EPI = false, bool SP2 = false>
; __device__ __forceinline__ void gemm_phase(PG8_LAS unsigned char* lds, const Gemm g, const Sched& S, const Epi& E) {
;     ...
;         for (int t = 0; t < nt; t += 2) {
;             const bool last = (t == nt - 2);
;             const char* a1 = cA + (size_t)(t + 1) * kstep;
;             const char* a2 = last ? nA : cA + (size_t)(t + 2) * kstep; const char* b2 = last ? nB : cB + (size_t)(t + 2) * kstep;
;             const char* a3 = a2 + kstep; const char* b3 = b2 + kstep;
;             if (last && has_next) S.a_ready(nxt);
;             if constexpr (SP2) {
;             PG8_LDB(B0, 0, 0); PG8_LDB(B1, 0, 1); PG8_SCHED; PG8_LDA(At, 0, 0); PG8_STAGE(PG8_SA(1, 1), a1 + hstep, voffA);
;             PG8_WAIT_V(8); PG8_WAIT_L(0); PG8_BAR; PG8_MMA(0, 0, At, B0); PG8_MMA(0, 1, At, B1); PG8_BAR; PG8_SCHED;
;             PG8_LDA(At, 0, 1); PG8_STAGE(PG8_SB(0, 0), b2, voffB); PG8_STAGE(PG8_SB(0, 1), b2 + hstep, voffB); PG8_STAGE(PG8_SA(0, 0), a2, voffA);
;             PG8_WAIT_V(8); PG8_WAIT_L(0); PG8_BAR; PG8_MMA(1, 0, At, B0); PG8_MMA(1, 1, At, B1); PG8_BAR; PG8_SCHED;
;             PG8_LDB(B0, 1, 0); PG8_LDB(B1, 1, 1); PG8_SCHED; PG8_LDA(At, 1, 0); PG8_STAGE(PG8_SA(0, 1), a2 + hstep, voffA);
;             PG8_WAIT_V(8); PG8_WAIT_L(0); PG8_BAR; PG8_MMA(0, 0, At, B0); PG8_MMA(0, 1, At, B1); PG8_BAR; PG8_SCHED;
;             PG8_LDA(At, 1, 1); PG8_STAGE(PG8_SB(1, 0), b3, voffB); PG8_STAGE(PG8_SB(1, 1), b3 + hstep, voffB); PG8_STAGE(PG8_SA(1, 0), a3, voffA);
;             PG8_WAIT_V(8); PG8_WAIT_L(0); PG8_BAR; PG8_MMA(1, 0, At, B0); PG8_MMA(1, 1, At, B1); PG8_BAR; PG8_SCHED;
	s_add_i32 s38, s58, s3
	v_lshl_add_u64 v[220:221], v[220:221], 0, s[16:17]
	s_mov_b32 m0, s38
	ds_read_b128 v[188:191], v155 offset:49152
	ds_read_b128 v[192:195], v155 offset:50176
	ds_read_b128 v[196:199], v155 offset:51200
	ds_read_b128 v[200:203], v155 offset:52224
	ds_read_b128 v[204:207], v155 offset:53248
	ds_read_b128 v[208:211], v155 offset:54272
	ds_read_b128 v[212:215], v155 offset:55296
	ds_read_b128 v[216:219], v155 offset:56320
	global_load_lds_dwordx4 v[220:221], off
	s_add_i32 m0, s38, 0x2000
	s_add_u32 s36, s36, 0x40080
	v_lshl_add_u64 v[220:221], v[222:223], 0, s[16:17]
	s_addc_u32 s37, s37, 0
	s_add_i32 s38, s59, s3
	global_load_lds_dwordx4 v[220:221], off
	v_lshl_add_u64 v[220:221], s[36:37], 0, v[130:131]
	s_mov_b32 m0, s38
	s_nop 0
	global_load_lds_dwordx4 v[220:221], off
	v_lshl_add_u64 v[220:221], s[36:37], 0, v[134:135]
	s_add_i32 m0, s38, 0x2000
	s_nop 0
	global_load_lds_dwordx4 v[220:221], off
	v_lshl_add_u64 v[220:221], v[224:225], 0, s[16:17]
	s_mov_b32 m0, s47
	s_nop 0
	global_load_lds_dwordx4 v[220:221], off
	v_lshl_add_u64 v[220:221], v[226:227], 0, s[16:17]
	s_mov_b32 m0, s48
	s_nop 0
	global_load_lds_dwordx4 v[220:221], off
	s_waitcnt vmcnt(8)
	s_waitcnt lgkmcnt(0)
	s_barrier
	s_waitcnt lgkmcnt(0)
	v_mfma_f32_16x16x32_bf16 v[60:63], v[144:147], v[188:191], v[60:63]
	v_mfma_f32_16x16x32_bf16 v[56:59], v[164:167], v[188:191], v[56:59]
	v_mfma_f32_16x16x32_bf16 v[44:47], v[144:147], v[196:199], v[44:47]
	v_mfma_f32_16x16x32_bf16 v[40:43], v[164:167], v[196:199], v[40:43]
	v_mfma_f32_16x16x32_bf16 v[28:31], v[144:147], v[204:207], v[28:31]
	v_mfma_f32_16x16x32_bf16 v[24:27], v[164:167], v[204:207], v[24:27]
	v_mfma_f32_16x16x32_bf16 v[12:15], v[144:147], v[212:215], v[12:15]
	v_mfma_f32_16x16x32_bf16 v[8:11], v[164:167], v[212:215], v[8:11]
	v_mfma_f32_16x16x32_bf16 v[60:63], v[158:161], v[192:195], v[60:63]
	v_mfma_f32_16x16x32_bf16 v[56:59], v[168:171], v[192:195], v[56:59]
	v_mfma_f32_16x16x32_bf16 v[44:47], v[158:161], v[200:203], v[44:47]
	v_mfma_f32_16x16x32_bf16 v[40:43], v[168:171], v[200:203], v[40:43]
	v_mfma_f32_16x16x32_bf16 v[28:31], v[158:161], v[208:211], v[28:31]
	v_mfma_f32_16x16x32_bf16 v[24:27], v[168:171], v[208:211], v[24:27]
	v_mfma_f32_16x16x32_bf16 v[12:15], v[158:161], v[216:219], v[12:15]
	v_mfma_f32_16x16x32_bf16 v[8:11], v[168:171], v[216:219], v[8:11]
	v_mfma_f32_16x16x32_bf16 v[52:55], v[172:175], v[188:191], v[52:55]
	v_mfma_f32_16x16x32_bf16 v[48:51], v[180:183], v[188:191], v[48:51]
	v_mfma_f32_16x16x32_bf16 v[36:39], v[172:175], v[196:199], v[36:39]
	v_mfma_f32_16x16x32_bf16 v[32:35], v[180:183], v[196:199], v[32:35]
	v_mfma_f32_16x16x32_bf16 v[20:23], v[172:175], v[204:207], v[20:23]
	v_mfma_f32_16x16x32_bf16 v[16:19], v[180:183], v[204:207], v[16:19]
	v_mfma_f32_16x16x32_bf16 v[4:7], v[172:175], v[212:215], v[4:7]
	v_mfma_f32_16x16x32_bf16 v[0:3], v[180:183], v[212:215], v[0:3]
	v_mfma_f32_16x16x32_bf16 v[52:55], v[176:179], v[192:195], v[52:55]
	v_mfma_f32_16x16x32_bf16 v[48:51], v[184:187], v[192:195], v[48:51]
	v_mfma_f32_16x16x32_bf16 v[36:39], v[176:179], v[200:203], v[36:39]
	v_mfma_f32_16x16x32_bf16 v[32:35], v[184:187], v[200:203], v[32:35]
	v_mfma_f32_16x16x32_bf16 v[20:23], v[176:179], v[208:211], v[20:23]
	v_mfma_f32_16x16x32_bf16 v[16:19], v[184:187], v[208:211], v[16:19]
	v_mfma_f32_16x16x32_bf16 v[4:7], v[176:179], v[216:219], v[4:7]
	v_mfma_f32_16x16x32_bf16 v[0:3], v[184:187], v[216:219], v[0:3]
	s_barrier
	s_add_i32 s55, s55, 2
	s_add_u32 s34, s34, 0x100
	s_addc_u32 s35, s35, 0
	s_add_u32 s53, s53, 0x100
	s_addc_u32 s54, s54, 0
	s_cmp_gt_u32 s55, 13
	s_cbranch_scc1 .Lpeel_exit3
.LBB0_803:
	ds_read_b128 v[144:147], v152
	ds_read_b128 v[158:161], v152 offset:1024
	ds_read_b128 v[164:167], v152 offset:2048
	ds_read_b128 v[168:171], v152 offset:3072
	ds_read_b128 v[172:175], v153
	ds_read_b128 v[176:179], v153 offset:1024
	ds_read_b128 v[180:183], v153 offset:2048
	ds_read_b128 v[184:187], v153 offset:3072
	s_add_u32 s36, s34, 0xfffc0080
	s_addc_u32 s37, s35, -1
	s_cmp_eq_u32 s55, 12
	s_cselect_b32 s39, s23, s37
	s_cselect_b32 s38, s29, s36
	s_cselect_b32 s37, s21, s54
	s_cselect_b32 s36, s52, s53
	v_lshl_add_u64 v[220:221], s[34:35], 0, v[136:137]
	s_add_i32 m0, s10, 0xc000
	ds_read_b128 v[188:191], v155
	ds_read_b128 v[192:195], v155 offset:1024
	ds_read_b128 v[196:199], v155 offset:2048
	ds_read_b128 v[200:203], v155 offset:3072
	ds_read_b128 v[204:207], v155 offset:4096
	ds_read_b128 v[208:211], v155 offset:5120
	ds_read_b128 v[212:215], v155 offset:6144
	ds_read_b128 v[216:219], v155 offset:7168
	global_load_lds_dwordx4 v[220:221], off
	v_lshl_add_u64 v[220:221], s[34:35], 0, v[138:139]
	s_add_i32 m0, s10, 0xe000
	s_nop 0
	global_load_lds_dwordx4 v[220:221], off
	s_waitcnt vmcnt(8)
	s_waitcnt lgkmcnt(0)
	s_barrier
; #define PG8_STAGE(bufoff, gbase, voff) do { _Pragma("unroll") for (int _i = 0; _i < 2; ++_i) \
;         __builtin_amdgcn_global_load_lds((const unsigned*)((const char*)(gbase) + (voff)[_i]), (PG8_LAS unsigned*)(lds + (bufoff) + ldsw + _i * 8192), 16, 0, 0); } while (0)
; #define PG8_LDA(dst, b, h) do { _Pragma("unroll") for (int m = 0; m < 4; ++m) _Pragma("unroll") for (int k = 0; k < 2; ++k) dst[m][k] = *(const PG8_LAS bf16x8*)(lds + PG8_SA(b, h) + aoff + m * 2048 + k * 1024); } while (0)
; #define PG8_LDB(dst, b, h) do { _Pragma("unroll") for (int n = 0; n < 2; ++n) _Pragma("unroll") for (int k = 0; k < 2; ++k) dst[n][k] = *(const PG8_LAS bf16x8*)(lds + PG8_SB(b, h) + boff + n * 2048 + k * 1024); } while (0)
; #define PG8_MMA(ai, bj, At, Bt) do { __builtin_amdgcn_s_setprio(1); _Pragma("unroll") for (int m = 0; m < 4; ++m) _Pragma("unroll") for (int n = 0; n < 2; ++n) _Pragma("unroll") for (int k = 0; k < 2; ++k) \
;         acc[ai][bj][m][n] = __builtin_amdgcn_mfma_f32_16x16x32_bf16(Bt[n][k], At[m][k], acc[ai][bj][m][n], 0, 0, 0); __builtin_amdgcn_s_setprio(0); } while (0)
; #define PG8_WAIT_V(n) asm volatile("s_waitcnt vmcnt(" #n ")" ::: "memory")
; #define PG8_WAIT_L(n) asm volatile("s_waitcnt lgkmcnt(" #n ")" ::: "memory")
; #define PG8_BAR __builtin_amdgcn_s_barrier()
; #define PG8_SCHED __builtin_amdgcn_sched_barrier(0)
; template <class Epi, class Sched, bool ALIGN_EPI = false, bool SP2 = false>
; __device__ __forceinline__ void gemm_phase(PG8_LAS unsigned char* lds, const Gemm g, const Sched& S, const Epi& E) {
;     ...
;             PG8_LDB(B0, 0, 0); PG8_LDB(B1, 0, 1); PG8_SCHED; PG8_LDA(At, 0, 0); PG8_STAGE(PG8_SA(1, 1), a1 + hstep, voffA);
;             PG8_WAIT_V(8); PG8_WAIT_L(0); PG8_BAR; PG8_MMA(0, 0, At, B0); PG8_MMA(0, 1, At, B1); PG8_BAR; PG8_SCHED;
;             PG8_LDA(At, 0, 1); PG8_STAGE(PG8_SB(0, 0), b2, voffB); PG8_STAGE(PG8_SB(0, 1), b2 + hstep, voffB); PG8_STAGE(PG8_SA(0, 0), a2, voffA);
;             PG8_WAIT_V(8); PG8_WAIT_L(0); PG8_BAR; PG8_MMA(1, 0, At, B0); PG8_MMA(1, 1, At, B1); PG8_BAR; PG8_SCHED;
	s_waitcnt lgkmcnt(0)
	v_mfma_f32_16x16x32_bf16 v[124:127], v[144:147], v[188:191], v[124:127]
	v_mfma_f32_16x16x32_bf16 v[120:123], v[164:167], v[188:191], v[120:123]
	v_mfma_f32_16x16x32_bf16 v[108:111], v[144:147], v[196:199], v[108:111]
	v_mfma_f32_16x16x32_bf16 v[104:107], v[164:167], v[196:199], v[104:107]
	v_mfma_f32_16x16x32_bf16 v[92:95], v[144:147], v[204:207], v[92:95]
	v_mfma_f32_16x16x32_bf16 v[88:91], v[164:167], v[204:207], v[88:91]
	v_mfma_f32_16x16x32_bf16 v[76:79], v[144:147], v[212:215], v[76:79]
	v_mfma_f32_16x16x32_bf16 v[72:75], v[164:167], v[212:215], v[72:75]
	v_mfma_f32_16x16x32_bf16 v[124:127], v[158:161], v[192:195], v[124:127]
	v_mfma_f32_16x16x32_bf16 v[120:123], v[168:171], v[192:195], v[120:123]
	v_mfma_f32_16x16x32_bf16 v[108:111], v[158:161], v[200:203], v[108:111]
	v_mfma_f32_16x16x32_bf16 v[104:107], v[168:171], v[200:203], v[104:107]
	v_mfma_f32_16x16x32_bf16 v[92:95], v[158:161], v[208:211], v[92:95]
	v_mfma_f32_16x16x32_bf16 v[88:91], v[168:171], v[208:211], v[88:91]
	v_mfma_f32_16x16x32_bf16 v[76:79], v[158:161], v[216:219], v[76:79]
	v_mfma_f32_16x16x32_bf16 v[72:75], v[168:171], v[216:219], v[72:75]
	v_mfma_f32_16x16x32_bf16 v[116:119], v[172:175], v[188:191], v[116:119]
	v_mfma_f32_16x16x32_bf16 v[112:115], v[180:183], v[188:191], v[112:115]
	v_mfma_f32_16x16x32_bf16 v[100:103], v[172:175], v[196:199], v[100:103]
	v_mfma_f32_16x16x32_bf16 v[96:99], v[180:183], v[196:199], v[96:99]
	v_mfma_f32_16x16x32_bf16 v[84:87], v[172:175], v[204:207], v[84:87]
	v_mfma_f32_16x16x32_bf16 v[80:83], v[180:183], v[204:207], v[80:83]
	v_mfma_f32_16x16x32_bf16 v[68:71], v[172:175], v[212:215], v[68:71]
	v_mfma_f32_16x16x32_bf16 v[64:67], v[180:183], v[212:215], v[64:67]
	v_mfma_f32_16x16x32_bf16 v[116:119], v[176:179], v[192:195], v[116:119]
	v_mfma_f32_16x16x32_bf16 v[112:115], v[184:187], v[192:195], v[112:115]
	v_mfma_f32_16x16x32_bf16 v[100:103], v[176:179], v[200:203], v[100:103]
	v_mfma_f32_16x16x32_bf16 v[96:99], v[184:187], v[200:203], v[96:99]
	v_mfma_f32_16x16x32_bf16 v[84:87], v[176:179], v[208:211], v[84:87]
	v_mfma_f32_16x16x32_bf16 v[80:83], v[184:187], v[208:211], v[80:83]
	v_mfma_f32_16x16x32_bf16 v[68:71], v[176:179], v[216:219], v[68:71]
	v_mfma_f32_16x16x32_bf16 v[64:67], v[184:187], v[216:219], v[64:67]
	s_barrier
	s_add_i32 s58, s49, s3
	v_lshl_add_u64 v[220:221], s[36:37], 0, v[130:131]
	s_mov_b32 m0, s58
	ds_read_b128 v[188:191], v155 offset:16384
	ds_read_b128 v[192:195], v155 offset:17408
	ds_read_b128 v[196:199], v155 offset:18432
	ds_read_b128 v[200:203], v155 offset:19456
	ds_read_b128 v[204:207], v155 offset:20480
	ds_read_b128 v[208:211], v155 offset:21504
	ds_read_b128 v[212:215], v155 offset:22528
	ds_read_b128 v[216:219], v155 offset:23552
	global_load_lds_dwordx4 v[220:221], off
	s_add_i32 m0, s58, 0x2000
	s_add_u32 s58, s36, 0x40000
	v_lshl_add_u64 v[222:223], s[36:37], 0, v[134:135]
	s_addc_u32 s59, s37, 0
	s_add_i32 s64, s50, s3
	global_load_lds_dwordx4 v[222:223], off
	v_lshl_add_u64 v[224:225], s[58:59], 0, v[130:131]
	s_mov_b32 m0, s64
	v_lshl_add_u64 v[226:227], s[38:39], 0, v[132:133]
	global_load_lds_dwordx4 v[224:225], off
	v_lshl_add_u64 v[224:225], s[58:59], 0, v[134:135]
	s_add_i32 m0, s64, 0x2000
	s_nop 0
	global_load_lds_dwordx4 v[224:225], off
	v_lshl_add_u64 v[224:225], s[38:39], 0, v[128:129]
	s_mov_b32 m0, s10
	s_nop 0
	global_load_lds_dwordx4 v[224:225], off
	s_mov_b32 m0, s11
	s_nop 0
	global_load_lds_dwordx4 v[226:227], off
	s_waitcnt vmcnt(8)
	s_waitcnt lgkmcnt(0)
	s_barrier
	s_waitcnt lgkmcnt(0)
	v_mfma_f32_16x16x32_bf16 v[60:63], v[144:147], v[188:191], v[60:63]
	v_mfma_f32_16x16x32_bf16 v[56:59], v[164:167], v[188:191], v[56:59]
	v_mfma_f32_16x16x32_bf16 v[44:47], v[144:147], v[196:199], v[44:47]
	v_mfma_f32_16x16x32_bf16 v[40:43], v[164:167], v[196:199], v[40:43]
	v_mfma_f32_16x16x32_bf16 v[28:31], v[144:147], v[204:207], v[28:31]
	v_mfma_f32_16x16x32_bf16 v[24:27], v[164:167], v[204:207], v[24:27]
	v_mfma_f32_16x16x32_bf16 v[12:15], v[144:147], v[212:215], v[12:15]
	v_mfma_f32_16x16x32_bf16 v[8:11], v[164:167], v[212:215], v[8:11]
	v_mfma_f32_16x16x32_bf16 v[60:63], v[158:161], v[192:195], v[60:63]
	v_mfma_f32_16x16x32_bf16 v[56:59], v[168:171], v[192:195], v[56:59]
	v_mfma_f32_16x16x32_bf16 v[44:47], v[158:161], v[200:203], v[44:47]
	v_mfma_f32_16x16x32_bf16 v[40:43], v[168:171], v[200:203], v[40:43]
	v_mfma_f32_16x16x32_bf16 v[28:31], v[158:161], v[208:211], v[28:31]
	v_mfma_f32_16x16x32_bf16 v[24:27], v[168:171], v[208:211], v[24:27]
	v_mfma_f32_16x16x32_bf16 v[12:15], v[158:161], v[216:219], v[12:15]
	v_mfma_f32_16x16x32_bf16 v[8:11], v[168:171], v[216:219], v[8:11]
	v_mfma_f32_16x16x32_bf16 v[52:55], v[172:175], v[188:191], v[52:55]
	v_mfma_f32_16x16x32_bf16 v[48:51], v[180:183], v[188:191], v[48:51]
	v_mfma_f32_16x16x32_bf16 v[36:39], v[172:175], v[196:199], v[36:39]
	v_mfma_f32_16x16x32_bf16 v[32:35], v[180:183], v[196:199], v[32:35]
	v_mfma_f32_16x16x32_bf16 v[20:23], v[172:175], v[204:207], v[20:23]
	v_mfma_f32_16x16x32_bf16 v[16:19], v[180:183], v[204:207], v[16:19]
	v_mfma_f32_16x16x32_bf16 v[4:7], v[172:175], v[212:215], v[4:7]
	v_mfma_f32_16x16x32_bf16 v[0:3], v[180:183], v[212:215], v[0:3]
	v_mfma_f32_16x16x32_bf16 v[52:55], v[176:179], v[192:195], v[52:55]
	v_mfma_f32_16x16x32_bf16 v[48:51], v[184:187], v[192:195], v[48:51]
	v_mfma_f32_16x16x32_bf16 v[36:39], v[176:179], v[200:203], v[36:39]
	v_mfma_f32_16x16x32_bf16 v[32:35], v[184:187], v[200:203], v[32:35]
	v_mfma_f32_16x16x32_bf16 v[20:23], v[176:179], v[208:211], v[20:23]
	v_mfma_f32_16x16x32_bf16 v[16:19], v[184:187], v[208:211], v[16:19]
	v_mfma_f32_16x16x32_bf16 v[4:7], v[176:179], v[216:219], v[4:7]
	v_mfma_f32_16x16x32_bf16 v[0:3], v[184:187], v[216:219], v[0:3]
	s_barrier
; #define PG8_STAGE(bufoff, gbase, voff) do { _Pragma("unroll") for (int _i = 0; _i < 2; ++_i) \
;         __builtin_amdgcn_global_load_lds((const unsigned*)((const char*)(gbase) + (voff)[_i]), (PG8_LAS unsigned*)(lds + (bufoff) + ldsw + _i * 8192), 16, 0, 0); } while (0)
; #define PG8_LDA(dst, b, h) do { _Pragma("unroll") for (int m = 0; m < 4; ++m) _Pragma("unroll") for (int k = 0; k < 2; ++k) dst[m][k] = *(const PG8_LAS bf16x8*)(lds + PG8_SA(b, h) + aoff + m * 2048 + k * 1024); } while (0)
; #define PG8_LDB(dst, b, h) do { _Pragma("unroll") for (int n = 0; n < 2; ++n) _Pragma("unroll") for (int k = 0; k < 2; ++k) dst[n][k] = *(const PG8_LAS bf16x8*)(lds + PG8_SB(b, h) + boff + n * 2048 + k * 1024); } while (0)
; #define PG8_MMA(ai, bj, At, Bt) do { __builtin_amdgcn_s_setprio(1); _Pragma("unroll") for (int m = 0; m < 4; ++m) _Pragma("unroll") for (int n = 0; n < 2; ++n) _Pragma("unroll") for (int k = 0; k < 2; ++k) \
;         acc[ai][bj][m][n] = __builtin_amdgcn_mfma_f32_16x16x32_bf16(Bt[n][k], At[m][k], acc[ai][bj][m][n], 0, 0, 0); __builtin_amdgcn_s_setprio(0); } while (0)
; #define PG8_WAIT_V(n) asm volatile("s_waitcnt vmcnt(" #n ")" ::: "memory")
; #define PG8_WAIT_L(n) asm volatile("s_waitcnt lgkmcnt(" #n ")" ::: "memory")
; #define PG8_BAR __builtin_amdgcn_s_barrier()
; #define PG8_SCHED __builtin_amdgcn_sched_barrier(0)
; template <class Epi, class Sched, bool ALIGN_EPI = false, bool SP2 = false>
; __device__ __forceinline__ void gemm_phase(PG8_LAS unsigned char* lds, const Gemm g, const Sched& S, const Epi& E) {
;     ...
;         for (int t = 0; t < nt; t += 2) {
;     ...
;             PG8_LDB(B0, 1, 0); PG8_LDB(B1, 1, 1); PG8_SCHED; PG8_LDA(At, 1, 0); PG8_STAGE(PG8_SA(0, 1), a2 + hstep, voffA);
;             PG8_WAIT_V(8); PG8_WAIT_L(0); PG8_BAR; PG8_MMA(0, 0, At, B0); PG8_MMA(0, 1, At, B1); PG8_BAR; PG8_SCHED;
;             PG8_LDA(At, 1, 1); PG8_STAGE(PG8_SB(1, 0), b3, voffB); PG8_STAGE(PG8_SB(1, 1), b3 + hstep, voffB); PG8_STAGE(PG8_SA(1, 0), a3, voffA);
;             PG8_WAIT_V(8); PG8_WAIT_L(0); PG8_BAR; PG8_MMA(1, 0, At, B0); PG8_MMA(1, 1, At, B1); PG8_BAR; PG8_SCHED;
	s_add_i32 s58, 0, 0x18000
	v_add_u32_e32 v157, s58, v150
	s_add_i32 s59, 0, 0x1c000
	ds_read_b128 v[144:147], v157
	ds_read_b128 v[158:161], v157 offset:1024
	ds_read_b128 v[164:167], v157 offset:2048
	ds_read_b128 v[168:171], v157 offset:3072
	v_add_u32_e32 v157, s59, v150
	ds_read_b128 v[172:175], v157
	ds_read_b128 v[176:179], v157 offset:1024
	ds_read_b128 v[180:183], v157 offset:2048
	ds_read_b128 v[184:187], v157 offset:3072
	s_add_u32 s38, s38, 0x40000
	s_addc_u32 s39, s39, 0
	s_mov_b32 m0, s31
	v_lshl_add_u64 v[228:229], s[38:39], 0, v[128:129]
	ds_read_b128 v[188:191], v155 offset:32768
	ds_read_b128 v[192:195], v155 offset:33792
	ds_read_b128 v[196:199], v155 offset:34816
	ds_read_b128 v[200:203], v155 offset:35840
	ds_read_b128 v[204:207], v155 offset:36864
	ds_read_b128 v[208:211], v155 offset:37888
	ds_read_b128 v[212:215], v155 offset:38912
	ds_read_b128 v[216:219], v155 offset:39936
	global_load_lds_dwordx4 v[228:229], off
	v_lshl_add_u64 v[228:229], s[38:39], 0, v[132:133]
	s_mov_b32 m0, s33
	s_nop 0
	global_load_lds_dwordx4 v[228:229], off
	s_waitcnt vmcnt(8)
	s_waitcnt lgkmcnt(0)
	s_barrier
	s_waitcnt lgkmcnt(0)
	v_mfma_f32_16x16x32_bf16 v[124:127], v[144:147], v[188:191], v[124:127]
	v_mfma_f32_16x16x32_bf16 v[120:123], v[164:167], v[188:191], v[120:123]
	v_mfma_f32_16x16x32_bf16 v[108:111], v[144:147], v[196:199], v[108:111]
	v_mfma_f32_16x16x32_bf16 v[104:107], v[164:167], v[196:199], v[104:107]
	v_mfma_f32_16x16x32_bf16 v[92:95], v[144:147], v[204:207], v[92:95]
	v_mfma_f32_16x16x32_bf16 v[88:91], v[164:167], v[204:207], v[88:91]
	v_mfma_f32_16x16x32_bf16 v[76:79], v[144:147], v[212:215], v[76:79]
	v_mfma_f32_16x16x32_bf16 v[72:75], v[164:167], v[212:215], v[72:75]
	v_mfma_f32_16x16x32_bf16 v[124:127], v[158:161], v[192:195], v[124:127]
	v_mfma_f32_16x16x32_bf16 v[120:123], v[168:171], v[192:195], v[120:123]
	v_mfma_f32_16x16x32_bf16 v[108:111], v[158:161], v[200:203], v[108:111]
	v_mfma_f32_16x16x32_bf16 v[104:107], v[168:171], v[200:203], v[104:107]
	v_mfma_f32_16x16x32_bf16 v[92:95], v[158:161], v[208:211], v[92:95]
	v_mfma_f32_16x16x32_bf16 v[88:91], v[168:171], v[208:211], v[88:91]
	v_mfma_f32_16x16x32_bf16 v[76:79], v[158:161], v[216:219], v[76:79]
	v_mfma_f32_16x16x32_bf16 v[72:75], v[168:171], v[216:219], v[72:75]
	v_mfma_f32_16x16x32_bf16 v[116:119], v[172:175], v[188:191], v[116:119]
	v_mfma_f32_16x16x32_bf16 v[112:115], v[180:183], v[188:191], v[112:115]
	v_mfma_f32_16x16x32_bf16 v[100:103], v[172:175], v[196:199], v[100:103]
	v_mfma_f32_16x16x32_bf16 v[96:99], v[180:183], v[196:199], v[96:99]
	v_mfma_f32_16x16x32_bf16 v[84:87], v[172:175], v[204:207], v[84:87]
	v_mfma_f32_16x16x32_bf16 v[80:83], v[180:183], v[204:207], v[80:83]
	v_mfma_f32_16x16x32_bf16 v[68:71], v[172:175], v[212:215], v[68:71]
	v_mfma_f32_16x16x32_bf16 v[64:67], v[180:183], v[212:215], v[64:67]
	v_mfma_f32_16x16x32_bf16 v[116:119], v[176:179], v[192:195], v[116:119]
	v_mfma_f32_16x16x32_bf16 v[112:115], v[184:187], v[192:195], v[112:115]
	v_mfma_f32_16x16x32_bf16 v[100:103], v[176:179], v[200:203], v[100:103]
	v_mfma_f32_16x16x32_bf16 v[96:99], v[184:187], v[200:203], v[96:99]
	v_mfma_f32_16x16x32_bf16 v[84:87], v[176:179], v[208:211], v[84:87]
	v_mfma_f32_16x16x32_bf16 v[80:83], v[184:187], v[208:211], v[80:83]
	v_mfma_f32_16x16x32_bf16 v[68:71], v[176:179], v[216:219], v[68:71]
	v_mfma_f32_16x16x32_bf16 v[64:67], v[184:187], v[216:219], v[64:67]
	s_barrier
	s_add_i32 s38, s58, s3
	v_lshl_add_u64 v[220:221], v[220:221], 0, s[16:17]
	s_mov_b32 m0, s38
	ds_read_b128 v[188:191], v155 offset:49152
	ds_read_b128 v[192:195], v155 offset:50176
	ds_read_b128 v[196:199], v155 offset:51200
	ds_read_b128 v[200:203], v155 offset:52224
	ds_read_b128 v[204:207], v155 offset:53248
	ds_read_b128 v[208:211], v155 offset:54272
	ds_read_b128 v[212:215], v155 offset:55296
	ds_read_b128 v[216:219], v155 offset:56320
	global_load_lds_dwordx4 v[220:221], off
	s_add_i32 m0, s38, 0x2000
	s_add_u32 s36, s36, 0x40080
	v_lshl_add_u64 v[220:221], v[222:223], 0, s[16:17]
	s_addc_u32 s37, s37, 0
	s_add_i32 s38, s59, s3
	global_load_lds_dwordx4 v[220:221], off
	v_lshl_add_u64 v[220:221], s[36:37], 0, v[130:131]
	s_mov_b32 m0, s38
	s_nop 0
	global_load_lds_dwordx4 v[220:221], off
	v_lshl_add_u64 v[220:221], s[36:37], 0, v[134:135]
	s_add_i32 m0, s38, 0x2000
	s_nop 0
	global_load_lds_dwordx4 v[220:221], off
	v_lshl_add_u64 v[220:221], v[224:225], 0, s[16:17]
	s_mov_b32 m0, s47
	s_nop 0
	global_load_lds_dwordx4 v[220:221], off
	v_lshl_add_u64 v[220:221], v[226:227], 0, s[16:17]
	s_mov_b32 m0, s48
	s_nop 0
	global_load_lds_dwordx4 v[220:221], off
	s_waitcnt vmcnt(8)
	s_waitcnt lgkmcnt(0)
	s_barrier
	s_waitcnt lgkmcnt(0)
	v_mfma_f32_16x16x32_bf16 v[60:63], v[144:147], v[188:191], v[60:63]
	v_mfma_f32_16x16x32_bf16 v[56:59], v[164:167], v[188:191], v[56:59]
	v_mfma_f32_16x16x32_bf16 v[44:47], v[144:147], v[196:199], v[44:47]
	v_mfma_f32_16x16x32_bf16 v[40:43], v[164:167], v[196:199], v[40:43]
	v_mfma_f32_16x16x32_bf16 v[28:31], v[144:147], v[204:207], v[28:31]
	v_mfma_f32_16x16x32_bf16 v[24:27], v[164:167], v[204:207], v[24:27]
	v_mfma_f32_16x16x32_bf16 v[12:15], v[144:147], v[212:215], v[12:15]
	v_mfma_f32_16x16x32_bf16 v[8:11], v[164:167], v[212:215], v[8:11]
	v_mfma_f32_16x16x32_bf16 v[60:63], v[158:161], v[192:195], v[60:63]
	v_mfma_f32_16x16x32_bf16 v[56:59], v[168:171], v[192:195], v[56:59]
	v_mfma_f32_16x16x32_bf16 v[44:47], v[158:161], v[200:203], v[44:47]
	v_mfma_f32_16x16x32_bf16 v[40:43], v[168:171], v[200:203], v[40:43]
	v_mfma_f32_16x16x32_bf16 v[28:31], v[158:161], v[208:211], v[28:31]
	v_mfma_f32_16x16x32_bf16 v[24:27], v[168:171], v[208:211], v[24:27]
	v_mfma_f32_16x16x32_bf16 v[12:15], v[158:161], v[216:219], v[12:15]
	v_mfma_f32_16x16x32_bf16 v[8:11], v[168:171], v[216:219], v[8:11]
	v_mfma_f32_16x16x32_bf16 v[52:55], v[172:175], v[188:191], v[52:55]
	v_mfma_f32_16x16x32_bf16 v[48:51], v[180:183], v[188:191], v[48:51]
	v_mfma_f32_16x16x32_bf16 v[36:39], v[172:175], v[196:199], v[36:39]
	v_mfma_f32_16x16x32_bf16 v[32:35], v[180:183], v[196:199], v[32:35]
	v_mfma_f32_16x16x32_bf16 v[20:23], v[172:175], v[204:207], v[20:23]
	v_mfma_f32_16x16x32_bf16 v[16:19], v[180:183], v[204:207], v[16:19]
	v_mfma_f32_16x16x32_bf16 v[4:7], v[172:175], v[212:215], v[4:7]
	v_mfma_f32_16x16x32_bf16 v[0:3], v[180:183], v[212:215], v[0:3]
	v_mfma_f32_16x16x32_bf16 v[52:55], v[176:179], v[192:195], v[52:55]
	v_mfma_f32_16x16x32_bf16 v[48:51], v[184:187], v[192:195], v[48:51]
	v_mfma_f32_16x16x32_bf16 v[36:39], v[176:179], v[200:203], v[36:39]
	v_mfma_f32_16x16x32_bf16 v[32:35], v[184:187], v[200:203], v[32:35]
	v_mfma_f32_16x16x32_bf16 v[20:23], v[176:179], v[208:211], v[20:23]
	v_mfma_f32_16x16x32_bf16 v[16:19], v[184:187], v[208:211], v[16:19]
	v_mfma_f32_16x16x32_bf16 v[4:7], v[176:179], v[216:219], v[4:7]
	v_mfma_f32_16x16x32_bf16 v[0:3], v[184:187], v[216:219], v[0:3]
	s_barrier
	s_add_i32 s55, s55, 2
	s_add_u32 s34, s34, 0x100
	s_addc_u32 s35, s35, 0
	s_add_u32 s53, s53, 0x100
	s_addc_u32 s54, s54, 0
	s_cmp_gt_u32 s55, 13
	s_cbranch_scc0 .LBB0_803

; #define PG8_STAGE(bufoff, gbase, voff) do { _Pragma("unroll") for (int _i = 0; _i < 2; ++_i) \
;         __builtin_amdgcn_global_load_lds((const unsigned*)((const char*)(gbase) + (voff)[_i]), (PG8_LAS unsigned*)(lds + (bufoff) + ldsw + _i * 8192), 16, 0, 0); } while (0)
; #define PG8_LDA(dst, b, h) do { _Pragma("unroll") for (int m = 0; m < 4; ++m) _Pragma("unroll") for (int k = 0; k < 2; ++k) dst[m][k] = *(const PG8_LAS bf16x8*)(lds + PG8_SA(b, h) + aoff + m * 2048 + k * 1024); } while (0)
; #define PG8_LDB(dst, b, h) do { _Pragma("unroll") for (int n = 0; n < 2; ++n) _Pragma("unroll") for (int k = 0; k < 2; ++k) dst[n][k] = *(const PG8_LAS bf16x8*)(lds + PG8_SB(b, h) + boff + n * 2048 + k * 1024); } while (0)
; template <class Epi, class Sched, bool ALIGN_EPI = false, bool SP2 = false>
; __device__ __forceinline__ void gemm_phase(PG8_LAS unsigned char* lds, const Gemm g, const Sched& S, const Epi& E) {
;     ...
;         const bool has_next = S.next(ui + 1, nxt);
;         const char* nA = has_next ? (const char*)g.A + (size_t)nxt.pm * tstep : cA; const char* nB = has_next ? (const char*)g.Bt + (size_t)nxt.pn * tstep : cB;
;         for (int t = 0; t < nt; t += 2) {
;             const bool last = (t == nt - 2);
;             const char* a1 = cA + (size_t)(t + 1) * kstep;
;             const char* a2 = last ? nA : cA + (size_t)(t + 2) * kstep; const char* b2 = last ? nB : cB + (size_t)(t + 2) * kstep;
;             const char* a3 = a2 + kstep; const char* b3 = b2 + kstep;
;             if (last && has_next) S.a_ready(nxt);
;             if constexpr (SP2) {
;             PG8_LDB(B0, 0, 0); PG8_LDB(B1, 0, 1); PG8_SCHED; PG8_LDA(At, 0, 0); PG8_STAGE(PG8_SA(1, 1), a1 + hstep, voffA);
;             PG8_WAIT_V(8); PG8_WAIT_L(0); PG8_BAR; PG8_MMA(0, 0, At, B0); PG8_MMA(0, 1, At, B1); PG8_BAR; PG8_SCHED;
;             PG8_LDA(At, 0, 1); PG8_STAGE(PG8_SB(0, 0), b2, voffB); PG8_STAGE(PG8_SB(0, 1), b2 + hstep, voffB); PG8_STAGE(PG8_SA(0, 0), a2, voffA);
;             PG8_WAIT_V(8); PG8_WAIT_L(0); PG8_BAR; PG8_MMA(1, 0, At, B0); PG8_MMA(1, 1, At, B1); PG8_BAR; PG8_SCHED;
;     ...
;         for (int a = 0; a < 2; ++a)
; #pragma unroll
;             for (int b = 0; b < 2; ++b)
; #pragma unroll
;                 for (int m = 0; m < 4; ++m)
; #pragma unroll
;                     for (int n = 0; n < 2; ++n) acc[a][b][m][n] = (f32x4){0.f, 0.f, 0.f, 0.f};
.LBB0_974:
	s_ashr_i32 s21, s20, 31
	s_lshl_b64 s[22:23], s[20:21], 19
	s_add_u32 s22, s44, s22
	s_addc_u32 s23, s45, s23
	s_and_b64 s[24:25], s[0:1], exec
	s_cselect_b32 s21, s23, s29
	s_cselect_b32 s51, s22, s28
	s_ashr_i32 s19, s18, 31
	s_lshl_b64 s[24:25], s[18:19], 19
	s_add_u32 s24, s62, s24
	s_addc_u32 s25, s63, s25
	s_and_b64 s[34:35], s[0:1], exec
	s_cselect_b32 s19, s25, s31
	s_cselect_b32 s52, s24, s30
	s_add_u32 s28, s28, 0x40080
	s_addc_u32 s29, s29, 0
	s_add_u32 s53, s30, 0x100
	s_addc_u32 s54, s31, 0
	s_mov_b32 s55, -2
	ds_read_b128 v[164:167], v157
	ds_read_b128 v[168:171], v157 offset:1024
	ds_read_b128 v[172:175], v157 offset:2048
	ds_read_b128 v[176:179], v157 offset:3072
	ds_read_b128 v[180:183], v158
	ds_read_b128 v[184:187], v158 offset:1024
	ds_read_b128 v[188:191], v158 offset:2048
	ds_read_b128 v[192:195], v158 offset:3072
	s_add_u32 s30, s28, 0xfffc0080
	s_addc_u32 s31, s29, -1
	s_cmp_eq_u32 s55, 12
	s_cselect_b32 s35, s21, s31
	s_cselect_b32 s34, s51, s30
	s_cselect_b32 s31, s19, s54
	s_cselect_b32 s30, s52, s53
	v_lshl_add_u64 v[160:161], s[28:29], 0, v[136:137]
	s_add_i32 m0, s27, 0xc000
	ds_read_b128 v[196:199], v159
	ds_read_b128 v[200:203], v159 offset:1024
	ds_read_b128 v[204:207], v159 offset:2048
	ds_read_b128 v[208:211], v159 offset:3072
	ds_read_b128 v[212:215], v159 offset:4096
	ds_read_b128 v[216:219], v159 offset:5120
	ds_read_b128 v[220:223], v159 offset:6144
	ds_read_b128 v[224:227], v159 offset:7168
	global_load_lds_dwordx4 v[160:161], off
	v_lshl_add_u64 v[160:161], s[28:29], 0, v[138:139]
	s_add_i32 m0, s27, 0xe000
	s_nop 0
	global_load_lds_dwordx4 v[160:161], off
	s_waitcnt vmcnt(8)
	s_waitcnt lgkmcnt(0)
	s_barrier
	s_waitcnt lgkmcnt(0)
	v_mfma_f32_16x16x32_bf16 v[124:127], v[164:167], v[196:199], 0
	v_mfma_f32_16x16x32_bf16 v[120:123], v[172:175], v[196:199], 0
	v_mfma_f32_16x16x32_bf16 v[108:111], v[164:167], v[204:207], 0
	v_mfma_f32_16x16x32_bf16 v[104:107], v[172:175], v[204:207], 0
	v_mfma_f32_16x16x32_bf16 v[92:95], v[164:167], v[212:215], 0
	v_mfma_f32_16x16x32_bf16 v[88:91], v[172:175], v[212:215], 0
	v_mfma_f32_16x16x32_bf16 v[76:79], v[164:167], v[220:223], 0
	v_mfma_f32_16x16x32_bf16 v[72:75], v[172:175], v[220:223], 0
	v_mfma_f32_16x16x32_bf16 v[124:127], v[168:171], v[200:203], v[124:127]
	v_mfma_f32_16x16x32_bf16 v[120:123], v[176:179], v[200:203], v[120:123]
	v_mfma_f32_16x16x32_bf16 v[108:111], v[168:171], v[208:211], v[108:111]
	v_mfma_f32_16x16x32_bf16 v[104:107], v[176:179], v[208:211], v[104:107]
	v_mfma_f32_16x16x32_bf16 v[92:95], v[168:171], v[216:219], v[92:95]
	v_mfma_f32_16x16x32_bf16 v[88:91], v[176:179], v[216:219], v[88:91]
	v_mfma_f32_16x16x32_bf16 v[76:79], v[168:171], v[224:227], v[76:79]
	v_mfma_f32_16x16x32_bf16 v[72:75], v[176:179], v[224:227], v[72:75]
	v_mfma_f32_16x16x32_bf16 v[116:119], v[180:183], v[196:199], 0
	v_mfma_f32_16x16x32_bf16 v[112:115], v[188:191], v[196:199], 0
	v_mfma_f32_16x16x32_bf16 v[100:103], v[180:183], v[204:207], 0
	v_mfma_f32_16x16x32_bf16 v[96:99], v[188:191], v[204:207], 0
	v_mfma_f32_16x16x32_bf16 v[84:87], v[180:183], v[212:215], 0
	v_mfma_f32_16x16x32_bf16 v[80:83], v[188:191], v[212:215], 0
	v_mfma_f32_16x16x32_bf16 v[68:71], v[180:183], v[220:223], 0
	v_mfma_f32_16x16x32_bf16 v[64:67], v[188:191], v[220:223], 0
	v_mfma_f32_16x16x32_bf16 v[116:119], v[184:187], v[200:203], v[116:119]
	v_mfma_f32_16x16x32_bf16 v[112:115], v[192:195], v[200:203], v[112:115]
	v_mfma_f32_16x16x32_bf16 v[100:103], v[184:187], v[208:211], v[100:103]
	v_mfma_f32_16x16x32_bf16 v[96:99], v[192:195], v[208:211], v[96:99]
	v_mfma_f32_16x16x32_bf16 v[84:87], v[184:187], v[216:219], v[84:87]
	v_mfma_f32_16x16x32_bf16 v[80:83], v[192:195], v[216:219], v[80:83]
	v_mfma_f32_16x16x32_bf16 v[68:71], v[184:187], v[224:227], v[68:71]
	v_mfma_f32_16x16x32_bf16 v[64:67], v[192:195], v[224:227], v[64:67]
	s_barrier
	s_add_i32 s58, s47, s3
	v_lshl_add_u64 v[160:161], s[30:31], 0, v[130:131]
	s_mov_b32 m0, s58
	ds_read_b128 v[196:199], v159 offset:16384
	ds_read_b128 v[200:203], v159 offset:17408
	ds_read_b128 v[204:207], v159 offset:18432
	ds_read_b128 v[208:211], v159 offset:19456
	ds_read_b128 v[212:215], v159 offset:20480
	ds_read_b128 v[216:219], v159 offset:21504
	ds_read_b128 v[220:223], v159 offset:22528
	ds_read_b128 v[224:227], v159 offset:23552
	global_load_lds_dwordx4 v[160:161], off
	s_add_i32 m0, s58, 0x2000
	s_add_u32 s58, s30, 0x40000
	v_lshl_add_u64 v[228:229], s[30:31], 0, v[134:135]
	s_addc_u32 s59, s31, 0
	s_add_i32 s60, s48, s3
	global_load_lds_dwordx4 v[228:229], off
	v_lshl_add_u64 v[230:231], s[58:59], 0, v[130:131]
	s_mov_b32 m0, s60
	v_lshl_add_u64 v[232:233], s[34:35], 0, v[132:133]
	global_load_lds_dwordx4 v[230:231], off
	v_lshl_add_u64 v[230:231], s[58:59], 0, v[134:135]
	s_add_i32 m0, s60, 0x2000
	s_nop 0
	global_load_lds_dwordx4 v[230:231], off
	v_lshl_add_u64 v[230:231], s[34:35], 0, v[128:129]
	s_mov_b32 m0, s27
	s_nop 0
	global_load_lds_dwordx4 v[230:231], off
	s_mov_b32 m0, s37
	s_nop 0
	global_load_lds_dwordx4 v[232:233], off
	s_waitcnt vmcnt(8)
	s_waitcnt lgkmcnt(0)
	s_barrier
; #define PG8_STAGE(bufoff, gbase, voff) do { _Pragma("unroll") for (int _i = 0; _i < 2; ++_i) \
;         __builtin_amdgcn_global_load_lds((const unsigned*)((const char*)(gbase) + (voff)[_i]), (PG8_LAS unsigned*)(lds + (bufoff) + ldsw + _i * 8192), 16, 0, 0); } while (0)
; #define PG8_LDA(dst, b, h) do { _Pragma("unroll") for (int m = 0; m < 4; ++m) _Pragma("unroll") for (int k = 0; k < 2; ++k) dst[m][k] = *(const PG8_LAS bf16x8*)(lds + PG8_SA(b, h) + aoff + m * 2048 + k * 1024); } while (0)
; #define PG8_LDB(dst, b, h) do { _Pragma("unroll") for (int n = 0; n < 2; ++n) _Pragma("unroll") for (int k = 0; k < 2; ++k) dst[n][k] = *(const PG8_LAS bf16x8*)(lds + PG8_SB(b, h) + boff + n * 2048 + k * 1024); } while (0)
; #define PG8_MMA(ai, bj, At, Bt) do { __builtin_amdgcn_s_setprio(1); _Pragma("unroll") for (int m = 0; m < 4; ++m) _Pragma("unroll") for (int n = 0; n < 2; ++n) _Pragma("unroll") for (int k = 0; k < 2; ++k) \
;         acc[ai][bj][m][n] = __builtin_amdgcn_mfma_f32_16x16x32_bf16(Bt[n][k], At[m][k], acc[ai][bj][m][n], 0, 0, 0); __builtin_amdgcn_s_setprio(0); } while (0)
; #define PG8_WAIT_V(n) asm volatile("s_waitcnt vmcnt(" #n ")" ::: "memory")
; #define PG8_WAIT_L(n) asm volatile("s_waitcnt lgkmcnt(" #n ")" ::: "memory")
; #define PG8_BAR __builtin_amdgcn_s_barrier()
; #define PG8_SCHED __builtin_amdgcn_sched_barrier(0)
; template <class Epi, class Sched, bool ALIGN_EPI = false, bool SP2 = false>
; __device__ __forceinline__ void gemm_phase(PG8_LAS unsigned char* lds, const Gemm g, const Sched& S, const Epi& E) {
;     ...
;             PG8_WAIT_V(8); PG8_WAIT_L(0); PG8_BAR; PG8_MMA(1, 0, At, B0); PG8_MMA(1, 1, At, B1); PG8_BAR; PG8_SCHED;
;             PG8_LDB(B0, 1, 0); PG8_LDB(B1, 1, 1); PG8_SCHED; PG8_LDA(At, 1, 0); PG8_STAGE(PG8_SA(0, 1), a2 + hstep, voffA);
;             PG8_WAIT_V(8); PG8_WAIT_L(0); PG8_BAR; PG8_MMA(0, 0, At, B0); PG8_MMA(0, 1, At, B1); PG8_BAR; PG8_SCHED;
	s_waitcnt lgkmcnt(0)
	v_mfma_f32_16x16x32_bf16 v[60:63], v[164:167], v[196:199], 0
	v_mfma_f32_16x16x32_bf16 v[56:59], v[172:175], v[196:199], 0
	v_mfma_f32_16x16x32_bf16 v[44:47], v[164:167], v[204:207], 0
	v_mfma_f32_16x16x32_bf16 v[40:43], v[172:175], v[204:207], 0
	v_mfma_f32_16x16x32_bf16 v[28:31], v[164:167], v[212:215], 0
	v_mfma_f32_16x16x32_bf16 v[24:27], v[172:175], v[212:215], 0
	v_mfma_f32_16x16x32_bf16 v[12:15], v[164:167], v[220:223], 0
	v_mfma_f32_16x16x32_bf16 v[8:11], v[172:175], v[220:223], 0
	v_mfma_f32_16x16x32_bf16 v[60:63], v[168:171], v[200:203], v[60:63]
	v_mfma_f32_16x16x32_bf16 v[56:59], v[176:179], v[200:203], v[56:59]
	v_mfma_f32_16x16x32_bf16 v[44:47], v[168:171], v[208:211], v[44:47]
	v_mfma_f32_16x16x32_bf16 v[40:43], v[176:179], v[208:211], v[40:43]
	v_mfma_f32_16x16x32_bf16 v[28:31], v[168:171], v[216:219], v[28:31]
	v_mfma_f32_16x16x32_bf16 v[24:27], v[176:179], v[216:219], v[24:27]
	v_mfma_f32_16x16x32_bf16 v[12:15], v[168:171], v[224:227], v[12:15]
	v_mfma_f32_16x16x32_bf16 v[8:11], v[176:179], v[224:227], v[8:11]
	v_mfma_f32_16x16x32_bf16 v[52:55], v[180:183], v[196:199], 0
	v_mfma_f32_16x16x32_bf16 v[48:51], v[188:191], v[196:199], 0
	v_mfma_f32_16x16x32_bf16 v[36:39], v[180:183], v[204:207], 0
	v_mfma_f32_16x16x32_bf16 v[32:35], v[188:191], v[204:207], 0
	v_mfma_f32_16x16x32_bf16 v[20:23], v[180:183], v[212:215], 0
	v_mfma_f32_16x16x32_bf16 v[16:19], v[188:191], v[212:215], 0
	v_mfma_f32_16x16x32_bf16 v[4:7], v[180:183], v[220:223], 0
	v_mfma_f32_16x16x32_bf16 v[0:3], v[188:191], v[220:223], 0
	v_mfma_f32_16x16x32_bf16 v[52:55], v[184:187], v[200:203], v[52:55]
	v_mfma_f32_16x16x32_bf16 v[48:51], v[192:195], v[200:203], v[48:51]
	v_mfma_f32_16x16x32_bf16 v[36:39], v[184:187], v[208:211], v[36:39]
	v_mfma_f32_16x16x32_bf16 v[32:35], v[192:195], v[208:211], v[32:35]
	v_mfma_f32_16x16x32_bf16 v[20:23], v[184:187], v[216:219], v[20:23]
	v_mfma_f32_16x16x32_bf16 v[16:19], v[192:195], v[216:219], v[16:19]
	v_mfma_f32_16x16x32_bf16 v[4:7], v[184:187], v[224:227], v[4:7]
	v_mfma_f32_16x16x32_bf16 v[0:3], v[192:195], v[224:227], v[0:3]
	s_barrier
	s_add_i32 s58, 0, 0x18000
	s_add_i32 s59, 0, 0x1c000
	v_add_u32_e32 v176, s58, v155
	v_add_u32_e32 v192, s59, v155
	ds_read_b128 v[164:167], v176
	ds_read_b128 v[168:171], v176 offset:1024
	ds_read_b128 v[172:175], v176 offset:2048
	ds_read_b128 v[176:179], v176 offset:3072
	ds_read_b128 v[180:183], v192
	ds_read_b128 v[184:187], v192 offset:1024
	ds_read_b128 v[188:191], v192 offset:2048
	ds_read_b128 v[192:195], v192 offset:3072
	s_add_u32 s34, s34, 0x40000
	s_addc_u32 s35, s35, 0
	s_mov_b32 m0, s38
	v_lshl_add_u64 v[234:235], s[34:35], 0, v[128:129]
	ds_read_b128 v[196:199], v159 offset:32768
	ds_read_b128 v[200:203], v159 offset:33792
	ds_read_b128 v[204:207], v159 offset:34816
	ds_read_b128 v[208:211], v159 offset:35840
	ds_read_b128 v[212:215], v159 offset:36864
	ds_read_b128 v[216:219], v159 offset:37888
	ds_read_b128 v[220:223], v159 offset:38912
	ds_read_b128 v[224:227], v159 offset:39936
	global_load_lds_dwordx4 v[234:235], off
	v_lshl_add_u64 v[234:235], s[34:35], 0, v[132:133]
	s_mov_b32 m0, s39
	s_nop 0
	global_load_lds_dwordx4 v[234:235], off
	s_waitcnt vmcnt(8)
	s_waitcnt lgkmcnt(0)
	s_barrier
	s_waitcnt lgkmcnt(0)
	v_mfma_f32_16x16x32_bf16 v[124:127], v[164:167], v[196:199], v[124:127]
	v_mfma_f32_16x16x32_bf16 v[120:123], v[172:175], v[196:199], v[120:123]
	v_mfma_f32_16x16x32_bf16 v[108:111], v[164:167], v[204:207], v[108:111]
	v_mfma_f32_16x16x32_bf16 v[104:107], v[172:175], v[204:207], v[104:107]
	v_mfma_f32_16x16x32_bf16 v[92:95], v[164:167], v[212:215], v[92:95]
	v_mfma_f32_16x16x32_bf16 v[88:91], v[172:175], v[212:215], v[88:91]
	v_mfma_f32_16x16x32_bf16 v[76:79], v[164:167], v[220:223], v[76:79]
	v_mfma_f32_16x16x32_bf16 v[72:75], v[172:175], v[220:223], v[72:75]
	v_mfma_f32_16x16x32_bf16 v[124:127], v[168:171], v[200:203], v[124:127]
	v_mfma_f32_16x16x32_bf16 v[120:123], v[176:179], v[200:203], v[120:123]
	v_mfma_f32_16x16x32_bf16 v[108:111], v[168:171], v[208:211], v[108:111]
	v_mfma_f32_16x16x32_bf16 v[104:107], v[176:179], v[208:211], v[104:107]
	v_mfma_f32_16x16x32_bf16 v[92:95], v[168:171], v[216:219], v[92:95]
	v_mfma_f32_16x16x32_bf16 v[88:91], v[176:179], v[216:219], v[88:91]
	v_mfma_f32_16x16x32_bf16 v[76:79], v[168:171], v[224:227], v[76:79]
	v_mfma_f32_16x16x32_bf16 v[72:75], v[176:179], v[224:227], v[72:75]
	v_mfma_f32_16x16x32_bf16 v[116:119], v[180:183], v[196:199], v[116:119]
	v_mfma_f32_16x16x32_bf16 v[112:115], v[188:191], v[196:199], v[112:115]
	v_mfma_f32_16x16x32_bf16 v[100:103], v[180:183], v[204:207], v[100:103]
	v_mfma_f32_16x16x32_bf16 v[96:99], v[188:191], v[204:207], v[96:99]
	v_mfma_f32_16x16x32_bf16 v[84:87], v[180:183], v[212:215], v[84:87]
	v_mfma_f32_16x16x32_bf16 v[80:83], v[188:191], v[212:215], v[80:83]
	v_mfma_f32_16x16x32_bf16 v[68:71], v[180:183], v[220:223], v[68:71]
	v_mfma_f32_16x16x32_bf16 v[64:67], v[188:191], v[220:223], v[64:67]
	v_mfma_f32_16x16x32_bf16 v[116:119], v[184:187], v[200:203], v[116:119]
	v_mfma_f32_16x16x32_bf16 v[112:115], v[192:195], v[200:203], v[112:115]
	v_mfma_f32_16x16x32_bf16 v[100:103], v[184:187], v[208:211], v[100:103]
	v_mfma_f32_16x16x32_bf16 v[96:99], v[192:195], v[208:211], v[96:99]
	v_mfma_f32_16x16x32_bf16 v[84:87], v[184:187], v[216:219], v[84:87]
	v_mfma_f32_16x16x32_bf16 v[80:83], v[192:195], v[216:219], v[80:83]
	v_mfma_f32_16x16x32_bf16 v[68:71], v[184:187], v[224:227], v[68:71]
	v_mfma_f32_16x16x32_bf16 v[64:67], v[192:195], v[224:227], v[64:67]
	s_barrier
; #define PG8_STAGE(bufoff, gbase, voff) do { _Pragma("unroll") for (int _i = 0; _i < 2; ++_i) \
;         __builtin_amdgcn_global_load_lds((const unsigned*)((const char*)(gbase) + (voff)[_i]), (PG8_LAS unsigned*)(lds + (bufoff) + ldsw + _i * 8192), 16, 0, 0); } while (0)
; #define PG8_LDA(dst, b, h) do { _Pragma("unroll") for (int m = 0; m < 4; ++m) _Pragma("unroll") for (int k = 0; k < 2; ++k) dst[m][k] = *(const PG8_LAS bf16x8*)(lds + PG8_SA(b, h) + aoff + m * 2048 + k * 1024); } while (0)
; #define PG8_LDB(dst, b, h) do { _Pragma("unroll") for (int n = 0; n < 2; ++n) _Pragma("unroll") for (int k = 0; k < 2; ++k) dst[n][k] = *(const PG8_LAS bf16x8*)(lds + PG8_SB(b, h) + boff + n * 2048 + k * 1024); } while (0)
; template <class Epi, class Sched, bool ALIGN_EPI = false, bool SP2 = false>
; __device__ __forceinline__ void gemm_phase(PG8_LAS unsigned char* lds, const Gemm g, const Sched& S, const Epi& E) {
;     ...
;         for (int t = 0; t < nt; t += 2) {
;             const bool last = (t == nt - 2);
;             const char* a1 = cA + (size_t)(t + 1) * kstep;
;             const char* a2 = last ? nA : cA + (size_t)(t + 2) * kstep; const char* b2 = last ? nB : cB + (size_t)(t + 2) * kstep;
;             const char* a3 = a2 + kstep; const char* b3 = b2 + kstep;
;             if (last && has_next) S.a_ready(nxt);
;             if constexpr (SP2) {
;             PG8_LDB(B0, 0, 0); PG8_LDB(B1, 0, 1); PG8_SCHED; PG8_LDA(At, 0, 0); PG8_STAGE(PG8_SA(1, 1), a1 + hstep, voffA);
;             PG8_WAIT_V(8); PG8_WAIT_L(0); PG8_BAR; PG8_MMA(0, 0, At, B0); PG8_MMA(0, 1, At, B1); PG8_BAR; PG8_SCHED;
;             PG8_LDA(At, 0, 1); PG8_STAGE(PG8_SB(0, 0), b2, voffB); PG8_STAGE(PG8_SB(0, 1), b2 + hstep, voffB); PG8_STAGE(PG8_SA(0, 0), a2, voffA);
;             PG8_WAIT_V(8); PG8_WAIT_L(0); PG8_BAR; PG8_MMA(1, 0, At, B0); PG8_MMA(1, 1, At, B1); PG8_BAR; PG8_SCHED;
;             PG8_LDB(B0, 1, 0); PG8_LDB(B1, 1, 1); PG8_SCHED; PG8_LDA(At, 1, 0); PG8_STAGE(PG8_SA(0, 1), a2 + hstep, voffA);
;             PG8_WAIT_V(8); PG8_WAIT_L(0); PG8_BAR; PG8_MMA(0, 0, At, B0); PG8_MMA(0, 1, At, B1); PG8_BAR; PG8_SCHED;
;             PG8_LDA(At, 1, 1); PG8_STAGE(PG8_SB(1, 0), b3, voffB); PG8_STAGE(PG8_SB(1, 1), b3 + hstep, voffB); PG8_STAGE(PG8_SA(1, 0), a3, voffA);
;             PG8_WAIT_V(8); PG8_WAIT_L(0); PG8_BAR; PG8_MMA(1, 0, At, B0); PG8_MMA(1, 1, At, B1); PG8_BAR; PG8_SCHED;
	s_add_i32 s34, s58, s3
	v_lshl_add_u64 v[160:161], v[160:161], 0, s[8:9]
	s_mov_b32 m0, s34
	ds_read_b128 v[196:199], v159 offset:49152
	ds_read_b128 v[200:203], v159 offset:50176
	ds_read_b128 v[204:207], v159 offset:51200
	ds_read_b128 v[208:211], v159 offset:52224
	ds_read_b128 v[212:215], v159 offset:53248
	ds_read_b128 v[216:219], v159 offset:54272
	ds_read_b128 v[220:223], v159 offset:55296
	ds_read_b128 v[224:227], v159 offset:56320
	global_load_lds_dwordx4 v[160:161], off
	s_add_i32 m0, s34, 0x2000
	s_add_u32 s30, s30, 0x40080
	v_lshl_add_u64 v[160:161], v[228:229], 0, s[8:9]
	s_addc_u32 s31, s31, 0
	s_add_i32 s34, s59, s3
	global_load_lds_dwordx4 v[160:161], off
	v_lshl_add_u64 v[160:161], s[30:31], 0, v[130:131]
	s_mov_b32 m0, s34
	s_nop 0
	global_load_lds_dwordx4 v[160:161], off
	v_lshl_add_u64 v[160:161], s[30:31], 0, v[134:135]
	s_add_i32 m0, s34, 0x2000
	s_nop 0
	global_load_lds_dwordx4 v[160:161], off
	v_lshl_add_u64 v[160:161], v[230:231], 0, s[8:9]
	s_mov_b32 m0, s43
	s_nop 0
	global_load_lds_dwordx4 v[160:161], off
	v_lshl_add_u64 v[160:161], v[232:233], 0, s[8:9]
	s_mov_b32 m0, s46
	s_nop 0
	global_load_lds_dwordx4 v[160:161], off
	s_waitcnt vmcnt(8)
	s_waitcnt lgkmcnt(0)
	s_barrier
	s_waitcnt lgkmcnt(0)
	v_mfma_f32_16x16x32_bf16 v[60:63], v[164:167], v[196:199], v[60:63]
	v_mfma_f32_16x16x32_bf16 v[56:59], v[172:175], v[196:199], v[56:59]
	v_mfma_f32_16x16x32_bf16 v[44:47], v[164:167], v[204:207], v[44:47]
	v_mfma_f32_16x16x32_bf16 v[40:43], v[172:175], v[204:207], v[40:43]
	v_mfma_f32_16x16x32_bf16 v[28:31], v[164:167], v[212:215], v[28:31]
	v_mfma_f32_16x16x32_bf16 v[24:27], v[172:175], v[212:215], v[24:27]
	v_mfma_f32_16x16x32_bf16 v[12:15], v[164:167], v[220:223], v[12:15]
	v_mfma_f32_16x16x32_bf16 v[8:11], v[172:175], v[220:223], v[8:11]
	v_mfma_f32_16x16x32_bf16 v[60:63], v[168:171], v[200:203], v[60:63]
	v_mfma_f32_16x16x32_bf16 v[56:59], v[176:179], v[200:203], v[56:59]
	v_mfma_f32_16x16x32_bf16 v[44:47], v[168:171], v[208:211], v[44:47]
	v_mfma_f32_16x16x32_bf16 v[40:43], v[176:179], v[208:211], v[40:43]
	v_mfma_f32_16x16x32_bf16 v[28:31], v[168:171], v[216:219], v[28:31]
	v_mfma_f32_16x16x32_bf16 v[24:27], v[176:179], v[216:219], v[24:27]
	v_mfma_f32_16x16x32_bf16 v[12:15], v[168:171], v[224:227], v[12:15]
	v_mfma_f32_16x16x32_bf16 v[8:11], v[176:179], v[224:227], v[8:11]
	v_mfma_f32_16x16x32_bf16 v[52:55], v[180:183], v[196:199], v[52:55]
	v_mfma_f32_16x16x32_bf16 v[48:51], v[188:191], v[196:199], v[48:51]
	v_mfma_f32_16x16x32_bf16 v[36:39], v[180:183], v[204:207], v[36:39]
	v_mfma_f32_16x16x32_bf16 v[32:35], v[188:191], v[204:207], v[32:35]
	v_mfma_f32_16x16x32_bf16 v[20:23], v[180:183], v[212:215], v[20:23]
	v_mfma_f32_16x16x32_bf16 v[16:19], v[188:191], v[212:215], v[16:19]
	v_mfma_f32_16x16x32_bf16 v[4:7], v[180:183], v[220:223], v[4:7]
	v_mfma_f32_16x16x32_bf16 v[0:3], v[188:191], v[220:223], v[0:3]
	v_mfma_f32_16x16x32_bf16 v[52:55], v[184:187], v[200:203], v[52:55]
	v_mfma_f32_16x16x32_bf16 v[48:51], v[192:195], v[200:203], v[48:51]
	v_mfma_f32_16x16x32_bf16 v[36:39], v[184:187], v[208:211], v[36:39]
	v_mfma_f32_16x16x32_bf16 v[32:35], v[192:195], v[208:211], v[32:35]
	v_mfma_f32_16x16x32_bf16 v[20:23], v[184:187], v[216:219], v[20:23]
	v_mfma_f32_16x16x32_bf16 v[16:19], v[192:195], v[216:219], v[16:19]
	v_mfma_f32_16x16x32_bf16 v[4:7], v[184:187], v[224:227], v[4:7]
	v_mfma_f32_16x16x32_bf16 v[0:3], v[192:195], v[224:227], v[0:3]
	s_barrier
	s_add_i32 s55, s55, 2
	s_add_u32 s28, s28, 0x100
	s_addc_u32 s29, s29, 0
	s_add_u32 s53, s53, 0x100
	s_addc_u32 s54, s54, 0
	s_cmp_gt_u32 s55, 13
	s_cbranch_scc1 .Lpeel_exit4
.LBB0_975:
	ds_read_b128 v[164:167], v157
	ds_read_b128 v[168:171], v157 offset:1024
	ds_read_b128 v[172:175], v157 offset:2048
	ds_read_b128 v[176:179], v157 offset:3072
	ds_read_b128 v[180:183], v158
	ds_read_b128 v[184:187], v158 offset:1024
	ds_read_b128 v[188:191], v158 offset:2048
	ds_read_b128 v[192:195], v158 offset:3072
	s_add_u32 s30, s28, 0xfffc0080
	s_addc_u32 s31, s29, -1
	s_cmp_eq_u32 s55, 12
	s_cselect_b32 s35, s21, s31
	s_cselect_b32 s34, s51, s30
	s_cselect_b32 s31, s19, s54
	s_cselect_b32 s30, s52, s53
	v_lshl_add_u64 v[160:161], s[28:29], 0, v[136:137]
	s_add_i32 m0, s27, 0xc000
	ds_read_b128 v[196:199], v159
	ds_read_b128 v[200:203], v159 offset:1024
	ds_read_b128 v[204:207], v159 offset:2048
	ds_read_b128 v[208:211], v159 offset:3072
	ds_read_b128 v[212:215], v159 offset:4096
	ds_read_b128 v[216:219], v159 offset:5120
	ds_read_b128 v[220:223], v159 offset:6144
	ds_read_b128 v[224:227], v159 offset:7168
	global_load_lds_dwordx4 v[160:161], off
	v_lshl_add_u64 v[160:161], s[28:29], 0, v[138:139]
	s_add_i32 m0, s27, 0xe000
	s_nop 0
	global_load_lds_dwordx4 v[160:161], off
	s_waitcnt vmcnt(8)
	s_waitcnt lgkmcnt(0)
	s_barrier
; #define PG8_STAGE(bufoff, gbase, voff) do { _Pragma("unroll") for (int _i = 0; _i < 2; ++_i) \
;         __builtin_amdgcn_global_load_lds((const unsigned*)((const char*)(gbase) + (voff)[_i]), (PG8_LAS unsigned*)(lds + (bufoff) + ldsw + _i * 8192), 16, 0, 0); } while (0)
; #define PG8_LDA(dst, b, h) do { _Pragma("unroll") for (int m = 0; m < 4; ++m) _Pragma("unroll") for (int k = 0; k < 2; ++k) dst[m][k] = *(const PG8_LAS bf16x8*)(lds + PG8_SA(b, h) + aoff + m * 2048 + k * 1024); } while (0)
; #define PG8_LDB(dst, b, h) do { _Pragma("unroll") for (int n = 0; n < 2; ++n) _Pragma("unroll") for (int k = 0; k < 2; ++k) dst[n][k] = *(const PG8_LAS bf16x8*)(lds + PG8_SB(b, h) + boff + n * 2048 + k * 1024); } while (0)
; #define PG8_MMA(ai, bj, At, Bt) do { __builtin_amdgcn_s_setprio(1); _Pragma("unroll") for (int m = 0; m < 4; ++m) _Pragma("unroll") for (int n = 0; n < 2; ++n) _Pragma("unroll") for (int k = 0; k < 2; ++k) \
;         acc[ai][bj][m][n] = __builtin_amdgcn_mfma_f32_16x16x32_bf16(Bt[n][k], At[m][k], acc[ai][bj][m][n], 0, 0, 0); __builtin_amdgcn_s_setprio(0); } while (0)
; #define PG8_WAIT_V(n) asm volatile("s_waitcnt vmcnt(" #n ")" ::: "memory")
; #define PG8_WAIT_L(n) asm volatile("s_waitcnt lgkmcnt(" #n ")" ::: "memory")
; #define PG8_BAR __builtin_amdgcn_s_barrier()
; #define PG8_SCHED __builtin_amdgcn_sched_barrier(0)
; template <class Epi, class Sched, bool ALIGN_EPI = false, bool SP2 = false>
; __device__ __forceinline__ void gemm_phase(PG8_LAS unsigned char* lds, const Gemm g, const Sched& S, const Epi& E) {
;     ...
;             PG8_LDB(B0, 0, 0); PG8_LDB(B1, 0, 1); PG8_SCHED; PG8_LDA(At, 0, 0); PG8_STAGE(PG8_SA(1, 1), a1 + hstep, voffA);
;             PG8_WAIT_V(8); PG8_WAIT_L(0); PG8_BAR; PG8_MMA(0, 0, At, B0); PG8_MMA(0, 1, At, B1); PG8_BAR; PG8_SCHED;
;             PG8_LDA(At, 0, 1); PG8_STAGE(PG8_SB(0, 0), b2, voffB); PG8_STAGE(PG8_SB(0, 1), b2 + hstep, voffB); PG8_STAGE(PG8_SA(0, 0), a2, voffA);
;             PG8_WAIT_V(8); PG8_WAIT_L(0); PG8_BAR; PG8_MMA(1, 0, At, B0); PG8_MMA(1, 1, At, B1); PG8_BAR; PG8_SCHED;
	s_waitcnt lgkmcnt(0)
	v_mfma_f32_16x16x32_bf16 v[124:127], v[164:167], v[196:199], v[124:127]
	v_mfma_f32_16x16x32_bf16 v[120:123], v[172:175], v[196:199], v[120:123]
	v_mfma_f32_16x16x32_bf16 v[108:111], v[164:167], v[204:207], v[108:111]
	v_mfma_f32_16x16x32_bf16 v[104:107], v[172:175], v[204:207], v[104:107]
	v_mfma_f32_16x16x32_bf16 v[92:95], v[164:167], v[212:215], v[92:95]
	v_mfma_f32_16x16x32_bf16 v[88:91], v[172:175], v[212:215], v[88:91]
	v_mfma_f32_16x16x32_bf16 v[76:79], v[164:167], v[220:223], v[76:79]
	v_mfma_f32_16x16x32_bf16 v[72:75], v[172:175], v[220:223], v[72:75]
	v_mfma_f32_16x16x32_bf16 v[124:127], v[168:171], v[200:203], v[124:127]
	v_mfma_f32_16x16x32_bf16 v[120:123], v[176:179], v[200:203], v[120:123]
	v_mfma_f32_16x16x32_bf16 v[108:111], v[168:171], v[208:211], v[108:111]
	v_mfma_f32_16x16x32_bf16 v[104:107], v[176:179], v[208:211], v[104:107]
	v_mfma_f32_16x16x32_bf16 v[92:95], v[168:171], v[216:219], v[92:95]
	v_mfma_f32_16x16x32_bf16 v[88:91], v[176:179], v[216:219], v[88:91]
	v_mfma_f32_16x16x32_bf16 v[76:79], v[168:171], v[224:227], v[76:79]
	v_mfma_f32_16x16x32_bf16 v[72:75], v[176:179], v[224:227], v[72:75]
	v_mfma_f32_16x16x32_bf16 v[116:119], v[180:183], v[196:199], v[116:119]
	v_mfma_f32_16x16x32_bf16 v[112:115], v[188:191], v[196:199], v[112:115]
	v_mfma_f32_16x16x32_bf16 v[100:103], v[180:183], v[204:207], v[100:103]
	v_mfma_f32_16x16x32_bf16 v[96:99], v[188:191], v[204:207], v[96:99]
	v_mfma_f32_16x16x32_bf16 v[84:87], v[180:183], v[212:215], v[84:87]
	v_mfma_f32_16x16x32_bf16 v[80:83], v[188:191], v[212:215], v[80:83]
	v_mfma_f32_16x16x32_bf16 v[68:71], v[180:183], v[220:223], v[68:71]
	v_mfma_f32_16x16x32_bf16 v[64:67], v[188:191], v[220:223], v[64:67]
	v_mfma_f32_16x16x32_bf16 v[116:119], v[184:187], v[200:203], v[116:119]
	v_mfma_f32_16x16x32_bf16 v[112:115], v[192:195], v[200:203], v[112:115]
	v_mfma_f32_16x16x32_bf16 v[100:103], v[184:187], v[208:211], v[100:103]
	v_mfma_f32_16x16x32_bf16 v[96:99], v[192:195], v[208:211], v[96:99]
	v_mfma_f32_16x16x32_bf16 v[84:87], v[184:187], v[216:219], v[84:87]
	v_mfma_f32_16x16x32_bf16 v[80:83], v[192:195], v[216:219], v[80:83]
	v_mfma_f32_16x16x32_bf16 v[68:71], v[184:187], v[224:227], v[68:71]
	v_mfma_f32_16x16x32_bf16 v[64:67], v[192:195], v[224:227], v[64:67]
	s_barrier
	s_add_i32 s58, s47, s3
	v_lshl_add_u64 v[160:161], s[30:31], 0, v[130:131]
	s_mov_b32 m0, s58
	ds_read_b128 v[196:199], v159 offset:16384
	ds_read_b128 v[200:203], v159 offset:17408
	ds_read_b128 v[204:207], v159 offset:18432
	ds_read_b128 v[208:211], v159 offset:19456
	ds_read_b128 v[212:215], v159 offset:20480
	ds_read_b128 v[216:219], v159 offset:21504
	ds_read_b128 v[220:223], v159 offset:22528
	ds_read_b128 v[224:227], v159 offset:23552
	global_load_lds_dwordx4 v[160:161], off
	s_add_i32 m0, s58, 0x2000
	s_add_u32 s58, s30, 0x40000
	v_lshl_add_u64 v[228:229], s[30:31], 0, v[134:135]
	s_addc_u32 s59, s31, 0
	s_add_i32 s60, s48, s3
	global_load_lds_dwordx4 v[228:229], off
	v_lshl_add_u64 v[230:231], s[58:59], 0, v[130:131]
	s_mov_b32 m0, s60
	v_lshl_add_u64 v[232:233], s[34:35], 0, v[132:133]
	global_load_lds_dwordx4 v[230:231], off
	v_lshl_add_u64 v[230:231], s[58:59], 0, v[134:135]
	s_add_i32 m0, s60, 0x2000
	s_nop 0
	global_load_lds_dwordx4 v[230:231], off
	v_lshl_add_u64 v[230:231], s[34:35], 0, v[128:129]
	s_mov_b32 m0, s27
	s_nop 0
	global_load_lds_dwordx4 v[230:231], off
	s_mov_b32 m0, s37
	s_nop 0
	global_load_lds_dwordx4 v[232:233], off
	s_waitcnt vmcnt(8)
	s_waitcnt lgkmcnt(0)
	s_barrier
	s_waitcnt lgkmcnt(0)
	v_mfma_f32_16x16x32_bf16 v[60:63], v[164:167], v[196:199], v[60:63]
	v_mfma_f32_16x16x32_bf16 v[56:59], v[172:175], v[196:199], v[56:59]
	v_mfma_f32_16x16x32_bf16 v[44:47], v[164:167], v[204:207], v[44:47]
	v_mfma_f32_16x16x32_bf16 v[40:43], v[172:175], v[204:207], v[40:43]
	v_mfma_f32_16x16x32_bf16 v[28:31], v[164:167], v[212:215], v[28:31]
	v_mfma_f32_16x16x32_bf16 v[24:27], v[172:175], v[212:215], v[24:27]
	v_mfma_f32_16x16x32_bf16 v[12:15], v[164:167], v[220:223], v[12:15]
	v_mfma_f32_16x16x32_bf16 v[8:11], v[172:175], v[220:223], v[8:11]
	v_mfma_f32_16x16x32_bf16 v[60:63], v[168:171], v[200:203], v[60:63]
	v_mfma_f32_16x16x32_bf16 v[56:59], v[176:179], v[200:203], v[56:59]
	v_mfma_f32_16x16x32_bf16 v[44:47], v[168:171], v[208:211], v[44:47]
	v_mfma_f32_16x16x32_bf16 v[40:43], v[176:179], v[208:211], v[40:43]
	v_mfma_f32_16x16x32_bf16 v[28:31], v[168:171], v[216:219], v[28:31]
	v_mfma_f32_16x16x32_bf16 v[24:27], v[176:179], v[216:219], v[24:27]
	v_mfma_f32_16x16x32_bf16 v[12:15], v[168:171], v[224:227], v[12:15]
	v_mfma_f32_16x16x32_bf16 v[8:11], v[176:179], v[224:227], v[8:11]
	v_mfma_f32_16x16x32_bf16 v[52:55], v[180:183], v[196:199], v[52:55]
	v_mfma_f32_16x16x32_bf16 v[48:51], v[188:191], v[196:199], v[48:51]
	v_mfma_f32_16x16x32_bf16 v[36:39], v[180:183], v[204:207], v[36:39]
	v_mfma_f32_16x16x32_bf16 v[32:35], v[188:191], v[204:207], v[32:35]
	v_mfma_f32_16x16x32_bf16 v[20:23], v[180:183], v[212:215], v[20:23]
	v_mfma_f32_16x16x32_bf16 v[16:19], v[188:191], v[212:215], v[16:19]
	v_mfma_f32_16x16x32_bf16 v[4:7], v[180:183], v[220:223], v[4:7]
	v_mfma_f32_16x16x32_bf16 v[0:3], v[188:191], v[220:223], v[0:3]
	v_mfma_f32_16x16x32_bf16 v[52:55], v[184:187], v[200:203], v[52:55]
	v_mfma_f32_16x16x32_bf16 v[48:51], v[192:195], v[200:203], v[48:51]
	v_mfma_f32_16x16x32_bf16 v[36:39], v[184:187], v[208:211], v[36:39]
	v_mfma_f32_16x16x32_bf16 v[32:35], v[192:195], v[208:211], v[32:35]
	v_mfma_f32_16x16x32_bf16 v[20:23], v[184:187], v[216:219], v[20:23]
	v_mfma_f32_16x16x32_bf16 v[16:19], v[192:195], v[216:219], v[16:19]
	v_mfma_f32_16x16x32_bf16 v[4:7], v[184:187], v[224:227], v[4:7]
	v_mfma_f32_16x16x32_bf16 v[0:3], v[192:195], v[224:227], v[0:3]
	s_barrier
; #define PG8_STAGE(bufoff, gbase, voff) do { _Pragma("unroll") for (int _i = 0; _i < 2; ++_i) \
;         __builtin_amdgcn_global_load_lds((const unsigned*)((const char*)(gbase) + (voff)[_i]), (PG8_LAS unsigned*)(lds + (bufoff) + ldsw + _i * 8192), 16, 0, 0); } while (0)
; #define PG8_LDA(dst, b, h) do { _Pragma("unroll") for (int m = 0; m < 4; ++m) _Pragma("unroll") for (int k = 0; k < 2; ++k) dst[m][k] = *(const PG8_LAS bf16x8*)(lds + PG8_SA(b, h) + aoff + m * 2048 + k * 1024); } while (0)
; #define PG8_LDB(dst, b, h) do { _Pragma("unroll") for (int n = 0; n < 2; ++n) _Pragma("unroll") for (int k = 0; k < 2; ++k) dst[n][k] = *(const PG8_LAS bf16x8*)(lds + PG8_SB(b, h) + boff + n * 2048 + k * 1024); } while (0)
; #define PG8_MMA(ai, bj, At, Bt) do { __builtin_amdgcn_s_setprio(1); _Pragma("unroll") for (int m = 0; m < 4; ++m) _Pragma("unroll") for (int n = 0; n < 2; ++n) _Pragma("unroll") for (int k = 0; k < 2; ++k) \
;         acc[ai][bj][m][n] = __builtin_amdgcn_mfma_f32_16x16x32_bf16(Bt[n][k], At[m][k], acc[ai][bj][m][n], 0, 0, 0); __builtin_amdgcn_s_setprio(0); } while (0)
; #define PG8_WAIT_V(n) asm volatile("s_waitcnt vmcnt(" #n ")" ::: "memory")
; #define PG8_WAIT_L(n) asm volatile("s_waitcnt lgkmcnt(" #n ")" ::: "memory")
; #define PG8_BAR __builtin_amdgcn_s_barrier()
; #define PG8_SCHED __builtin_amdgcn_sched_barrier(0)
; template <class Epi, class Sched, bool ALIGN_EPI = false, bool SP2 = false>
; __device__ __forceinline__ void gemm_phase(PG8_LAS unsigned char* lds, const Gemm g, const Sched& S, const Epi& E) {
;     ...
;         for (int t = 0; t < nt; t += 2) {
;     ...
;             PG8_LDB(B0, 1, 0); PG8_LDB(B1, 1, 1); PG8_SCHED; PG8_LDA(At, 1, 0); PG8_STAGE(PG8_SA(0, 1), a2 + hstep, voffA);
;             PG8_WAIT_V(8); PG8_WAIT_L(0); PG8_BAR; PG8_MMA(0, 0, At, B0); PG8_MMA(0, 1, At, B1); PG8_BAR; PG8_SCHED;
;             PG8_LDA(At, 1, 1); PG8_STAGE(PG8_SB(1, 0), b3, voffB); PG8_STAGE(PG8_SB(1, 1), b3 + hstep, voffB); PG8_STAGE(PG8_SA(1, 0), a3, voffA);
;             PG8_WAIT_V(8); PG8_WAIT_L(0); PG8_BAR; PG8_MMA(1, 0, At, B0); PG8_MMA(1, 1, At, B1); PG8_BAR; PG8_SCHED;
	s_add_i32 s58, 0, 0x18000
	s_add_i32 s59, 0, 0x1c000
	v_add_u32_e32 v176, s58, v155
	v_add_u32_e32 v192, s59, v155
	ds_read_b128 v[164:167], v176
	ds_read_b128 v[168:171], v176 offset:1024
	ds_read_b128 v[172:175], v176 offset:2048
	ds_read_b128 v[176:179], v176 offset:3072
	ds_read_b128 v[180:183], v192
	ds_read_b128 v[184:187], v192 offset:1024
	ds_read_b128 v[188:191], v192 offset:2048
	ds_read_b128 v[192:195], v192 offset:3072
	s_add_u32 s34, s34, 0x40000
	s_addc_u32 s35, s35, 0
	s_mov_b32 m0, s38
	v_lshl_add_u64 v[234:235], s[34:35], 0, v[128:129]
	ds_read_b128 v[196:199], v159 offset:32768
	ds_read_b128 v[200:203], v159 offset:33792
	ds_read_b128 v[204:207], v159 offset:34816
	ds_read_b128 v[208:211], v159 offset:35840
	ds_read_b128 v[212:215], v159 offset:36864
	ds_read_b128 v[216:219], v159 offset:37888
	ds_read_b128 v[220:223], v159 offset:38912
	ds_read_b128 v[224:227], v159 offset:39936
	global_load_lds_dwordx4 v[234:235], off
	v_lshl_add_u64 v[234:235], s[34:35], 0, v[132:133]
	s_mov_b32 m0, s39
	s_nop 0
	global_load_lds_dwordx4 v[234:235], off
	s_waitcnt vmcnt(8)
	s_waitcnt lgkmcnt(0)
	s_barrier
	s_waitcnt lgkmcnt(0)
	v_mfma_f32_16x16x32_bf16 v[124:127], v[164:167], v[196:199], v[124:127]
	v_mfma_f32_16x16x32_bf16 v[120:123], v[172:175], v[196:199], v[120:123]
	v_mfma_f32_16x16x32_bf16 v[108:111], v[164:167], v[204:207], v[108:111]
	v_mfma_f32_16x16x32_bf16 v[104:107], v[172:175], v[204:207], v[104:107]
	v_mfma_f32_16x16x32_bf16 v[92:95], v[164:167], v[212:215], v[92:95]
	v_mfma_f32_16x16x32_bf16 v[88:91], v[172:175], v[212:215], v[88:91]
	v_mfma_f32_16x16x32_bf16 v[76:79], v[164:167], v[220:223], v[76:79]
	v_mfma_f32_16x16x32_bf16 v[72:75], v[172:175], v[220:223], v[72:75]
	v_mfma_f32_16x16x32_bf16 v[124:127], v[168:171], v[200:203], v[124:127]
	v_mfma_f32_16x16x32_bf16 v[120:123], v[176:179], v[200:203], v[120:123]
	v_mfma_f32_16x16x32_bf16 v[108:111], v[168:171], v[208:211], v[108:111]
	v_mfma_f32_16x16x32_bf16 v[104:107], v[176:179], v[208:211], v[104:107]
	v_mfma_f32_16x16x32_bf16 v[92:95], v[168:171], v[216:219], v[92:95]
	v_mfma_f32_16x16x32_bf16 v[88:91], v[176:179], v[216:219], v[88:91]
	v_mfma_f32_16x16x32_bf16 v[76:79], v[168:171], v[224:227], v[76:79]
	v_mfma_f32_16x16x32_bf16 v[72:75], v[176:179], v[224:227], v[72:75]
	v_mfma_f32_16x16x32_bf16 v[116:119], v[180:183], v[196:199], v[116:119]
	v_mfma_f32_16x16x32_bf16 v[112:115], v[188:191], v[196:199], v[112:115]
	v_mfma_f32_16x16x32_bf16 v[100:103], v[180:183], v[204:207], v[100:103]
	v_mfma_f32_16x16x32_bf16 v[96:99], v[188:191], v[204:207], v[96:99]
	v_mfma_f32_16x16x32_bf16 v[84:87], v[180:183], v[212:215], v[84:87]
	v_mfma_f32_16x16x32_bf16 v[80:83], v[188:191], v[212:215], v[80:83]
	v_mfma_f32_16x16x32_bf16 v[68:71], v[180:183], v[220:223], v[68:71]
	v_mfma_f32_16x16x32_bf16 v[64:67], v[188:191], v[220:223], v[64:67]
	v_mfma_f32_16x16x32_bf16 v[116:119], v[184:187], v[200:203], v[116:119]
	v_mfma_f32_16x16x32_bf16 v[112:115], v[192:195], v[200:203], v[112:115]
	v_mfma_f32_16x16x32_bf16 v[100:103], v[184:187], v[208:211], v[100:103]
	v_mfma_f32_16x16x32_bf16 v[96:99], v[192:195], v[208:211], v[96:99]
	v_mfma_f32_16x16x32_bf16 v[84:87], v[184:187], v[216:219], v[84:87]
	v_mfma_f32_16x16x32_bf16 v[80:83], v[192:195], v[216:219], v[80:83]
	v_mfma_f32_16x16x32_bf16 v[68:71], v[184:187], v[224:227], v[68:71]
	v_mfma_f32_16x16x32_bf16 v[64:67], v[192:195], v[224:227], v[64:67]
	s_barrier
	s_add_i32 s34, s58, s3
	v_lshl_add_u64 v[160:161], v[160:161], 0, s[8:9]
	s_mov_b32 m0, s34
	ds_read_b128 v[196:199], v159 offset:49152
	ds_read_b128 v[200:203], v159 offset:50176
	ds_read_b128 v[204:207], v159 offset:51200
	ds_read_b128 v[208:211], v159 offset:52224
	ds_read_b128 v[212:215], v159 offset:53248
	ds_read_b128 v[216:219], v159 offset:54272
	ds_read_b128 v[220:223], v159 offset:55296
	ds_read_b128 v[224:227], v159 offset:56320
	global_load_lds_dwordx4 v[160:161], off
	s_add_i32 m0, s34, 0x2000
	s_add_u32 s30, s30, 0x40080
	v_lshl_add_u64 v[160:161], v[228:229], 0, s[8:9]
	s_addc_u32 s31, s31, 0
	s_add_i32 s34, s59, s3
	global_load_lds_dwordx4 v[160:161], off
	v_lshl_add_u64 v[160:161], s[30:31], 0, v[130:131]
	s_mov_b32 m0, s34
	s_nop 0
	global_load_lds_dwordx4 v[160:161], off
	v_lshl_add_u64 v[160:161], s[30:31], 0, v[134:135]
	s_add_i32 m0, s34, 0x2000
	s_nop 0
	global_load_lds_dwordx4 v[160:161], off
	v_lshl_add_u64 v[160:161], v[230:231], 0, s[8:9]
	s_mov_b32 m0, s43
	s_nop 0
	global_load_lds_dwordx4 v[160:161], off
	v_lshl_add_u64 v[160:161], v[232:233], 0, s[8:9]
	s_mov_b32 m0, s46
	s_nop 0
	global_load_lds_dwordx4 v[160:161], off
	s_waitcnt vmcnt(8)
	s_waitcnt lgkmcnt(0)
	s_barrier
	s_waitcnt lgkmcnt(0)
	v_mfma_f32_16x16x32_bf16 v[60:63], v[164:167], v[196:199], v[60:63]
	v_mfma_f32_16x16x32_bf16 v[56:59], v[172:175], v[196:199], v[56:59]
	v_mfma_f32_16x16x32_bf16 v[44:47], v[164:167], v[204:207], v[44:47]
	v_mfma_f32_16x16x32_bf16 v[40:43], v[172:175], v[204:207], v[40:43]
	v_mfma_f32_16x16x32_bf16 v[28:31], v[164:167], v[212:215], v[28:31]
	v_mfma_f32_16x16x32_bf16 v[24:27], v[172:175], v[212:215], v[24:27]
	v_mfma_f32_16x16x32_bf16 v[12:15], v[164:167], v[220:223], v[12:15]
	v_mfma_f32_16x16x32_bf16 v[8:11], v[172:175], v[220:223], v[8:11]
	v_mfma_f32_16x16x32_bf16 v[60:63], v[168:171], v[200:203], v[60:63]
	v_mfma_f32_16x16x32_bf16 v[56:59], v[176:179], v[200:203], v[56:59]
	v_mfma_f32_16x16x32_bf16 v[44:47], v[168:171], v[208:211], v[44:47]
	v_mfma_f32_16x16x32_bf16 v[40:43], v[176:179], v[208:211], v[40:43]
	v_mfma_f32_16x16x32_bf16 v[28:31], v[168:171], v[216:219], v[28:31]
	v_mfma_f32_16x16x32_bf16 v[24:27], v[176:179], v[216:219], v[24:27]
	v_mfma_f32_16x16x32_bf16 v[12:15], v[168:171], v[224:227], v[12:15]
	v_mfma_f32_16x16x32_bf16 v[8:11], v[176:179], v[224:227], v[8:11]
	v_mfma_f32_16x16x32_bf16 v[52:55], v[180:183], v[196:199], v[52:55]
	v_mfma_f32_16x16x32_bf16 v[48:51], v[188:191], v[196:199], v[48:51]
	v_mfma_f32_16x16x32_bf16 v[36:39], v[180:183], v[204:207], v[36:39]
	v_mfma_f32_16x16x32_bf16 v[32:35], v[188:191], v[204:207], v[32:35]
	v_mfma_f32_16x16x32_bf16 v[20:23], v[180:183], v[212:215], v[20:23]
	v_mfma_f32_16x16x32_bf16 v[16:19], v[188:191], v[212:215], v[16:19]
	v_mfma_f32_16x16x32_bf16 v[4:7], v[180:183], v[220:223], v[4:7]
	v_mfma_f32_16x16x32_bf16 v[0:3], v[188:191], v[220:223], v[0:3]
	v_mfma_f32_16x16x32_bf16 v[52:55], v[184:187], v[200:203], v[52:55]
	v_mfma_f32_16x16x32_bf16 v[48:51], v[192:195], v[200:203], v[48:51]
	v_mfma_f32_16x16x32_bf16 v[36:39], v[184:187], v[208:211], v[36:39]
	v_mfma_f32_16x16x32_bf16 v[32:35], v[192:195], v[208:211], v[32:35]
	v_mfma_f32_16x16x32_bf16 v[20:23], v[184:187], v[216:219], v[20:23]
	v_mfma_f32_16x16x32_bf16 v[16:19], v[192:195], v[216:219], v[16:19]
	v_mfma_f32_16x16x32_bf16 v[4:7], v[184:187], v[224:227], v[4:7]
	v_mfma_f32_16x16x32_bf16 v[0:3], v[192:195], v[224:227], v[0:3]
	s_barrier
	s_add_i32 s55, s55, 2
	s_add_u32 s28, s28, 0x100
	s_addc_u32 s29, s29, 0
	s_add_u32 s53, s53, 0x100
	s_addc_u32 s54, s54, 0
	s_cmp_gt_u32 s55, 13
	s_cbranch_scc0 .LBB0_975
; #define PG8_BAR __builtin_amdgcn_s_barrier()
; template <class Epi, class Sched, bool ALIGN_EPI = false, bool SP2 = false>
; __device__ __forceinline__ void gemm_phase(PG8_LAS unsigned char* lds, const Gemm g, const Sched& S, const Epi& E) {
;     ...
;         if constexpr (ALIGN_EPI) { if (wr == 0) PG8_BAR; }
.Lpeel_exit4:
	s_and_b64 vcc, exec, s[10:11]
	s_cbranch_vccz .LBB0_978
	s_barrier

; #define PG8_STAGE(bufoff, gbase, voff) do { _Pragma("unroll") for (int _i = 0; _i < 2; ++_i) \
;         __builtin_amdgcn_global_load_lds((const unsigned*)((const char*)(gbase) + (voff)[_i]), (PG8_LAS unsigned*)(lds + (bufoff) + ldsw + _i * 8192), 16, 0, 0); } while (0)
; #define PG8_LDA(dst, b, h) do { _Pragma("unroll") for (int m = 0; m < 4; ++m) _Pragma("unroll") for (int k = 0; k < 2; ++k) dst[m][k] = *(const PG8_LAS bf16x8*)(lds + PG8_SA(b, h) + aoff + m * 2048 + k * 1024); } while (0)
; #define PG8_LDB(dst, b, h) do { _Pragma("unroll") for (int n = 0; n < 2; ++n) _Pragma("unroll") for (int k = 0; k < 2; ++k) dst[n][k] = *(const PG8_LAS bf16x8*)(lds + PG8_SB(b, h) + boff + n * 2048 + k * 1024); } while (0)
; #define PG8_MMA(ai, bj, At, Bt) do { __builtin_amdgcn_s_setprio(1); _Pragma("unroll") for (int m = 0; m < 4; ++m) _Pragma("unroll") for (int n = 0; n < 2; ++n) _Pragma("unroll") for (int k = 0; k < 2; ++k) \
;         acc[ai][bj][m][n] = __builtin_amdgcn_mfma_f32_16x16x32_bf16(Bt[n][k], At[m][k], acc[ai][bj][m][n], 0, 0, 0); __builtin_amdgcn_s_setprio(0); } while (0)
; #define PG8_WAIT_V(n) asm volatile("s_waitcnt vmcnt(" #n ")" ::: "memory")
; #define PG8_WAIT_L(n) asm volatile("s_waitcnt lgkmcnt(" #n ")" ::: "memory")
; #define PG8_BAR __builtin_amdgcn_s_barrier()
; #define PG8_SCHED __builtin_amdgcn_sched_barrier(0)
; template <class Epi, class Sched, bool ALIGN_EPI = false, bool SP2 = false>
; __device__ __forceinline__ void gemm_phase(PG8_LAS unsigned char* lds, const Gemm g, const Sched& S, const Epi& E) {
;     ...
;             PG8_LDB(B0, 0, 0); PG8_LDB(B1, 0, 1); PG8_SCHED; PG8_LDA(At, 0, 0); PG8_STAGE(PG8_SA(1, 1), a1 + hstep, voffA);
;             PG8_WAIT_V(8); PG8_WAIT_L(0); PG8_BAR; PG8_MMA(0, 0, At, B0); PG8_MMA(0, 1, At, B1); PG8_BAR; PG8_SCHED;
;             PG8_LDA(At, 0, 1); PG8_STAGE(PG8_SB(0, 0), b2, voffB); PG8_STAGE(PG8_SB(0, 1), b2 + hstep, voffB); PG8_STAGE(PG8_SA(0, 0), a2, voffA);
;             PG8_WAIT_V(8); PG8_WAIT_L(0); PG8_BAR; PG8_MMA(1, 0, At, B0); PG8_MMA(1, 1, At, B1); PG8_BAR; PG8_SCHED;
.LBB0_1004:
	s_add_u32 s39, s28, s38
	s_addc_u32 s48, s29, 0
	s_add_u32 s46, s39, 0x100
	s_addc_u32 s47, s48, 0
	s_and_b64 s[40:41], s[36:37], exec
	s_cselect_b32 s41, s21, s47
	s_cselect_b32 s40, s65, s46
	s_add_u32 s38, s24, s38
	s_addc_u32 s46, s25, 0
	s_add_u32 s38, s38, 0x100
	s_addc_u32 s46, s46, 0
	s_and_b64 s[36:37], s[36:37], exec
	s_cselect_b32 s47, s19, s46
	s_cselect_b32 s46, s66, s38
	s_add_u32 s50, s39, 0x10080
	ds_read_b128 v[146:149], v143
	ds_read_b128 v[150:153], v143 offset:1024
	ds_read_b128 v[156:159], v143 offset:2048
	ds_read_b128 v[164:167], v143 offset:3072
	ds_read_b128 v[168:171], v144
	ds_read_b128 v[172:175], v144 offset:1024
	ds_read_b128 v[176:179], v144 offset:2048
	ds_read_b128 v[180:183], v144 offset:3072
	s_addc_u32 s51, s48, 0
	s_add_i32 s80, s62, s33
	s_add_i32 m0, s23, 0xc000
	s_add_i32 s81, s23, 0xe000
	s_add_i32 s77, s80, 0x2000
	s_add_u32 s48, s46, 0x10000
	s_addc_u32 s49, s47, 0
	s_add_i32 s79, s63, s33
	s_add_i32 s78, s79, 0x2000
	s_add_i32 s76, 0, 0x18000
	s_add_i32 s75, 0, 0x1c000
	s_add_u32 s38, s40, 0x10000
	s_addc_u32 s39, s41, 0
	s_add_i32 s74, s76, s33
	s_add_i32 s70, s74, 0x2000
	s_add_u32 s36, s46, 0x10080
	s_addc_u32 s37, s47, 0
	s_add_i32 s71, s75, s33
	s_add_i32 s67, s71, 0x2000
	v_lshl_add_u64 v[160:161], s[50:51], 0, v[128:129]
	ds_read_b128 v[184:187], v145
	ds_read_b128 v[188:191], v145 offset:1024
	ds_read_b128 v[192:195], v145 offset:2048
	ds_read_b128 v[196:199], v145 offset:3072
	ds_read_b128 v[200:203], v145 offset:4096
	ds_read_b128 v[204:207], v145 offset:5120
	ds_read_b128 v[208:211], v145 offset:6144
	ds_read_b128 v[212:215], v145 offset:7168
	global_load_lds_dwordx4 v[160:161], off
	v_lshl_add_u64 v[160:161], s[50:51], 0, v[132:133]
	s_mov_b32 m0, s81
	s_nop 0
	global_load_lds_dwordx4 v[160:161], off
	s_waitcnt vmcnt(8)
	s_waitcnt lgkmcnt(0)
	s_barrier
	s_waitcnt lgkmcnt(0)
	v_mfma_f32_16x16x32_bf16 v[124:127], v[146:149], v[184:187], v[124:127]
	v_mfma_f32_16x16x32_bf16 v[120:123], v[156:159], v[184:187], v[120:123]
	v_mfma_f32_16x16x32_bf16 v[116:119], v[146:149], v[192:195], v[116:119]
	v_mfma_f32_16x16x32_bf16 v[112:115], v[156:159], v[192:195], v[112:115]
	v_mfma_f32_16x16x32_bf16 v[100:103], v[146:149], v[200:203], v[100:103]
	v_mfma_f32_16x16x32_bf16 v[96:99], v[156:159], v[200:203], v[96:99]
	v_mfma_f32_16x16x32_bf16 v[84:87], v[146:149], v[208:211], v[84:87]
	v_mfma_f32_16x16x32_bf16 v[80:83], v[156:159], v[208:211], v[80:83]
	v_mfma_f32_16x16x32_bf16 v[124:127], v[150:153], v[188:191], v[124:127]
	v_mfma_f32_16x16x32_bf16 v[120:123], v[164:167], v[188:191], v[120:123]
	v_mfma_f32_16x16x32_bf16 v[116:119], v[150:153], v[196:199], v[116:119]
	v_mfma_f32_16x16x32_bf16 v[112:115], v[164:167], v[196:199], v[112:115]
	v_mfma_f32_16x16x32_bf16 v[100:103], v[150:153], v[204:207], v[100:103]
	v_mfma_f32_16x16x32_bf16 v[96:99], v[164:167], v[204:207], v[96:99]
	v_mfma_f32_16x16x32_bf16 v[84:87], v[150:153], v[212:215], v[84:87]
	v_mfma_f32_16x16x32_bf16 v[80:83], v[164:167], v[212:215], v[80:83]
	v_mfma_f32_16x16x32_bf16 v[108:111], v[168:171], v[184:187], v[108:111]
	v_mfma_f32_16x16x32_bf16 v[104:107], v[176:179], v[184:187], v[104:107]
	v_mfma_f32_16x16x32_bf16 v[92:95], v[168:171], v[192:195], v[92:95]
	v_mfma_f32_16x16x32_bf16 v[88:91], v[176:179], v[192:195], v[88:91]
	v_mfma_f32_16x16x32_bf16 v[76:79], v[168:171], v[200:203], v[76:79]
	v_mfma_f32_16x16x32_bf16 v[72:75], v[176:179], v[200:203], v[72:75]
	v_mfma_f32_16x16x32_bf16 v[68:71], v[168:171], v[208:211], v[68:71]
	v_mfma_f32_16x16x32_bf16 v[64:67], v[176:179], v[208:211], v[64:67]
	v_mfma_f32_16x16x32_bf16 v[108:111], v[172:175], v[188:191], v[108:111]
	v_mfma_f32_16x16x32_bf16 v[104:107], v[180:183], v[188:191], v[104:107]
	v_mfma_f32_16x16x32_bf16 v[92:95], v[172:175], v[196:199], v[92:95]
	v_mfma_f32_16x16x32_bf16 v[88:91], v[180:183], v[196:199], v[88:91]
	v_mfma_f32_16x16x32_bf16 v[76:79], v[172:175], v[204:207], v[76:79]
	v_mfma_f32_16x16x32_bf16 v[72:75], v[180:183], v[204:207], v[72:75]
	v_mfma_f32_16x16x32_bf16 v[68:71], v[172:175], v[212:215], v[68:71]
	v_mfma_f32_16x16x32_bf16 v[64:67], v[180:183], v[212:215], v[64:67]
	s_barrier
	s_mov_b32 m0, s80
	v_lshl_add_u64 v[160:161], s[46:47], 0, v[130:131]
	ds_read_b128 v[184:187], v145 offset:16384
	ds_read_b128 v[188:191], v145 offset:17408
	ds_read_b128 v[192:195], v145 offset:18432
	ds_read_b128 v[196:199], v145 offset:19456
	ds_read_b128 v[200:203], v145 offset:20480
	ds_read_b128 v[204:207], v145 offset:21504
	ds_read_b128 v[208:211], v145 offset:22528
	ds_read_b128 v[212:215], v145 offset:23552
	global_load_lds_dwordx4 v[160:161], off
	v_lshl_add_u64 v[216:217], s[46:47], 0, v[134:135]
	s_mov_b32 m0, s77
	v_lshl_add_u64 v[218:219], s[48:49], 0, v[130:131]
	global_load_lds_dwordx4 v[216:217], off
	s_mov_b32 m0, s79
	v_lshl_add_u64 v[220:221], s[40:41], 0, v[132:133]
	global_load_lds_dwordx4 v[218:219], off
	v_lshl_add_u64 v[218:219], s[48:49], 0, v[134:135]
	s_mov_b32 m0, s78
	s_nop 0
	global_load_lds_dwordx4 v[218:219], off
	v_lshl_add_u64 v[218:219], s[40:41], 0, v[128:129]
	s_mov_b32 m0, s23
	s_nop 0
	global_load_lds_dwordx4 v[218:219], off
	s_mov_b32 m0, s52
	s_nop 0
	global_load_lds_dwordx4 v[220:221], off
	s_waitcnt vmcnt(8)
	s_waitcnt lgkmcnt(0)
	s_barrier
; #define PG8_STAGE(bufoff, gbase, voff) do { _Pragma("unroll") for (int _i = 0; _i < 2; ++_i) \
;         __builtin_amdgcn_global_load_lds((const unsigned*)((const char*)(gbase) + (voff)[_i]), (PG8_LAS unsigned*)(lds + (bufoff) + ldsw + _i * 8192), 16, 0, 0); } while (0)
; #define PG8_LDA(dst, b, h) do { _Pragma("unroll") for (int m = 0; m < 4; ++m) _Pragma("unroll") for (int k = 0; k < 2; ++k) dst[m][k] = *(const PG8_LAS bf16x8*)(lds + PG8_SA(b, h) + aoff + m * 2048 + k * 1024); } while (0)
; #define PG8_LDB(dst, b, h) do { _Pragma("unroll") for (int n = 0; n < 2; ++n) _Pragma("unroll") for (int k = 0; k < 2; ++k) dst[n][k] = *(const PG8_LAS bf16x8*)(lds + PG8_SB(b, h) + boff + n * 2048 + k * 1024); } while (0)
; #define PG8_MMA(ai, bj, At, Bt) do { __builtin_amdgcn_s_setprio(1); _Pragma("unroll") for (int m = 0; m < 4; ++m) _Pragma("unroll") for (int n = 0; n < 2; ++n) _Pragma("unroll") for (int k = 0; k < 2; ++k) \
;         acc[ai][bj][m][n] = __builtin_amdgcn_mfma_f32_16x16x32_bf16(Bt[n][k], At[m][k], acc[ai][bj][m][n], 0, 0, 0); __builtin_amdgcn_s_setprio(0); } while (0)
; #define PG8_WAIT_V(n) asm volatile("s_waitcnt vmcnt(" #n ")" ::: "memory")
; #define PG8_WAIT_L(n) asm volatile("s_waitcnt lgkmcnt(" #n ")" ::: "memory")
; #define PG8_BAR __builtin_amdgcn_s_barrier()
; #define PG8_SCHED __builtin_amdgcn_sched_barrier(0)
; template <class Epi, class Sched, bool ALIGN_EPI = false, bool SP2 = false>
; __device__ __forceinline__ void gemm_phase(PG8_LAS unsigned char* lds, const Gemm g, const Sched& S, const Epi& E) {
;     ...
;             PG8_WAIT_V(8); PG8_WAIT_L(0); PG8_BAR; PG8_MMA(1, 0, At, B0); PG8_MMA(1, 1, At, B1); PG8_BAR; PG8_SCHED;
;             PG8_LDB(B0, 1, 0); PG8_LDB(B1, 1, 1); PG8_SCHED; PG8_LDA(At, 1, 0); PG8_STAGE(PG8_SA(0, 1), a2 + hstep, voffA);
;             PG8_WAIT_V(8); PG8_WAIT_L(0); PG8_BAR; PG8_MMA(0, 0, At, B0); PG8_MMA(0, 1, At, B1); PG8_BAR; PG8_SCHED;
	s_waitcnt lgkmcnt(0)
	v_mfma_f32_16x16x32_bf16 v[60:63], v[146:149], v[184:187], v[60:63]
	v_mfma_f32_16x16x32_bf16 v[56:59], v[156:159], v[184:187], v[56:59]
	v_mfma_f32_16x16x32_bf16 v[52:55], v[146:149], v[192:195], v[52:55]
	v_mfma_f32_16x16x32_bf16 v[48:51], v[156:159], v[192:195], v[48:51]
	v_mfma_f32_16x16x32_bf16 v[36:39], v[146:149], v[200:203], v[36:39]
	v_mfma_f32_16x16x32_bf16 v[32:35], v[156:159], v[200:203], v[32:35]
	v_mfma_f32_16x16x32_bf16 v[20:23], v[146:149], v[208:211], v[20:23]
	v_mfma_f32_16x16x32_bf16 v[16:19], v[156:159], v[208:211], v[16:19]
	v_mfma_f32_16x16x32_bf16 v[60:63], v[150:153], v[188:191], v[60:63]
	v_mfma_f32_16x16x32_bf16 v[56:59], v[164:167], v[188:191], v[56:59]
	v_mfma_f32_16x16x32_bf16 v[52:55], v[150:153], v[196:199], v[52:55]
	v_mfma_f32_16x16x32_bf16 v[48:51], v[164:167], v[196:199], v[48:51]
	v_mfma_f32_16x16x32_bf16 v[36:39], v[150:153], v[204:207], v[36:39]
	v_mfma_f32_16x16x32_bf16 v[32:35], v[164:167], v[204:207], v[32:35]
	v_mfma_f32_16x16x32_bf16 v[20:23], v[150:153], v[212:215], v[20:23]
	v_mfma_f32_16x16x32_bf16 v[16:19], v[164:167], v[212:215], v[16:19]
	v_mfma_f32_16x16x32_bf16 v[44:47], v[168:171], v[184:187], v[44:47]
	v_mfma_f32_16x16x32_bf16 v[40:43], v[176:179], v[184:187], v[40:43]
	v_mfma_f32_16x16x32_bf16 v[28:31], v[168:171], v[192:195], v[28:31]
	v_mfma_f32_16x16x32_bf16 v[24:27], v[176:179], v[192:195], v[24:27]
	v_mfma_f32_16x16x32_bf16 v[12:15], v[168:171], v[200:203], v[12:15]
	v_mfma_f32_16x16x32_bf16 v[8:11], v[176:179], v[200:203], v[8:11]
	v_mfma_f32_16x16x32_bf16 v[4:7], v[168:171], v[208:211], v[4:7]
	v_mfma_f32_16x16x32_bf16 v[0:3], v[176:179], v[208:211], v[0:3]
	v_mfma_f32_16x16x32_bf16 v[44:47], v[172:175], v[188:191], v[44:47]
	v_mfma_f32_16x16x32_bf16 v[40:43], v[180:183], v[188:191], v[40:43]
	v_mfma_f32_16x16x32_bf16 v[28:31], v[172:175], v[196:199], v[28:31]
	v_mfma_f32_16x16x32_bf16 v[24:27], v[180:183], v[196:199], v[24:27]
	v_mfma_f32_16x16x32_bf16 v[12:15], v[172:175], v[204:207], v[12:15]
	v_mfma_f32_16x16x32_bf16 v[8:11], v[180:183], v[204:207], v[8:11]
	v_mfma_f32_16x16x32_bf16 v[4:7], v[172:175], v[212:215], v[4:7]
	v_mfma_f32_16x16x32_bf16 v[0:3], v[180:183], v[212:215], v[0:3]
	s_barrier
	v_add_u32_e32 v155, s76, v141
	ds_read_b128 v[146:149], v155
	ds_read_b128 v[150:153], v155 offset:1024
	ds_read_b128 v[156:159], v155 offset:2048
	ds_read_b128 v[164:167], v155 offset:3072
	v_add_u32_e32 v155, s75, v141
	ds_read_b128 v[168:171], v155
	ds_read_b128 v[172:175], v155 offset:1024
	ds_read_b128 v[176:179], v155 offset:2048
	ds_read_b128 v[180:183], v155 offset:3072
	s_mov_b32 m0, s53
	v_lshl_add_u64 v[222:223], s[38:39], 0, v[128:129]
	ds_read_b128 v[184:187], v145 offset:32768
	ds_read_b128 v[188:191], v145 offset:33792
	ds_read_b128 v[192:195], v145 offset:34816
	ds_read_b128 v[196:199], v145 offset:35840
	ds_read_b128 v[200:203], v145 offset:36864
	ds_read_b128 v[204:207], v145 offset:37888
	ds_read_b128 v[208:211], v145 offset:38912
	ds_read_b128 v[212:215], v145 offset:39936
	global_load_lds_dwordx4 v[222:223], off
	v_lshl_add_u64 v[222:223], s[38:39], 0, v[132:133]
	s_mov_b32 m0, s54
	s_nop 0
	global_load_lds_dwordx4 v[222:223], off
	s_waitcnt vmcnt(8)
	s_waitcnt lgkmcnt(0)
	s_barrier
	s_waitcnt lgkmcnt(0)
	v_mfma_f32_16x16x32_bf16 v[124:127], v[146:149], v[184:187], v[124:127]
	v_mfma_f32_16x16x32_bf16 v[120:123], v[156:159], v[184:187], v[120:123]
	v_mfma_f32_16x16x32_bf16 v[116:119], v[146:149], v[192:195], v[116:119]
	v_mfma_f32_16x16x32_bf16 v[112:115], v[156:159], v[192:195], v[112:115]
	v_mfma_f32_16x16x32_bf16 v[100:103], v[146:149], v[200:203], v[100:103]
	v_mfma_f32_16x16x32_bf16 v[96:99], v[156:159], v[200:203], v[96:99]
	v_mfma_f32_16x16x32_bf16 v[84:87], v[146:149], v[208:211], v[84:87]
	v_mfma_f32_16x16x32_bf16 v[80:83], v[156:159], v[208:211], v[80:83]
	v_mfma_f32_16x16x32_bf16 v[124:127], v[150:153], v[188:191], v[124:127]
	v_mfma_f32_16x16x32_bf16 v[120:123], v[164:167], v[188:191], v[120:123]
	v_mfma_f32_16x16x32_bf16 v[116:119], v[150:153], v[196:199], v[116:119]
	v_mfma_f32_16x16x32_bf16 v[112:115], v[164:167], v[196:199], v[112:115]
	v_mfma_f32_16x16x32_bf16 v[100:103], v[150:153], v[204:207], v[100:103]
	v_mfma_f32_16x16x32_bf16 v[96:99], v[164:167], v[204:207], v[96:99]
	v_mfma_f32_16x16x32_bf16 v[84:87], v[150:153], v[212:215], v[84:87]
	v_mfma_f32_16x16x32_bf16 v[80:83], v[164:167], v[212:215], v[80:83]
	v_mfma_f32_16x16x32_bf16 v[108:111], v[168:171], v[184:187], v[108:111]
	v_mfma_f32_16x16x32_bf16 v[104:107], v[176:179], v[184:187], v[104:107]
	v_mfma_f32_16x16x32_bf16 v[92:95], v[168:171], v[192:195], v[92:95]
	v_mfma_f32_16x16x32_bf16 v[88:91], v[176:179], v[192:195], v[88:91]
	v_mfma_f32_16x16x32_bf16 v[76:79], v[168:171], v[200:203], v[76:79]
	v_mfma_f32_16x16x32_bf16 v[72:75], v[176:179], v[200:203], v[72:75]
	v_mfma_f32_16x16x32_bf16 v[68:71], v[168:171], v[208:211], v[68:71]
	v_mfma_f32_16x16x32_bf16 v[64:67], v[176:179], v[208:211], v[64:67]
	v_mfma_f32_16x16x32_bf16 v[108:111], v[172:175], v[188:191], v[108:111]
	v_mfma_f32_16x16x32_bf16 v[104:107], v[180:183], v[188:191], v[104:107]
	v_mfma_f32_16x16x32_bf16 v[92:95], v[172:175], v[196:199], v[92:95]
	v_mfma_f32_16x16x32_bf16 v[88:91], v[180:183], v[196:199], v[88:91]
	v_mfma_f32_16x16x32_bf16 v[76:79], v[172:175], v[204:207], v[76:79]
	v_mfma_f32_16x16x32_bf16 v[72:75], v[180:183], v[204:207], v[72:75]
	v_mfma_f32_16x16x32_bf16 v[68:71], v[172:175], v[212:215], v[68:71]
	v_mfma_f32_16x16x32_bf16 v[64:67], v[180:183], v[212:215], v[64:67]
	s_barrier
; #define PG8_STAGE(bufoff, gbase, voff) do { _Pragma("unroll") for (int _i = 0; _i < 2; ++_i) \
;         __builtin_amdgcn_global_load_lds((const unsigned*)((const char*)(gbase) + (voff)[_i]), (PG8_LAS unsigned*)(lds + (bufoff) + ldsw + _i * 8192), 16, 0, 0); } while (0)
; #define PG8_LDA(dst, b, h) do { _Pragma("unroll") for (int m = 0; m < 4; ++m) _Pragma("unroll") for (int k = 0; k < 2; ++k) dst[m][k] = *(const PG8_LAS bf16x8*)(lds + PG8_SA(b, h) + aoff + m * 2048 + k * 1024); } while (0)
; #define PG8_MMA(ai, bj, At, Bt) do { __builtin_amdgcn_s_setprio(1); _Pragma("unroll") for (int m = 0; m < 4; ++m) _Pragma("unroll") for (int n = 0; n < 2; ++n) _Pragma("unroll") for (int k = 0; k < 2; ++k) \
;         acc[ai][bj][m][n] = __builtin_amdgcn_mfma_f32_16x16x32_bf16(Bt[n][k], At[m][k], acc[ai][bj][m][n], 0, 0, 0); __builtin_amdgcn_s_setprio(0); } while (0)
; #define PG8_WAIT_V(n) asm volatile("s_waitcnt vmcnt(" #n ")" ::: "memory")
; #define PG8_WAIT_L(n) asm volatile("s_waitcnt lgkmcnt(" #n ")" ::: "memory")
; #define PG8_BAR __builtin_amdgcn_s_barrier()
; #define PG8_SCHED __builtin_amdgcn_sched_barrier(0)
; template <class Epi, class Sched, bool ALIGN_EPI = false, bool SP2 = false>
; __device__ __forceinline__ void gemm_phase(PG8_LAS unsigned char* lds, const Gemm g, const Sched& S, const Epi& E) {
;     ...
;             PG8_WAIT_V(8); PG8_WAIT_L(0); PG8_BAR; PG8_MMA(0, 0, At, B0); PG8_MMA(0, 1, At, B1); PG8_BAR; PG8_SCHED;
;             PG8_LDA(At, 1, 1); PG8_STAGE(PG8_SB(1, 0), b3, voffB); PG8_STAGE(PG8_SB(1, 1), b3 + hstep, voffB); PG8_STAGE(PG8_SA(1, 0), a3, voffA);
;             PG8_WAIT_V(8); PG8_WAIT_L(0); PG8_BAR; PG8_MMA(1, 0, At, B0); PG8_MMA(1, 1, At, B1); PG8_BAR; PG8_SCHED;
;     ...
;         if constexpr (ALIGN_EPI) { if (wr == 0) PG8_BAR; }
	s_mov_b32 m0, s74
	v_lshl_add_u64 v[160:161], v[160:161], 0, s[8:9]
	ds_read_b128 v[184:187], v145 offset:49152
	ds_read_b128 v[188:191], v145 offset:50176
	ds_read_b128 v[192:195], v145 offset:51200
	ds_read_b128 v[196:199], v145 offset:52224
	ds_read_b128 v[200:203], v145 offset:53248
	ds_read_b128 v[204:207], v145 offset:54272
	ds_read_b128 v[208:211], v145 offset:55296
	ds_read_b128 v[212:215], v145 offset:56320
	global_load_lds_dwordx4 v[160:161], off
	v_lshl_add_u64 v[160:161], v[216:217], 0, s[8:9]
	s_mov_b32 m0, s70
	s_nop 0
	global_load_lds_dwordx4 v[160:161], off
	v_lshl_add_u64 v[160:161], s[36:37], 0, v[130:131]
	s_mov_b32 m0, s71
	s_nop 0
	global_load_lds_dwordx4 v[160:161], off
	v_lshl_add_u64 v[160:161], s[36:37], 0, v[134:135]
	s_mov_b32 m0, s67
	s_nop 0
	global_load_lds_dwordx4 v[160:161], off
	v_lshl_add_u64 v[160:161], v[218:219], 0, s[8:9]
	s_mov_b32 m0, s60
	s_nop 0
	global_load_lds_dwordx4 v[160:161], off
	v_lshl_add_u64 v[160:161], v[220:221], 0, s[8:9]
	s_mov_b32 m0, s61
	s_nop 0
	global_load_lds_dwordx4 v[160:161], off
	s_waitcnt vmcnt(8)
	s_waitcnt lgkmcnt(0)
	s_barrier
	s_waitcnt lgkmcnt(0)
	v_mfma_f32_16x16x32_bf16 v[60:63], v[146:149], v[184:187], v[60:63]
	v_mfma_f32_16x16x32_bf16 v[56:59], v[156:159], v[184:187], v[56:59]
	v_mfma_f32_16x16x32_bf16 v[52:55], v[146:149], v[192:195], v[52:55]
	v_mfma_f32_16x16x32_bf16 v[48:51], v[156:159], v[192:195], v[48:51]
	v_mfma_f32_16x16x32_bf16 v[36:39], v[146:149], v[200:203], v[36:39]
	v_mfma_f32_16x16x32_bf16 v[32:35], v[156:159], v[200:203], v[32:35]
	v_mfma_f32_16x16x32_bf16 v[20:23], v[146:149], v[208:211], v[20:23]
	v_mfma_f32_16x16x32_bf16 v[16:19], v[156:159], v[208:211], v[16:19]
	v_mfma_f32_16x16x32_bf16 v[60:63], v[150:153], v[188:191], v[60:63]
	v_mfma_f32_16x16x32_bf16 v[56:59], v[164:167], v[188:191], v[56:59]
	v_mfma_f32_16x16x32_bf16 v[52:55], v[150:153], v[196:199], v[52:55]
	v_mfma_f32_16x16x32_bf16 v[48:51], v[164:167], v[196:199], v[48:51]
	v_mfma_f32_16x16x32_bf16 v[36:39], v[150:153], v[204:207], v[36:39]
	v_mfma_f32_16x16x32_bf16 v[32:35], v[164:167], v[204:207], v[32:35]
	v_mfma_f32_16x16x32_bf16 v[20:23], v[150:153], v[212:215], v[20:23]
	v_mfma_f32_16x16x32_bf16 v[16:19], v[164:167], v[212:215], v[16:19]
	v_mfma_f32_16x16x32_bf16 v[44:47], v[168:171], v[184:187], v[44:47]
	v_mfma_f32_16x16x32_bf16 v[40:43], v[176:179], v[184:187], v[40:43]
	v_mfma_f32_16x16x32_bf16 v[28:31], v[168:171], v[192:195], v[28:31]
	v_mfma_f32_16x16x32_bf16 v[24:27], v[176:179], v[192:195], v[24:27]
	v_mfma_f32_16x16x32_bf16 v[12:15], v[168:171], v[200:203], v[12:15]
	v_mfma_f32_16x16x32_bf16 v[8:11], v[176:179], v[200:203], v[8:11]
	v_mfma_f32_16x16x32_bf16 v[4:7], v[168:171], v[208:211], v[4:7]
	v_mfma_f32_16x16x32_bf16 v[0:3], v[176:179], v[208:211], v[0:3]
	v_mfma_f32_16x16x32_bf16 v[44:47], v[172:175], v[188:191], v[44:47]
	v_mfma_f32_16x16x32_bf16 v[40:43], v[180:183], v[188:191], v[40:43]
	v_mfma_f32_16x16x32_bf16 v[28:31], v[172:175], v[196:199], v[28:31]
	v_mfma_f32_16x16x32_bf16 v[24:27], v[180:183], v[196:199], v[24:27]
	v_mfma_f32_16x16x32_bf16 v[12:15], v[172:175], v[204:207], v[12:15]
	v_mfma_f32_16x16x32_bf16 v[8:11], v[180:183], v[204:207], v[8:11]
	v_mfma_f32_16x16x32_bf16 v[4:7], v[172:175], v[212:215], v[4:7]
	v_mfma_f32_16x16x32_bf16 v[0:3], v[180:183], v[212:215], v[0:3]
	s_barrier
	s_movk_i32 s38, 0x100
	s_andn2_b64 vcc, exec, s[34:35]
	s_mov_b64 s[36:37], -1
	s_mov_b64 s[34:35], 0
	s_cbranch_vccz .LBB0_1004
	s_and_b64 vcc, exec, s[10:11]
	s_cbranch_vccz .LBB0_1007
	s_barrier

; #define PG8_STAGE(bufoff, gbase, voff) do { _Pragma("unroll") for (int _i = 0; _i < 2; ++_i) \
;         __builtin_amdgcn_global_load_lds((const unsigned*)((const char*)(gbase) + (voff)[_i]), (PG8_LAS unsigned*)(lds + (bufoff) + ldsw + _i * 8192), 16, 0, 0); } while (0)
; #define PG8_LDA(dst, b, h) do { _Pragma("unroll") for (int m = 0; m < 4; ++m) _Pragma("unroll") for (int k = 0; k < 2; ++k) dst[m][k] = *(const PG8_LAS bf16x8*)(lds + PG8_SA(b, h) + aoff + m * 2048 + k * 1024); } while (0)
; #define PG8_LDB(dst, b, h) do { _Pragma("unroll") for (int n = 0; n < 2; ++n) _Pragma("unroll") for (int k = 0; k < 2; ++k) dst[n][k] = *(const PG8_LAS bf16x8*)(lds + PG8_SB(b, h) + boff + n * 2048 + k * 1024); } while (0)
; #define PG8_MMA(ai, bj, At, Bt) do { __builtin_amdgcn_s_setprio(1); _Pragma("unroll") for (int m = 0; m < 4; ++m) _Pragma("unroll") for (int n = 0; n < 2; ++n) _Pragma("unroll") for (int k = 0; k < 2; ++k) \
;         acc[ai][bj][m][n] = __builtin_amdgcn_mfma_f32_16x16x32_bf16(Bt[n][k], At[m][k], acc[ai][bj][m][n], 0, 0, 0); __builtin_amdgcn_s_setprio(0); } while (0)
; #define PG8_WAIT_V(n) asm volatile("s_waitcnt vmcnt(" #n ")" ::: "memory")
; #define PG8_WAIT_L(n) asm volatile("s_waitcnt lgkmcnt(" #n ")" ::: "memory")
; #define PG8_BAR __builtin_amdgcn_s_barrier()
; #define PG8_SCHED __builtin_amdgcn_sched_barrier(0)
; template <class Epi, class Sched, bool ALIGN_EPI = false, bool SP2 = false>
; __device__ __forceinline__ void gemm_phase(PG8_LAS unsigned char* lds, const Gemm g, const Sched& S, const Epi& E) {
;     ...
;             PG8_LDB(B0, 0, 0); PG8_LDB(B1, 0, 1); PG8_SCHED; PG8_LDA(At, 0, 0); PG8_STAGE(PG8_SA(1, 1), a1 + hstep, voffA);
;             PG8_WAIT_V(8); PG8_WAIT_L(0); PG8_BAR; PG8_MMA(0, 0, At, B0); PG8_MMA(0, 1, At, B1); PG8_BAR; PG8_SCHED;
;             PG8_LDA(At, 0, 1); PG8_STAGE(PG8_SB(0, 0), b2, voffB); PG8_STAGE(PG8_SB(0, 1), b2 + hstep, voffB); PG8_STAGE(PG8_SA(0, 0), a2, voffA);
;             PG8_WAIT_V(8); PG8_WAIT_L(0); PG8_BAR; PG8_MMA(1, 0, At, B0); PG8_MMA(1, 1, At, B1); PG8_BAR; PG8_SCHED;
;     ...
;         for (int a = 0; a < 2; ++a)
; #pragma unroll
;             for (int b = 0; b < 2; ++b)
; #pragma unroll
;                 for (int m = 0; m < 4; ++m)
; #pragma unroll
;                     for (int n = 0; n < 2; ++n) acc[a][b][m][n] = (f32x4){0.f, 0.f, 0.f, 0.f};
.LBB0_1084:
	s_add_u32 s34, s34, 0xb0080
	s_addc_u32 s35, s35, 0
	s_add_u32 s64, s36, 0x100
	s_addc_u32 s65, s37, 0
	s_mov_b32 s66, -2
	s_waitcnt lgkmcnt(0)
	ds_read_b128 v[144:147], v152
	ds_read_b128 v[158:161], v152 offset:1024
	ds_read_b128 v[164:167], v152 offset:2048
	ds_read_b128 v[168:171], v152 offset:3072
	ds_read_b128 v[172:175], v153
	ds_read_b128 v[176:179], v153 offset:1024
	ds_read_b128 v[180:183], v153 offset:2048
	ds_read_b128 v[184:187], v153 offset:3072
	s_add_u32 s36, s34, 0xfff50080
	s_addc_u32 s37, s35, -1
	s_cmp_eq_u32 s66, 40
	s_cselect_b32 s39, s7, s37
	s_cselect_b32 s38, s6, s36
	s_cselect_b32 s37, s31, s65
	s_cselect_b32 s36, s30, s64
	v_lshl_add_u64 v[220:221], s[34:35], 0, v[136:137]
	s_add_i32 m0, s33, 0xc000
	ds_read_b128 v[188:191], v155
	ds_read_b128 v[192:195], v155 offset:1024
	ds_read_b128 v[196:199], v155 offset:2048
	ds_read_b128 v[200:203], v155 offset:3072
	ds_read_b128 v[204:207], v155 offset:4096
	ds_read_b128 v[208:211], v155 offset:5120
	ds_read_b128 v[212:215], v155 offset:6144
	ds_read_b128 v[216:219], v155 offset:7168
	global_load_lds_dwordx4 v[220:221], off
	v_lshl_add_u64 v[220:221], s[34:35], 0, v[138:139]
	s_add_i32 m0, s33, 0xe000
	s_nop 0
	global_load_lds_dwordx4 v[220:221], off
	s_waitcnt vmcnt(8)
	s_waitcnt lgkmcnt(0)
	s_barrier
	s_waitcnt lgkmcnt(0)
	v_mfma_f32_16x16x32_bf16 v[124:127], v[144:147], v[188:191], 0
	v_mfma_f32_16x16x32_bf16 v[120:123], v[164:167], v[188:191], 0
	v_mfma_f32_16x16x32_bf16 v[108:111], v[144:147], v[196:199], 0
	v_mfma_f32_16x16x32_bf16 v[104:107], v[164:167], v[196:199], 0
	v_mfma_f32_16x16x32_bf16 v[92:95], v[144:147], v[204:207], 0
	v_mfma_f32_16x16x32_bf16 v[88:91], v[164:167], v[204:207], 0
	v_mfma_f32_16x16x32_bf16 v[76:79], v[144:147], v[212:215], 0
	v_mfma_f32_16x16x32_bf16 v[72:75], v[164:167], v[212:215], 0
	v_mfma_f32_16x16x32_bf16 v[124:127], v[158:161], v[192:195], v[124:127]
	v_mfma_f32_16x16x32_bf16 v[120:123], v[168:171], v[192:195], v[120:123]
	v_mfma_f32_16x16x32_bf16 v[108:111], v[158:161], v[200:203], v[108:111]
	v_mfma_f32_16x16x32_bf16 v[104:107], v[168:171], v[200:203], v[104:107]
	v_mfma_f32_16x16x32_bf16 v[92:95], v[158:161], v[208:211], v[92:95]
	v_mfma_f32_16x16x32_bf16 v[88:91], v[168:171], v[208:211], v[88:91]
	v_mfma_f32_16x16x32_bf16 v[76:79], v[158:161], v[216:219], v[76:79]
	v_mfma_f32_16x16x32_bf16 v[72:75], v[168:171], v[216:219], v[72:75]
	v_mfma_f32_16x16x32_bf16 v[116:119], v[172:175], v[188:191], 0
	v_mfma_f32_16x16x32_bf16 v[112:115], v[180:183], v[188:191], 0
	v_mfma_f32_16x16x32_bf16 v[100:103], v[172:175], v[196:199], 0
	v_mfma_f32_16x16x32_bf16 v[96:99], v[180:183], v[196:199], 0
	v_mfma_f32_16x16x32_bf16 v[84:87], v[172:175], v[204:207], 0
	v_mfma_f32_16x16x32_bf16 v[80:83], v[180:183], v[204:207], 0
	v_mfma_f32_16x16x32_bf16 v[68:71], v[172:175], v[212:215], 0
	v_mfma_f32_16x16x32_bf16 v[64:67], v[180:183], v[212:215], 0
	v_mfma_f32_16x16x32_bf16 v[116:119], v[176:179], v[192:195], v[116:119]
	v_mfma_f32_16x16x32_bf16 v[112:115], v[184:187], v[192:195], v[112:115]
	v_mfma_f32_16x16x32_bf16 v[100:103], v[176:179], v[200:203], v[100:103]
	v_mfma_f32_16x16x32_bf16 v[96:99], v[184:187], v[200:203], v[96:99]
	v_mfma_f32_16x16x32_bf16 v[84:87], v[176:179], v[208:211], v[84:87]
	v_mfma_f32_16x16x32_bf16 v[80:83], v[184:187], v[208:211], v[80:83]
	v_mfma_f32_16x16x32_bf16 v[68:71], v[176:179], v[216:219], v[68:71]
	v_mfma_f32_16x16x32_bf16 v[64:67], v[184:187], v[216:219], v[64:67]
	s_barrier
	s_add_i32 s67, s52, s3
	v_lshl_add_u64 v[220:221], s[36:37], 0, v[130:131]
	s_mov_b32 m0, s67
	ds_read_b128 v[188:191], v155 offset:16384
	ds_read_b128 v[192:195], v155 offset:17408
	ds_read_b128 v[196:199], v155 offset:18432
	ds_read_b128 v[200:203], v155 offset:19456
	ds_read_b128 v[204:207], v155 offset:20480
	ds_read_b128 v[208:211], v155 offset:21504
	ds_read_b128 v[212:215], v155 offset:22528
	ds_read_b128 v[216:219], v155 offset:23552
	global_load_lds_dwordx4 v[220:221], off
	s_add_i32 m0, s67, 0x2000
	s_add_u32 s70, s36, 0xb0000
	v_lshl_add_u64 v[222:223], s[36:37], 0, v[134:135]
	s_addc_u32 s71, s37, 0
	s_add_i32 s67, s53, s3
	global_load_lds_dwordx4 v[222:223], off
	v_lshl_add_u64 v[224:225], s[70:71], 0, v[130:131]
	s_mov_b32 m0, s67
	v_lshl_add_u64 v[226:227], s[38:39], 0, v[132:133]
	global_load_lds_dwordx4 v[224:225], off
	v_lshl_add_u64 v[224:225], s[70:71], 0, v[134:135]
	s_add_i32 m0, s67, 0x2000
	s_nop 0
	global_load_lds_dwordx4 v[224:225], off
	v_lshl_add_u64 v[224:225], s[38:39], 0, v[128:129]
	s_mov_b32 m0, s33
	s_nop 0
	global_load_lds_dwordx4 v[224:225], off
	s_mov_b32 m0, s40
	s_nop 0
	global_load_lds_dwordx4 v[226:227], off
	s_waitcnt vmcnt(8)
	s_waitcnt lgkmcnt(0)
	s_barrier
; #define PG8_STAGE(bufoff, gbase, voff) do { _Pragma("unroll") for (int _i = 0; _i < 2; ++_i) \
;         __builtin_amdgcn_global_load_lds((const unsigned*)((const char*)(gbase) + (voff)[_i]), (PG8_LAS unsigned*)(lds + (bufoff) + ldsw + _i * 8192), 16, 0, 0); } while (0)
; #define PG8_LDA(dst, b, h) do { _Pragma("unroll") for (int m = 0; m < 4; ++m) _Pragma("unroll") for (int k = 0; k < 2; ++k) dst[m][k] = *(const PG8_LAS bf16x8*)(lds + PG8_SA(b, h) + aoff + m * 2048 + k * 1024); } while (0)
; #define PG8_LDB(dst, b, h) do { _Pragma("unroll") for (int n = 0; n < 2; ++n) _Pragma("unroll") for (int k = 0; k < 2; ++k) dst[n][k] = *(const PG8_LAS bf16x8*)(lds + PG8_SB(b, h) + boff + n * 2048 + k * 1024); } while (0)
; #define PG8_MMA(ai, bj, At, Bt) do { __builtin_amdgcn_s_setprio(1); _Pragma("unroll") for (int m = 0; m < 4; ++m) _Pragma("unroll") for (int n = 0; n < 2; ++n) _Pragma("unroll") for (int k = 0; k < 2; ++k) \
;         acc[ai][bj][m][n] = __builtin_amdgcn_mfma_f32_16x16x32_bf16(Bt[n][k], At[m][k], acc[ai][bj][m][n], 0, 0, 0); __builtin_amdgcn_s_setprio(0); } while (0)
; #define PG8_WAIT_V(n) asm volatile("s_waitcnt vmcnt(" #n ")" ::: "memory")
; #define PG8_WAIT_L(n) asm volatile("s_waitcnt lgkmcnt(" #n ")" ::: "memory")
; #define PG8_BAR __builtin_amdgcn_s_barrier()
; #define PG8_SCHED __builtin_amdgcn_sched_barrier(0)
; template <class Epi, class Sched, bool ALIGN_EPI = false, bool SP2 = false>
; __device__ __forceinline__ void gemm_phase(PG8_LAS unsigned char* lds, const Gemm g, const Sched& S, const Epi& E) {
;     ...
;             PG8_WAIT_V(8); PG8_WAIT_L(0); PG8_BAR; PG8_MMA(1, 0, At, B0); PG8_MMA(1, 1, At, B1); PG8_BAR; PG8_SCHED;
;             PG8_LDB(B0, 1, 0); PG8_LDB(B1, 1, 1); PG8_SCHED; PG8_LDA(At, 1, 0); PG8_STAGE(PG8_SA(0, 1), a2 + hstep, voffA);
;             PG8_WAIT_V(8); PG8_WAIT_L(0); PG8_BAR; PG8_MMA(0, 0, At, B0); PG8_MMA(0, 1, At, B1); PG8_BAR; PG8_SCHED;
	s_waitcnt lgkmcnt(0)
	v_mfma_f32_16x16x32_bf16 v[60:63], v[144:147], v[188:191], 0
	v_mfma_f32_16x16x32_bf16 v[56:59], v[164:167], v[188:191], 0
	v_mfma_f32_16x16x32_bf16 v[44:47], v[144:147], v[196:199], 0
	v_mfma_f32_16x16x32_bf16 v[40:43], v[164:167], v[196:199], 0
	v_mfma_f32_16x16x32_bf16 v[28:31], v[144:147], v[204:207], 0
	v_mfma_f32_16x16x32_bf16 v[24:27], v[164:167], v[204:207], 0
	v_mfma_f32_16x16x32_bf16 v[12:15], v[144:147], v[212:215], 0
	v_mfma_f32_16x16x32_bf16 v[8:11], v[164:167], v[212:215], 0
	v_mfma_f32_16x16x32_bf16 v[60:63], v[158:161], v[192:195], v[60:63]
	v_mfma_f32_16x16x32_bf16 v[56:59], v[168:171], v[192:195], v[56:59]
	v_mfma_f32_16x16x32_bf16 v[44:47], v[158:161], v[200:203], v[44:47]
	v_mfma_f32_16x16x32_bf16 v[40:43], v[168:171], v[200:203], v[40:43]
	v_mfma_f32_16x16x32_bf16 v[28:31], v[158:161], v[208:211], v[28:31]
	v_mfma_f32_16x16x32_bf16 v[24:27], v[168:171], v[208:211], v[24:27]
	v_mfma_f32_16x16x32_bf16 v[12:15], v[158:161], v[216:219], v[12:15]
	v_mfma_f32_16x16x32_bf16 v[8:11], v[168:171], v[216:219], v[8:11]
	v_mfma_f32_16x16x32_bf16 v[52:55], v[172:175], v[188:191], 0
	v_mfma_f32_16x16x32_bf16 v[48:51], v[180:183], v[188:191], 0
	v_mfma_f32_16x16x32_bf16 v[36:39], v[172:175], v[196:199], 0
	v_mfma_f32_16x16x32_bf16 v[32:35], v[180:183], v[196:199], 0
	v_mfma_f32_16x16x32_bf16 v[20:23], v[172:175], v[204:207], 0
	v_mfma_f32_16x16x32_bf16 v[16:19], v[180:183], v[204:207], 0
	v_mfma_f32_16x16x32_bf16 v[4:7], v[172:175], v[212:215], 0
	v_mfma_f32_16x16x32_bf16 v[0:3], v[180:183], v[212:215], 0
	v_mfma_f32_16x16x32_bf16 v[52:55], v[176:179], v[192:195], v[52:55]
	v_mfma_f32_16x16x32_bf16 v[48:51], v[184:187], v[192:195], v[48:51]
	v_mfma_f32_16x16x32_bf16 v[36:39], v[176:179], v[200:203], v[36:39]
	v_mfma_f32_16x16x32_bf16 v[32:35], v[184:187], v[200:203], v[32:35]
	v_mfma_f32_16x16x32_bf16 v[20:23], v[176:179], v[208:211], v[20:23]
	v_mfma_f32_16x16x32_bf16 v[16:19], v[184:187], v[208:211], v[16:19]
	v_mfma_f32_16x16x32_bf16 v[4:7], v[176:179], v[216:219], v[4:7]
	v_mfma_f32_16x16x32_bf16 v[0:3], v[184:187], v[216:219], v[0:3]
	s_barrier
	s_add_i32 s67, 0, 0x18000
	v_add_u32_e32 v157, s67, v150
	s_add_i32 s70, 0, 0x1c000
	ds_read_b128 v[144:147], v157
	ds_read_b128 v[158:161], v157 offset:1024
	ds_read_b128 v[164:167], v157 offset:2048
	ds_read_b128 v[168:171], v157 offset:3072
	v_add_u32_e32 v157, s70, v150
	ds_read_b128 v[172:175], v157
	ds_read_b128 v[176:179], v157 offset:1024
	ds_read_b128 v[180:183], v157 offset:2048
	ds_read_b128 v[184:187], v157 offset:3072
	s_add_u32 s38, s38, 0xb0000
	s_addc_u32 s39, s39, 0
	s_mov_b32 m0, s41
	v_lshl_add_u64 v[228:229], s[38:39], 0, v[128:129]
	ds_read_b128 v[188:191], v155 offset:32768
	ds_read_b128 v[192:195], v155 offset:33792
	ds_read_b128 v[196:199], v155 offset:34816
	ds_read_b128 v[200:203], v155 offset:35840
	ds_read_b128 v[204:207], v155 offset:36864
	ds_read_b128 v[208:211], v155 offset:37888
	ds_read_b128 v[212:215], v155 offset:38912
	ds_read_b128 v[216:219], v155 offset:39936
	global_load_lds_dwordx4 v[228:229], off
	v_lshl_add_u64 v[228:229], s[38:39], 0, v[132:133]
	s_mov_b32 m0, s43
	s_nop 0
	global_load_lds_dwordx4 v[228:229], off
	s_waitcnt vmcnt(8)
	s_waitcnt lgkmcnt(0)
	s_barrier
	s_waitcnt lgkmcnt(0)
	v_mfma_f32_16x16x32_bf16 v[124:127], v[144:147], v[188:191], v[124:127]
	v_mfma_f32_16x16x32_bf16 v[120:123], v[164:167], v[188:191], v[120:123]
	v_mfma_f32_16x16x32_bf16 v[108:111], v[144:147], v[196:199], v[108:111]
	v_mfma_f32_16x16x32_bf16 v[104:107], v[164:167], v[196:199], v[104:107]
	v_mfma_f32_16x16x32_bf16 v[92:95], v[144:147], v[204:207], v[92:95]
	v_mfma_f32_16x16x32_bf16 v[88:91], v[164:167], v[204:207], v[88:91]
	v_mfma_f32_16x16x32_bf16 v[76:79], v[144:147], v[212:215], v[76:79]
	v_mfma_f32_16x16x32_bf16 v[72:75], v[164:167], v[212:215], v[72:75]
	v_mfma_f32_16x16x32_bf16 v[124:127], v[158:161], v[192:195], v[124:127]
	v_mfma_f32_16x16x32_bf16 v[120:123], v[168:171], v[192:195], v[120:123]
	v_mfma_f32_16x16x32_bf16 v[108:111], v[158:161], v[200:203], v[108:111]
	v_mfma_f32_16x16x32_bf16 v[104:107], v[168:171], v[200:203], v[104:107]
	v_mfma_f32_16x16x32_bf16 v[92:95], v[158:161], v[208:211], v[92:95]
	v_mfma_f32_16x16x32_bf16 v[88:91], v[168:171], v[208:211], v[88:91]
	v_mfma_f32_16x16x32_bf16 v[76:79], v[158:161], v[216:219], v[76:79]
	v_mfma_f32_16x16x32_bf16 v[72:75], v[168:171], v[216:219], v[72:75]
	v_mfma_f32_16x16x32_bf16 v[116:119], v[172:175], v[188:191], v[116:119]
	v_mfma_f32_16x16x32_bf16 v[112:115], v[180:183], v[188:191], v[112:115]
	v_mfma_f32_16x16x32_bf16 v[100:103], v[172:175], v[196:199], v[100:103]
	v_mfma_f32_16x16x32_bf16 v[96:99], v[180:183], v[196:199], v[96:99]
	v_mfma_f32_16x16x32_bf16 v[84:87], v[172:175], v[204:207], v[84:87]
	v_mfma_f32_16x16x32_bf16 v[80:83], v[180:183], v[204:207], v[80:83]
	v_mfma_f32_16x16x32_bf16 v[68:71], v[172:175], v[212:215], v[68:71]
	v_mfma_f32_16x16x32_bf16 v[64:67], v[180:183], v[212:215], v[64:67]
	v_mfma_f32_16x16x32_bf16 v[116:119], v[176:179], v[192:195], v[116:119]
	v_mfma_f32_16x16x32_bf16 v[112:115], v[184:187], v[192:195], v[112:115]
	v_mfma_f32_16x16x32_bf16 v[100:103], v[176:179], v[200:203], v[100:103]
	v_mfma_f32_16x16x32_bf16 v[96:99], v[184:187], v[200:203], v[96:99]
	v_mfma_f32_16x16x32_bf16 v[84:87], v[176:179], v[208:211], v[84:87]
	v_mfma_f32_16x16x32_bf16 v[80:83], v[184:187], v[208:211], v[80:83]
	v_mfma_f32_16x16x32_bf16 v[68:71], v[176:179], v[216:219], v[68:71]
	v_mfma_f32_16x16x32_bf16 v[64:67], v[184:187], v[216:219], v[64:67]
	s_barrier
; #define PG8_STAGE(bufoff, gbase, voff) do { _Pragma("unroll") for (int _i = 0; _i < 2; ++_i) \
;         __builtin_amdgcn_global_load_lds((const unsigned*)((const char*)(gbase) + (voff)[_i]), (PG8_LAS unsigned*)(lds + (bufoff) + ldsw + _i * 8192), 16, 0, 0); } while (0)
; #define PG8_LDA(dst, b, h) do { _Pragma("unroll") for (int m = 0; m < 4; ++m) _Pragma("unroll") for (int k = 0; k < 2; ++k) dst[m][k] = *(const PG8_LAS bf16x8*)(lds + PG8_SA(b, h) + aoff + m * 2048 + k * 1024); } while (0)
; #define PG8_LDB(dst, b, h) do { _Pragma("unroll") for (int n = 0; n < 2; ++n) _Pragma("unroll") for (int k = 0; k < 2; ++k) dst[n][k] = *(const PG8_LAS bf16x8*)(lds + PG8_SB(b, h) + boff + n * 2048 + k * 1024); } while (0)
; template <class Epi, class Sched, bool ALIGN_EPI = false, bool SP2 = false>
; __device__ __forceinline__ void gemm_phase(PG8_LAS unsigned char* lds, const Gemm g, const Sched& S, const Epi& E) {
;     ...
;         for (int t = 0; t < nt; t += 2) {
;             const bool last = (t == nt - 2);
;             const char* a1 = cA + (size_t)(t + 1) * kstep;
;             const char* a2 = last ? nA : cA + (size_t)(t + 2) * kstep; const char* b2 = last ? nB : cB + (size_t)(t + 2) * kstep;
;             const char* a3 = a2 + kstep; const char* b3 = b2 + kstep;
;             if (last && has_next) S.a_ready(nxt);
;             if constexpr (SP2) {
;             PG8_LDB(B0, 0, 0); PG8_LDB(B1, 0, 1); PG8_SCHED; PG8_LDA(At, 0, 0); PG8_STAGE(PG8_SA(1, 1), a1 + hstep, voffA);
;             PG8_WAIT_V(8); PG8_WAIT_L(0); PG8_BAR; PG8_MMA(0, 0, At, B0); PG8_MMA(0, 1, At, B1); PG8_BAR; PG8_SCHED;
;             PG8_LDA(At, 0, 1); PG8_STAGE(PG8_SB(0, 0), b2, voffB); PG8_STAGE(PG8_SB(0, 1), b2 + hstep, voffB); PG8_STAGE(PG8_SA(0, 0), a2, voffA);
;             PG8_WAIT_V(8); PG8_WAIT_L(0); PG8_BAR; PG8_MMA(1, 0, At, B0); PG8_MMA(1, 1, At, B1); PG8_BAR; PG8_SCHED;
;             PG8_LDB(B0, 1, 0); PG8_LDB(B1, 1, 1); PG8_SCHED; PG8_LDA(At, 1, 0); PG8_STAGE(PG8_SA(0, 1), a2 + hstep, voffA);
;             PG8_WAIT_V(8); PG8_WAIT_L(0); PG8_BAR; PG8_MMA(0, 0, At, B0); PG8_MMA(0, 1, At, B1); PG8_BAR; PG8_SCHED;
;             PG8_LDA(At, 1, 1); PG8_STAGE(PG8_SB(1, 0), b3, voffB); PG8_STAGE(PG8_SB(1, 1), b3 + hstep, voffB); PG8_STAGE(PG8_SA(1, 0), a3, voffA);
;             PG8_WAIT_V(8); PG8_WAIT_L(0); PG8_BAR; PG8_MMA(1, 0, At, B0); PG8_MMA(1, 1, At, B1); PG8_BAR; PG8_SCHED;
	s_add_i32 s38, s67, s3
	v_lshl_add_u64 v[220:221], v[220:221], 0, s[10:11]
	s_mov_b32 m0, s38
	ds_read_b128 v[188:191], v155 offset:49152
	ds_read_b128 v[192:195], v155 offset:50176
	ds_read_b128 v[196:199], v155 offset:51200
	ds_read_b128 v[200:203], v155 offset:52224
	ds_read_b128 v[204:207], v155 offset:53248
	ds_read_b128 v[208:211], v155 offset:54272
	ds_read_b128 v[212:215], v155 offset:55296
	ds_read_b128 v[216:219], v155 offset:56320
	global_load_lds_dwordx4 v[220:221], off
	s_add_i32 m0, s38, 0x2000
	s_add_u32 s36, s36, 0xb0080
	v_lshl_add_u64 v[220:221], v[222:223], 0, s[10:11]
	s_addc_u32 s37, s37, 0
	s_add_i32 s38, s70, s3
	global_load_lds_dwordx4 v[220:221], off
	v_lshl_add_u64 v[220:221], s[36:37], 0, v[130:131]
	s_mov_b32 m0, s38
	s_nop 0
	global_load_lds_dwordx4 v[220:221], off
	v_lshl_add_u64 v[220:221], s[36:37], 0, v[134:135]
	s_add_i32 m0, s38, 0x2000
	s_nop 0
	global_load_lds_dwordx4 v[220:221], off
	v_lshl_add_u64 v[220:221], v[224:225], 0, s[10:11]
	s_mov_b32 m0, s50
	s_nop 0
	global_load_lds_dwordx4 v[220:221], off
	v_lshl_add_u64 v[220:221], v[226:227], 0, s[10:11]
	s_mov_b32 m0, s51
	s_nop 0
	global_load_lds_dwordx4 v[220:221], off
	s_waitcnt vmcnt(8)
	s_waitcnt lgkmcnt(0)
	s_barrier
	s_waitcnt lgkmcnt(0)
	v_mfma_f32_16x16x32_bf16 v[60:63], v[144:147], v[188:191], v[60:63]
	v_mfma_f32_16x16x32_bf16 v[56:59], v[164:167], v[188:191], v[56:59]
	v_mfma_f32_16x16x32_bf16 v[44:47], v[144:147], v[196:199], v[44:47]
	v_mfma_f32_16x16x32_bf16 v[40:43], v[164:167], v[196:199], v[40:43]
	v_mfma_f32_16x16x32_bf16 v[28:31], v[144:147], v[204:207], v[28:31]
	v_mfma_f32_16x16x32_bf16 v[24:27], v[164:167], v[204:207], v[24:27]
	v_mfma_f32_16x16x32_bf16 v[12:15], v[144:147], v[212:215], v[12:15]
	v_mfma_f32_16x16x32_bf16 v[8:11], v[164:167], v[212:215], v[8:11]
	v_mfma_f32_16x16x32_bf16 v[60:63], v[158:161], v[192:195], v[60:63]
	v_mfma_f32_16x16x32_bf16 v[56:59], v[168:171], v[192:195], v[56:59]
	v_mfma_f32_16x16x32_bf16 v[44:47], v[158:161], v[200:203], v[44:47]
	v_mfma_f32_16x16x32_bf16 v[40:43], v[168:171], v[200:203], v[40:43]
	v_mfma_f32_16x16x32_bf16 v[28:31], v[158:161], v[208:211], v[28:31]
	v_mfma_f32_16x16x32_bf16 v[24:27], v[168:171], v[208:211], v[24:27]
	v_mfma_f32_16x16x32_bf16 v[12:15], v[158:161], v[216:219], v[12:15]
	v_mfma_f32_16x16x32_bf16 v[8:11], v[168:171], v[216:219], v[8:11]
	v_mfma_f32_16x16x32_bf16 v[52:55], v[172:175], v[188:191], v[52:55]
	v_mfma_f32_16x16x32_bf16 v[48:51], v[180:183], v[188:191], v[48:51]
	v_mfma_f32_16x16x32_bf16 v[36:39], v[172:175], v[196:199], v[36:39]
	v_mfma_f32_16x16x32_bf16 v[32:35], v[180:183], v[196:199], v[32:35]
	v_mfma_f32_16x16x32_bf16 v[20:23], v[172:175], v[204:207], v[20:23]
	v_mfma_f32_16x16x32_bf16 v[16:19], v[180:183], v[204:207], v[16:19]
	v_mfma_f32_16x16x32_bf16 v[4:7], v[172:175], v[212:215], v[4:7]
	v_mfma_f32_16x16x32_bf16 v[0:3], v[180:183], v[212:215], v[0:3]
	v_mfma_f32_16x16x32_bf16 v[52:55], v[176:179], v[192:195], v[52:55]
	v_mfma_f32_16x16x32_bf16 v[48:51], v[184:187], v[192:195], v[48:51]
	v_mfma_f32_16x16x32_bf16 v[36:39], v[176:179], v[200:203], v[36:39]
	v_mfma_f32_16x16x32_bf16 v[32:35], v[184:187], v[200:203], v[32:35]
	v_mfma_f32_16x16x32_bf16 v[20:23], v[176:179], v[208:211], v[20:23]
	v_mfma_f32_16x16x32_bf16 v[16:19], v[184:187], v[208:211], v[16:19]
	v_mfma_f32_16x16x32_bf16 v[4:7], v[176:179], v[216:219], v[4:7]
	v_mfma_f32_16x16x32_bf16 v[0:3], v[184:187], v[216:219], v[0:3]
	s_barrier
	s_add_i32 s66, s66, 2
	s_add_u32 s34, s34, 0x100
	s_addc_u32 s35, s35, 0
	s_add_u32 s64, s64, 0x100
	s_addc_u32 s65, s65, 0
	s_cmp_gt_u32 s66, 41
	s_cbranch_scc1 .Lpeel_exit5
.LBB0_1085:
	ds_read_b128 v[144:147], v152
	ds_read_b128 v[158:161], v152 offset:1024
	ds_read_b128 v[164:167], v152 offset:2048
	ds_read_b128 v[168:171], v152 offset:3072
	ds_read_b128 v[172:175], v153
	ds_read_b128 v[176:179], v153 offset:1024
	ds_read_b128 v[180:183], v153 offset:2048
	ds_read_b128 v[184:187], v153 offset:3072
	s_add_u32 s36, s34, 0xfff50080
	s_addc_u32 s37, s35, -1
	s_cmp_eq_u32 s66, 40
	s_cselect_b32 s39, s7, s37
	s_cselect_b32 s38, s6, s36
	s_cselect_b32 s37, s31, s65
	s_cselect_b32 s36, s30, s64
	v_lshl_add_u64 v[220:221], s[34:35], 0, v[136:137]
	s_add_i32 m0, s33, 0xc000
	ds_read_b128 v[188:191], v155
	ds_read_b128 v[192:195], v155 offset:1024
	ds_read_b128 v[196:199], v155 offset:2048
	ds_read_b128 v[200:203], v155 offset:3072
	ds_read_b128 v[204:207], v155 offset:4096
	ds_read_b128 v[208:211], v155 offset:5120
	ds_read_b128 v[212:215], v155 offset:6144
	ds_read_b128 v[216:219], v155 offset:7168
	global_load_lds_dwordx4 v[220:221], off
	v_lshl_add_u64 v[220:221], s[34:35], 0, v[138:139]
	s_add_i32 m0, s33, 0xe000
	s_nop 0
	global_load_lds_dwordx4 v[220:221], off
	s_waitcnt vmcnt(8)
	s_waitcnt lgkmcnt(0)
	s_barrier
; #define PG8_STAGE(bufoff, gbase, voff) do { _Pragma("unroll") for (int _i = 0; _i < 2; ++_i) \
;         __builtin_amdgcn_global_load_lds((const unsigned*)((const char*)(gbase) + (voff)[_i]), (PG8_LAS unsigned*)(lds + (bufoff) + ldsw + _i * 8192), 16, 0, 0); } while (0)
; #define PG8_LDA(dst, b, h) do { _Pragma("unroll") for (int m = 0; m < 4; ++m) _Pragma("unroll") for (int k = 0; k < 2; ++k) dst[m][k] = *(const PG8_LAS bf16x8*)(lds + PG8_SA(b, h) + aoff + m * 2048 + k * 1024); } while (0)
; #define PG8_LDB(dst, b, h) do { _Pragma("unroll") for (int n = 0; n < 2; ++n) _Pragma("unroll") for (int k = 0; k < 2; ++k) dst[n][k] = *(const PG8_LAS bf16x8*)(lds + PG8_SB(b, h) + boff + n * 2048 + k * 1024); } while (0)
; #define PG8_MMA(ai, bj, At, Bt) do { __builtin_amdgcn_s_setprio(1); _Pragma("unroll") for (int m = 0; m < 4; ++m) _Pragma("unroll") for (int n = 0; n < 2; ++n) _Pragma("unroll") for (int k = 0; k < 2; ++k) \
;         acc[ai][bj][m][n] = __builtin_amdgcn_mfma_f32_16x16x32_bf16(Bt[n][k], At[m][k], acc[ai][bj][m][n], 0, 0, 0); __builtin_amdgcn_s_setprio(0); } while (0)
; #define PG8_WAIT_V(n) asm volatile("s_waitcnt vmcnt(" #n ")" ::: "memory")
; #define PG8_WAIT_L(n) asm volatile("s_waitcnt lgkmcnt(" #n ")" ::: "memory")
; #define PG8_BAR __builtin_amdgcn_s_barrier()
; #define PG8_SCHED __builtin_amdgcn_sched_barrier(0)
; template <class Epi, class Sched, bool ALIGN_EPI = false, bool SP2 = false>
; __device__ __forceinline__ void gemm_phase(PG8_LAS unsigned char* lds, const Gemm g, const Sched& S, const Epi& E) {
;     ...
;             PG8_LDB(B0, 0, 0); PG8_LDB(B1, 0, 1); PG8_SCHED; PG8_LDA(At, 0, 0); PG8_STAGE(PG8_SA(1, 1), a1 + hstep, voffA);
;             PG8_WAIT_V(8); PG8_WAIT_L(0); PG8_BAR; PG8_MMA(0, 0, At, B0); PG8_MMA(0, 1, At, B1); PG8_BAR; PG8_SCHED;
;             PG8_LDA(At, 0, 1); PG8_STAGE(PG8_SB(0, 0), b2, voffB); PG8_STAGE(PG8_SB(0, 1), b2 + hstep, voffB); PG8_STAGE(PG8_SA(0, 0), a2, voffA);
;             PG8_WAIT_V(8); PG8_WAIT_L(0); PG8_BAR; PG8_MMA(1, 0, At, B0); PG8_MMA(1, 1, At, B1); PG8_BAR; PG8_SCHED;
	s_waitcnt lgkmcnt(0)
	v_mfma_f32_16x16x32_bf16 v[124:127], v[144:147], v[188:191], v[124:127]
	v_mfma_f32_16x16x32_bf16 v[120:123], v[164:167], v[188:191], v[120:123]
	v_mfma_f32_16x16x32_bf16 v[108:111], v[144:147], v[196:199], v[108:111]
	v_mfma_f32_16x16x32_bf16 v[104:107], v[164:167], v[196:199], v[104:107]
	v_mfma_f32_16x16x32_bf16 v[92:95], v[144:147], v[204:207], v[92:95]
	v_mfma_f32_16x16x32_bf16 v[88:91], v[164:167], v[204:207], v[88:91]
	v_mfma_f32_16x16x32_bf16 v[76:79], v[144:147], v[212:215], v[76:79]
	v_mfma_f32_16x16x32_bf16 v[72:75], v[164:167], v[212:215], v[72:75]
	v_mfma_f32_16x16x32_bf16 v[124:127], v[158:161], v[192:195], v[124:127]
	v_mfma_f32_16x16x32_bf16 v[120:123], v[168:171], v[192:195], v[120:123]
	v_mfma_f32_16x16x32_bf16 v[108:111], v[158:161], v[200:203], v[108:111]
	v_mfma_f32_16x16x32_bf16 v[104:107], v[168:171], v[200:203], v[104:107]
	v_mfma_f32_16x16x32_bf16 v[92:95], v[158:161], v[208:211], v[92:95]
	v_mfma_f32_16x16x32_bf16 v[88:91], v[168:171], v[208:211], v[88:91]
	v_mfma_f32_16x16x32_bf16 v[76:79], v[158:161], v[216:219], v[76:79]
	v_mfma_f32_16x16x32_bf16 v[72:75], v[168:171], v[216:219], v[72:75]
	v_mfma_f32_16x16x32_bf16 v[116:119], v[172:175], v[188:191], v[116:119]
	v_mfma_f32_16x16x32_bf16 v[112:115], v[180:183], v[188:191], v[112:115]
	v_mfma_f32_16x16x32_bf16 v[100:103], v[172:175], v[196:199], v[100:103]
	v_mfma_f32_16x16x32_bf16 v[96:99], v[180:183], v[196:199], v[96:99]
	v_mfma_f32_16x16x32_bf16 v[84:87], v[172:175], v[204:207], v[84:87]
	v_mfma_f32_16x16x32_bf16 v[80:83], v[180:183], v[204:207], v[80:83]
	v_mfma_f32_16x16x32_bf16 v[68:71], v[172:175], v[212:215], v[68:71]
	v_mfma_f32_16x16x32_bf16 v[64:67], v[180:183], v[212:215], v[64:67]
	v_mfma_f32_16x16x32_bf16 v[116:119], v[176:179], v[192:195], v[116:119]
	v_mfma_f32_16x16x32_bf16 v[112:115], v[184:187], v[192:195], v[112:115]
	v_mfma_f32_16x16x32_bf16 v[100:103], v[176:179], v[200:203], v[100:103]
	v_mfma_f32_16x16x32_bf16 v[96:99], v[184:187], v[200:203], v[96:99]
	v_mfma_f32_16x16x32_bf16 v[84:87], v[176:179], v[208:211], v[84:87]
	v_mfma_f32_16x16x32_bf16 v[80:83], v[184:187], v[208:211], v[80:83]
	v_mfma_f32_16x16x32_bf16 v[68:71], v[176:179], v[216:219], v[68:71]
	v_mfma_f32_16x16x32_bf16 v[64:67], v[184:187], v[216:219], v[64:67]
	s_barrier
	s_add_i32 s67, s52, s3
	v_lshl_add_u64 v[220:221], s[36:37], 0, v[130:131]
	s_mov_b32 m0, s67
	ds_read_b128 v[188:191], v155 offset:16384
	ds_read_b128 v[192:195], v155 offset:17408
	ds_read_b128 v[196:199], v155 offset:18432
	ds_read_b128 v[200:203], v155 offset:19456
	ds_read_b128 v[204:207], v155 offset:20480
	ds_read_b128 v[208:211], v155 offset:21504
	ds_read_b128 v[212:215], v155 offset:22528
	ds_read_b128 v[216:219], v155 offset:23552
	global_load_lds_dwordx4 v[220:221], off
	s_add_i32 m0, s67, 0x2000
	s_add_u32 s70, s36, 0xb0000
	v_lshl_add_u64 v[222:223], s[36:37], 0, v[134:135]
	s_addc_u32 s71, s37, 0
	s_add_i32 s67, s53, s3
	global_load_lds_dwordx4 v[222:223], off
	v_lshl_add_u64 v[224:225], s[70:71], 0, v[130:131]
	s_mov_b32 m0, s67
	v_lshl_add_u64 v[226:227], s[38:39], 0, v[132:133]
	global_load_lds_dwordx4 v[224:225], off
	v_lshl_add_u64 v[224:225], s[70:71], 0, v[134:135]
	s_add_i32 m0, s67, 0x2000
	s_nop 0
	global_load_lds_dwordx4 v[224:225], off
	v_lshl_add_u64 v[224:225], s[38:39], 0, v[128:129]
	s_mov_b32 m0, s33
	s_nop 0
	global_load_lds_dwordx4 v[224:225], off
	s_mov_b32 m0, s40
	s_nop 0
	global_load_lds_dwordx4 v[226:227], off
	s_waitcnt vmcnt(8)
	s_waitcnt lgkmcnt(0)
	s_barrier
	s_waitcnt lgkmcnt(0)
	v_mfma_f32_16x16x32_bf16 v[60:63], v[144:147], v[188:191], v[60:63]
	v_mfma_f32_16x16x32_bf16 v[56:59], v[164:167], v[188:191], v[56:59]
	v_mfma_f32_16x16x32_bf16 v[44:47], v[144:147], v[196:199], v[44:47]
	v_mfma_f32_16x16x32_bf16 v[40:43], v[164:167], v[196:199], v[40:43]
	v_mfma_f32_16x16x32_bf16 v[28:31], v[144:147], v[204:207], v[28:31]
	v_mfma_f32_16x16x32_bf16 v[24:27], v[164:167], v[204:207], v[24:27]
	v_mfma_f32_16x16x32_bf16 v[12:15], v[144:147], v[212:215], v[12:15]
	v_mfma_f32_16x16x32_bf16 v[8:11], v[164:167], v[212:215], v[8:11]
	v_mfma_f32_16x16x32_bf16 v[60:63], v[158:161], v[192:195], v[60:63]
	v_mfma_f32_16x16x32_bf16 v[56:59], v[168:171], v[192:195], v[56:59]
	v_mfma_f32_16x16x32_bf16 v[44:47], v[158:161], v[200:203], v[44:47]
	v_mfma_f32_16x16x32_bf16 v[40:43], v[168:171], v[200:203], v[40:43]
	v_mfma_f32_16x16x32_bf16 v[28:31], v[158:161], v[208:211], v[28:31]
	v_mfma_f32_16x16x32_bf16 v[24:27], v[168:171], v[208:211], v[24:27]
	v_mfma_f32_16x16x32_bf16 v[12:15], v[158:161], v[216:219], v[12:15]
	v_mfma_f32_16x16x32_bf16 v[8:11], v[168:171], v[216:219], v[8:11]
	v_mfma_f32_16x16x32_bf16 v[52:55], v[172:175], v[188:191], v[52:55]
	v_mfma_f32_16x16x32_bf16 v[48:51], v[180:183], v[188:191], v[48:51]
	v_mfma_f32_16x16x32_bf16 v[36:39], v[172:175], v[196:199], v[36:39]
	v_mfma_f32_16x16x32_bf16 v[32:35], v[180:183], v[196:199], v[32:35]
	v_mfma_f32_16x16x32_bf16 v[20:23], v[172:175], v[204:207], v[20:23]
	v_mfma_f32_16x16x32_bf16 v[16:19], v[180:183], v[204:207], v[16:19]
	v_mfma_f32_16x16x32_bf16 v[4:7], v[172:175], v[212:215], v[4:7]
	v_mfma_f32_16x16x32_bf16 v[0:3], v[180:183], v[212:215], v[0:3]
	v_mfma_f32_16x16x32_bf16 v[52:55], v[176:179], v[192:195], v[52:55]
	v_mfma_f32_16x16x32_bf16 v[48:51], v[184:187], v[192:195], v[48:51]
	v_mfma_f32_16x16x32_bf16 v[36:39], v[176:179], v[200:203], v[36:39]
	v_mfma_f32_16x16x32_bf16 v[32:35], v[184:187], v[200:203], v[32:35]
	v_mfma_f32_16x16x32_bf16 v[20:23], v[176:179], v[208:211], v[20:23]
	v_mfma_f32_16x16x32_bf16 v[16:19], v[184:187], v[208:211], v[16:19]
	v_mfma_f32_16x16x32_bf16 v[4:7], v[176:179], v[216:219], v[4:7]
	v_mfma_f32_16x16x32_bf16 v[0:3], v[184:187], v[216:219], v[0:3]
	s_barrier
; #define PG8_STAGE(bufoff, gbase, voff) do { _Pragma("unroll") for (int _i = 0; _i < 2; ++_i) \
;         __builtin_amdgcn_global_load_lds((const unsigned*)((const char*)(gbase) + (voff)[_i]), (PG8_LAS unsigned*)(lds + (bufoff) + ldsw + _i * 8192), 16, 0, 0); } while (0)
; #define PG8_LDA(dst, b, h) do { _Pragma("unroll") for (int m = 0; m < 4; ++m) _Pragma("unroll") for (int k = 0; k < 2; ++k) dst[m][k] = *(const PG8_LAS bf16x8*)(lds + PG8_SA(b, h) + aoff + m * 2048 + k * 1024); } while (0)
; #define PG8_LDB(dst, b, h) do { _Pragma("unroll") for (int n = 0; n < 2; ++n) _Pragma("unroll") for (int k = 0; k < 2; ++k) dst[n][k] = *(const PG8_LAS bf16x8*)(lds + PG8_SB(b, h) + boff + n * 2048 + k * 1024); } while (0)
; #define PG8_MMA(ai, bj, At, Bt) do { __builtin_amdgcn_s_setprio(1); _Pragma("unroll") for (int m = 0; m < 4; ++m) _Pragma("unroll") for (int n = 0; n < 2; ++n) _Pragma("unroll") for (int k = 0; k < 2; ++k) \
;         acc[ai][bj][m][n] = __builtin_amdgcn_mfma_f32_16x16x32_bf16(Bt[n][k], At[m][k], acc[ai][bj][m][n], 0, 0, 0); __builtin_amdgcn_s_setprio(0); } while (0)
; #define PG8_WAIT_V(n) asm volatile("s_waitcnt vmcnt(" #n ")" ::: "memory")
; #define PG8_WAIT_L(n) asm volatile("s_waitcnt lgkmcnt(" #n ")" ::: "memory")
; #define PG8_BAR __builtin_amdgcn_s_barrier()
; #define PG8_SCHED __builtin_amdgcn_sched_barrier(0)
; template <class Epi, class Sched, bool ALIGN_EPI = false, bool SP2 = false>
; __device__ __forceinline__ void gemm_phase(PG8_LAS unsigned char* lds, const Gemm g, const Sched& S, const Epi& E) {
;     ...
;         for (int t = 0; t < nt; t += 2) {
;     ...
;             PG8_LDB(B0, 1, 0); PG8_LDB(B1, 1, 1); PG8_SCHED; PG8_LDA(At, 1, 0); PG8_STAGE(PG8_SA(0, 1), a2 + hstep, voffA);
;             PG8_WAIT_V(8); PG8_WAIT_L(0); PG8_BAR; PG8_MMA(0, 0, At, B0); PG8_MMA(0, 1, At, B1); PG8_BAR; PG8_SCHED;
;             PG8_LDA(At, 1, 1); PG8_STAGE(PG8_SB(1, 0), b3, voffB); PG8_STAGE(PG8_SB(1, 1), b3 + hstep, voffB); PG8_STAGE(PG8_SA(1, 0), a3, voffA);
;             PG8_WAIT_V(8); PG8_WAIT_L(0); PG8_BAR; PG8_MMA(1, 0, At, B0); PG8_MMA(1, 1, At, B1); PG8_BAR; PG8_SCHED;
	s_add_i32 s67, 0, 0x18000
	v_add_u32_e32 v157, s67, v150
	s_add_i32 s70, 0, 0x1c000
	ds_read_b128 v[144:147], v157
	ds_read_b128 v[158:161], v157 offset:1024
	ds_read_b128 v[164:167], v157 offset:2048
	ds_read_b128 v[168:171], v157 offset:3072
	v_add_u32_e32 v157, s70, v150
	ds_read_b128 v[172:175], v157
	ds_read_b128 v[176:179], v157 offset:1024
	ds_read_b128 v[180:183], v157 offset:2048
	ds_read_b128 v[184:187], v157 offset:3072
	s_add_u32 s38, s38, 0xb0000
	s_addc_u32 s39, s39, 0
	s_mov_b32 m0, s41
	v_lshl_add_u64 v[228:229], s[38:39], 0, v[128:129]
	ds_read_b128 v[188:191], v155 offset:32768
	ds_read_b128 v[192:195], v155 offset:33792
	ds_read_b128 v[196:199], v155 offset:34816
	ds_read_b128 v[200:203], v155 offset:35840
	ds_read_b128 v[204:207], v155 offset:36864
	ds_read_b128 v[208:211], v155 offset:37888
	ds_read_b128 v[212:215], v155 offset:38912
	ds_read_b128 v[216:219], v155 offset:39936
	global_load_lds_dwordx4 v[228:229], off
	v_lshl_add_u64 v[228:229], s[38:39], 0, v[132:133]
	s_mov_b32 m0, s43
	s_nop 0
	global_load_lds_dwordx4 v[228:229], off
	s_waitcnt vmcnt(8)
	s_waitcnt lgkmcnt(0)
	s_barrier
	s_waitcnt lgkmcnt(0)
	v_mfma_f32_16x16x32_bf16 v[124:127], v[144:147], v[188:191], v[124:127]
	v_mfma_f32_16x16x32_bf16 v[120:123], v[164:167], v[188:191], v[120:123]
	v_mfma_f32_16x16x32_bf16 v[108:111], v[144:147], v[196:199], v[108:111]
	v_mfma_f32_16x16x32_bf16 v[104:107], v[164:167], v[196:199], v[104:107]
	v_mfma_f32_16x16x32_bf16 v[92:95], v[144:147], v[204:207], v[92:95]
	v_mfma_f32_16x16x32_bf16 v[88:91], v[164:167], v[204:207], v[88:91]
	v_mfma_f32_16x16x32_bf16 v[76:79], v[144:147], v[212:215], v[76:79]
	v_mfma_f32_16x16x32_bf16 v[72:75], v[164:167], v[212:215], v[72:75]
	v_mfma_f32_16x16x32_bf16 v[124:127], v[158:161], v[192:195], v[124:127]
	v_mfma_f32_16x16x32_bf16 v[120:123], v[168:171], v[192:195], v[120:123]
	v_mfma_f32_16x16x32_bf16 v[108:111], v[158:161], v[200:203], v[108:111]
	v_mfma_f32_16x16x32_bf16 v[104:107], v[168:171], v[200:203], v[104:107]
	v_mfma_f32_16x16x32_bf16 v[92:95], v[158:161], v[208:211], v[92:95]
	v_mfma_f32_16x16x32_bf16 v[88:91], v[168:171], v[208:211], v[88:91]
	v_mfma_f32_16x16x32_bf16 v[76:79], v[158:161], v[216:219], v[76:79]
	v_mfma_f32_16x16x32_bf16 v[72:75], v[168:171], v[216:219], v[72:75]
	v_mfma_f32_16x16x32_bf16 v[116:119], v[172:175], v[188:191], v[116:119]
	v_mfma_f32_16x16x32_bf16 v[112:115], v[180:183], v[188:191], v[112:115]
	v_mfma_f32_16x16x32_bf16 v[100:103], v[172:175], v[196:199], v[100:103]
	v_mfma_f32_16x16x32_bf16 v[96:99], v[180:183], v[196:199], v[96:99]
	v_mfma_f32_16x16x32_bf16 v[84:87], v[172:175], v[204:207], v[84:87]
	v_mfma_f32_16x16x32_bf16 v[80:83], v[180:183], v[204:207], v[80:83]
	v_mfma_f32_16x16x32_bf16 v[68:71], v[172:175], v[212:215], v[68:71]
	v_mfma_f32_16x16x32_bf16 v[64:67], v[180:183], v[212:215], v[64:67]
	v_mfma_f32_16x16x32_bf16 v[116:119], v[176:179], v[192:195], v[116:119]
	v_mfma_f32_16x16x32_bf16 v[112:115], v[184:187], v[192:195], v[112:115]
	v_mfma_f32_16x16x32_bf16 v[100:103], v[176:179], v[200:203], v[100:103]
	v_mfma_f32_16x16x32_bf16 v[96:99], v[184:187], v[200:203], v[96:99]
	v_mfma_f32_16x16x32_bf16 v[84:87], v[176:179], v[208:211], v[84:87]
	v_mfma_f32_16x16x32_bf16 v[80:83], v[184:187], v[208:211], v[80:83]
	v_mfma_f32_16x16x32_bf16 v[68:71], v[176:179], v[216:219], v[68:71]
	v_mfma_f32_16x16x32_bf16 v[64:67], v[184:187], v[216:219], v[64:67]
	s_barrier
	s_add_i32 s38, s67, s3
	v_lshl_add_u64 v[220:221], v[220:221], 0, s[10:11]
	s_mov_b32 m0, s38
	ds_read_b128 v[188:191], v155 offset:49152
	ds_read_b128 v[192:195], v155 offset:50176
	ds_read_b128 v[196:199], v155 offset:51200
	ds_read_b128 v[200:203], v155 offset:52224
	ds_read_b128 v[204:207], v155 offset:53248
	ds_read_b128 v[208:211], v155 offset:54272
	ds_read_b128 v[212:215], v155 offset:55296
	ds_read_b128 v[216:219], v155 offset:56320
	global_load_lds_dwordx4 v[220:221], off
	s_add_i32 m0, s38, 0x2000
	s_add_u32 s36, s36, 0xb0080
	v_lshl_add_u64 v[220:221], v[222:223], 0, s[10:11]
	s_addc_u32 s37, s37, 0
	s_add_i32 s38, s70, s3
	global_load_lds_dwordx4 v[220:221], off
	v_lshl_add_u64 v[220:221], s[36:37], 0, v[130:131]
	s_mov_b32 m0, s38
	s_nop 0
	global_load_lds_dwordx4 v[220:221], off
	v_lshl_add_u64 v[220:221], s[36:37], 0, v[134:135]
	s_add_i32 m0, s38, 0x2000
	s_nop 0
	global_load_lds_dwordx4 v[220:221], off
	v_lshl_add_u64 v[220:221], v[224:225], 0, s[10:11]
	s_mov_b32 m0, s50
	s_nop 0
	global_load_lds_dwordx4 v[220:221], off
	v_lshl_add_u64 v[220:221], v[226:227], 0, s[10:11]
	s_mov_b32 m0, s51
	s_nop 0
	global_load_lds_dwordx4 v[220:221], off
	s_waitcnt vmcnt(8)
	s_waitcnt lgkmcnt(0)
	s_barrier
	s_waitcnt lgkmcnt(0)
	v_mfma_f32_16x16x32_bf16 v[60:63], v[144:147], v[188:191], v[60:63]
	v_mfma_f32_16x16x32_bf16 v[56:59], v[164:167], v[188:191], v[56:59]
	v_mfma_f32_16x16x32_bf16 v[44:47], v[144:147], v[196:199], v[44:47]
	v_mfma_f32_16x16x32_bf16 v[40:43], v[164:167], v[196:199], v[40:43]
	v_mfma_f32_16x16x32_bf16 v[28:31], v[144:147], v[204:207], v[28:31]
	v_mfma_f32_16x16x32_bf16 v[24:27], v[164:167], v[204:207], v[24:27]
	v_mfma_f32_16x16x32_bf16 v[12:15], v[144:147], v[212:215], v[12:15]
	v_mfma_f32_16x16x32_bf16 v[8:11], v[164:167], v[212:215], v[8:11]
	v_mfma_f32_16x16x32_bf16 v[60:63], v[158:161], v[192:195], v[60:63]
	v_mfma_f32_16x16x32_bf16 v[56:59], v[168:171], v[192:195], v[56:59]
	v_mfma_f32_16x16x32_bf16 v[44:47], v[158:161], v[200:203], v[44:47]
	v_mfma_f32_16x16x32_bf16 v[40:43], v[168:171], v[200:203], v[40:43]
	v_mfma_f32_16x16x32_bf16 v[28:31], v[158:161], v[208:211], v[28:31]
	v_mfma_f32_16x16x32_bf16 v[24:27], v[168:171], v[208:211], v[24:27]
	v_mfma_f32_16x16x32_bf16 v[12:15], v[158:161], v[216:219], v[12:15]
	v_mfma_f32_16x16x32_bf16 v[8:11], v[168:171], v[216:219], v[8:11]
	v_mfma_f32_16x16x32_bf16 v[52:55], v[172:175], v[188:191], v[52:55]
	v_mfma_f32_16x16x32_bf16 v[48:51], v[180:183], v[188:191], v[48:51]
	v_mfma_f32_16x16x32_bf16 v[36:39], v[172:175], v[196:199], v[36:39]
	v_mfma_f32_16x16x32_bf16 v[32:35], v[180:183], v[196:199], v[32:35]
	v_mfma_f32_16x16x32_bf16 v[20:23], v[172:175], v[204:207], v[20:23]
	v_mfma_f32_16x16x32_bf16 v[16:19], v[180:183], v[204:207], v[16:19]
	v_mfma_f32_16x16x32_bf16 v[4:7], v[172:175], v[212:215], v[4:7]
	v_mfma_f32_16x16x32_bf16 v[0:3], v[180:183], v[212:215], v[0:3]
	v_mfma_f32_16x16x32_bf16 v[52:55], v[176:179], v[192:195], v[52:55]
	v_mfma_f32_16x16x32_bf16 v[48:51], v[184:187], v[192:195], v[48:51]
	v_mfma_f32_16x16x32_bf16 v[36:39], v[176:179], v[200:203], v[36:39]
	v_mfma_f32_16x16x32_bf16 v[32:35], v[184:187], v[200:203], v[32:35]
	v_mfma_f32_16x16x32_bf16 v[20:23], v[176:179], v[208:211], v[20:23]
	v_mfma_f32_16x16x32_bf16 v[16:19], v[184:187], v[208:211], v[16:19]
	v_mfma_f32_16x16x32_bf16 v[4:7], v[176:179], v[216:219], v[4:7]
	v_mfma_f32_16x16x32_bf16 v[0:3], v[184:187], v[216:219], v[0:3]
	s_barrier
	s_add_i32 s66, s66, 2
	s_add_u32 s34, s34, 0x100
	s_addc_u32 s35, s35, 0
	s_add_u32 s64, s64, 0x100
	s_addc_u32 s65, s65, 0
	s_cmp_gt_u32 s66, 41
	s_cbranch_scc0 .LBB0_1085
; #define PG8_BAR __builtin_amdgcn_s_barrier()
; template <class Epi, class Sched, bool ALIGN_EPI = false, bool SP2 = false>
; __device__ __forceinline__ void gemm_phase(PG8_LAS unsigned char* lds, const Gemm g, const Sched& S, const Epi& E) {
;     ...
;         if constexpr (ALIGN_EPI) { if (wr == 0) PG8_BAR; }
.Lpeel_exit5:
	s_and_b64 vcc, exec, s[20:21]
	s_cbranch_vccz .LBB0_1088
	s_barrier

; #define PG8_STAGE(bufoff, gbase, voff) do { _Pragma("unroll") for (int _i = 0; _i < 2; ++_i) \
;         __builtin_amdgcn_global_load_lds((const unsigned*)((const char*)(gbase) + (voff)[_i]), (PG8_LAS unsigned*)(lds + (bufoff) + ldsw + _i * 8192), 16, 0, 0); } while (0)
; #define PG8_LDA(dst, b, h) do { _Pragma("unroll") for (int m = 0; m < 4; ++m) _Pragma("unroll") for (int k = 0; k < 2; ++k) dst[m][k] = *(const PG8_LAS bf16x8*)(lds + PG8_SA(b, h) + aoff + m * 2048 + k * 1024); } while (0)
; #define PG8_LDB(dst, b, h) do { _Pragma("unroll") for (int n = 0; n < 2; ++n) _Pragma("unroll") for (int k = 0; k < 2; ++k) dst[n][k] = *(const PG8_LAS bf16x8*)(lds + PG8_SB(b, h) + boff + n * 2048 + k * 1024); } while (0)
; template <class Epi, class Sched, bool ALIGN_EPI = false, bool SP2 = false>
; __device__ __forceinline__ void gemm_phase(PG8_LAS unsigned char* lds, const Gemm g, const Sched& S, const Epi& E) {
;     ...
;         const bool has_next = S.next(ui + 1, nxt);
;         const char* nA = has_next ? (const char*)g.A + (size_t)nxt.pm * tstep : cA; const char* nB = has_next ? (const char*)g.Bt + (size_t)nxt.pn * tstep : cB;
;         for (int t = 0; t < nt; t += 2) {
;             const bool last = (t == nt - 2);
;             const char* a1 = cA + (size_t)(t + 1) * kstep;
;             const char* a2 = last ? nA : cA + (size_t)(t + 2) * kstep; const char* b2 = last ? nB : cB + (size_t)(t + 2) * kstep;
;             const char* a3 = a2 + kstep; const char* b3 = b2 + kstep;
;             if (last && has_next) S.a_ready(nxt);
;             if constexpr (SP2) {
;             PG8_LDB(B0, 0, 0); PG8_LDB(B1, 0, 1); PG8_SCHED; PG8_LDA(At, 0, 0); PG8_STAGE(PG8_SA(1, 1), a1 + hstep, voffA);
;             PG8_WAIT_V(8); PG8_WAIT_L(0); PG8_BAR; PG8_MMA(0, 0, At, B0); PG8_MMA(0, 1, At, B1); PG8_BAR; PG8_SCHED;
;             PG8_LDA(At, 0, 1); PG8_STAGE(PG8_SB(0, 0), b2, voffB); PG8_STAGE(PG8_SB(0, 1), b2 + hstep, voffB); PG8_STAGE(PG8_SA(0, 0), a2, voffA);
;             PG8_WAIT_V(8); PG8_WAIT_L(0); PG8_BAR; PG8_MMA(1, 0, At, B0); PG8_MMA(1, 1, At, B1); PG8_BAR; PG8_SCHED;
;     ...
;         for (int a = 0; a < 2; ++a)
; #pragma unroll
;             for (int b = 0; b < 2; ++b)
; #pragma unroll
;                 for (int m = 0; m < 4; ++m)
; #pragma unroll
;                     for (int n = 0; n < 2; ++n) acc[a][b][m][n] = (f32x4){0.f, 0.f, 0.f, 0.f};
.LBB0_1262:
	s_ashr_i32 s29, s28, 31
	s_lshl_b64 s[30:31], s[28:29], 19
	s_add_u32 s30, s44, s30
	s_addc_u32 s31, s45, s31
	s_and_b64 s[34:35], s[6:7], exec
	s_cselect_b32 s29, s31, s41
	s_cselect_b32 s37, s30, s40
	s_ashr_i32 s27, s26, 31
	s_lshl_b64 s[34:35], s[26:27], 19
	s_add_u32 s34, s70, s34
	s_addc_u32 s35, s71, s35
	s_and_b64 s[48:49], s[6:7], exec
	s_cselect_b32 s27, s35, s47
	s_cselect_b32 s61, s34, s46
	s_add_u32 s40, s40, 0x40080
	s_addc_u32 s41, s41, 0
	s_add_u32 s62, s46, 0x100
	s_addc_u32 s63, s47, 0
	s_mov_b32 s64, -2
	s_waitcnt lgkmcnt(0)
	s_waitcnt vmcnt(0)
	ds_read_b128 v[144:147], v155
	ds_read_b128 v[164:167], v155 offset:1024
	ds_read_b128 v[168:171], v155 offset:2048
	ds_read_b128 v[172:175], v155 offset:3072
	ds_read_b128 v[176:179], v156
	ds_read_b128 v[180:183], v156 offset:1024
	ds_read_b128 v[184:187], v156 offset:2048
	ds_read_b128 v[188:191], v156 offset:3072
	s_add_u32 s46, s40, 0xfffc0080
	s_addc_u32 s47, s41, -1
	s_cmp_eq_u32 s64, 12
	s_cselect_b32 s49, s29, s47
	s_cselect_b32 s48, s37, s46
	s_cselect_b32 s47, s27, s63
	s_cselect_b32 s46, s61, s62
	v_lshl_add_u64 v[148:149], s[40:41], 0, v[136:137]
	s_add_i32 m0, s33, 0xc000
	ds_read_b128 v[192:195], v157
	ds_read_b128 v[196:199], v157 offset:1024
	ds_read_b128 v[200:203], v157 offset:2048
	ds_read_b128 v[204:207], v157 offset:3072
	ds_read_b128 v[208:211], v157 offset:4096
	ds_read_b128 v[212:215], v157 offset:5120
	ds_read_b128 v[216:219], v157 offset:6144
	ds_read_b128 v[220:223], v157 offset:7168
	global_load_lds_dwordx4 v[148:149], off
	v_lshl_add_u64 v[148:149], s[40:41], 0, v[138:139]
	s_add_i32 m0, s33, 0xe000
	s_nop 0
	global_load_lds_dwordx4 v[148:149], off
	s_waitcnt vmcnt(8)
	s_waitcnt lgkmcnt(0)
	s_barrier
	s_waitcnt lgkmcnt(0)
	v_mfma_f32_16x16x32_bf16 v[124:127], v[144:147], v[192:195], 0
	v_mfma_f32_16x16x32_bf16 v[120:123], v[168:171], v[192:195], 0
	v_mfma_f32_16x16x32_bf16 v[108:111], v[144:147], v[200:203], 0
	v_mfma_f32_16x16x32_bf16 v[104:107], v[168:171], v[200:203], 0
	v_mfma_f32_16x16x32_bf16 v[92:95], v[144:147], v[208:211], 0
	v_mfma_f32_16x16x32_bf16 v[88:91], v[168:171], v[208:211], 0
	v_mfma_f32_16x16x32_bf16 v[76:79], v[144:147], v[216:219], 0
	v_mfma_f32_16x16x32_bf16 v[72:75], v[168:171], v[216:219], 0
	v_mfma_f32_16x16x32_bf16 v[124:127], v[164:167], v[196:199], v[124:127]
	v_mfma_f32_16x16x32_bf16 v[120:123], v[172:175], v[196:199], v[120:123]
	v_mfma_f32_16x16x32_bf16 v[108:111], v[164:167], v[204:207], v[108:111]
	v_mfma_f32_16x16x32_bf16 v[104:107], v[172:175], v[204:207], v[104:107]
	v_mfma_f32_16x16x32_bf16 v[92:95], v[164:167], v[212:215], v[92:95]
	v_mfma_f32_16x16x32_bf16 v[88:91], v[172:175], v[212:215], v[88:91]
	v_mfma_f32_16x16x32_bf16 v[76:79], v[164:167], v[220:223], v[76:79]
	v_mfma_f32_16x16x32_bf16 v[72:75], v[172:175], v[220:223], v[72:75]
	v_mfma_f32_16x16x32_bf16 v[116:119], v[176:179], v[192:195], 0
	v_mfma_f32_16x16x32_bf16 v[112:115], v[184:187], v[192:195], 0
	v_mfma_f32_16x16x32_bf16 v[100:103], v[176:179], v[200:203], 0
	v_mfma_f32_16x16x32_bf16 v[96:99], v[184:187], v[200:203], 0
	v_mfma_f32_16x16x32_bf16 v[84:87], v[176:179], v[208:211], 0
	v_mfma_f32_16x16x32_bf16 v[80:83], v[184:187], v[208:211], 0
	v_mfma_f32_16x16x32_bf16 v[68:71], v[176:179], v[216:219], 0
	v_mfma_f32_16x16x32_bf16 v[64:67], v[184:187], v[216:219], 0
	v_mfma_f32_16x16x32_bf16 v[116:119], v[180:183], v[196:199], v[116:119]
	v_mfma_f32_16x16x32_bf16 v[112:115], v[188:191], v[196:199], v[112:115]
	v_mfma_f32_16x16x32_bf16 v[100:103], v[180:183], v[204:207], v[100:103]
	v_mfma_f32_16x16x32_bf16 v[96:99], v[188:191], v[204:207], v[96:99]
	v_mfma_f32_16x16x32_bf16 v[84:87], v[180:183], v[212:215], v[84:87]
	v_mfma_f32_16x16x32_bf16 v[80:83], v[188:191], v[212:215], v[80:83]
	v_mfma_f32_16x16x32_bf16 v[68:71], v[180:183], v[220:223], v[68:71]
	v_mfma_f32_16x16x32_bf16 v[64:67], v[188:191], v[220:223], v[64:67]
	s_barrier
	s_add_i32 s65, s59, s3
	v_lshl_add_u64 v[148:149], s[46:47], 0, v[130:131]
	s_mov_b32 m0, s65
	ds_read_b128 v[192:195], v157 offset:16384
	ds_read_b128 v[196:199], v157 offset:17408
	ds_read_b128 v[200:203], v157 offset:18432
	ds_read_b128 v[204:207], v157 offset:19456
	ds_read_b128 v[208:211], v157 offset:20480
	ds_read_b128 v[212:215], v157 offset:21504
	ds_read_b128 v[216:219], v157 offset:22528
	ds_read_b128 v[220:223], v157 offset:23552
	global_load_lds_dwordx4 v[148:149], off
	s_add_i32 m0, s65, 0x2000
	s_add_u32 s66, s46, 0x40000
	v_lshl_add_u64 v[160:161], s[46:47], 0, v[134:135]
	s_addc_u32 s67, s47, 0
	s_add_i32 s65, s60, s3
	global_load_lds_dwordx4 v[160:161], off
	v_lshl_add_u64 v[224:225], s[66:67], 0, v[130:131]
	s_mov_b32 m0, s65
	v_lshl_add_u64 v[226:227], s[48:49], 0, v[132:133]
	global_load_lds_dwordx4 v[224:225], off
	v_lshl_add_u64 v[224:225], s[66:67], 0, v[134:135]
	s_add_i32 m0, s65, 0x2000
	s_nop 0
	global_load_lds_dwordx4 v[224:225], off
	v_lshl_add_u64 v[224:225], s[48:49], 0, v[128:129]
	s_mov_b32 m0, s33
	s_nop 0
	global_load_lds_dwordx4 v[224:225], off
	s_mov_b32 m0, s39
	s_nop 0
	global_load_lds_dwordx4 v[226:227], off
	s_waitcnt vmcnt(8)
	s_waitcnt lgkmcnt(0)
	s_barrier
; #define PG8_STAGE(bufoff, gbase, voff) do { _Pragma("unroll") for (int _i = 0; _i < 2; ++_i) \
;         __builtin_amdgcn_global_load_lds((const unsigned*)((const char*)(gbase) + (voff)[_i]), (PG8_LAS unsigned*)(lds + (bufoff) + ldsw + _i * 8192), 16, 0, 0); } while (0)
; #define PG8_LDA(dst, b, h) do { _Pragma("unroll") for (int m = 0; m < 4; ++m) _Pragma("unroll") for (int k = 0; k < 2; ++k) dst[m][k] = *(const PG8_LAS bf16x8*)(lds + PG8_SA(b, h) + aoff + m * 2048 + k * 1024); } while (0)
; #define PG8_LDB(dst, b, h) do { _Pragma("unroll") for (int n = 0; n < 2; ++n) _Pragma("unroll") for (int k = 0; k < 2; ++k) dst[n][k] = *(const PG8_LAS bf16x8*)(lds + PG8_SB(b, h) + boff + n * 2048 + k * 1024); } while (0)
; #define PG8_MMA(ai, bj, At, Bt) do { __builtin_amdgcn_s_setprio(1); _Pragma("unroll") for (int m = 0; m < 4; ++m) _Pragma("unroll") for (int n = 0; n < 2; ++n) _Pragma("unroll") for (int k = 0; k < 2; ++k) \
;         acc[ai][bj][m][n] = __builtin_amdgcn_mfma_f32_16x16x32_bf16(Bt[n][k], At[m][k], acc[ai][bj][m][n], 0, 0, 0); __builtin_amdgcn_s_setprio(0); } while (0)
; #define PG8_WAIT_V(n) asm volatile("s_waitcnt vmcnt(" #n ")" ::: "memory")
; #define PG8_WAIT_L(n) asm volatile("s_waitcnt lgkmcnt(" #n ")" ::: "memory")
; #define PG8_BAR __builtin_amdgcn_s_barrier()
; #define PG8_SCHED __builtin_amdgcn_sched_barrier(0)
; template <class Epi, class Sched, bool ALIGN_EPI = false, bool SP2 = false>
; __device__ __forceinline__ void gemm_phase(PG8_LAS unsigned char* lds, const Gemm g, const Sched& S, const Epi& E) {
;     ...
;             PG8_WAIT_V(8); PG8_WAIT_L(0); PG8_BAR; PG8_MMA(1, 0, At, B0); PG8_MMA(1, 1, At, B1); PG8_BAR; PG8_SCHED;
;             PG8_LDB(B0, 1, 0); PG8_LDB(B1, 1, 1); PG8_SCHED; PG8_LDA(At, 1, 0); PG8_STAGE(PG8_SA(0, 1), a2 + hstep, voffA);
;             PG8_WAIT_V(8); PG8_WAIT_L(0); PG8_BAR; PG8_MMA(0, 0, At, B0); PG8_MMA(0, 1, At, B1); PG8_BAR; PG8_SCHED;
	s_waitcnt lgkmcnt(0)
	v_mfma_f32_16x16x32_bf16 v[60:63], v[144:147], v[192:195], 0
	v_mfma_f32_16x16x32_bf16 v[56:59], v[168:171], v[192:195], 0
	v_mfma_f32_16x16x32_bf16 v[44:47], v[144:147], v[200:203], 0
	v_mfma_f32_16x16x32_bf16 v[40:43], v[168:171], v[200:203], 0
	v_mfma_f32_16x16x32_bf16 v[28:31], v[144:147], v[208:211], 0
	v_mfma_f32_16x16x32_bf16 v[24:27], v[168:171], v[208:211], 0
	v_mfma_f32_16x16x32_bf16 v[12:15], v[144:147], v[216:219], 0
	v_mfma_f32_16x16x32_bf16 v[8:11], v[168:171], v[216:219], 0
	v_mfma_f32_16x16x32_bf16 v[60:63], v[164:167], v[196:199], v[60:63]
	v_mfma_f32_16x16x32_bf16 v[56:59], v[172:175], v[196:199], v[56:59]
	v_mfma_f32_16x16x32_bf16 v[44:47], v[164:167], v[204:207], v[44:47]
	v_mfma_f32_16x16x32_bf16 v[40:43], v[172:175], v[204:207], v[40:43]
	v_mfma_f32_16x16x32_bf16 v[28:31], v[164:167], v[212:215], v[28:31]
	v_mfma_f32_16x16x32_bf16 v[24:27], v[172:175], v[212:215], v[24:27]
	v_mfma_f32_16x16x32_bf16 v[12:15], v[164:167], v[220:223], v[12:15]
	v_mfma_f32_16x16x32_bf16 v[8:11], v[172:175], v[220:223], v[8:11]
	v_mfma_f32_16x16x32_bf16 v[52:55], v[176:179], v[192:195], 0
	v_mfma_f32_16x16x32_bf16 v[48:51], v[184:187], v[192:195], 0
	v_mfma_f32_16x16x32_bf16 v[36:39], v[176:179], v[200:203], 0
	v_mfma_f32_16x16x32_bf16 v[32:35], v[184:187], v[200:203], 0
	v_mfma_f32_16x16x32_bf16 v[20:23], v[176:179], v[208:211], 0
	v_mfma_f32_16x16x32_bf16 v[16:19], v[184:187], v[208:211], 0
	v_mfma_f32_16x16x32_bf16 v[4:7], v[176:179], v[216:219], 0
	v_mfma_f32_16x16x32_bf16 v[0:3], v[184:187], v[216:219], 0
	v_mfma_f32_16x16x32_bf16 v[52:55], v[180:183], v[196:199], v[52:55]
	v_mfma_f32_16x16x32_bf16 v[48:51], v[188:191], v[196:199], v[48:51]
	v_mfma_f32_16x16x32_bf16 v[36:39], v[180:183], v[204:207], v[36:39]
	v_mfma_f32_16x16x32_bf16 v[32:35], v[188:191], v[204:207], v[32:35]
	v_mfma_f32_16x16x32_bf16 v[20:23], v[180:183], v[212:215], v[20:23]
	v_mfma_f32_16x16x32_bf16 v[16:19], v[188:191], v[212:215], v[16:19]
	v_mfma_f32_16x16x32_bf16 v[4:7], v[180:183], v[220:223], v[4:7]
	v_mfma_f32_16x16x32_bf16 v[0:3], v[188:191], v[220:223], v[0:3]
	s_barrier
	s_add_i32 s65, 0, 0x18000
	v_add_u32_e32 v159, s65, v152
	s_add_i32 s66, 0, 0x1c000
	ds_read_b128 v[144:147], v159
	ds_read_b128 v[164:167], v159 offset:1024
	ds_read_b128 v[168:171], v159 offset:2048
	ds_read_b128 v[172:175], v159 offset:3072
	v_add_u32_e32 v159, s66, v152
	ds_read_b128 v[176:179], v159
	ds_read_b128 v[180:183], v159 offset:1024
	ds_read_b128 v[184:187], v159 offset:2048
	ds_read_b128 v[188:191], v159 offset:3072
	s_add_u32 s48, s48, 0x40000
	s_addc_u32 s49, s49, 0
	s_mov_b32 m0, s43
	v_lshl_add_u64 v[228:229], s[48:49], 0, v[128:129]
	ds_read_b128 v[192:195], v157 offset:32768
	ds_read_b128 v[196:199], v157 offset:33792
	ds_read_b128 v[200:203], v157 offset:34816
	ds_read_b128 v[204:207], v157 offset:35840
	ds_read_b128 v[208:211], v157 offset:36864
	ds_read_b128 v[212:215], v157 offset:37888
	ds_read_b128 v[216:219], v157 offset:38912
	ds_read_b128 v[220:223], v157 offset:39936
	global_load_lds_dwordx4 v[228:229], off
	v_lshl_add_u64 v[228:229], s[48:49], 0, v[132:133]
	s_mov_b32 m0, s50
	s_nop 0
	global_load_lds_dwordx4 v[228:229], off
	s_waitcnt vmcnt(8)
	s_waitcnt lgkmcnt(0)
	s_barrier
	s_waitcnt lgkmcnt(0)
	v_mfma_f32_16x16x32_bf16 v[124:127], v[144:147], v[192:195], v[124:127]
	v_mfma_f32_16x16x32_bf16 v[120:123], v[168:171], v[192:195], v[120:123]
	v_mfma_f32_16x16x32_bf16 v[108:111], v[144:147], v[200:203], v[108:111]
	v_mfma_f32_16x16x32_bf16 v[104:107], v[168:171], v[200:203], v[104:107]
	v_mfma_f32_16x16x32_bf16 v[92:95], v[144:147], v[208:211], v[92:95]
	v_mfma_f32_16x16x32_bf16 v[88:91], v[168:171], v[208:211], v[88:91]
	v_mfma_f32_16x16x32_bf16 v[76:79], v[144:147], v[216:219], v[76:79]
	v_mfma_f32_16x16x32_bf16 v[72:75], v[168:171], v[216:219], v[72:75]
	v_mfma_f32_16x16x32_bf16 v[124:127], v[164:167], v[196:199], v[124:127]
	v_mfma_f32_16x16x32_bf16 v[120:123], v[172:175], v[196:199], v[120:123]
	v_mfma_f32_16x16x32_bf16 v[108:111], v[164:167], v[204:207], v[108:111]
	v_mfma_f32_16x16x32_bf16 v[104:107], v[172:175], v[204:207], v[104:107]
	v_mfma_f32_16x16x32_bf16 v[92:95], v[164:167], v[212:215], v[92:95]
	v_mfma_f32_16x16x32_bf16 v[88:91], v[172:175], v[212:215], v[88:91]
	v_mfma_f32_16x16x32_bf16 v[76:79], v[164:167], v[220:223], v[76:79]
	v_mfma_f32_16x16x32_bf16 v[72:75], v[172:175], v[220:223], v[72:75]
	v_mfma_f32_16x16x32_bf16 v[116:119], v[176:179], v[192:195], v[116:119]
	v_mfma_f32_16x16x32_bf16 v[112:115], v[184:187], v[192:195], v[112:115]
	v_mfma_f32_16x16x32_bf16 v[100:103], v[176:179], v[200:203], v[100:103]
	v_mfma_f32_16x16x32_bf16 v[96:99], v[184:187], v[200:203], v[96:99]
	v_mfma_f32_16x16x32_bf16 v[84:87], v[176:179], v[208:211], v[84:87]
	v_mfma_f32_16x16x32_bf16 v[80:83], v[184:187], v[208:211], v[80:83]
	v_mfma_f32_16x16x32_bf16 v[68:71], v[176:179], v[216:219], v[68:71]
	v_mfma_f32_16x16x32_bf16 v[64:67], v[184:187], v[216:219], v[64:67]
	v_mfma_f32_16x16x32_bf16 v[116:119], v[180:183], v[196:199], v[116:119]
	v_mfma_f32_16x16x32_bf16 v[112:115], v[188:191], v[196:199], v[112:115]
	v_mfma_f32_16x16x32_bf16 v[100:103], v[180:183], v[204:207], v[100:103]
	v_mfma_f32_16x16x32_bf16 v[96:99], v[188:191], v[204:207], v[96:99]
	v_mfma_f32_16x16x32_bf16 v[84:87], v[180:183], v[212:215], v[84:87]
	v_mfma_f32_16x16x32_bf16 v[80:83], v[188:191], v[212:215], v[80:83]
	v_mfma_f32_16x16x32_bf16 v[68:71], v[180:183], v[220:223], v[68:71]
	v_mfma_f32_16x16x32_bf16 v[64:67], v[188:191], v[220:223], v[64:67]
	s_barrier
; #define PG8_STAGE(bufoff, gbase, voff) do { _Pragma("unroll") for (int _i = 0; _i < 2; ++_i) \
;         __builtin_amdgcn_global_load_lds((const unsigned*)((const char*)(gbase) + (voff)[_i]), (PG8_LAS unsigned*)(lds + (bufoff) + ldsw + _i * 8192), 16, 0, 0); } while (0)
; #define PG8_LDA(dst, b, h) do { _Pragma("unroll") for (int m = 0; m < 4; ++m) _Pragma("unroll") for (int k = 0; k < 2; ++k) dst[m][k] = *(const PG8_LAS bf16x8*)(lds + PG8_SA(b, h) + aoff + m * 2048 + k * 1024); } while (0)
; #define PG8_LDB(dst, b, h) do { _Pragma("unroll") for (int n = 0; n < 2; ++n) _Pragma("unroll") for (int k = 0; k < 2; ++k) dst[n][k] = *(const PG8_LAS bf16x8*)(lds + PG8_SB(b, h) + boff + n * 2048 + k * 1024); } while (0)
; #define PG8_MMA(ai, bj, At, Bt) do { __builtin_amdgcn_s_setprio(1); _Pragma("unroll") for (int m = 0; m < 4; ++m) _Pragma("unroll") for (int n = 0; n < 2; ++n) _Pragma("unroll") for (int k = 0; k < 2; ++k) \
;         acc[ai][bj][m][n] = __builtin_amdgcn_mfma_f32_16x16x32_bf16(Bt[n][k], At[m][k], acc[ai][bj][m][n], 0, 0, 0); __builtin_amdgcn_s_setprio(0); } while (0)
; #define PG8_BAR __builtin_amdgcn_s_barrier()
; template <class Epi, class Sched, bool ALIGN_EPI = false, bool SP2 = false>
; __device__ __forceinline__ void gemm_phase(PG8_LAS unsigned char* lds, const Gemm g, const Sched& S, const Epi& E) {
;     ...
;             if constexpr (SP2) {
;             PG8_LDB(B0, 0, 0); PG8_LDB(B1, 0, 1); PG8_SCHED; PG8_LDA(At, 0, 0); PG8_STAGE(PG8_SA(1, 1), a1 + hstep, voffA);
;             PG8_WAIT_V(8); PG8_WAIT_L(0); PG8_BAR; PG8_MMA(0, 0, At, B0); PG8_MMA(0, 1, At, B1); PG8_BAR; PG8_SCHED;
;             PG8_LDA(At, 0, 1); PG8_STAGE(PG8_SB(0, 0), b2, voffB); PG8_STAGE(PG8_SB(0, 1), b2 + hstep, voffB); PG8_STAGE(PG8_SA(0, 0), a2, voffA);
;             PG8_WAIT_V(8); PG8_WAIT_L(0); PG8_BAR; PG8_MMA(1, 0, At, B0); PG8_MMA(1, 1, At, B1); PG8_BAR; PG8_SCHED;
;             PG8_LDB(B0, 1, 0); PG8_LDB(B1, 1, 1); PG8_SCHED; PG8_LDA(At, 1, 0); PG8_STAGE(PG8_SA(0, 1), a2 + hstep, voffA);
;             PG8_WAIT_V(8); PG8_WAIT_L(0); PG8_BAR; PG8_MMA(0, 0, At, B0); PG8_MMA(0, 1, At, B1); PG8_BAR; PG8_SCHED;
;             PG8_LDA(At, 1, 1); PG8_STAGE(PG8_SB(1, 0), b3, voffB); PG8_STAGE(PG8_SB(1, 1), b3 + hstep, voffB); PG8_STAGE(PG8_SA(1, 0), a3, voffA);
;             PG8_WAIT_V(8); PG8_WAIT_L(0); PG8_BAR; PG8_MMA(1, 0, At, B0); PG8_MMA(1, 1, At, B1); PG8_BAR; PG8_SCHED;
	s_add_i32 s48, s65, s3
	v_lshl_add_u64 v[148:149], v[148:149], 0, s[16:17]
	s_mov_b32 m0, s48
	ds_read_b128 v[192:195], v157 offset:49152
	ds_read_b128 v[196:199], v157 offset:50176
	ds_read_b128 v[200:203], v157 offset:51200
	ds_read_b128 v[204:207], v157 offset:52224
	ds_read_b128 v[208:211], v157 offset:53248
	ds_read_b128 v[212:215], v157 offset:54272
	ds_read_b128 v[216:219], v157 offset:55296
	ds_read_b128 v[220:223], v157 offset:56320
	global_load_lds_dwordx4 v[148:149], off
	s_add_i32 m0, s48, 0x2000
	s_add_u32 s46, s46, 0x40080
	v_lshl_add_u64 v[148:149], v[160:161], 0, s[16:17]
	s_addc_u32 s47, s47, 0
	s_add_i32 s48, s66, s3
	global_load_lds_dwordx4 v[148:149], off
	v_lshl_add_u64 v[148:149], s[46:47], 0, v[130:131]
	s_mov_b32 m0, s48
	s_nop 0
	global_load_lds_dwordx4 v[148:149], off
	v_lshl_add_u64 v[148:149], s[46:47], 0, v[134:135]
	s_add_i32 m0, s48, 0x2000
	s_nop 0
	global_load_lds_dwordx4 v[148:149], off
	v_lshl_add_u64 v[148:149], v[224:225], 0, s[16:17]
	s_mov_b32 m0, s55
	s_nop 0
	global_load_lds_dwordx4 v[148:149], off
	v_lshl_add_u64 v[148:149], v[226:227], 0, s[16:17]
	s_mov_b32 m0, s58
	s_nop 0
	global_load_lds_dwordx4 v[148:149], off
	s_waitcnt vmcnt(8)
	s_waitcnt lgkmcnt(0)
	s_barrier
	s_waitcnt lgkmcnt(0)
	v_mfma_f32_16x16x32_bf16 v[60:63], v[144:147], v[192:195], v[60:63]
	v_mfma_f32_16x16x32_bf16 v[56:59], v[168:171], v[192:195], v[56:59]
	v_mfma_f32_16x16x32_bf16 v[44:47], v[144:147], v[200:203], v[44:47]
	v_mfma_f32_16x16x32_bf16 v[40:43], v[168:171], v[200:203], v[40:43]
	v_mfma_f32_16x16x32_bf16 v[28:31], v[144:147], v[208:211], v[28:31]
	v_mfma_f32_16x16x32_bf16 v[24:27], v[168:171], v[208:211], v[24:27]
	v_mfma_f32_16x16x32_bf16 v[12:15], v[144:147], v[216:219], v[12:15]
	v_mfma_f32_16x16x32_bf16 v[8:11], v[168:171], v[216:219], v[8:11]
	v_mfma_f32_16x16x32_bf16 v[60:63], v[164:167], v[196:199], v[60:63]
	v_mfma_f32_16x16x32_bf16 v[56:59], v[172:175], v[196:199], v[56:59]
	v_mfma_f32_16x16x32_bf16 v[44:47], v[164:167], v[204:207], v[44:47]
	v_mfma_f32_16x16x32_bf16 v[40:43], v[172:175], v[204:207], v[40:43]
	v_mfma_f32_16x16x32_bf16 v[28:31], v[164:167], v[212:215], v[28:31]
	v_mfma_f32_16x16x32_bf16 v[24:27], v[172:175], v[212:215], v[24:27]
	v_mfma_f32_16x16x32_bf16 v[12:15], v[164:167], v[220:223], v[12:15]
	v_mfma_f32_16x16x32_bf16 v[8:11], v[172:175], v[220:223], v[8:11]
	v_mfma_f32_16x16x32_bf16 v[52:55], v[176:179], v[192:195], v[52:55]
	v_mfma_f32_16x16x32_bf16 v[48:51], v[184:187], v[192:195], v[48:51]
	v_mfma_f32_16x16x32_bf16 v[36:39], v[176:179], v[200:203], v[36:39]
	v_mfma_f32_16x16x32_bf16 v[32:35], v[184:187], v[200:203], v[32:35]
	v_mfma_f32_16x16x32_bf16 v[20:23], v[176:179], v[208:211], v[20:23]
	v_mfma_f32_16x16x32_bf16 v[16:19], v[184:187], v[208:211], v[16:19]
	v_mfma_f32_16x16x32_bf16 v[4:7], v[176:179], v[216:219], v[4:7]
	v_mfma_f32_16x16x32_bf16 v[0:3], v[184:187], v[216:219], v[0:3]
	v_mfma_f32_16x16x32_bf16 v[52:55], v[180:183], v[196:199], v[52:55]
	v_mfma_f32_16x16x32_bf16 v[48:51], v[188:191], v[196:199], v[48:51]
	v_mfma_f32_16x16x32_bf16 v[36:39], v[180:183], v[204:207], v[36:39]
	v_mfma_f32_16x16x32_bf16 v[32:35], v[188:191], v[204:207], v[32:35]
	v_mfma_f32_16x16x32_bf16 v[20:23], v[180:183], v[212:215], v[20:23]
	v_mfma_f32_16x16x32_bf16 v[16:19], v[188:191], v[212:215], v[16:19]
	v_mfma_f32_16x16x32_bf16 v[4:7], v[180:183], v[220:223], v[4:7]
	v_mfma_f32_16x16x32_bf16 v[0:3], v[188:191], v[220:223], v[0:3]
	s_barrier
	s_add_i32 s64, s64, 2
	s_add_u32 s40, s40, 0x100
	s_addc_u32 s41, s41, 0
	s_add_u32 s62, s62, 0x100
	s_addc_u32 s63, s63, 0
	s_cmp_gt_u32 s64, 13
	s_cbranch_scc1 .Lpeel_exit6
.LBB0_1263:
	ds_read_b128 v[144:147], v155
	ds_read_b128 v[164:167], v155 offset:1024
	ds_read_b128 v[168:171], v155 offset:2048
	ds_read_b128 v[172:175], v155 offset:3072
	ds_read_b128 v[176:179], v156
	ds_read_b128 v[180:183], v156 offset:1024
	ds_read_b128 v[184:187], v156 offset:2048
	ds_read_b128 v[188:191], v156 offset:3072
	s_add_u32 s46, s40, 0xfffc0080
	s_addc_u32 s47, s41, -1
	s_cmp_eq_u32 s64, 12
	s_cselect_b32 s49, s29, s47
	s_cselect_b32 s48, s37, s46
	s_cselect_b32 s47, s27, s63
	s_cselect_b32 s46, s61, s62
	v_lshl_add_u64 v[148:149], s[40:41], 0, v[136:137]
	s_add_i32 m0, s33, 0xc000
	ds_read_b128 v[192:195], v157
	ds_read_b128 v[196:199], v157 offset:1024
	ds_read_b128 v[200:203], v157 offset:2048
	ds_read_b128 v[204:207], v157 offset:3072
	ds_read_b128 v[208:211], v157 offset:4096
	ds_read_b128 v[212:215], v157 offset:5120
	ds_read_b128 v[216:219], v157 offset:6144
	ds_read_b128 v[220:223], v157 offset:7168
	global_load_lds_dwordx4 v[148:149], off
	v_lshl_add_u64 v[148:149], s[40:41], 0, v[138:139]
	s_add_i32 m0, s33, 0xe000
	s_nop 0
	global_load_lds_dwordx4 v[148:149], off
	s_waitcnt vmcnt(8)
	s_waitcnt lgkmcnt(0)
	s_barrier
; #define PG8_STAGE(bufoff, gbase, voff) do { _Pragma("unroll") for (int _i = 0; _i < 2; ++_i) \
;         __builtin_amdgcn_global_load_lds((const unsigned*)((const char*)(gbase) + (voff)[_i]), (PG8_LAS unsigned*)(lds + (bufoff) + ldsw + _i * 8192), 16, 0, 0); } while (0)
; #define PG8_LDA(dst, b, h) do { _Pragma("unroll") for (int m = 0; m < 4; ++m) _Pragma("unroll") for (int k = 0; k < 2; ++k) dst[m][k] = *(const PG8_LAS bf16x8*)(lds + PG8_SA(b, h) + aoff + m * 2048 + k * 1024); } while (0)
; #define PG8_LDB(dst, b, h) do { _Pragma("unroll") for (int n = 0; n < 2; ++n) _Pragma("unroll") for (int k = 0; k < 2; ++k) dst[n][k] = *(const PG8_LAS bf16x8*)(lds + PG8_SB(b, h) + boff + n * 2048 + k * 1024); } while (0)
; #define PG8_MMA(ai, bj, At, Bt) do { __builtin_amdgcn_s_setprio(1); _Pragma("unroll") for (int m = 0; m < 4; ++m) _Pragma("unroll") for (int n = 0; n < 2; ++n) _Pragma("unroll") for (int k = 0; k < 2; ++k) \
;         acc[ai][bj][m][n] = __builtin_amdgcn_mfma_f32_16x16x32_bf16(Bt[n][k], At[m][k], acc[ai][bj][m][n], 0, 0, 0); __builtin_amdgcn_s_setprio(0); } while (0)
; #define PG8_WAIT_V(n) asm volatile("s_waitcnt vmcnt(" #n ")" ::: "memory")
; #define PG8_WAIT_L(n) asm volatile("s_waitcnt lgkmcnt(" #n ")" ::: "memory")
; #define PG8_BAR __builtin_amdgcn_s_barrier()
; #define PG8_SCHED __builtin_amdgcn_sched_barrier(0)
; template <class Epi, class Sched, bool ALIGN_EPI = false, bool SP2 = false>
; __device__ __forceinline__ void gemm_phase(PG8_LAS unsigned char* lds, const Gemm g, const Sched& S, const Epi& E) {
;     ...
;             PG8_LDB(B0, 0, 0); PG8_LDB(B1, 0, 1); PG8_SCHED; PG8_LDA(At, 0, 0); PG8_STAGE(PG8_SA(1, 1), a1 + hstep, voffA);
;             PG8_WAIT_V(8); PG8_WAIT_L(0); PG8_BAR; PG8_MMA(0, 0, At, B0); PG8_MMA(0, 1, At, B1); PG8_BAR; PG8_SCHED;
;             PG8_LDA(At, 0, 1); PG8_STAGE(PG8_SB(0, 0), b2, voffB); PG8_STAGE(PG8_SB(0, 1), b2 + hstep, voffB); PG8_STAGE(PG8_SA(0, 0), a2, voffA);
;             PG8_WAIT_V(8); PG8_WAIT_L(0); PG8_BAR; PG8_MMA(1, 0, At, B0); PG8_MMA(1, 1, At, B1); PG8_BAR; PG8_SCHED;
	s_waitcnt lgkmcnt(0)
	v_mfma_f32_16x16x32_bf16 v[124:127], v[144:147], v[192:195], v[124:127]
	v_mfma_f32_16x16x32_bf16 v[120:123], v[168:171], v[192:195], v[120:123]
	v_mfma_f32_16x16x32_bf16 v[108:111], v[144:147], v[200:203], v[108:111]
	v_mfma_f32_16x16x32_bf16 v[104:107], v[168:171], v[200:203], v[104:107]
	v_mfma_f32_16x16x32_bf16 v[92:95], v[144:147], v[208:211], v[92:95]
	v_mfma_f32_16x16x32_bf16 v[88:91], v[168:171], v[208:211], v[88:91]
	v_mfma_f32_16x16x32_bf16 v[76:79], v[144:147], v[216:219], v[76:79]
	v_mfma_f32_16x16x32_bf16 v[72:75], v[168:171], v[216:219], v[72:75]
	v_mfma_f32_16x16x32_bf16 v[124:127], v[164:167], v[196:199], v[124:127]
	v_mfma_f32_16x16x32_bf16 v[120:123], v[172:175], v[196:199], v[120:123]
	v_mfma_f32_16x16x32_bf16 v[108:111], v[164:167], v[204:207], v[108:111]
	v_mfma_f32_16x16x32_bf16 v[104:107], v[172:175], v[204:207], v[104:107]
	v_mfma_f32_16x16x32_bf16 v[92:95], v[164:167], v[212:215], v[92:95]
	v_mfma_f32_16x16x32_bf16 v[88:91], v[172:175], v[212:215], v[88:91]
	v_mfma_f32_16x16x32_bf16 v[76:79], v[164:167], v[220:223], v[76:79]
	v_mfma_f32_16x16x32_bf16 v[72:75], v[172:175], v[220:223], v[72:75]
	v_mfma_f32_16x16x32_bf16 v[116:119], v[176:179], v[192:195], v[116:119]
	v_mfma_f32_16x16x32_bf16 v[112:115], v[184:187], v[192:195], v[112:115]
	v_mfma_f32_16x16x32_bf16 v[100:103], v[176:179], v[200:203], v[100:103]
	v_mfma_f32_16x16x32_bf16 v[96:99], v[184:187], v[200:203], v[96:99]
	v_mfma_f32_16x16x32_bf16 v[84:87], v[176:179], v[208:211], v[84:87]
	v_mfma_f32_16x16x32_bf16 v[80:83], v[184:187], v[208:211], v[80:83]
	v_mfma_f32_16x16x32_bf16 v[68:71], v[176:179], v[216:219], v[68:71]
	v_mfma_f32_16x16x32_bf16 v[64:67], v[184:187], v[216:219], v[64:67]
	v_mfma_f32_16x16x32_bf16 v[116:119], v[180:183], v[196:199], v[116:119]
	v_mfma_f32_16x16x32_bf16 v[112:115], v[188:191], v[196:199], v[112:115]
	v_mfma_f32_16x16x32_bf16 v[100:103], v[180:183], v[204:207], v[100:103]
	v_mfma_f32_16x16x32_bf16 v[96:99], v[188:191], v[204:207], v[96:99]
	v_mfma_f32_16x16x32_bf16 v[84:87], v[180:183], v[212:215], v[84:87]
	v_mfma_f32_16x16x32_bf16 v[80:83], v[188:191], v[212:215], v[80:83]
	v_mfma_f32_16x16x32_bf16 v[68:71], v[180:183], v[220:223], v[68:71]
	v_mfma_f32_16x16x32_bf16 v[64:67], v[188:191], v[220:223], v[64:67]
	s_barrier
	s_add_i32 s65, s59, s3
	v_lshl_add_u64 v[148:149], s[46:47], 0, v[130:131]
	s_mov_b32 m0, s65
	ds_read_b128 v[192:195], v157 offset:16384
	ds_read_b128 v[196:199], v157 offset:17408
	ds_read_b128 v[200:203], v157 offset:18432
	ds_read_b128 v[204:207], v157 offset:19456
	ds_read_b128 v[208:211], v157 offset:20480
	ds_read_b128 v[212:215], v157 offset:21504
	ds_read_b128 v[216:219], v157 offset:22528
	ds_read_b128 v[220:223], v157 offset:23552
	global_load_lds_dwordx4 v[148:149], off
	s_add_i32 m0, s65, 0x2000
	s_add_u32 s66, s46, 0x40000
	v_lshl_add_u64 v[160:161], s[46:47], 0, v[134:135]
	s_addc_u32 s67, s47, 0
	s_add_i32 s65, s60, s3
	global_load_lds_dwordx4 v[160:161], off
	v_lshl_add_u64 v[224:225], s[66:67], 0, v[130:131]
	s_mov_b32 m0, s65
	v_lshl_add_u64 v[226:227], s[48:49], 0, v[132:133]
	global_load_lds_dwordx4 v[224:225], off
	v_lshl_add_u64 v[224:225], s[66:67], 0, v[134:135]
	s_add_i32 m0, s65, 0x2000
	s_nop 0
	global_load_lds_dwordx4 v[224:225], off
	v_lshl_add_u64 v[224:225], s[48:49], 0, v[128:129]
	s_mov_b32 m0, s33
	s_nop 0
	global_load_lds_dwordx4 v[224:225], off
	s_mov_b32 m0, s39
	s_nop 0
	global_load_lds_dwordx4 v[226:227], off
	s_waitcnt vmcnt(8)
	s_waitcnt lgkmcnt(0)
	s_barrier
	s_waitcnt lgkmcnt(0)
	v_mfma_f32_16x16x32_bf16 v[60:63], v[144:147], v[192:195], v[60:63]
	v_mfma_f32_16x16x32_bf16 v[56:59], v[168:171], v[192:195], v[56:59]
	v_mfma_f32_16x16x32_bf16 v[44:47], v[144:147], v[200:203], v[44:47]
	v_mfma_f32_16x16x32_bf16 v[40:43], v[168:171], v[200:203], v[40:43]
	v_mfma_f32_16x16x32_bf16 v[28:31], v[144:147], v[208:211], v[28:31]
	v_mfma_f32_16x16x32_bf16 v[24:27], v[168:171], v[208:211], v[24:27]
	v_mfma_f32_16x16x32_bf16 v[12:15], v[144:147], v[216:219], v[12:15]
	v_mfma_f32_16x16x32_bf16 v[8:11], v[168:171], v[216:219], v[8:11]
	v_mfma_f32_16x16x32_bf16 v[60:63], v[164:167], v[196:199], v[60:63]
	v_mfma_f32_16x16x32_bf16 v[56:59], v[172:175], v[196:199], v[56:59]
	v_mfma_f32_16x16x32_bf16 v[44:47], v[164:167], v[204:207], v[44:47]
	v_mfma_f32_16x16x32_bf16 v[40:43], v[172:175], v[204:207], v[40:43]
	v_mfma_f32_16x16x32_bf16 v[28:31], v[164:167], v[212:215], v[28:31]
	v_mfma_f32_16x16x32_bf16 v[24:27], v[172:175], v[212:215], v[24:27]
	v_mfma_f32_16x16x32_bf16 v[12:15], v[164:167], v[220:223], v[12:15]
	v_mfma_f32_16x16x32_bf16 v[8:11], v[172:175], v[220:223], v[8:11]
	v_mfma_f32_16x16x32_bf16 v[52:55], v[176:179], v[192:195], v[52:55]
	v_mfma_f32_16x16x32_bf16 v[48:51], v[184:187], v[192:195], v[48:51]
	v_mfma_f32_16x16x32_bf16 v[36:39], v[176:179], v[200:203], v[36:39]
	v_mfma_f32_16x16x32_bf16 v[32:35], v[184:187], v[200:203], v[32:35]
	v_mfma_f32_16x16x32_bf16 v[20:23], v[176:179], v[208:211], v[20:23]
	v_mfma_f32_16x16x32_bf16 v[16:19], v[184:187], v[208:211], v[16:19]
	v_mfma_f32_16x16x32_bf16 v[4:7], v[176:179], v[216:219], v[4:7]
	v_mfma_f32_16x16x32_bf16 v[0:3], v[184:187], v[216:219], v[0:3]
	v_mfma_f32_16x16x32_bf16 v[52:55], v[180:183], v[196:199], v[52:55]
	v_mfma_f32_16x16x32_bf16 v[48:51], v[188:191], v[196:199], v[48:51]
	v_mfma_f32_16x16x32_bf16 v[36:39], v[180:183], v[204:207], v[36:39]
	v_mfma_f32_16x16x32_bf16 v[32:35], v[188:191], v[204:207], v[32:35]
	v_mfma_f32_16x16x32_bf16 v[20:23], v[180:183], v[212:215], v[20:23]
	v_mfma_f32_16x16x32_bf16 v[16:19], v[188:191], v[212:215], v[16:19]
	v_mfma_f32_16x16x32_bf16 v[4:7], v[180:183], v[220:223], v[4:7]
	v_mfma_f32_16x16x32_bf16 v[0:3], v[188:191], v[220:223], v[0:3]
	s_barrier
; #define PG8_STAGE(bufoff, gbase, voff) do { _Pragma("unroll") for (int _i = 0; _i < 2; ++_i) \
;         __builtin_amdgcn_global_load_lds((const unsigned*)((const char*)(gbase) + (voff)[_i]), (PG8_LAS unsigned*)(lds + (bufoff) + ldsw + _i * 8192), 16, 0, 0); } while (0)
; #define PG8_LDA(dst, b, h) do { _Pragma("unroll") for (int m = 0; m < 4; ++m) _Pragma("unroll") for (int k = 0; k < 2; ++k) dst[m][k] = *(const PG8_LAS bf16x8*)(lds + PG8_SA(b, h) + aoff + m * 2048 + k * 1024); } while (0)
; #define PG8_LDB(dst, b, h) do { _Pragma("unroll") for (int n = 0; n < 2; ++n) _Pragma("unroll") for (int k = 0; k < 2; ++k) dst[n][k] = *(const PG8_LAS bf16x8*)(lds + PG8_SB(b, h) + boff + n * 2048 + k * 1024); } while (0)
; #define PG8_MMA(ai, bj, At, Bt) do { __builtin_amdgcn_s_setprio(1); _Pragma("unroll") for (int m = 0; m < 4; ++m) _Pragma("unroll") for (int n = 0; n < 2; ++n) _Pragma("unroll") for (int k = 0; k < 2; ++k) \
;         acc[ai][bj][m][n] = __builtin_amdgcn_mfma_f32_16x16x32_bf16(Bt[n][k], At[m][k], acc[ai][bj][m][n], 0, 0, 0); __builtin_amdgcn_s_setprio(0); } while (0)
; #define PG8_WAIT_V(n) asm volatile("s_waitcnt vmcnt(" #n ")" ::: "memory")
; #define PG8_WAIT_L(n) asm volatile("s_waitcnt lgkmcnt(" #n ")" ::: "memory")
; #define PG8_BAR __builtin_amdgcn_s_barrier()
; #define PG8_SCHED __builtin_amdgcn_sched_barrier(0)
; template <class Epi, class Sched, bool ALIGN_EPI = false, bool SP2 = false>
; __device__ __forceinline__ void gemm_phase(PG8_LAS unsigned char* lds, const Gemm g, const Sched& S, const Epi& E) {
;     ...
;         for (int t = 0; t < nt; t += 2) {
;     ...
;             PG8_LDB(B0, 1, 0); PG8_LDB(B1, 1, 1); PG8_SCHED; PG8_LDA(At, 1, 0); PG8_STAGE(PG8_SA(0, 1), a2 + hstep, voffA);
;             PG8_WAIT_V(8); PG8_WAIT_L(0); PG8_BAR; PG8_MMA(0, 0, At, B0); PG8_MMA(0, 1, At, B1); PG8_BAR; PG8_SCHED;
;             PG8_LDA(At, 1, 1); PG8_STAGE(PG8_SB(1, 0), b3, voffB); PG8_STAGE(PG8_SB(1, 1), b3 + hstep, voffB); PG8_STAGE(PG8_SA(1, 0), a3, voffA);
;             PG8_WAIT_V(8); PG8_WAIT_L(0); PG8_BAR; PG8_MMA(1, 0, At, B0); PG8_MMA(1, 1, At, B1); PG8_BAR; PG8_SCHED;
	s_add_i32 s65, 0, 0x18000
	v_add_u32_e32 v159, s65, v152
	s_add_i32 s66, 0, 0x1c000
	ds_read_b128 v[144:147], v159
	ds_read_b128 v[164:167], v159 offset:1024
	ds_read_b128 v[168:171], v159 offset:2048
	ds_read_b128 v[172:175], v159 offset:3072
	v_add_u32_e32 v159, s66, v152
	ds_read_b128 v[176:179], v159
	ds_read_b128 v[180:183], v159 offset:1024
	ds_read_b128 v[184:187], v159 offset:2048
	ds_read_b128 v[188:191], v159 offset:3072
	s_add_u32 s48, s48, 0x40000
	s_addc_u32 s49, s49, 0
	s_mov_b32 m0, s43
	v_lshl_add_u64 v[228:229], s[48:49], 0, v[128:129]
	ds_read_b128 v[192:195], v157 offset:32768
	ds_read_b128 v[196:199], v157 offset:33792
	ds_read_b128 v[200:203], v157 offset:34816
	ds_read_b128 v[204:207], v157 offset:35840
	ds_read_b128 v[208:211], v157 offset:36864
	ds_read_b128 v[212:215], v157 offset:37888
	ds_read_b128 v[216:219], v157 offset:38912
	ds_read_b128 v[220:223], v157 offset:39936
	global_load_lds_dwordx4 v[228:229], off
	v_lshl_add_u64 v[228:229], s[48:49], 0, v[132:133]
	s_mov_b32 m0, s50
	s_nop 0
	global_load_lds_dwordx4 v[228:229], off
	s_waitcnt vmcnt(8)
	s_waitcnt lgkmcnt(0)
	s_barrier
	s_waitcnt lgkmcnt(0)
	v_mfma_f32_16x16x32_bf16 v[124:127], v[144:147], v[192:195], v[124:127]
	v_mfma_f32_16x16x32_bf16 v[120:123], v[168:171], v[192:195], v[120:123]
	v_mfma_f32_16x16x32_bf16 v[108:111], v[144:147], v[200:203], v[108:111]
	v_mfma_f32_16x16x32_bf16 v[104:107], v[168:171], v[200:203], v[104:107]
	v_mfma_f32_16x16x32_bf16 v[92:95], v[144:147], v[208:211], v[92:95]
	v_mfma_f32_16x16x32_bf16 v[88:91], v[168:171], v[208:211], v[88:91]
	v_mfma_f32_16x16x32_bf16 v[76:79], v[144:147], v[216:219], v[76:79]
	v_mfma_f32_16x16x32_bf16 v[72:75], v[168:171], v[216:219], v[72:75]
	v_mfma_f32_16x16x32_bf16 v[124:127], v[164:167], v[196:199], v[124:127]
	v_mfma_f32_16x16x32_bf16 v[120:123], v[172:175], v[196:199], v[120:123]
	v_mfma_f32_16x16x32_bf16 v[108:111], v[164:167], v[204:207], v[108:111]
	v_mfma_f32_16x16x32_bf16 v[104:107], v[172:175], v[204:207], v[104:107]
	v_mfma_f32_16x16x32_bf16 v[92:95], v[164:167], v[212:215], v[92:95]
	v_mfma_f32_16x16x32_bf16 v[88:91], v[172:175], v[212:215], v[88:91]
	v_mfma_f32_16x16x32_bf16 v[76:79], v[164:167], v[220:223], v[76:79]
	v_mfma_f32_16x16x32_bf16 v[72:75], v[172:175], v[220:223], v[72:75]
	v_mfma_f32_16x16x32_bf16 v[116:119], v[176:179], v[192:195], v[116:119]
	v_mfma_f32_16x16x32_bf16 v[112:115], v[184:187], v[192:195], v[112:115]
	v_mfma_f32_16x16x32_bf16 v[100:103], v[176:179], v[200:203], v[100:103]
	v_mfma_f32_16x16x32_bf16 v[96:99], v[184:187], v[200:203], v[96:99]
	v_mfma_f32_16x16x32_bf16 v[84:87], v[176:179], v[208:211], v[84:87]
	v_mfma_f32_16x16x32_bf16 v[80:83], v[184:187], v[208:211], v[80:83]
	v_mfma_f32_16x16x32_bf16 v[68:71], v[176:179], v[216:219], v[68:71]
	v_mfma_f32_16x16x32_bf16 v[64:67], v[184:187], v[216:219], v[64:67]
	v_mfma_f32_16x16x32_bf16 v[116:119], v[180:183], v[196:199], v[116:119]
	v_mfma_f32_16x16x32_bf16 v[112:115], v[188:191], v[196:199], v[112:115]
	v_mfma_f32_16x16x32_bf16 v[100:103], v[180:183], v[204:207], v[100:103]
	v_mfma_f32_16x16x32_bf16 v[96:99], v[188:191], v[204:207], v[96:99]
	v_mfma_f32_16x16x32_bf16 v[84:87], v[180:183], v[212:215], v[84:87]
	v_mfma_f32_16x16x32_bf16 v[80:83], v[188:191], v[212:215], v[80:83]
	v_mfma_f32_16x16x32_bf16 v[68:71], v[180:183], v[220:223], v[68:71]
	v_mfma_f32_16x16x32_bf16 v[64:67], v[188:191], v[220:223], v[64:67]
	s_barrier
	s_add_i32 s48, s65, s3
	v_lshl_add_u64 v[148:149], v[148:149], 0, s[16:17]
	s_mov_b32 m0, s48
	ds_read_b128 v[192:195], v157 offset:49152
	ds_read_b128 v[196:199], v157 offset:50176
	ds_read_b128 v[200:203], v157 offset:51200
	ds_read_b128 v[204:207], v157 offset:52224
	ds_read_b128 v[208:211], v157 offset:53248
	ds_read_b128 v[212:215], v157 offset:54272
	ds_read_b128 v[216:219], v157 offset:55296
	ds_read_b128 v[220:223], v157 offset:56320
	global_load_lds_dwordx4 v[148:149], off
	s_add_i32 m0, s48, 0x2000
	s_add_u32 s46, s46, 0x40080
	v_lshl_add_u64 v[148:149], v[160:161], 0, s[16:17]
	s_addc_u32 s47, s47, 0
	s_add_i32 s48, s66, s3
	global_load_lds_dwordx4 v[148:149], off
	v_lshl_add_u64 v[148:149], s[46:47], 0, v[130:131]
	s_mov_b32 m0, s48
	s_nop 0
	global_load_lds_dwordx4 v[148:149], off
	v_lshl_add_u64 v[148:149], s[46:47], 0, v[134:135]
	s_add_i32 m0, s48, 0x2000
	s_nop 0
	global_load_lds_dwordx4 v[148:149], off
	v_lshl_add_u64 v[148:149], v[224:225], 0, s[16:17]
	s_mov_b32 m0, s55
	s_nop 0
	global_load_lds_dwordx4 v[148:149], off
	v_lshl_add_u64 v[148:149], v[226:227], 0, s[16:17]
	s_mov_b32 m0, s58
	s_nop 0
	global_load_lds_dwordx4 v[148:149], off
	s_waitcnt vmcnt(8)
	s_waitcnt lgkmcnt(0)
	s_barrier
	s_waitcnt lgkmcnt(0)
	v_mfma_f32_16x16x32_bf16 v[60:63], v[144:147], v[192:195], v[60:63]
	v_mfma_f32_16x16x32_bf16 v[56:59], v[168:171], v[192:195], v[56:59]
	v_mfma_f32_16x16x32_bf16 v[44:47], v[144:147], v[200:203], v[44:47]
	v_mfma_f32_16x16x32_bf16 v[40:43], v[168:171], v[200:203], v[40:43]
	v_mfma_f32_16x16x32_bf16 v[28:31], v[144:147], v[208:211], v[28:31]
	v_mfma_f32_16x16x32_bf16 v[24:27], v[168:171], v[208:211], v[24:27]
	v_mfma_f32_16x16x32_bf16 v[12:15], v[144:147], v[216:219], v[12:15]
	v_mfma_f32_16x16x32_bf16 v[8:11], v[168:171], v[216:219], v[8:11]
	v_mfma_f32_16x16x32_bf16 v[60:63], v[164:167], v[196:199], v[60:63]
	v_mfma_f32_16x16x32_bf16 v[56:59], v[172:175], v[196:199], v[56:59]
	v_mfma_f32_16x16x32_bf16 v[44:47], v[164:167], v[204:207], v[44:47]
	v_mfma_f32_16x16x32_bf16 v[40:43], v[172:175], v[204:207], v[40:43]
	v_mfma_f32_16x16x32_bf16 v[28:31], v[164:167], v[212:215], v[28:31]
	v_mfma_f32_16x16x32_bf16 v[24:27], v[172:175], v[212:215], v[24:27]
	v_mfma_f32_16x16x32_bf16 v[12:15], v[164:167], v[220:223], v[12:15]
	v_mfma_f32_16x16x32_bf16 v[8:11], v[172:175], v[220:223], v[8:11]
	v_mfma_f32_16x16x32_bf16 v[52:55], v[176:179], v[192:195], v[52:55]
	v_mfma_f32_16x16x32_bf16 v[48:51], v[184:187], v[192:195], v[48:51]
	v_mfma_f32_16x16x32_bf16 v[36:39], v[176:179], v[200:203], v[36:39]
	v_mfma_f32_16x16x32_bf16 v[32:35], v[184:187], v[200:203], v[32:35]
	v_mfma_f32_16x16x32_bf16 v[20:23], v[176:179], v[208:211], v[20:23]
	v_mfma_f32_16x16x32_bf16 v[16:19], v[184:187], v[208:211], v[16:19]
	v_mfma_f32_16x16x32_bf16 v[4:7], v[176:179], v[216:219], v[4:7]
	v_mfma_f32_16x16x32_bf16 v[0:3], v[184:187], v[216:219], v[0:3]
	v_mfma_f32_16x16x32_bf16 v[52:55], v[180:183], v[196:199], v[52:55]
	v_mfma_f32_16x16x32_bf16 v[48:51], v[188:191], v[196:199], v[48:51]
	v_mfma_f32_16x16x32_bf16 v[36:39], v[180:183], v[204:207], v[36:39]
	v_mfma_f32_16x16x32_bf16 v[32:35], v[188:191], v[204:207], v[32:35]
	v_mfma_f32_16x16x32_bf16 v[20:23], v[180:183], v[212:215], v[20:23]
	v_mfma_f32_16x16x32_bf16 v[16:19], v[188:191], v[212:215], v[16:19]
	v_mfma_f32_16x16x32_bf16 v[4:7], v[180:183], v[220:223], v[4:7]
	v_mfma_f32_16x16x32_bf16 v[0:3], v[188:191], v[220:223], v[0:3]
	s_barrier
	s_add_i32 s64, s64, 2
	s_add_u32 s40, s40, 0x100
	s_addc_u32 s41, s41, 0
	s_add_u32 s62, s62, 0x100
	s_addc_u32 s63, s63, 0
	s_cmp_gt_u32 s64, 13
	s_cbranch_scc0 .LBB0_1263
